# P1 waT copy: 64 loads in flight; gla_out epilogue: 32 GR loads hoisted above the store/load ladder; norm_rows gain loads hoisted out of row loops; gla_cumdecay LDS reads software-pipelined one step ah
# speedup vs baseline: 1.0080x; 1.0080x over previous
; #define LAS __attribute__((address_space(3)))
; __device__ __forceinline__ unsigned pk2(float lo, float hi) { return f2bf(lo) | (f2bf(hi) << 16); }
; __device__ __forceinline__ float wave_sum(float v) { return swap32_sum(red32(v)); }
; __device__ __forceinline__ int opaque(int x) { asm volatile("" : "+v"(x)); return x; }
; template <bool GA, bool XBF = false>
; __device__ __forceinline__ void norm_rows(const float* X, const float* gain, bf16* H, float* GA1, const LAS float* waT, int nrows, int gw, int NGW, int lane_) {
;     const int lane = opaque(lane_);
;     for (int m = gw; m < nrows; m += NGW) {
;         f32x4 v[8]; float s = 0.f;
;         if constexpr (XBF) { const u32x2* xb = (const u32x2*)((const bf16*)X + (size_t)m * DM) + lane;
; #pragma unroll
;             for (int j = 0; j < 8; ++j) { const u32x2 w = xb[64 * j]; v[j] = (f32x4){bflo(w.x), bfhi(w.x), bflo(w.y), bfhi(w.y)}; }
;         } else { const f32x4* xr = (const f32x4*)(X + (size_t)m * DM) + lane;
; #pragma unroll
;             for (int j = 0; j < 8; ++j) v[j] = __builtin_nontemporal_load(xr + 64 * j); }
; #pragma unroll
;         for (int j = 0; j < 8; ++j) s += (v[j].x * v[j].x + v[j].y * v[j].y) + (v[j].z * v[j].z + v[j].w * v[j].w);
;         const float rinv = 1.0f / sqrtf(wave_sum(s) * (1.0f / DM) + EPS);
;         unsigned long long* o8 = (unsigned long long*)(H + (size_t)m * DM) + lane;
; #pragma unroll
;         for (int j = 0; j < 8; ++j) { const f32x4 g = ((const f32x4*)gain)[lane + 64 * j]; v[j] = v[j] * rinv * g;
;             o8[64 * j] = (unsigned long long)pk2(v[j].x, v[j].y) | ((unsigned long long)pk2(v[j].z, v[j].w) << 32); }
.LBB0_50:
	s_or_b64 exec, exec, s[0:1]
	s_waitcnt lgkmcnt(0)
	s_barrier
	v_mov_b32 v2, s77
	ds_read_b64 v[2:3], v2
	v_mov_b32 v4, s77
	ds_read_b64 v[4:5], v4 offset:16
	v_mov_b32_e32 v36, v34
	s_cmpk_gt_i32 s6, 0x3fff
	s_waitcnt lgkmcnt(1)
	v_readfirstlane_b32 s3, v3
	v_readfirstlane_b32 s2, v2
	s_waitcnt lgkmcnt(0)
	v_readfirstlane_b32 s5, v5
	v_readfirstlane_b32 s4, v4
	v_cmp_eq_u32_e64 s[0:1], 32, v205
	s_cbranch_scc1 .LBB0_57
	v_ashrrev_i32_e32 v37, 31, v36
	v_lshlrev_b64 v[2:3], 4, v[36:37]
	v_lshl_add_u64 v[44:45], s[4:5], 0, v[2:3]
	s_mov_b64 s[4:5], 0x1000
	v_lshl_add_u64 v[46:47], v[44:45], 0, s[4:5]
	s_mov_b64 s[4:5], 0x1400
	v_lshl_add_u64 v[38:39], s[2:3], 0, v[2:3]
	v_lshl_add_u64 v[4:5], v[36:37], 3, s[10:11]
	s_mov_b64 s[2:3], 0x9a00000
	v_lshl_add_u64 v[48:49], v[44:45], 0, s[4:5]
	s_mov_b64 s[4:5], 0x1800
	v_lshl_add_u64 v[40:41], v[4:5], 0, s[2:3]
	v_lshl_add_u64 v[4:5], v[36:37], 2, s[10:11]
	s_mov_b64 s[12:13], 0x2da00000
	v_lshl_add_u64 v[50:51], v[44:45], 0, s[4:5]
	s_mov_b64 s[4:5], 0x1c00
	v_lshl_add_u32 v35, v36, 4, 0
	v_cmp_gt_i32_e64 s[2:3], 16, v36
	v_lshl_add_u64 v[42:43], v[4:5], 0, s[12:13]
	v_lshl_add_u64 v[52:53], v[44:45], 0, s[4:5]
	v_mov_b32_e32 v37, 0x358637bd
	s_mov_b32 s7, 0xf800000
	v_mov_b32_e32 v56, 0x260
	s_movk_i32 s9, 0x7fff
	s_mov_b32 s14, 0xffff0000
	s_mov_b32 s12, s6
	global_load_dwordx4 v[208:211], v[44:45], off
	global_load_dwordx4 v[212:215], v[44:45], off offset:1024
	global_load_dwordx4 v[216:219], v[44:45], off offset:2048
	global_load_dwordx4 v[220:223], v[44:45], off offset:3072
	global_load_dwordx4 v[224:227], v[46:47], off
	global_load_dwordx4 v[228:231], v[48:49], off
	global_load_dwordx4 v[232:235], v[50:51], off
	global_load_dwordx4 v[236:239], v[52:53], off
	s_waitcnt vmcnt(0)
	s_branch .LBB0_53

; __device__ __forceinline__ float wave_sum(float v) { return swap32_sum(red32(v)); }
; template <bool GA, bool XBF = false>
; __device__ __forceinline__ void norm_rows(const float* X, const float* gain, bf16* H, float* GA1, const LAS float* waT, int nrows, int gw, int NGW, int lane_) {
;     ...
;     for (int m = gw; m < nrows; m += NGW) {
;         f32x4 v[8]; float s = 0.f;
;         if constexpr (XBF) { const u32x2* xb = (const u32x2*)((const bf16*)X + (size_t)m * DM) + lane;
; #pragma unroll
;             for (int j = 0; j < 8; ++j) { const u32x2 w = xb[64 * j]; v[j] = (f32x4){bflo(w.x), bfhi(w.x), bflo(w.y), bfhi(w.y)}; }
;         } else { const f32x4* xr = (const f32x4*)(X + (size_t)m * DM) + lane;
; #pragma unroll
;             for (int j = 0; j < 8; ++j) v[j] = __builtin_nontemporal_load(xr + 64 * j); }
; #pragma unroll
;         for (int j = 0; j < 8; ++j) s += (v[j].x * v[j].x + v[j].y * v[j].y) + (v[j].z * v[j].z + v[j].w * v[j].w);
;         const float rinv = 1.0f / sqrtf(wave_sum(s) * (1.0f / DM) + EPS);
.LBB0_53:
	s_ashr_i32 s13, s12, 31
	s_lshl_b64 s[4:5], s[12:13], 13
	v_lshl_add_u64 v[2:3], v[38:39], 0, s[4:5]
	global_load_dwordx4 v[30:33], v[2:3], off nt
	global_load_dwordx4 v[26:29], v[2:3], off offset:1024 nt
	global_load_dwordx4 v[22:25], v[2:3], off offset:2048 nt
	global_load_dwordx4 v[18:21], v[2:3], off offset:3072 nt
	v_add_co_u32_e32 v54, vcc, 0x1000, v2
	s_lshl_b64 s[16:17], s[12:13], 12
	s_nop 0
	v_addc_co_u32_e32 v55, vcc, 0, v3, vcc
	global_load_dwordx4 v[14:17], v[54:55], off nt
	global_load_dwordx4 v[10:13], v[54:55], off offset:1024 nt
	global_load_dwordx4 v[2:5], v[54:55], off offset:3072 nt
	global_load_dwordx4 v[6:9], v[54:55], off offset:2048 nt
	v_mov_b32_e32 v58, v208
	v_mov_b32_e32 v59, v209
	v_mov_b32_e32 v60, v210
	v_mov_b32_e32 v61, v211
	s_waitcnt vmcnt(7)
	v_mov_b32_e32 v62, v31
	s_waitcnt vmcnt(6)
	v_mov_b32_e32 v63, v27
	v_mov_b32_e32 v66, v33
	v_mov_b32_e32 v67, v29
	v_mov_b32_e32 v54, v30
	v_mov_b32_e32 v55, v26
	v_mov_b32_e32 v64, v32
	v_mov_b32_e32 v65, v28
	s_waitcnt vmcnt(5)
	v_pk_mul_f32 v[68:69], v[24:25], v[24:25]
	v_pk_mul_f32 v[70:71], v[22:23], v[22:23]
	v_pk_mul_f32 v[62:63], v[62:63], v[62:63]
	v_pk_mul_f32 v[66:67], v[66:67], v[66:67]
	v_pk_mov_b32 v[76:77], v[70:71], v[68:69] op_sel:[1,0]
	v_mov_b32_e32 v71, v69
	v_pk_fma_f32 v[54:55], v[54:55], v[54:55], v[62:63]
	v_pk_fma_f32 v[62:63], v[64:65], v[64:65], v[66:67]
	s_waitcnt vmcnt(4)
	v_mul_f32_e32 v72, v19, v19
	v_mul_f32_e32 v74, v21, v21
	v_pk_add_f32 v[64:65], v[76:77], v[70:71]
	v_pk_add_f32 v[54:55], v[54:55], v[62:63]
	v_pk_fma_f32 v[68:69], v[18:19], v[18:19], v[72:73] op_sel_hi:[1,1,0]
	v_pk_fma_f32 v[72:73], v[20:21], v[20:21], v[74:75] op_sel_hi:[1,1,0]
	s_waitcnt vmcnt(3)
	v_mul_f32_e32 v57, v14, v14
	v_mul_f32_e32 v77, v15, v15
	v_pk_add_f32 v[64:65], v[64:65], v[64:65] op_sel:[0,1] op_sel_hi:[1,0]
	v_pk_add_f32 v[54:55], v[54:55], v[54:55] op_sel:[0,1] op_sel_hi:[1,0]
	v_mul_f32_e32 v69, v16, v16
	v_mul_f32_e32 v73, v17, v17
	s_waitcnt vmcnt(2)
	v_pk_mul_f32 v[66:67], v[12:13], v[12:13]
	v_pk_mul_f32 v[70:71], v[10:11], v[10:11]
	v_mov_b32_e32 v65, v77
	v_mov_b32_e32 v55, v57
	v_pk_mov_b32 v[62:63], v[70:71], v[66:67] op_sel:[1,0]
	v_mov_b32_e32 v71, v67
	v_pk_add_f32 v[68:69], v[68:69], v[72:73]
	v_pk_add_f32 v[54:55], v[54:55], v[64:65]
	s_waitcnt vmcnt(0)
	v_mul_f32_e32 v74, v7, v7
	v_mul_f32_e32 v76, v9, v9
	v_pk_add_f32 v[62:63], v[62:63], v[70:71]
	v_pk_add_f32 v[54:55], v[54:55], v[68:69]
	v_mul_f32_e32 v78, v2, v2
	v_mul_f32_e32 v79, v3, v3
	v_mul_f32_e32 v80, v4, v4
	v_mul_f32_e32 v81, v5, v5
	v_pk_fma_f32 v[66:67], v[6:7], v[6:7], v[74:75] op_sel_hi:[1,1,0]
	v_pk_fma_f32 v[74:75], v[8:9], v[8:9], v[76:77] op_sel_hi:[1,1,0]
	v_pk_add_f32 v[62:63], v[62:63], v[62:63] op_sel:[0,1] op_sel_hi:[1,0]
	v_pk_add_f32 v[54:55], v[54:55], v[54:55] op_sel:[0,1] op_sel_hi:[1,0]
	v_mov_b32_e32 v67, v80
	v_mov_b32_e32 v75, v81
	v_mov_b32_e32 v63, v79
	v_mov_b32_e32 v55, v78
	v_pk_add_f32 v[66:67], v[66:67], v[74:75]
	v_pk_add_f32 v[54:55], v[54:55], v[62:63]
	s_nop 0
	v_pk_add_f32 v[54:55], v[54:55], v[66:67]
	s_nop 0
	v_add_f32_e32 v54, v54, v55
	s_nop 1
	v_add_f32_dpp v54, v54, v54 quad_perm:[1,0,3,2] row_mask:0xf bank_mask:0xf bound_ctrl:1
	s_nop 1
	v_add_f32_dpp v54, v54, v54 quad_perm:[2,3,0,1] row_mask:0xf bank_mask:0xf bound_ctrl:1
	s_nop 1
	v_add_f32_dpp v54, v54, v54 row_half_mirror row_mask:0xf bank_mask:0xf bound_ctrl:1
	s_nop 1
	v_add_f32_dpp v54, v54, v54 row_mirror row_mask:0xf bank_mask:0xf bound_ctrl:1
	ds_swizzle_b32 v55, v54 offset:swizzle(SWAP,16)
	s_waitcnt lgkmcnt(0)
	v_add_f32_e32 v54, v54, v55
	v_mov_b32_e32 v55, v54
	v_mov_b32_e32 v57, v54
	s_nop 1
	v_permlane32_swap_b32_e32 v55, v57
	v_cndmask_b32_e64 v55, v57, v55, s[0:1]
	v_add_f32_e32 v54, v54, v55
	v_fmamk_f32 v54, v54, 0x3a000000, v37
	v_mul_f32_e32 v55, 0x4f800000, v54
	v_cmp_gt_f32_e32 vcc, s7, v54
	s_nop 1
	v_cndmask_b32_e32 v54, v54, v55, vcc
	v_sqrt_f32_e32 v55, v54
	s_nop 0
	v_add_u32_e32 v57, -1, v55
	v_add_u32_e32 v62, 1, v55
	v_fma_f32 v63, -v57, v55, v54
	v_fma_f32 v64, -v62, v55, v54
	v_cmp_ge_f32_e64 s[4:5], 0, v63
	s_nop 1
	v_cndmask_b32_e64 v55, v55, v57, s[4:5]
	v_cmp_lt_f32_e64 s[4:5], 0, v64
	s_nop 1
	v_cndmask_b32_e64 v55, v55, v62, s[4:5]
	v_mul_f32_e32 v57, 0x37800000, v55
	v_cndmask_b32_e32 v55, v55, v57, vcc
	v_cmp_class_f32_e32 vcc, v54, v56
	s_nop 1
	v_cndmask_b32_e32 v57, v55, v54, vcc
	v_div_scale_f32 v62, s[4:5], v57, v57, 1.0
	v_rcp_f32_e32 v63, v62
	v_div_scale_f32 v64, vcc, 1.0, v57, 1.0
	v_lshl_add_u64 v[54:55], v[40:41], 0, s[16:17]
	v_fma_f32 v65, -v62, v63, 1.0
	v_fmac_f32_e32 v63, v65, v63
	v_mul_f32_e32 v65, v64, v63
	v_fma_f32 v66, -v62, v65, v64
	v_fmac_f32_e32 v65, v66, v63
	v_fma_f32 v62, -v62, v65, v64
	v_div_fmas_f32 v62, v62, v63, v65
	v_div_fixup_f32 v62, v62, v57, 1.0
	v_pk_mul_f32 v[30:31], v[30:31], v[62:63] op_sel_hi:[1,0]
	v_pk_mul_f32 v[32:33], v[32:33], v[62:63] op_sel_hi:[1,0]
	s_waitcnt vmcnt(0)
; __device__ __forceinline__ unsigned pk2(float lo, float hi) { return f2bf(lo) | (f2bf(hi) << 16); }
; template <bool GA, bool XBF = false>
; __device__ __forceinline__ void norm_rows(const float* X, const float* gain, bf16* H, float* GA1, const LAS float* waT, int nrows, int gw, int NGW, int lane_) {
;     ...
;         unsigned long long* o8 = (unsigned long long*)(H + (size_t)m * DM) + lane;
; #pragma unroll
;         for (int j = 0; j < 8; ++j) { const f32x4 g = ((const f32x4*)gain)[lane + 64 * j]; v[j] = v[j] * rinv * g;
;             o8[64 * j] = (unsigned long long)pk2(v[j].x, v[j].y) | ((unsigned long long)pk2(v[j].z, v[j].w) << 32); }
	v_pk_mul_f32 v[66:67], v[58:59], v[30:31]
	v_pk_mul_f32 v[64:65], v[60:61], v[32:33]
	v_bfe_u32 v30, v66, 16, 1
	v_bfe_u32 v32, v64, 16, 1
	v_bfe_u32 v31, v67, 16, 1
	v_bfe_u32 v33, v65, 16, 1
	v_add3_u32 v30, v66, v30, s9
	v_add3_u32 v32, v64, v32, s9
	v_add3_u32 v31, v67, v31, s9
	v_add3_u32 v33, v65, v33, s9
	v_lshrrev_b32_e32 v30, 16, v30
	v_lshrrev_b32_e32 v32, 16, v32
	v_and_or_b32 v30, v31, s14, v30
	v_and_or_b32 v31, v33, s14, v32
	global_store_dwordx2 v[54:55], v[30:31], off
	v_mov_b32_e32 v30, v212
	v_mov_b32_e32 v31, v213
	v_mov_b32_e32 v32, v214
	v_mov_b32_e32 v33, v215
	v_pk_mul_f32 v[58:59], v[26:27], v[62:63] op_sel_hi:[1,0]
	v_pk_mul_f32 v[26:27], v[28:29], v[62:63] op_sel_hi:[1,0]
	v_pk_mul_f32 v[24:25], v[24:25], v[62:63] op_sel_hi:[1,0]
	v_pk_mul_f32 v[22:23], v[22:23], v[62:63] op_sel_hi:[1,0]
	v_pk_mul_f32 v[20:21], v[20:21], v[62:63] op_sel_hi:[1,0]
	v_pk_mul_f32 v[18:19], v[18:19], v[62:63] op_sel_hi:[1,0]
	v_pk_mul_f32 v[12:13], v[12:13], v[62:63] op_sel_hi:[1,0]
	v_pk_mul_f32 v[10:11], v[10:11], v[62:63] op_sel_hi:[1,0]
	v_pk_mul_f32 v[8:9], v[8:9], v[62:63] op_sel_hi:[1,0]
	v_pk_mul_f32 v[6:7], v[6:7], v[62:63] op_sel_hi:[1,0]
	s_mov_b32 s4, 0
	v_mov_b32_e32 v57, 0
	v_pk_mul_f32 v[26:27], v[32:33], v[26:27]
	v_pk_mul_f32 v[28:29], v[30:31], v[58:59]
	v_bfe_u32 v32, v26, 16, 1
	v_bfe_u32 v30, v28, 16, 1
	v_bfe_u32 v31, v29, 16, 1
	v_bfe_u32 v33, v27, 16, 1
	v_add3_u32 v30, v28, v30, s9
	v_add3_u32 v32, v26, v32, s9
	v_add3_u32 v31, v29, v31, s9
	v_add3_u32 v33, v27, v33, s9
	v_lshrrev_b32_e32 v30, 16, v30
	v_lshrrev_b32_e32 v32, 16, v32
	v_and_or_b32 v30, v31, s14, v30
	v_and_or_b32 v31, v33, s14, v32
	global_store_dwordx2 v[54:55], v[30:31], off offset:512
	v_mov_b32_e32 v30, v216
	v_mov_b32_e32 v31, v217
	v_mov_b32_e32 v32, v218
	v_mov_b32_e32 v33, v219
	v_pk_mul_f32 v[58:59], v[14:15], v[62:63] op_sel_hi:[1,0]
	v_pk_mul_f32 v[14:15], v[16:17], v[62:63] op_sel_hi:[1,0]
	v_pk_mul_f32 v[22:23], v[30:31], v[22:23]
	v_pk_mul_f32 v[24:25], v[32:33], v[24:25]
	v_bfe_u32 v30, v22, 16, 1
	v_bfe_u32 v32, v24, 16, 1
	v_bfe_u32 v31, v23, 16, 1
	v_bfe_u32 v33, v25, 16, 1
	v_add3_u32 v30, v22, v30, s9
	v_add3_u32 v32, v24, v32, s9
	v_add3_u32 v31, v23, v31, s9
	v_add3_u32 v33, v25, v33, s9
	v_lshrrev_b32_e32 v30, 16, v30
	v_lshrrev_b32_e32 v32, 16, v32
	v_and_or_b32 v30, v31, s14, v30
	v_and_or_b32 v31, v33, s14, v32
	global_store_dwordx2 v[54:55], v[30:31], off offset:1024
	v_mov_b32_e32 v30, v220
	v_mov_b32_e32 v31, v221
	v_mov_b32_e32 v32, v222
	v_mov_b32_e32 v33, v223
	v_pk_mul_f32 v[18:19], v[30:31], v[18:19]
	v_pk_mul_f32 v[20:21], v[32:33], v[20:21]
	v_bfe_u32 v30, v18, 16, 1
	v_bfe_u32 v32, v20, 16, 1
	v_bfe_u32 v31, v19, 16, 1
	v_bfe_u32 v33, v21, 16, 1
	v_add3_u32 v30, v18, v30, s9
	v_add3_u32 v32, v20, v32, s9
	v_add3_u32 v31, v19, v31, s9
	v_add3_u32 v33, v21, v33, s9
	v_lshrrev_b32_e32 v30, 16, v30
	v_lshrrev_b32_e32 v32, 16, v32
	v_and_or_b32 v30, v31, s14, v30
	v_and_or_b32 v31, v33, s14, v32
	global_store_dwordx2 v[54:55], v[30:31], off offset:1536
	v_mov_b32_e32 v30, v224
	v_mov_b32_e32 v31, v225
	v_mov_b32_e32 v32, v226
	v_mov_b32_e32 v33, v227
	v_pk_mul_f32 v[14:15], v[32:33], v[14:15]
	v_pk_mul_f32 v[16:17], v[30:31], v[58:59]
	v_bfe_u32 v32, v14, 16, 1
	v_bfe_u32 v30, v16, 16, 1
	v_bfe_u32 v31, v17, 16, 1
	v_bfe_u32 v33, v15, 16, 1
	v_add3_u32 v30, v16, v30, s9
	v_add3_u32 v32, v14, v32, s9
	v_add3_u32 v31, v17, v31, s9
	v_add3_u32 v33, v15, v33, s9
	v_lshrrev_b32_e32 v30, 16, v30
	v_lshrrev_b32_e32 v32, 16, v32
	v_and_or_b32 v30, v31, s14, v30
	v_and_or_b32 v31, v33, s14, v32
	global_store_dwordx2 v[54:55], v[30:31], off offset:2048
	v_mov_b32_e32 v30, v228
	v_mov_b32_e32 v31, v229
	v_mov_b32_e32 v32, v230
	v_mov_b32_e32 v33, v231
	v_pk_mul_f32 v[10:11], v[30:31], v[10:11]
	v_pk_mul_f32 v[12:13], v[32:33], v[12:13]
	v_bfe_u32 v30, v10, 16, 1
	v_bfe_u32 v32, v12, 16, 1
	v_bfe_u32 v31, v11, 16, 1
	v_bfe_u32 v33, v13, 16, 1
	v_add3_u32 v30, v10, v30, s9
	v_add3_u32 v32, v12, v32, s9
	v_add3_u32 v31, v11, v31, s9
	v_add3_u32 v33, v13, v33, s9
	v_lshrrev_b32_e32 v30, 16, v30
	v_lshrrev_b32_e32 v32, 16, v32
	v_and_or_b32 v30, v31, s14, v30
	v_and_or_b32 v31, v33, s14, v32
	global_store_dwordx2 v[54:55], v[30:31], off offset:2560
	v_mov_b32_e32 v30, v232
	v_mov_b32_e32 v31, v233
	v_mov_b32_e32 v32, v234
	v_mov_b32_e32 v33, v235
	v_pk_mul_f32 v[6:7], v[6:7], v[30:31]
	v_pk_mul_f32 v[8:9], v[8:9], v[32:33]
	v_bfe_u32 v30, v6, 16, 1
	v_bfe_u32 v32, v8, 16, 1
	v_bfe_u32 v31, v7, 16, 1
	v_bfe_u32 v33, v9, 16, 1
	v_add3_u32 v30, v6, v30, s9
	v_add3_u32 v32, v8, v32, s9
	v_add3_u32 v31, v7, v31, s9
	v_add3_u32 v33, v9, v33, s9
	v_lshrrev_b32_e32 v30, 16, v30
	v_lshrrev_b32_e32 v32, 16, v32
	v_and_or_b32 v30, v31, s14, v30
	v_and_or_b32 v31, v33, s14, v32
	global_store_dwordx2 v[54:55], v[30:31], off offset:3072
	v_mov_b32_e32 v58, v236
	v_mov_b32_e32 v59, v237
	v_mov_b32_e32 v60, v238
	v_mov_b32_e32 v61, v239
	v_pk_mul_f32 v[32:33], v[2:3], v[62:63] op_sel_hi:[1,0]
	v_pk_mul_f32 v[30:31], v[4:5], v[62:63] op_sel_hi:[1,0]
	v_mov_b32_e32 v2, v66
	v_mov_b32_e32 v4, v64
	v_mov_b32_e32 v3, v28
	v_mov_b32_e32 v5, v26
	v_mov_b32_e32 v28, v67
	v_mov_b32_e32 v26, v65
	v_pk_mul_f32 v[30:31], v[30:31], v[60:61]
	v_pk_mul_f32 v[32:33], v[32:33], v[58:59]
	v_bfe_u32 v60, v30, 16, 1
	v_bfe_u32 v58, v32, 16, 1
	v_bfe_u32 v59, v33, 16, 1
	v_bfe_u32 v61, v31, 16, 1
	v_add3_u32 v58, v32, v58, s9
	v_add3_u32 v60, v30, v60, s9
	v_add3_u32 v59, v33, v59, s9
	v_add3_u32 v61, v31, v61, s9
	v_lshrrev_b32_e32 v58, 16, v58
	v_lshrrev_b32_e32 v60, 16, v60
	v_and_or_b32 v58, v59, s14, v58
	v_and_or_b32 v59, v61, s14, v60
	global_store_dwordx2 v[54:55], v[58:59], off offset:3584
	v_mov_b32_e32 v54, v35

; #define LAS __attribute__((address_space(3)))
; #define TID() (wv0 * 64 + (int)__builtin_amdgcn_mbcnt_hi(~0u, __builtin_amdgcn_mbcnt_lo(~0u, 0u)))
; __device__ __forceinline__ int opaque(int x) { asm volatile("" : "+v"(x)); return x; }
;     __device__ __forceinline__ const float* in(int k) const { return (const float*)(const __attribute__((address_space(1))) float*)get(k); }
;     __device__ __forceinline__ unsigned char* ws() const { return (unsigned char*)(__attribute__((address_space(1))) unsigned char*)get(21); }
; __device__ __forceinline__ void gla_cumdecay(const Ptrs& A, int l, int n, int hd, LAS float* bl, const int wv0) {
;     const int tid = opaque(TID()), d = tid & 127, tq = __builtin_amdgcn_readfirstlane(tid >> 7);
;     const float* wa2 = A.in(4) + (size_t)l * 16 * 512 + hd * 128 + d;
;     float w[16];
; #pragma unroll
;     for (int r = 0; r < 16; ++r) w[r] = wa2[r * 512];
;     const float bias = A.in(5)[(size_t)l * 512 + hd * 128 + d];
;     LAS float* gal = bl + 29184;
;     *(LAS f32x2*)(gal + 2 * tid) = *(const f32x2*)((const float*)(A.ws() + WS_GA1) + (size_t)n * 64 * 16 + 2 * tid);
;     __syncthreads();
;     const LAS float* ga = gal + 16 * tq * 16;
;     float run = 0.f;
;     for (int tt = 0; tt < 16; ++tt) {
;         float pre = bias;
;         const f32x4 g0 = *(const LAS f32x4*)(ga + tt * 16), g1 = *(const LAS f32x4*)(ga + tt * 16 + 4), g2 = *(const LAS f32x4*)(ga + tt * 16 + 8), g3 = *(const LAS f32x4*)(ga + tt * 16 + 12);
;         pre += (g0.x * w[0] + g0.y * w[1]) + (g0.z * w[2] + g0.w * w[3]); pre += (g1.x * w[4] + g1.y * w[5]) + (g1.z * w[6] + g1.w * w[7]);
;         pre += (g2.x * w[8] + g2.y * w[9]) + (g2.z * w[10] + g2.w * w[11]); pre += (g3.x * w[12] + g3.y * w[13]) + (g3.z * w[14] + g3.w * w[15]);
;         const float la = (fminf(pre, 0.f) - __logf(1.0f + __expf(-fabsf(pre)))) * (1.0f / 16.0f);
;         run += la; bl[(16 * tq + tt) * BLS + d] = run;
; __device__ __forceinline__ void gla_state(const Ptrs& A, int l, LAS unsigned char* lds, int c, int G, int wave, int lane_, const int wv0) {
;     ...
;         for (int i = 0; i < 2; ++i) kk[i] = *(const u32x4*)(GK + (size_t)(t0 + lane) * 512 + hd * 128 + (wave + 8 * i) * 8);
.LBB0_211:
	s_ashr_i32 s2, s6, 2
	s_lshl_b32 s20, s2, 6
	v_or_b32_e32 v0, s20, v64
	v_ashrrev_i32_e32 v1, 31, v0
	s_and_b32 s3, s6, 3
	v_lshlrev_b64 v[0:1], 10, v[0:1]
	v_lshl_add_u64 v[0:1], s[12:13], 0, v[0:1]
	s_lshl_b32 s8, s3, 8
	v_lshl_add_u64 v[0:1], v[0:1], 0, s[8:9]
	v_lshl_add_u64 v[8:9], s[14:15], 1, v[0:1]
	v_mov_b32_e32 v34, v204
	global_load_dwordx4 v[4:7], v[8:9], off
	global_load_dwordx4 v[0:3], v[8:9], off offset:128
	v_mov_b32 v8, s77
	ds_read_b64 v[8:9], v8 offset:32
	s_lshl_b32 s8, s3, 9
	v_readfirstlane_b32 s3, v34
	s_waitcnt lgkmcnt(0)
	v_readfirstlane_b32 s47, v8
	v_readfirstlane_b32 s21, v9
	s_add_u32 s48, s47, s8
	v_lshlrev_b32_e32 v8, 2, v34
	s_addc_u32 s49, s21, 0
	v_and_b32_e32 v48, 0x1fc, v8
	v_lshl_add_u64 v[18:19], s[48:49], 0, v[48:49]
	v_add_co_u32_e32 v26, vcc, s5, v18
	s_ashr_i32 s21, s3, 7
	s_nop 0
	v_addc_co_u32_e32 v27, vcc, 0, v19, vcc
	v_add_co_u32_e32 v20, vcc, s7, v18
	s_nop 1
	v_addc_co_u32_e32 v21, vcc, 0, v19, vcc
	v_add_co_u32_e32 v28, vcc, s28, v18
	s_nop 1
	v_addc_co_u32_e32 v29, vcc, 0, v19, vcc
	v_add_co_u32_e32 v10, vcc, s29, v18
	s_nop 1
	v_addc_co_u32_e32 v11, vcc, 0, v19, vcc
	v_add_co_u32_e32 v30, vcc, s30, v18
	s_nop 1
	v_addc_co_u32_e32 v31, vcc, 0, v19, vcc
	v_add_co_u32_e32 v22, vcc, s31, v18
	s_nop 1
	v_addc_co_u32_e32 v23, vcc, 0, v19, vcc
	v_add_co_u32_e32 v32, vcc, s34, v18
	global_load_dword v14, v[20:21], off
	global_load_dword v16, v[20:21], off offset:2048
	global_load_dword v13, v[10:11], off offset:-4096
	global_load_dword v9, v[10:11], off
	global_load_dword v12, v[10:11], off offset:2048
	s_nop 0
	global_load_dword v10, v[22:23], off offset:-4096
	global_load_dword v8, v[22:23], off
	global_load_dword v11, v[22:23], off offset:2048
	v_addc_co_u32_e32 v33, vcc, 0, v19, vcc
	global_load_dword v22, v48, s[48:49]
	global_load_dword v24, v48, s[48:49] offset:2048
	s_nop 0
	global_load_dword v21, v[20:21], off offset:-4096
	s_nop 0
	global_load_dword v23, v[26:27], off offset:2048
	global_load_dword v20, v[28:29], off offset:2048
	global_load_dword v18, v[30:31], off offset:2048
	global_load_dword v15, v[32:33], off
	global_load_dword v17, v[32:33], off offset:2048
	v_mov_b32 v19, s77
	ds_read_b64 v[26:27], v19 offset:40
	s_waitcnt lgkmcnt(0)
	v_readfirstlane_b32 s47, v26
	v_readfirstlane_b32 s3, v27
	s_add_u32 s48, s47, s8
	s_addc_u32 s49, s3, 0
	global_load_dword v25, v48, s[48:49]
	v_mov_b32 v19, s77
	ds_read_b64 v[26:27], v19 offset:168
	s_ashr_i32 s3, s2, 31
	s_lshl_b64 s[2:3], s[2:3], 12
	v_lshl_add_u32 v19, v34, 3, s36
	s_waitcnt lgkmcnt(0)
	v_readfirstlane_b32 s48, v26
	v_readfirstlane_b32 s47, v27
	s_add_u32 s2, s48, s2
	v_lshlrev_b32_e32 v26, 1, v34
	s_addc_u32 s3, s47, s3
	v_ashrrev_i32_e32 v27, 31, v26
	v_lshl_add_u64 v[26:27], v[26:27], 2, s[2:3]
	v_add_co_u32_e32 v26, vcc, s35, v26
	s_lshl_b32 s2, s21, 10
	s_nop 0
	v_addc_co_u32_e32 v27, vcc, 0, v27, vcc
	global_load_dwordx2 v[28:29], v[26:27], off
	s_add_i32 s2, s36, s2
	v_mov_b32_e32 v27, s2
	s_mul_i32 s2, s21, 0x2100
	s_cmp_gt_i32 s21, 0
	s_waitcnt vmcnt(0)
	ds_write_b64 v19, v[28:29]
	s_waitcnt lgkmcnt(0)
	s_barrier
	ds_read_b128 v[28:31], v27
	ds_read_b128 v[32:35], v27 offset:16
	ds_read_b128 v[36:39], v27 offset:32
	ds_read_b128 v[40:43], v27 offset:48
	s_waitcnt lgkmcnt(3)
	v_mul_f32_e32 v19, v24, v29
	v_mul_f32_e32 v26, v23, v31
	s_waitcnt lgkmcnt(2)
	v_mul_f32_e32 v29, v16, v33
	v_mul_f32_e32 v31, v20, v35
	v_fmac_f32_e32 v19, v22, v28
	v_fmac_f32_e32 v26, v21, v30
	s_waitcnt lgkmcnt(1)
	v_mul_f32_e32 v33, v12, v37
	v_mul_f32_e32 v35, v18, v39
	v_fmac_f32_e32 v29, v14, v32
	v_fmac_f32_e32 v31, v13, v34
	v_add_f32_e32 v19, v19, v26
	s_waitcnt lgkmcnt(0)
	ds_read_b128 v[166:169], v27 offset:64
	ds_read_b128 v[170:173], v27 offset:80
	ds_read_b128 v[174:177], v27 offset:96
	ds_read_b128 v[178:181], v27 offset:112
	v_mul_f32_e32 v37, v11, v41
	v_mul_f32_e32 v39, v17, v43
	v_fmac_f32_e32 v33, v9, v36
	v_fmac_f32_e32 v35, v10, v38
	v_add_f32_e32 v26, v29, v31
	v_add_f32_e32 v19, v25, v19
	v_fmac_f32_e32 v37, v8, v40
	v_fmac_f32_e32 v39, v15, v42
	v_add_f32_e32 v28, v33, v35
	v_add_f32_e32 v19, v19, v26
	v_add_f32_e32 v29, v37, v39
	v_add_f32_e32 v19, v19, v28
	v_add_f32_e32 v28, v19, v29
	v_mul_f32_e64 v19, |v28|, s37
	v_exp_f32_e32 v19, v19
	v_min_f32_e32 v28, 0, v28
	v_add_u32_e32 v26, 0, v48
	v_add_f32_e32 v19, 1.0, v19
	v_cmp_gt_f32_e32 vcc, s38, v19
	s_nop 1
	v_cndmask_b32_e64 v29, 0, 32, vcc
	v_ldexp_f32 v19, v19, v29
	v_log_f32_e32 v29, v19
	v_cndmask_b32_e32 v30, 0, v69, vcc
	v_add_u32_e32 v19, s2, v26
	v_mul_f32_e32 v31, 0x3f317217, v29
	v_fma_f32 v31, v29, s39, -v31
	v_fmac_f32_e32 v31, 0x3377d1cf, v29
	v_fmac_f32_e32 v31, 0x3f317217, v29
	v_cmp_lt_f32_e64 vcc, |v29|, s40
	s_nop 1
	v_cndmask_b32_e32 v29, v29, v31, vcc
	v_sub_f32_e32 v29, v29, v30
	v_sub_f32_e32 v28, v28, v29
	v_fma_f32 v28, v28, s41, 0
	ds_write_b32 v19, v28
	s_waitcnt lgkmcnt(3)
	v_mul_f32_e32 v29, v24, v167
	v_mul_f32_e32 v31, v23, v169
	v_fmac_f32_e32 v29, v22, v166
	v_fmac_f32_e32 v31, v21, v168
	v_add_f32_e32 v29, v29, v31
	s_waitcnt lgkmcnt(2)
	v_mul_f32_e32 v30, v16, v171
	v_mul_f32_e32 v31, v20, v173
	v_fmac_f32_e32 v30, v14, v170
	v_fmac_f32_e32 v31, v13, v172
	v_add_f32_e32 v29, v25, v29
	v_add_f32_e32 v30, v30, v31
	v_add_f32_e32 v29, v29, v30
	s_waitcnt lgkmcnt(1)
	v_mul_f32_e32 v30, v12, v175
	v_mul_f32_e32 v31, v18, v177
	v_fmac_f32_e32 v30, v9, v174
	v_fmac_f32_e32 v31, v10, v176
	v_add_f32_e32 v30, v30, v31
	v_add_f32_e32 v29, v29, v30
	s_waitcnt lgkmcnt(0)
; #define LAS __attribute__((address_space(3)))
; __device__ __forceinline__ void gla_cumdecay(const Ptrs& A, int l, int n, int hd, LAS float* bl, const int wv0) {
;     ...
;     for (int tt = 0; tt < 16; ++tt) {
;         float pre = bias;
;         const f32x4 g0 = *(const LAS f32x4*)(ga + tt * 16), g1 = *(const LAS f32x4*)(ga + tt * 16 + 4), g2 = *(const LAS f32x4*)(ga + tt * 16 + 8), g3 = *(const LAS f32x4*)(ga + tt * 16 + 12);
;         pre += (g0.x * w[0] + g0.y * w[1]) + (g0.z * w[2] + g0.w * w[3]); pre += (g1.x * w[4] + g1.y * w[5]) + (g1.z * w[6] + g1.w * w[7]);
;         pre += (g2.x * w[8] + g2.y * w[9]) + (g2.z * w[10] + g2.w * w[11]); pre += (g3.x * w[12] + g3.y * w[13]) + (g3.z * w[14] + g3.w * w[15]);
;         const float la = (fminf(pre, 0.f) - __logf(1.0f + __expf(-fabsf(pre)))) * (1.0f / 16.0f);
;         run += la; bl[(16 * tq + tt) * BLS + d] = run;
	ds_read_b128 v[150:153], v27 offset:128
	ds_read_b128 v[154:157], v27 offset:144
	ds_read_b128 v[158:161], v27 offset:160
	ds_read_b128 v[162:165], v27 offset:176
	v_mul_f32_e32 v30, v11, v179
	v_mul_f32_e32 v31, v17, v181
	v_fmac_f32_e32 v30, v8, v178
	v_fmac_f32_e32 v31, v15, v180
	v_add_f32_e32 v30, v30, v31
	v_add_f32_e32 v29, v29, v30
	v_mul_f32_e64 v30, |v29|, s37
	v_exp_f32_e32 v30, v30
	v_min_f32_e32 v29, 0, v29
	v_add_f32_e32 v30, 1.0, v30
	v_cmp_gt_f32_e32 vcc, s38, v30
	s_nop 1
	v_cndmask_b32_e64 v31, 0, 32, vcc
	v_ldexp_f32 v30, v30, v31
	v_log_f32_e32 v30, v30
	s_nop 0
	v_mul_f32_e32 v31, 0x3f317217, v30
	v_fma_f32 v31, v30, s39, -v31
	v_fmac_f32_e32 v31, 0x3377d1cf, v30
	v_fmac_f32_e32 v31, 0x3f317217, v30
	v_cmp_lt_f32_e64 s[2:3], |v30|, s40
	s_nop 1
	v_cndmask_b32_e64 v30, v30, v31, s[2:3]
	v_cndmask_b32_e32 v31, 0, v69, vcc
	v_sub_f32_e32 v30, v30, v31
	v_sub_f32_e32 v29, v29, v30
	v_fmac_f32_e32 v28, 0x3d800000, v29
	ds_write_b32 v19, v28 offset:528
	s_waitcnt lgkmcnt(3)
	v_mul_f32_e32 v29, v24, v151
	v_fmac_f32_e32 v29, v22, v150
	v_mul_f32_e32 v30, v23, v153
	v_fmac_f32_e32 v30, v21, v152
	v_add_f32_e32 v29, v29, v30
	s_waitcnt lgkmcnt(2)
	v_mul_f32_e32 v30, v16, v155
	v_mul_f32_e32 v31, v20, v157
	v_fmac_f32_e32 v30, v14, v154
	v_fmac_f32_e32 v31, v13, v156
	v_add_f32_e32 v29, v25, v29
	v_add_f32_e32 v30, v30, v31
	v_add_f32_e32 v29, v29, v30
	s_waitcnt lgkmcnt(1)
	v_mul_f32_e32 v30, v12, v159
	v_mul_f32_e32 v31, v18, v161
	v_fmac_f32_e32 v30, v9, v158
	v_fmac_f32_e32 v31, v10, v160
	v_add_f32_e32 v30, v30, v31
	v_add_f32_e32 v29, v29, v30
	s_waitcnt lgkmcnt(0)
	ds_read_b128 v[166:169], v27 offset:192
	ds_read_b128 v[170:173], v27 offset:208
	ds_read_b128 v[174:177], v27 offset:224
	ds_read_b128 v[178:181], v27 offset:240
	v_mul_f32_e32 v30, v11, v163
	v_mul_f32_e32 v31, v17, v165
	v_fmac_f32_e32 v30, v8, v162
	v_fmac_f32_e32 v31, v15, v164
	v_add_f32_e32 v30, v30, v31
	v_add_f32_e32 v29, v29, v30
	v_mul_f32_e64 v30, |v29|, s37
	v_exp_f32_e32 v30, v30
	v_min_f32_e32 v29, 0, v29
	v_add_f32_e32 v30, 1.0, v30
	v_cmp_gt_f32_e32 vcc, s38, v30
	s_nop 1
	v_cndmask_b32_e64 v31, 0, 32, vcc
	v_ldexp_f32 v30, v30, v31
	v_log_f32_e32 v30, v30
	s_nop 0
	v_mul_f32_e32 v31, 0x3f317217, v30
	v_fma_f32 v31, v30, s39, -v31
	v_fmac_f32_e32 v31, 0x3377d1cf, v30
	v_fmac_f32_e32 v31, 0x3f317217, v30
	v_cmp_lt_f32_e64 s[2:3], |v30|, s40
	s_nop 1
	v_cndmask_b32_e64 v30, v30, v31, s[2:3]
	v_cndmask_b32_e32 v31, 0, v69, vcc
	v_sub_f32_e32 v30, v30, v31
	v_sub_f32_e32 v29, v29, v30
	v_fmac_f32_e32 v28, 0x3d800000, v29
	ds_write_b32 v19, v28 offset:1056
	s_waitcnt lgkmcnt(3)
	v_mul_f32_e32 v29, v24, v167
	v_fmac_f32_e32 v29, v22, v166
	v_mul_f32_e32 v30, v23, v169
	v_fmac_f32_e32 v30, v21, v168
	v_add_f32_e32 v29, v29, v30
	s_waitcnt lgkmcnt(2)
	v_mul_f32_e32 v30, v16, v171
	v_mul_f32_e32 v31, v20, v173
	v_fmac_f32_e32 v30, v14, v170
	v_fmac_f32_e32 v31, v13, v172
	v_add_f32_e32 v29, v25, v29
	v_add_f32_e32 v30, v30, v31
	v_add_f32_e32 v29, v29, v30
	s_waitcnt lgkmcnt(1)
	v_mul_f32_e32 v30, v12, v175
	v_mul_f32_e32 v31, v18, v177
	v_fmac_f32_e32 v30, v9, v174
	v_fmac_f32_e32 v31, v10, v176
	v_add_f32_e32 v30, v30, v31
	v_add_f32_e32 v29, v29, v30
	s_waitcnt lgkmcnt(0)
	ds_read_b128 v[150:153], v27 offset:256
	ds_read_b128 v[154:157], v27 offset:272
	ds_read_b128 v[158:161], v27 offset:288
	ds_read_b128 v[162:165], v27 offset:304
	v_mul_f32_e32 v30, v11, v179
	v_mul_f32_e32 v31, v17, v181
	v_fmac_f32_e32 v30, v8, v178
	v_fmac_f32_e32 v31, v15, v180
	v_add_f32_e32 v30, v30, v31
	v_add_f32_e32 v29, v29, v30
	v_mul_f32_e64 v30, |v29|, s37
	v_exp_f32_e32 v30, v30
	v_min_f32_e32 v29, 0, v29
	v_add_f32_e32 v30, 1.0, v30
	v_cmp_gt_f32_e32 vcc, s38, v30
	s_nop 1
	v_cndmask_b32_e64 v31, 0, 32, vcc
	v_ldexp_f32 v30, v30, v31
	v_log_f32_e32 v30, v30
	s_nop 0
	v_mul_f32_e32 v31, 0x3f317217, v30
	v_fma_f32 v31, v30, s39, -v31
	v_fmac_f32_e32 v31, 0x3377d1cf, v30
	v_fmac_f32_e32 v31, 0x3f317217, v30
	v_cmp_lt_f32_e64 s[2:3], |v30|, s40
	s_nop 1
	v_cndmask_b32_e64 v30, v30, v31, s[2:3]
	v_cndmask_b32_e32 v31, 0, v69, vcc
	v_sub_f32_e32 v30, v30, v31
	v_sub_f32_e32 v29, v29, v30
	v_fmac_f32_e32 v28, 0x3d800000, v29
	ds_write_b32 v19, v28 offset:1584
	s_waitcnt lgkmcnt(3)
	v_mul_f32_e32 v29, v24, v151
	v_fmac_f32_e32 v29, v22, v150
	v_mul_f32_e32 v30, v23, v153
	v_fmac_f32_e32 v30, v21, v152
	v_add_f32_e32 v29, v29, v30
	s_waitcnt lgkmcnt(2)
	v_mul_f32_e32 v30, v16, v155
	v_mul_f32_e32 v31, v20, v157
	v_fmac_f32_e32 v30, v14, v154
	v_fmac_f32_e32 v31, v13, v156
	v_add_f32_e32 v29, v25, v29
	v_add_f32_e32 v30, v30, v31
	v_add_f32_e32 v29, v29, v30
	s_waitcnt lgkmcnt(1)
	v_mul_f32_e32 v30, v12, v159
	v_mul_f32_e32 v31, v18, v161
	v_fmac_f32_e32 v30, v9, v158
	v_fmac_f32_e32 v31, v10, v160
	v_add_f32_e32 v30, v30, v31
	v_add_f32_e32 v29, v29, v30
	s_waitcnt lgkmcnt(0)
	ds_read_b128 v[166:169], v27 offset:320
	ds_read_b128 v[170:173], v27 offset:336
	ds_read_b128 v[174:177], v27 offset:352
	ds_read_b128 v[178:181], v27 offset:368
	v_mul_f32_e32 v30, v11, v163
	v_mul_f32_e32 v31, v17, v165
	v_fmac_f32_e32 v30, v8, v162
	v_fmac_f32_e32 v31, v15, v164
	v_add_f32_e32 v30, v30, v31
	v_add_f32_e32 v29, v29, v30
	v_mul_f32_e64 v30, |v29|, s37
	v_exp_f32_e32 v30, v30
	v_min_f32_e32 v29, 0, v29
	v_add_f32_e32 v30, 1.0, v30
	v_cmp_gt_f32_e32 vcc, s38, v30
	s_nop 1
	v_cndmask_b32_e64 v31, 0, 32, vcc
	v_ldexp_f32 v30, v30, v31
	v_log_f32_e32 v30, v30
	s_nop 0
	v_mul_f32_e32 v31, 0x3f317217, v30
	v_fma_f32 v31, v30, s39, -v31
	v_fmac_f32_e32 v31, 0x3377d1cf, v30
	v_fmac_f32_e32 v31, 0x3f317217, v30
	v_cmp_lt_f32_e64 s[2:3], |v30|, s40
	s_nop 1
	v_cndmask_b32_e64 v30, v30, v31, s[2:3]
	v_cndmask_b32_e32 v31, 0, v69, vcc
	v_sub_f32_e32 v30, v30, v31
	v_sub_f32_e32 v29, v29, v30
	v_fmac_f32_e32 v28, 0x3d800000, v29
	ds_write_b32 v19, v28 offset:2112
	s_waitcnt lgkmcnt(3)
; #define LAS __attribute__((address_space(3)))
; __device__ __forceinline__ void gla_cumdecay(const Ptrs& A, int l, int n, int hd, LAS float* bl, const int wv0) {
;     ...
;     for (int tt = 0; tt < 16; ++tt) {
;         float pre = bias;
;         const f32x4 g0 = *(const LAS f32x4*)(ga + tt * 16), g1 = *(const LAS f32x4*)(ga + tt * 16 + 4), g2 = *(const LAS f32x4*)(ga + tt * 16 + 8), g3 = *(const LAS f32x4*)(ga + tt * 16 + 12);
;         pre += (g0.x * w[0] + g0.y * w[1]) + (g0.z * w[2] + g0.w * w[3]); pre += (g1.x * w[4] + g1.y * w[5]) + (g1.z * w[6] + g1.w * w[7]);
;         pre += (g2.x * w[8] + g2.y * w[9]) + (g2.z * w[10] + g2.w * w[11]); pre += (g3.x * w[12] + g3.y * w[13]) + (g3.z * w[14] + g3.w * w[15]);
;         const float la = (fminf(pre, 0.f) - __logf(1.0f + __expf(-fabsf(pre)))) * (1.0f / 16.0f);
;         run += la; bl[(16 * tq + tt) * BLS + d] = run;
	v_mul_f32_e32 v29, v24, v167
	v_fmac_f32_e32 v29, v22, v166
	v_mul_f32_e32 v30, v23, v169
	v_fmac_f32_e32 v30, v21, v168
	v_add_f32_e32 v29, v29, v30
	s_waitcnt lgkmcnt(2)
	v_mul_f32_e32 v30, v16, v171
	v_mul_f32_e32 v31, v20, v173
	v_fmac_f32_e32 v30, v14, v170
	v_fmac_f32_e32 v31, v13, v172
	v_add_f32_e32 v29, v25, v29
	v_add_f32_e32 v30, v30, v31
	v_add_f32_e32 v29, v29, v30
	s_waitcnt lgkmcnt(1)
	v_mul_f32_e32 v30, v12, v175
	v_mul_f32_e32 v31, v18, v177
	v_fmac_f32_e32 v30, v9, v174
	v_fmac_f32_e32 v31, v10, v176
	v_add_f32_e32 v30, v30, v31
	v_add_f32_e32 v29, v29, v30
	s_waitcnt lgkmcnt(0)
	ds_read_b128 v[150:153], v27 offset:384
	ds_read_b128 v[154:157], v27 offset:400
	ds_read_b128 v[158:161], v27 offset:416
	ds_read_b128 v[162:165], v27 offset:432
	v_mul_f32_e32 v30, v11, v179
	v_mul_f32_e32 v31, v17, v181
	v_fmac_f32_e32 v30, v8, v178
	v_fmac_f32_e32 v31, v15, v180
	v_add_f32_e32 v30, v30, v31
	v_add_f32_e32 v29, v29, v30
	v_mul_f32_e64 v30, |v29|, s37
	v_exp_f32_e32 v30, v30
	v_min_f32_e32 v29, 0, v29
	v_add_f32_e32 v30, 1.0, v30
	v_cmp_gt_f32_e32 vcc, s38, v30
	s_nop 1
	v_cndmask_b32_e64 v31, 0, 32, vcc
	v_ldexp_f32 v30, v30, v31
	v_log_f32_e32 v30, v30
	s_nop 0
	v_mul_f32_e32 v31, 0x3f317217, v30
	v_fma_f32 v31, v30, s39, -v31
	v_fmac_f32_e32 v31, 0x3377d1cf, v30
	v_fmac_f32_e32 v31, 0x3f317217, v30
	v_cmp_lt_f32_e64 s[2:3], |v30|, s40
	s_nop 1
	v_cndmask_b32_e64 v30, v30, v31, s[2:3]
	v_cndmask_b32_e32 v31, 0, v69, vcc
	v_sub_f32_e32 v30, v30, v31
	v_sub_f32_e32 v29, v29, v30
	v_fmac_f32_e32 v28, 0x3d800000, v29
	ds_write_b32 v19, v28 offset:2640
	s_waitcnt lgkmcnt(3)
	v_mul_f32_e32 v29, v24, v151
	v_fmac_f32_e32 v29, v22, v150
	v_mul_f32_e32 v30, v23, v153
	v_fmac_f32_e32 v30, v21, v152
	v_add_f32_e32 v29, v29, v30
	s_waitcnt lgkmcnt(2)
	v_mul_f32_e32 v30, v16, v155
	v_mul_f32_e32 v31, v20, v157
	v_fmac_f32_e32 v30, v14, v154
	v_fmac_f32_e32 v31, v13, v156
	v_add_f32_e32 v29, v25, v29
	v_add_f32_e32 v30, v30, v31
	v_add_f32_e32 v29, v29, v30
	s_waitcnt lgkmcnt(1)
	v_mul_f32_e32 v30, v12, v159
	v_mul_f32_e32 v31, v18, v161
	v_fmac_f32_e32 v30, v9, v158
	v_fmac_f32_e32 v31, v10, v160
	v_add_f32_e32 v30, v30, v31
	v_add_f32_e32 v29, v29, v30
	s_waitcnt lgkmcnt(0)
	ds_read_b128 v[166:169], v27 offset:448
	ds_read_b128 v[170:173], v27 offset:464
	ds_read_b128 v[174:177], v27 offset:480
	ds_read_b128 v[178:181], v27 offset:496
	v_mul_f32_e32 v30, v11, v163
	v_mul_f32_e32 v31, v17, v165
	v_fmac_f32_e32 v30, v8, v162
	v_fmac_f32_e32 v31, v15, v164
	v_add_f32_e32 v30, v30, v31
	v_add_f32_e32 v29, v29, v30
	v_mul_f32_e64 v30, |v29|, s37
	v_exp_f32_e32 v30, v30
	v_min_f32_e32 v29, 0, v29
	v_add_f32_e32 v30, 1.0, v30
	v_cmp_gt_f32_e32 vcc, s38, v30
	s_nop 1
	v_cndmask_b32_e64 v31, 0, 32, vcc
	v_ldexp_f32 v30, v30, v31
	v_log_f32_e32 v30, v30
	s_nop 0
	v_mul_f32_e32 v31, 0x3f317217, v30
	v_fma_f32 v31, v30, s39, -v31
	v_fmac_f32_e32 v31, 0x3377d1cf, v30
	v_fmac_f32_e32 v31, 0x3f317217, v30
	v_cmp_lt_f32_e64 s[2:3], |v30|, s40
	s_nop 1
	v_cndmask_b32_e64 v30, v30, v31, s[2:3]
	v_cndmask_b32_e32 v31, 0, v69, vcc
	v_sub_f32_e32 v30, v30, v31
	v_sub_f32_e32 v29, v29, v30
	v_fmac_f32_e32 v28, 0x3d800000, v29
	ds_write_b32 v19, v28 offset:3168
	s_waitcnt lgkmcnt(3)
	v_mul_f32_e32 v29, v24, v167
	v_fmac_f32_e32 v29, v22, v166
	v_mul_f32_e32 v30, v23, v169
	v_fmac_f32_e32 v30, v21, v168
	v_add_f32_e32 v29, v29, v30
	s_waitcnt lgkmcnt(2)
	v_mul_f32_e32 v30, v16, v171
	v_mul_f32_e32 v31, v20, v173
	v_fmac_f32_e32 v30, v14, v170
	v_fmac_f32_e32 v31, v13, v172
	v_add_f32_e32 v29, v25, v29
	v_add_f32_e32 v30, v30, v31
	v_add_f32_e32 v29, v29, v30
	s_waitcnt lgkmcnt(1)
	v_mul_f32_e32 v30, v12, v175
	v_mul_f32_e32 v31, v18, v177
	v_fmac_f32_e32 v30, v9, v174
	v_fmac_f32_e32 v31, v10, v176
	v_add_f32_e32 v30, v30, v31
	v_add_f32_e32 v29, v29, v30
	s_waitcnt lgkmcnt(0)
	ds_read_b128 v[150:153], v27 offset:512
	ds_read_b128 v[154:157], v27 offset:528
	ds_read_b128 v[158:161], v27 offset:544
	ds_read_b128 v[162:165], v27 offset:560
	v_mul_f32_e32 v30, v11, v179
	v_mul_f32_e32 v31, v17, v181
	v_fmac_f32_e32 v30, v8, v178
	v_fmac_f32_e32 v31, v15, v180
	v_add_f32_e32 v30, v30, v31
	v_add_f32_e32 v29, v29, v30
	v_mul_f32_e64 v30, |v29|, s37
	v_exp_f32_e32 v30, v30
	v_min_f32_e32 v29, 0, v29
	v_add_f32_e32 v30, 1.0, v30
	v_cmp_gt_f32_e32 vcc, s38, v30
	s_nop 1
	v_cndmask_b32_e64 v31, 0, 32, vcc
	v_ldexp_f32 v30, v30, v31
	v_log_f32_e32 v30, v30
	s_nop 0
	v_mul_f32_e32 v31, 0x3f317217, v30
	v_fma_f32 v31, v30, s39, -v31
	v_fmac_f32_e32 v31, 0x3377d1cf, v30
	v_fmac_f32_e32 v31, 0x3f317217, v30
	v_cmp_lt_f32_e64 s[2:3], |v30|, s40
	s_nop 1
	v_cndmask_b32_e64 v30, v30, v31, s[2:3]
	v_cndmask_b32_e32 v31, 0, v69, vcc
	v_sub_f32_e32 v30, v30, v31
	v_sub_f32_e32 v29, v29, v30
	v_fmac_f32_e32 v28, 0x3d800000, v29
	ds_write_b32 v19, v28 offset:3696
	s_waitcnt lgkmcnt(3)
	v_mul_f32_e32 v29, v24, v151
	v_fmac_f32_e32 v29, v22, v150
	v_mul_f32_e32 v30, v23, v153
	v_fmac_f32_e32 v30, v21, v152
	v_add_f32_e32 v29, v29, v30
	s_waitcnt lgkmcnt(2)
	v_mul_f32_e32 v30, v16, v155
	v_mul_f32_e32 v31, v20, v157
	v_fmac_f32_e32 v30, v14, v154
	v_fmac_f32_e32 v31, v13, v156
	v_add_f32_e32 v29, v25, v29
	v_add_f32_e32 v30, v30, v31
	v_add_f32_e32 v29, v29, v30
	s_waitcnt lgkmcnt(1)
	v_mul_f32_e32 v30, v12, v159
	v_mul_f32_e32 v31, v18, v161
	v_fmac_f32_e32 v30, v9, v158
	v_fmac_f32_e32 v31, v10, v160
	v_add_f32_e32 v30, v30, v31
	v_add_f32_e32 v29, v29, v30
	s_waitcnt lgkmcnt(0)
; #define LAS __attribute__((address_space(3)))
; __device__ __forceinline__ void gla_cumdecay(const Ptrs& A, int l, int n, int hd, LAS float* bl, const int wv0) {
;     ...
;     for (int tt = 0; tt < 16; ++tt) {
;         float pre = bias;
;         const f32x4 g0 = *(const LAS f32x4*)(ga + tt * 16), g1 = *(const LAS f32x4*)(ga + tt * 16 + 4), g2 = *(const LAS f32x4*)(ga + tt * 16 + 8), g3 = *(const LAS f32x4*)(ga + tt * 16 + 12);
;         pre += (g0.x * w[0] + g0.y * w[1]) + (g0.z * w[2] + g0.w * w[3]); pre += (g1.x * w[4] + g1.y * w[5]) + (g1.z * w[6] + g1.w * w[7]);
;         pre += (g2.x * w[8] + g2.y * w[9]) + (g2.z * w[10] + g2.w * w[11]); pre += (g3.x * w[12] + g3.y * w[13]) + (g3.z * w[14] + g3.w * w[15]);
;         const float la = (fminf(pre, 0.f) - __logf(1.0f + __expf(-fabsf(pre)))) * (1.0f / 16.0f);
;         run += la; bl[(16 * tq + tt) * BLS + d] = run;
	ds_read_b128 v[166:169], v27 offset:576
	ds_read_b128 v[170:173], v27 offset:592
	ds_read_b128 v[174:177], v27 offset:608
	ds_read_b128 v[178:181], v27 offset:624
	v_mul_f32_e32 v30, v11, v163
	v_mul_f32_e32 v31, v17, v165
	v_fmac_f32_e32 v30, v8, v162
	v_fmac_f32_e32 v31, v15, v164
	v_add_f32_e32 v30, v30, v31
	v_add_f32_e32 v29, v29, v30
	v_mul_f32_e64 v30, |v29|, s37
	v_exp_f32_e32 v30, v30
	v_min_f32_e32 v29, 0, v29
	v_add_f32_e32 v30, 1.0, v30
	v_cmp_gt_f32_e32 vcc, s38, v30
	s_nop 1
	v_cndmask_b32_e64 v31, 0, 32, vcc
	v_ldexp_f32 v30, v30, v31
	v_log_f32_e32 v30, v30
	s_nop 0
	v_mul_f32_e32 v31, 0x3f317217, v30
	v_fma_f32 v31, v30, s39, -v31
	v_fmac_f32_e32 v31, 0x3377d1cf, v30
	v_fmac_f32_e32 v31, 0x3f317217, v30
	v_cmp_lt_f32_e64 s[2:3], |v30|, s40
	s_nop 1
	v_cndmask_b32_e64 v30, v30, v31, s[2:3]
	v_cndmask_b32_e32 v31, 0, v69, vcc
	v_sub_f32_e32 v30, v30, v31
	v_sub_f32_e32 v29, v29, v30
	v_fmac_f32_e32 v28, 0x3d800000, v29
	ds_write_b32 v19, v28 offset:4224
	s_waitcnt lgkmcnt(3)
	v_mul_f32_e32 v29, v24, v167
	v_fmac_f32_e32 v29, v22, v166
	v_mul_f32_e32 v30, v23, v169
	v_fmac_f32_e32 v30, v21, v168
	v_add_f32_e32 v29, v29, v30
	s_waitcnt lgkmcnt(2)
	v_mul_f32_e32 v30, v16, v171
	v_mul_f32_e32 v31, v20, v173
	v_fmac_f32_e32 v30, v14, v170
	v_fmac_f32_e32 v31, v13, v172
	v_add_f32_e32 v29, v25, v29
	v_add_f32_e32 v30, v30, v31
	v_add_f32_e32 v29, v29, v30
	s_waitcnt lgkmcnt(1)
	v_mul_f32_e32 v30, v12, v175
	v_mul_f32_e32 v31, v18, v177
	v_fmac_f32_e32 v30, v9, v174
	v_fmac_f32_e32 v31, v10, v176
	v_add_f32_e32 v30, v30, v31
	v_add_f32_e32 v29, v29, v30
	s_waitcnt lgkmcnt(0)
	ds_read_b128 v[150:153], v27 offset:640
	ds_read_b128 v[154:157], v27 offset:656
	ds_read_b128 v[158:161], v27 offset:672
	ds_read_b128 v[162:165], v27 offset:688
	v_mul_f32_e32 v30, v11, v179
	v_mul_f32_e32 v31, v17, v181
	v_fmac_f32_e32 v30, v8, v178
	v_fmac_f32_e32 v31, v15, v180
	v_add_f32_e32 v30, v30, v31
	v_add_f32_e32 v29, v29, v30
	v_mul_f32_e64 v30, |v29|, s37
	v_exp_f32_e32 v30, v30
	v_min_f32_e32 v29, 0, v29
	v_add_f32_e32 v30, 1.0, v30
	v_cmp_gt_f32_e32 vcc, s38, v30
	s_nop 1
	v_cndmask_b32_e64 v31, 0, 32, vcc
	v_ldexp_f32 v30, v30, v31
	v_log_f32_e32 v30, v30
	s_nop 0
	v_mul_f32_e32 v31, 0x3f317217, v30
	v_fma_f32 v31, v30, s39, -v31
	v_fmac_f32_e32 v31, 0x3377d1cf, v30
	v_fmac_f32_e32 v31, 0x3f317217, v30
	v_cmp_lt_f32_e64 s[2:3], |v30|, s40
	s_nop 1
	v_cndmask_b32_e64 v30, v30, v31, s[2:3]
	v_cndmask_b32_e32 v31, 0, v69, vcc
	v_sub_f32_e32 v30, v30, v31
	v_sub_f32_e32 v29, v29, v30
	v_fmac_f32_e32 v28, 0x3d800000, v29
	ds_write_b32 v19, v28 offset:4752
	s_waitcnt lgkmcnt(3)
	v_mul_f32_e32 v29, v24, v151
	v_fmac_f32_e32 v29, v22, v150
	v_mul_f32_e32 v30, v23, v153
	v_fmac_f32_e32 v30, v21, v152
	v_add_f32_e32 v29, v29, v30
	s_waitcnt lgkmcnt(2)
	v_mul_f32_e32 v30, v16, v155
	v_mul_f32_e32 v31, v20, v157
	v_fmac_f32_e32 v30, v14, v154
	v_fmac_f32_e32 v31, v13, v156
	v_add_f32_e32 v29, v25, v29
	v_add_f32_e32 v30, v30, v31
	v_add_f32_e32 v29, v29, v30
	s_waitcnt lgkmcnt(1)
	v_mul_f32_e32 v30, v12, v159
	v_mul_f32_e32 v31, v18, v161
	v_fmac_f32_e32 v30, v9, v158
	v_fmac_f32_e32 v31, v10, v160
	v_add_f32_e32 v30, v30, v31
	v_add_f32_e32 v29, v29, v30
	s_waitcnt lgkmcnt(0)
	ds_read_b128 v[166:169], v27 offset:704
	ds_read_b128 v[170:173], v27 offset:720
	ds_read_b128 v[174:177], v27 offset:736
	ds_read_b128 v[178:181], v27 offset:752
	v_mul_f32_e32 v30, v11, v163
	v_mul_f32_e32 v31, v17, v165
	v_fmac_f32_e32 v30, v8, v162
	v_fmac_f32_e32 v31, v15, v164
	v_add_f32_e32 v30, v30, v31
	v_add_f32_e32 v29, v29, v30
	v_mul_f32_e64 v30, |v29|, s37
	v_exp_f32_e32 v30, v30
	v_min_f32_e32 v29, 0, v29
	v_add_f32_e32 v30, 1.0, v30
	v_cmp_gt_f32_e32 vcc, s38, v30
	s_nop 1
	v_cndmask_b32_e64 v31, 0, 32, vcc
	v_ldexp_f32 v30, v30, v31
	v_log_f32_e32 v30, v30
	s_nop 0
	v_mul_f32_e32 v31, 0x3f317217, v30
	v_fma_f32 v31, v30, s39, -v31
	v_fmac_f32_e32 v31, 0x3377d1cf, v30
	v_fmac_f32_e32 v31, 0x3f317217, v30
	v_cmp_lt_f32_e64 s[2:3], |v30|, s40
	s_nop 1
	v_cndmask_b32_e64 v30, v30, v31, s[2:3]
	v_cndmask_b32_e32 v31, 0, v69, vcc
	v_sub_f32_e32 v30, v30, v31
	v_sub_f32_e32 v29, v29, v30
	v_fmac_f32_e32 v28, 0x3d800000, v29
	ds_write_b32 v19, v28 offset:5280
	s_waitcnt lgkmcnt(3)
	v_mul_f32_e32 v29, v24, v167
	v_fmac_f32_e32 v29, v22, v166
	v_mul_f32_e32 v30, v23, v169
	v_fmac_f32_e32 v30, v21, v168
	v_add_f32_e32 v29, v29, v30
	s_waitcnt lgkmcnt(2)
	v_mul_f32_e32 v30, v16, v171
	v_mul_f32_e32 v31, v20, v173
	v_fmac_f32_e32 v30, v14, v170
	v_fmac_f32_e32 v31, v13, v172
	v_add_f32_e32 v29, v25, v29
	v_add_f32_e32 v30, v30, v31
	v_add_f32_e32 v29, v29, v30
	s_waitcnt lgkmcnt(1)
	v_mul_f32_e32 v30, v12, v175
	v_mul_f32_e32 v31, v18, v177
	v_fmac_f32_e32 v30, v9, v174
	v_fmac_f32_e32 v31, v10, v176
	v_add_f32_e32 v30, v30, v31
	v_add_f32_e32 v29, v29, v30
	s_waitcnt lgkmcnt(0)
	ds_read_b128 v[150:153], v27 offset:768
	ds_read_b128 v[154:157], v27 offset:784
	ds_read_b128 v[158:161], v27 offset:800
	ds_read_b128 v[162:165], v27 offset:816
	v_mul_f32_e32 v30, v11, v179
	v_mul_f32_e32 v31, v17, v181
	v_fmac_f32_e32 v30, v8, v178
	v_fmac_f32_e32 v31, v15, v180
	v_add_f32_e32 v30, v30, v31
	v_add_f32_e32 v29, v29, v30
	v_mul_f32_e64 v30, |v29|, s37
	v_exp_f32_e32 v30, v30
	v_min_f32_e32 v29, 0, v29
	v_add_f32_e32 v30, 1.0, v30
	v_cmp_gt_f32_e32 vcc, s38, v30
	s_nop 1
	v_cndmask_b32_e64 v31, 0, 32, vcc
	v_ldexp_f32 v30, v30, v31
	v_log_f32_e32 v30, v30
	s_nop 0
	v_mul_f32_e32 v31, 0x3f317217, v30
	v_fma_f32 v31, v30, s39, -v31
	v_fmac_f32_e32 v31, 0x3377d1cf, v30
	v_fmac_f32_e32 v31, 0x3f317217, v30
	v_cmp_lt_f32_e64 s[2:3], |v30|, s40
	s_nop 1
	v_cndmask_b32_e64 v30, v30, v31, s[2:3]
	v_cndmask_b32_e32 v31, 0, v69, vcc
	v_sub_f32_e32 v30, v30, v31
	v_sub_f32_e32 v29, v29, v30
	v_fmac_f32_e32 v28, 0x3d800000, v29
	ds_write_b32 v19, v28 offset:5808
	s_waitcnt lgkmcnt(3)
; #define LAS __attribute__((address_space(3)))
; __device__ __forceinline__ void gla_cumdecay(const Ptrs& A, int l, int n, int hd, LAS float* bl, const int wv0) {
;     ...
;     for (int tt = 0; tt < 16; ++tt) {
;         float pre = bias;
;         const f32x4 g0 = *(const LAS f32x4*)(ga + tt * 16), g1 = *(const LAS f32x4*)(ga + tt * 16 + 4), g2 = *(const LAS f32x4*)(ga + tt * 16 + 8), g3 = *(const LAS f32x4*)(ga + tt * 16 + 12);
;         pre += (g0.x * w[0] + g0.y * w[1]) + (g0.z * w[2] + g0.w * w[3]); pre += (g1.x * w[4] + g1.y * w[5]) + (g1.z * w[6] + g1.w * w[7]);
;         pre += (g2.x * w[8] + g2.y * w[9]) + (g2.z * w[10] + g2.w * w[11]); pre += (g3.x * w[12] + g3.y * w[13]) + (g3.z * w[14] + g3.w * w[15]);
;         const float la = (fminf(pre, 0.f) - __logf(1.0f + __expf(-fabsf(pre)))) * (1.0f / 16.0f);
;         run += la; bl[(16 * tq + tt) * BLS + d] = run;
;     }
;     __syncthreads();
;     float add = 0.f;
; #pragma unroll
;     for (int q = 0; q < 3; ++q) if (q < tq) add += bl[(16 * q + 15) * BLS + d];
	v_mul_f32_e32 v29, v24, v151
	v_fmac_f32_e32 v29, v22, v150
	v_mul_f32_e32 v30, v23, v153
	v_fmac_f32_e32 v30, v21, v152
	v_add_f32_e32 v29, v29, v30
	s_waitcnt lgkmcnt(2)
	v_mul_f32_e32 v30, v16, v155
	v_mul_f32_e32 v31, v20, v157
	v_fmac_f32_e32 v30, v14, v154
	v_fmac_f32_e32 v31, v13, v156
	v_add_f32_e32 v29, v25, v29
	v_add_f32_e32 v30, v30, v31
	v_add_f32_e32 v29, v29, v30
	s_waitcnt lgkmcnt(1)
	v_mul_f32_e32 v30, v12, v159
	v_mul_f32_e32 v31, v18, v161
	v_fmac_f32_e32 v30, v9, v158
	v_fmac_f32_e32 v31, v10, v160
	v_add_f32_e32 v30, v30, v31
	v_add_f32_e32 v29, v29, v30
	s_waitcnt lgkmcnt(0)
	ds_read_b128 v[166:169], v27 offset:832
	ds_read_b128 v[170:173], v27 offset:848
	ds_read_b128 v[174:177], v27 offset:864
	ds_read_b128 v[178:181], v27 offset:880
	v_mul_f32_e32 v30, v11, v163
	v_mul_f32_e32 v31, v17, v165
	v_fmac_f32_e32 v30, v8, v162
	v_fmac_f32_e32 v31, v15, v164
	v_add_f32_e32 v30, v30, v31
	v_add_f32_e32 v29, v29, v30
	v_mul_f32_e64 v30, |v29|, s37
	v_exp_f32_e32 v30, v30
	v_min_f32_e32 v29, 0, v29
	v_add_f32_e32 v30, 1.0, v30
	v_cmp_gt_f32_e32 vcc, s38, v30
	s_nop 1
	v_cndmask_b32_e64 v31, 0, 32, vcc
	v_ldexp_f32 v30, v30, v31
	v_log_f32_e32 v30, v30
	s_nop 0
	v_mul_f32_e32 v31, 0x3f317217, v30
	v_fma_f32 v31, v30, s39, -v31
	v_fmac_f32_e32 v31, 0x3377d1cf, v30
	v_fmac_f32_e32 v31, 0x3f317217, v30
	v_cmp_lt_f32_e64 s[2:3], |v30|, s40
	s_nop 1
	v_cndmask_b32_e64 v30, v30, v31, s[2:3]
	v_cndmask_b32_e32 v31, 0, v69, vcc
	v_sub_f32_e32 v30, v30, v31
	v_sub_f32_e32 v29, v29, v30
	v_fmac_f32_e32 v28, 0x3d800000, v29
	ds_write_b32 v19, v28 offset:6336
	s_waitcnt lgkmcnt(3)
	v_mul_f32_e32 v29, v24, v167
	v_fmac_f32_e32 v29, v22, v166
	v_mul_f32_e32 v30, v23, v169
	v_fmac_f32_e32 v30, v21, v168
	v_add_f32_e32 v29, v29, v30
	s_waitcnt lgkmcnt(2)
	v_mul_f32_e32 v30, v16, v171
	v_mul_f32_e32 v31, v20, v173
	v_fmac_f32_e32 v30, v14, v170
	v_fmac_f32_e32 v31, v13, v172
	v_add_f32_e32 v29, v25, v29
	v_add_f32_e32 v30, v30, v31
	v_add_f32_e32 v29, v29, v30
	s_waitcnt lgkmcnt(1)
	v_mul_f32_e32 v30, v12, v175
	v_mul_f32_e32 v31, v18, v177
	v_fmac_f32_e32 v30, v9, v174
	v_fmac_f32_e32 v31, v10, v176
	v_add_f32_e32 v30, v30, v31
	v_add_f32_e32 v29, v29, v30
	s_waitcnt lgkmcnt(0)
	ds_read_b128 v[150:153], v27 offset:896
	ds_read_b128 v[154:157], v27 offset:912
	ds_read_b128 v[158:161], v27 offset:928
	ds_read_b128 v[162:165], v27 offset:944
	v_mul_f32_e32 v30, v11, v179
	v_mul_f32_e32 v31, v17, v181
	v_fmac_f32_e32 v30, v8, v178
	v_fmac_f32_e32 v31, v15, v180
	v_add_f32_e32 v30, v30, v31
	v_add_f32_e32 v29, v29, v30
	v_mul_f32_e64 v30, |v29|, s37
	v_exp_f32_e32 v30, v30
	v_min_f32_e32 v29, 0, v29
	v_add_f32_e32 v30, 1.0, v30
	v_cmp_gt_f32_e32 vcc, s38, v30
	s_nop 1
	v_cndmask_b32_e64 v31, 0, 32, vcc
	v_ldexp_f32 v30, v30, v31
	v_log_f32_e32 v30, v30
	s_nop 0
	v_mul_f32_e32 v31, 0x3f317217, v30
	v_fma_f32 v31, v30, s39, -v31
	v_fmac_f32_e32 v31, 0x3377d1cf, v30
	v_fmac_f32_e32 v31, 0x3f317217, v30
	v_cmp_lt_f32_e64 s[2:3], |v30|, s40
	s_nop 1
	v_cndmask_b32_e64 v30, v30, v31, s[2:3]
	v_cndmask_b32_e32 v31, 0, v69, vcc
	v_sub_f32_e32 v30, v30, v31
	v_sub_f32_e32 v29, v29, v30
	v_fmac_f32_e32 v28, 0x3d800000, v29
	ds_write_b32 v19, v28 offset:6864
	s_waitcnt lgkmcnt(3)
	v_mul_f32_e32 v29, v24, v151
	v_fmac_f32_e32 v29, v22, v150
	v_mul_f32_e32 v30, v23, v153
	v_fmac_f32_e32 v30, v21, v152
	v_add_f32_e32 v29, v29, v30
	s_waitcnt lgkmcnt(2)
	v_mul_f32_e32 v30, v16, v155
	v_mul_f32_e32 v31, v20, v157
	v_fmac_f32_e32 v30, v14, v154
	v_fmac_f32_e32 v31, v13, v156
	v_add_f32_e32 v29, v25, v29
	v_add_f32_e32 v30, v30, v31
	v_add_f32_e32 v29, v29, v30
	s_waitcnt lgkmcnt(1)
	v_mul_f32_e32 v30, v12, v159
	v_mul_f32_e32 v31, v18, v161
	v_fmac_f32_e32 v30, v9, v158
	v_fmac_f32_e32 v31, v10, v160
	v_add_f32_e32 v30, v30, v31
	v_add_f32_e32 v29, v29, v30
	s_waitcnt lgkmcnt(0)
	ds_read_b128 v[166:169], v27 offset:960
	ds_read_b128 v[170:173], v27 offset:976
	ds_read_b128 v[174:177], v27 offset:992
	ds_read_b128 v[178:181], v27 offset:1008
	v_mul_f32_e32 v30, v11, v163
	v_mul_f32_e32 v31, v17, v165
	v_fmac_f32_e32 v30, v8, v162
	v_fmac_f32_e32 v31, v15, v164
	v_add_f32_e32 v30, v30, v31
	v_add_f32_e32 v29, v29, v30
	v_mul_f32_e64 v30, |v29|, s37
	v_exp_f32_e32 v30, v30
	v_min_f32_e32 v29, 0, v29
	v_add_f32_e32 v30, 1.0, v30
	v_cmp_gt_f32_e32 vcc, s38, v30
	s_nop 1
	v_cndmask_b32_e64 v31, 0, 32, vcc
	v_ldexp_f32 v30, v30, v31
	v_log_f32_e32 v30, v30
	s_nop 0
	v_mul_f32_e32 v31, 0x3f317217, v30
	v_fma_f32 v31, v30, s39, -v31
	v_fmac_f32_e32 v31, 0x3377d1cf, v30
	v_fmac_f32_e32 v31, 0x3f317217, v30
	v_cmp_lt_f32_e64 s[2:3], |v30|, s40
	s_nop 1
	v_cndmask_b32_e64 v30, v30, v31, s[2:3]
	v_cndmask_b32_e32 v31, 0, v69, vcc
	v_sub_f32_e32 v30, v30, v31
	v_sub_f32_e32 v29, v29, v30
	v_fmac_f32_e32 v28, 0x3d800000, v29
	ds_write_b32 v19, v28 offset:7392
	s_waitcnt lgkmcnt(3)
	v_mul_f32_e32 v24, v24, v167
	v_fmac_f32_e32 v24, v22, v166
	v_mul_f32_e32 v22, v23, v169
	s_waitcnt lgkmcnt(2)
	v_mul_f32_e32 v16, v16, v171
	s_waitcnt lgkmcnt(1)
	v_mul_f32_e32 v12, v12, v175
	v_fmac_f32_e32 v22, v21, v168
	v_fmac_f32_e32 v16, v14, v170
	v_mul_f32_e32 v14, v20, v173
	v_fmac_f32_e32 v12, v9, v174
	v_mul_f32_e32 v9, v18, v177
	v_add_f32_e32 v21, v24, v22
	v_fmac_f32_e32 v14, v13, v172
	v_fmac_f32_e32 v9, v10, v176
	s_waitcnt lgkmcnt(0)
	v_mul_f32_e32 v10, v11, v179
	v_add_f32_e32 v21, v25, v21
	v_add_f32_e32 v13, v16, v14
	v_fmac_f32_e32 v10, v8, v178
	v_mul_f32_e32 v8, v17, v181
	v_add_f32_e32 v13, v21, v13
	v_add_f32_e32 v9, v12, v9
	v_fmac_f32_e32 v8, v15, v180
	v_add_f32_e32 v9, v13, v9
	v_add_f32_e32 v8, v10, v8
	v_add_f32_e32 v8, v9, v8
	v_mul_f32_e64 v9, |v8|, s37
	v_exp_f32_e32 v9, v9
	v_min_f32_e32 v8, 0, v8
	v_add_f32_e32 v9, 1.0, v9
	v_cmp_gt_f32_e32 vcc, s38, v9
	s_nop 1
	v_cndmask_b32_e64 v10, 0, 32, vcc
	v_ldexp_f32 v9, v9, v10
	v_log_f32_e32 v9, v9
	s_nop 0
	v_mul_f32_e32 v10, 0x3f317217, v9
	v_fma_f32 v10, v9, s39, -v10
	v_fmac_f32_e32 v10, 0x3377d1cf, v9
	v_fmac_f32_e32 v10, 0x3f317217, v9
	v_cmp_lt_f32_e64 s[2:3], |v9|, s40
	s_nop 1
	v_cndmask_b32_e64 v9, v9, v10, s[2:3]
	v_cndmask_b32_e32 v10, 0, v69, vcc
	v_sub_f32_e32 v9, v9, v10
	v_sub_f32_e32 v8, v8, v9
	s_cselect_b64 s[2:3], -1, 0
	v_fmac_f32_e32 v28, 0x3d800000, v8
	s_and_b64 vcc, exec, s[2:3]
	v_mov_b32_e32 v8, 0
	ds_write_b32 v19, v28 offset:7920
	s_waitcnt lgkmcnt(0)
	s_barrier
	s_cbranch_vccz .LBB0_213
	ds_read_b32 v8, v26 offset:7920
	s_waitcnt lgkmcnt(0)
	v_add_f32_e32 v8, 0, v8

; __device__ __forceinline__ unsigned f2bf(float f) { unsigned u = __builtin_bit_cast(unsigned, f); return (u + 0x7fffu + ((u >> 16) & 1u)) >> 16; }
; __device__ __forceinline__ float red32(float v) { return swap16_sum(red16(v)); }
; __device__ __forceinline__ int crow(int r, int hi) { return (r & 3) + 8 * (r >> 2) + 4 * hi; }
; __device__ __forceinline__ float sigmoid_f(float x) { return __builtin_amdgcn_rcpf(1.0f + __builtin_amdgcn_exp2f(-x * LOG2E)); }
; __device__ __forceinline__ void gla_out(const Ptrs& A, int l, LAS unsigned char* lds, int c, int G, int wave, int lane_, const int wv0) {
;     ...
; #pragma unroll
;         for (int r = 0; r < 16; ++r) { float p = o0[r] * o0[r] + o1[r] * o1[r];
;             p = red32(p);
;             if (r32 == 0) red[vq * 64 + 32 * ti + crow(r, hi)] = p; }
;         __syncthreads();
;         const float g0 = gout[64 * vq + r32], g1 = gout[64 * vq + 32 + r32];
; #pragma unroll
;         for (int r = 0; r < 16; ++r) { const int t = 32 * ti + crow(r, hi);
;             const float tot = (red[t] + red[64 + t]) + (red[128 + t] + red[192 + t]); const float rinv = 1.0f / sqrtf(tot * (1.0f / 256.0f) + EPS);
;             const size_t off = (size_t)(t0 + t) * 1024 + hd * 256 + 64 * vq + r32;
;             const float r0 = bf2f(GR[off]), r1 = bf2f(GR[off + 32]);
;             AG[off] = (bf16)f2bf(o0[r] * rinv * g0 * r0 * pg8::sigmoid_f(r0)); AG[off + 32] = (bf16)f2bf(o1[r] * rinv * g1 * r1 * pg8::sigmoid_f(r1)); }
.LBB0_382:
	s_or_b64 exec, exec, s[36:37]
	v_or_b32_e32 v32, s66, v70
	v_ashrrev_i32_e32 v33, 31, v32
	v_lshl_add_u64 v[60:61], v[50:51], 0, s[56:57]
	v_lshlrev_b64 v[32:33], 10, v[32:33]
	v_lshl_add_u64 v[32:33], v[32:33], 0, v[60:61]
	v_lshlrev_b64 v[96:97], 1, v[32:33]
	v_lshl_add_u64 v[32:33], s[50:51], 0, v[96:97]
	v_or_b32_e32 v98, 64, v96
	v_mov_b32_e32 v99, v97
	s_waitcnt lgkmcnt(0)
	s_barrier
	v_or_b32_e32 v144, s66, v70
	v_lshl_add_u32 v144, v144, 10, v60
	v_lshlrev_b32_e32 v144, 1, v144
	global_load_ushort v108, v144, s[50:51]
	global_load_ushort v109, v144, s[50:51] offset:64
	v_or_b32_e32 v144, s66, v74
	v_lshl_add_u32 v144, v144, 10, v60
	v_lshlrev_b32_e32 v144, 1, v144
	global_load_ushort v114, v144, s[50:51]
	global_load_ushort v115, v144, s[50:51] offset:64
	v_or_b32_e32 v144, s66, v75
	v_lshl_add_u32 v144, v144, 10, v60
	v_lshlrev_b32_e32 v144, 1, v144
	global_load_ushort v116, v144, s[50:51]
	global_load_ushort v117, v144, s[50:51] offset:64
	v_or_b32_e32 v144, s66, v76
	v_lshl_add_u32 v144, v144, 10, v60
	v_lshlrev_b32_e32 v144, 1, v144
	global_load_ushort v118, v144, s[50:51]
	global_load_ushort v119, v144, s[50:51] offset:64
	v_or_b32_e32 v144, s66, v77
	v_lshl_add_u32 v144, v144, 10, v60
	v_lshlrev_b32_e32 v144, 1, v144
	global_load_ushort v120, v144, s[50:51]
	global_load_ushort v121, v144, s[50:51] offset:64
	v_or_b32_e32 v144, s66, v79
	v_lshl_add_u32 v144, v144, 10, v60
	v_lshlrev_b32_e32 v144, 1, v144
	global_load_ushort v122, v144, s[50:51]
	global_load_ushort v123, v144, s[50:51] offset:64
	v_or_b32_e32 v144, s66, v80
	v_lshl_add_u32 v144, v144, 10, v60
	v_lshlrev_b32_e32 v144, 1, v144
	global_load_ushort v124, v144, s[50:51]
	global_load_ushort v125, v144, s[50:51] offset:64
	v_or_b32_e32 v144, s66, v81
	v_lshl_add_u32 v144, v144, 10, v60
	v_lshlrev_b32_e32 v144, 1, v144
	global_load_ushort v126, v144, s[50:51]
	global_load_ushort v127, v144, s[50:51] offset:64
	v_or_b32_e32 v144, s66, v82
	v_lshl_add_u32 v144, v144, 10, v60
	v_lshlrev_b32_e32 v144, 1, v144
	global_load_ushort v128, v144, s[50:51]
	global_load_ushort v129, v144, s[50:51] offset:64
	v_or_b32_e32 v144, s66, v84
	v_lshl_add_u32 v144, v144, 10, v60
	v_lshlrev_b32_e32 v144, 1, v144
	global_load_ushort v130, v144, s[50:51]
	global_load_ushort v131, v144, s[50:51] offset:64
	v_or_b32_e32 v144, s66, v85
	v_lshl_add_u32 v144, v144, 10, v60
	v_lshlrev_b32_e32 v144, 1, v144
	global_load_ushort v132, v144, s[50:51]
	global_load_ushort v133, v144, s[50:51] offset:64
	v_or_b32_e32 v144, s66, v86
	v_lshl_add_u32 v144, v144, 10, v60
	v_lshlrev_b32_e32 v144, 1, v144
	global_load_ushort v134, v144, s[50:51]
	global_load_ushort v135, v144, s[50:51] offset:64
	v_or_b32_e32 v144, s66, v87
	v_lshl_add_u32 v144, v144, 10, v60
	v_lshlrev_b32_e32 v144, 1, v144
	global_load_ushort v136, v144, s[50:51]
	global_load_ushort v137, v144, s[50:51] offset:64
	v_or_b32_e32 v144, s66, v89
	v_lshl_add_u32 v144, v144, 10, v60
	v_lshlrev_b32_e32 v144, 1, v144
	global_load_ushort v138, v144, s[50:51]
	global_load_ushort v139, v144, s[50:51] offset:64
	v_or_b32_e32 v144, s66, v90
	v_lshl_add_u32 v144, v144, 10, v60
	v_lshlrev_b32_e32 v144, 1, v144
	global_load_ushort v140, v144, s[50:51]
	global_load_ushort v141, v144, s[50:51] offset:64
	v_or_b32_e32 v144, s66, v91
	v_lshl_add_u32 v144, v144, 10, v60
	v_lshlrev_b32_e32 v144, 1, v144
	global_load_ushort v142, v144, s[50:51]
	global_load_ushort v143, v144, s[50:51] offset:64
	global_load_dword v48, v[52:53], off
	global_load_dword v59, v[54:55], off
	v_lshl_add_u64 v[34:35], s[50:51], 0, v[98:99]
	ds_read_b128 v[32:35], v71
	ds_read_b128 v[36:39], v71 offset:256
	ds_read_b128 v[40:43], v71 offset:512
	ds_read_b128 v[44:47], v71 offset:768
	v_or_b32_e32 v100, s66, v74
	v_ashrrev_i32_e32 v101, 31, v100
	s_waitcnt lgkmcnt(2)
	v_add_f32_e32 v32, v32, v36
	v_lshlrev_b64 v[100:101], 10, v[100:101]
	s_waitcnt lgkmcnt(0)
	v_add_f32_e32 v36, v40, v44
	v_add_f32_e32 v32, v32, v36
	v_fmamk_f32 v32, v32, 0x3b800000, v93
	v_mul_f32_e32 v36, 0x4f800000, v32
	v_cmp_gt_f32_e32 vcc, s90, v32
	v_lshl_add_u64 v[100:101], v[100:101], 0, v[60:61]
	v_lshlrev_b64 v[100:101], 1, v[100:101]
	v_cndmask_b32_e32 v32, v32, v36, vcc
	v_sqrt_f32_e32 v36, v32
	v_lshl_add_u64 v[96:97], s[52:53], 0, v[96:97]
	v_lshl_add_u64 v[98:99], s[52:53], 0, v[98:99]
	v_lshl_add_u64 v[102:103], s[50:51], 0, v[100:101]
	v_add_u32_e32 v40, -1, v36
	v_add_u32_e32 v44, 1, v36
	v_fma_f32 v106, -v40, v36, v32
	v_fma_f32 v107, -v44, v36, v32
	v_cmp_ge_f32_e64 s[36:37], 0, v106
	v_or_b32_e32 v104, 64, v100
	v_mov_b32_e32 v105, v101
	v_cndmask_b32_e64 v36, v36, v40, s[36:37]
	v_cmp_lt_f32_e64 s[36:37], 0, v107
	v_lshl_add_u64 v[106:107], s[50:51], 0, v[104:105]
	v_add_f32_e32 v41, v41, v45
	v_cndmask_b32_e64 v36, v36, v44, s[36:37]
	v_mul_f32_e32 v40, 0x37800000, v36
	v_cndmask_b32_e32 v36, v36, v40, vcc
	v_cmp_class_f32_e32 vcc, v32, v94
	v_add_f32_e32 v34, v34, v38
	s_add_i32 s44, s44, s38
	v_cndmask_b32_e32 v32, v36, v32, vcc
	v_div_scale_f32 v36, s[36:37], v32, v32, 1.0
	v_rcp_f32_e32 v40, v36
	v_div_scale_f32 v44, vcc, 1.0, v32, 1.0
	s_cmpk_lt_i32 s44, 0x400
	v_fma_f32 v110, -v36, v40, 1.0
	v_fmac_f32_e32 v40, v110, v40
	v_mul_f32_e32 v110, v44, v40
	v_fma_f32 v111, -v36, v110, v44
	v_fmac_f32_e32 v110, v111, v40
	v_fma_f32 v36, -v36, v110, v44
	v_div_fmas_f32 v36, v36, v40, v110
	v_div_fixup_f32 v32, v36, v32, 1.0
	v_mul_f32_e32 v16, v16, v32
	v_mul_f32_e32 v0, v0, v32
	v_lshl_add_u64 v[56:57], v[56:57], 0, s[62:63]
	s_waitcnt vmcnt(0)
; __device__ __forceinline__ unsigned f2bf(float f) { unsigned u = __builtin_bit_cast(unsigned, f); return (u + 0x7fffu + ((u >> 16) & 1u)) >> 16; }
; __device__ __forceinline__ int crow(int r, int hi) { return (r & 3) + 8 * (r >> 2) + 4 * hi; }
; __device__ __forceinline__ float sigmoid_f(float x) { return __builtin_amdgcn_rcpf(1.0f + __builtin_amdgcn_exp2f(-x * LOG2E)); }
; __device__ __forceinline__ void gla_out(const Ptrs& A, int l, LAS unsigned char* lds, int c, int G, int wave, int lane_, const int wv0) {
;     ...
;         for (int r = 0; r < 16; ++r) { const int t = 32 * ti + crow(r, hi);
;             const float tot = (red[t] + red[64 + t]) + (red[128 + t] + red[192 + t]); const float rinv = 1.0f / sqrtf(tot * (1.0f / 256.0f) + EPS);
;             const size_t off = (size_t)(t0 + t) * 1024 + hd * 256 + 64 * vq + r32;
;             const float r0 = bf2f(GR[off]), r1 = bf2f(GR[off + 32]);
;             AG[off] = (bf16)f2bf(o0[r] * rinv * g0 * r0 * pg8::sigmoid_f(r0)); AG[off + 32] = (bf16)f2bf(o1[r] * rinv * g1 * r1 * pg8::sigmoid_f(r1)); }
	v_mul_f32_e32 v16, v48, v16
	v_mul_f32_e32 v0, v59, v0
	v_lshlrev_b32_e32 v32, 16, v108
	v_lshlrev_b32_e32 v36, 16, v109
	v_mul_f32_e32 v40, 0xbfb8aa3b, v32
	v_exp_f32_e32 v40, v40
	v_mul_f32_e32 v44, 0xbfb8aa3b, v36
	v_exp_f32_e32 v44, v44
	v_mul_f32_e32 v16, v16, v32
	v_add_f32_e32 v32, 1.0, v40
	v_rcp_f32_e32 v32, v32
	v_add_f32_e32 v40, 1.0, v44
	v_rcp_f32_e32 v40, v40
	v_mul_f32_e32 v0, v0, v36
	v_mul_f32_e32 v16, v32, v16
	v_bfe_u32 v32, v16, 16, 1
	v_mul_f32_e32 v0, v0, v40
	v_add3_u32 v16, v16, v32, s89
	v_bfe_u32 v32, v0, 16, 1
	v_add3_u32 v0, v0, v32, s89
	global_store_short_d16_hi v[96:97], v16, off
	global_store_short_d16_hi v[98:99], v0, off
	v_mov_b32_e32 v0, v114
	s_nop 0
	v_mov_b32_e32 v16, v115
	v_add_f32_e32 v40, v33, v37
	v_add_f32_e32 v40, v40, v41
	v_fmamk_f32 v40, v40, 0x3b800000, v93
	v_mul_f32_e32 v41, 0x4f800000, v40
	v_cmp_gt_f32_e32 vcc, s90, v40
	v_lshl_add_u64 v[32:33], s[52:53], 0, v[100:101]
	v_lshl_add_u64 v[44:45], s[52:53], 0, v[104:105]
	v_cndmask_b32_e32 v98, v40, v41, vcc
	v_sqrt_f32_e32 v99, v98
	v_or_b32_e32 v96, s66, v75
	v_ashrrev_i32_e32 v97, 31, v96
	v_lshlrev_b64 v[96:97], 10, v[96:97]
	v_add_u32_e32 v100, -1, v99
	v_add_u32_e32 v101, 1, v99
	v_fma_f32 v102, -v100, v99, v98
	v_fma_f32 v103, -v101, v99, v98
	v_cmp_ge_f32_e64 s[36:37], 0, v102
	v_lshl_add_u64 v[96:97], v[96:97], 0, v[60:61]
	v_lshlrev_b64 v[96:97], 1, v[96:97]
	v_cndmask_b32_e64 v99, v99, v100, s[36:37]
	v_cmp_lt_f32_e64 s[36:37], 0, v103
	v_or_b32_e32 v40, 64, v96
	v_mov_b32_e32 v41, v97
	v_cndmask_b32_e64 v99, v99, v101, s[36:37]
	v_mul_f32_e32 v100, 0x37800000, v99
	v_cndmask_b32_e32 v99, v99, v100, vcc
	v_cmp_class_f32_e32 vcc, v98, v94
	v_lshl_add_u64 v[36:37], s[50:51], 0, v[96:97]
	v_lshlrev_b32_e32 v0, 16, v0
	v_cndmask_b32_e32 v100, v99, v98, vcc
	v_div_scale_f32 v101, s[36:37], v100, v100, 1.0
	v_rcp_f32_e32 v102, v101
	v_div_scale_f32 v103, vcc, 1.0, v100, 1.0
	v_lshlrev_b32_e32 v16, 16, v16
	v_fma_f32 v104, -v101, v102, 1.0
	v_fmac_f32_e32 v102, v104, v102
	v_mul_f32_e32 v104, v103, v102
	v_fma_f32 v105, -v101, v104, v103
	v_fmac_f32_e32 v104, v105, v102
	v_fma_f32 v101, -v101, v104, v103
	v_div_fmas_f32 v101, v101, v102, v104
	v_div_fixup_f32 v100, v101, v100, 1.0
	v_mul_f32_e32 v17, v17, v100
	v_mul_f32_e32 v1, v1, v100
	v_mul_f32_e32 v100, 0xbfb8aa3b, v0
	v_mul_f32_e32 v101, 0xbfb8aa3b, v16
	v_exp_f32_e32 v100, v100
	v_exp_f32_e32 v101, v101
	v_mul_f32_e32 v17, v48, v17
	v_mul_f32_e32 v1, v59, v1
	v_add_f32_e32 v100, 1.0, v100
	v_add_f32_e32 v101, 1.0, v101
	v_rcp_f32_e32 v100, v100
	v_rcp_f32_e32 v101, v101
	v_mul_f32_e32 v0, v17, v0
	v_mul_f32_e32 v1, v1, v16
	v_mul_f32_e32 v0, v100, v0
	v_mul_f32_e32 v1, v1, v101
	v_bfe_u32 v16, v0, 16, 1
	v_bfe_u32 v17, v1, 16, 1
	v_add3_u32 v0, v0, v16, s89
	v_lshl_add_u64 v[98:99], s[50:51], 0, v[40:41]
	v_add3_u32 v1, v1, v17, s89
	global_store_short_d16_hi v[32:33], v0, off
	global_store_short_d16_hi v[44:45], v1, off
	v_mov_b32_e32 v100, v116
	s_nop 0
	v_mov_b32_e32 v98, v117
	v_add_f32_e32 v36, v42, v46
	v_add_f32_e32 v34, v34, v36
	v_fmamk_f32 v34, v34, 0x3b800000, v93
	v_mul_f32_e32 v36, 0x4f800000, v34
	v_cmp_gt_f32_e32 vcc, s90, v34
	v_lshl_add_u64 v[16:17], s[52:53], 0, v[96:97]
	v_or_b32_e32 v0, s66, v76
	v_cndmask_b32_e32 v34, v34, v36, vcc
	v_sqrt_f32_e32 v38, v34
	v_ashrrev_i32_e32 v1, 31, v0
	v_lshlrev_b64 v[0:1], 10, v[0:1]
	v_lshl_add_u64 v[0:1], v[0:1], 0, v[60:61]
	v_add_u32_e32 v42, -1, v38
	v_add_u32_e32 v44, 1, v38
	v_fma_f32 v45, -v42, v38, v34
	v_fma_f32 v46, -v44, v38, v34
	v_cmp_ge_f32_e64 s[36:37], 0, v45
	v_lshlrev_b64 v[0:1], 1, v[0:1]
	v_lshl_add_u64 v[32:33], s[50:51], 0, v[0:1]
	v_cndmask_b32_e64 v38, v38, v42, s[36:37]
	v_cmp_lt_f32_e64 s[36:37], 0, v46
	v_or_b32_e32 v36, 64, v0
	v_mov_b32_e32 v37, v1
	v_cndmask_b32_e64 v38, v38, v44, s[36:37]
	v_mul_f32_e32 v42, 0x37800000, v38
	v_cndmask_b32_e32 v38, v38, v42, vcc
	v_cmp_class_f32_e32 vcc, v34, v94
	v_lshl_add_u64 v[40:41], s[52:53], 0, v[40:41]
	v_lshl_add_u64 v[44:45], s[50:51], 0, v[36:37]
	v_cndmask_b32_e32 v34, v38, v34, vcc
	v_div_scale_f32 v38, s[36:37], v34, v34, 1.0
	v_rcp_f32_e32 v42, v38
	v_div_scale_f32 v46, vcc, 1.0, v34, 1.0
	v_lshl_add_u64 v[0:1], s[52:53], 0, v[0:1]
	v_fma_f32 v96, -v38, v42, 1.0
	v_fmac_f32_e32 v42, v96, v42
	v_mul_f32_e32 v96, v46, v42
	v_fma_f32 v97, -v38, v96, v46
	v_fmac_f32_e32 v96, v97, v42
	v_fma_f32 v38, -v38, v96, v46
	v_div_fmas_f32 v38, v38, v42, v96
	v_div_fixup_f32 v34, v38, v34, 1.0
	v_mul_f32_e32 v18, v18, v34
	v_mul_f32_e32 v2, v2, v34
	v_mul_f32_e32 v18, v48, v18
	v_mul_f32_e32 v2, v59, v2
	v_lshlrev_b32_e32 v34, 16, v100
	v_lshlrev_b32_e32 v38, 16, v98
	v_mul_f32_e32 v42, 0xbfb8aa3b, v34
	v_mul_f32_e32 v46, 0xbfb8aa3b, v38
	v_exp_f32_e32 v42, v42
	v_exp_f32_e32 v46, v46
	v_mul_f32_e32 v18, v18, v34
	v_mul_f32_e32 v2, v2, v38
	v_add_f32_e32 v42, 1.0, v42
	v_add_f32_e32 v46, 1.0, v46
	v_rcp_f32_e32 v42, v42
	v_rcp_f32_e32 v46, v46
	v_mul_f32_e32 v18, v42, v18
	v_mul_f32_e32 v2, v2, v46
	v_bfe_u32 v34, v18, 16, 1
	v_bfe_u32 v38, v2, 16, 1
	v_add3_u32 v18, v18, v34, s89
	v_add3_u32 v2, v2, v38, s89
	global_store_short_d16_hi v[16:17], v18, off
	global_store_short_d16_hi v[40:41], v2, off
	v_mov_b32_e32 v2, v118
	s_nop 0
	v_mov_b32_e32 v18, v119
	v_add_f32_e32 v32, v35, v39
	v_add_f32_e32 v33, v43, v47
	v_add_f32_e32 v32, v32, v33
	v_fmamk_f32 v32, v32, 0x3b800000, v93
	v_mul_f32_e32 v33, 0x4f800000, v32
	v_cmp_gt_f32_e32 vcc, s90, v32
	v_or_b32_e32 v16, s66, v77
	v_ashrrev_i32_e32 v17, 31, v16
	v_cndmask_b32_e32 v34, v32, v33, vcc
	v_sqrt_f32_e32 v35, v34
	v_lshl_add_u64 v[32:33], s[52:53], 0, v[36:37]
	v_lshlrev_b64 v[16:17], 10, v[16:17]
; __device__ __forceinline__ unsigned f2bf(float f) { unsigned u = __builtin_bit_cast(unsigned, f); return (u + 0x7fffu + ((u >> 16) & 1u)) >> 16; }
; __device__ __forceinline__ int crow(int r, int hi) { return (r & 3) + 8 * (r >> 2) + 4 * hi; }
; __device__ __forceinline__ float sigmoid_f(float x) { return __builtin_amdgcn_rcpf(1.0f + __builtin_amdgcn_exp2f(-x * LOG2E)); }
; __device__ __forceinline__ void gla_out(const Ptrs& A, int l, LAS unsigned char* lds, int c, int G, int wave, int lane_, const int wv0) {
;     ...
;         for (int r = 0; r < 16; ++r) { const int t = 32 * ti + crow(r, hi);
;             const float tot = (red[t] + red[64 + t]) + (red[128 + t] + red[192 + t]); const float rinv = 1.0f / sqrtf(tot * (1.0f / 256.0f) + EPS);
;             const size_t off = (size_t)(t0 + t) * 1024 + hd * 256 + 64 * vq + r32;
;             const float r0 = bf2f(GR[off]), r1 = bf2f(GR[off + 32]);
;             AG[off] = (bf16)f2bf(o0[r] * rinv * g0 * r0 * pg8::sigmoid_f(r0)); AG[off + 32] = (bf16)f2bf(o1[r] * rinv * g1 * r1 * pg8::sigmoid_f(r1)); }
	v_lshl_add_u64 v[16:17], v[16:17], 0, v[60:61]
	v_add_u32_e32 v36, -1, v35
	v_add_u32_e32 v37, 1, v35
	v_fma_f32 v38, -v36, v35, v34
	v_fma_f32 v39, -v37, v35, v34
	v_cmp_ge_f32_e64 s[36:37], 0, v38
	v_lshlrev_b64 v[40:41], 1, v[16:17]
	v_lshl_add_u64 v[16:17], s[50:51], 0, v[40:41]
	v_cndmask_b32_e64 v35, v35, v36, s[36:37]
	v_cmp_lt_f32_e64 s[36:37], 0, v39
	v_or_b32_e32 v42, 64, v40
	v_mov_b32_e32 v43, v41
	v_cndmask_b32_e64 v35, v35, v37, s[36:37]
	v_mul_f32_e32 v36, 0x37800000, v35
	v_cndmask_b32_e32 v35, v35, v36, vcc
	v_cmp_class_f32_e32 vcc, v34, v94
	v_lshl_add_u64 v[40:41], s[52:53], 0, v[40:41]
	v_lshlrev_b32_e32 v2, 16, v2
	v_cndmask_b32_e32 v36, v35, v34, vcc
	v_div_scale_f32 v37, s[36:37], v36, v36, 1.0
	v_rcp_f32_e32 v38, v37
	v_div_scale_f32 v39, vcc, 1.0, v36, 1.0
	v_lshlrev_b32_e32 v18, 16, v18
	v_fma_f32 v44, -v37, v38, 1.0
	v_fmac_f32_e32 v38, v44, v38
	v_mul_f32_e32 v44, v39, v38
	v_fma_f32 v45, -v37, v44, v39
	v_fmac_f32_e32 v44, v45, v38
	v_fma_f32 v37, -v37, v44, v39
	v_div_fmas_f32 v37, v37, v38, v44
	v_div_fixup_f32 v36, v37, v36, 1.0
	v_mul_f32_e32 v19, v19, v36
	v_mul_f32_e32 v3, v3, v36
	v_mul_f32_e32 v36, 0xbfb8aa3b, v2
	v_mul_f32_e32 v37, 0xbfb8aa3b, v18
	v_exp_f32_e32 v36, v36
	v_exp_f32_e32 v37, v37
	v_mul_f32_e32 v19, v48, v19
	v_mul_f32_e32 v3, v59, v3
	v_add_f32_e32 v36, 1.0, v36
	v_add_f32_e32 v37, 1.0, v37
	v_rcp_f32_e32 v36, v36
	v_rcp_f32_e32 v37, v37
	v_mul_f32_e32 v2, v19, v2
	v_mul_f32_e32 v3, v3, v18
	v_mul_f32_e32 v2, v36, v2
	v_mul_f32_e32 v3, v3, v37
	v_bfe_u32 v18, v2, 16, 1
	v_bfe_u32 v19, v3, 16, 1
	v_add3_u32 v2, v2, v18, s89
	v_add3_u32 v3, v3, v19, s89
	global_store_short_d16_hi v[0:1], v2, off
	global_store_short_d16_hi v[32:33], v3, off
	v_lshl_add_u64 v[34:35], s[50:51], 0, v[42:43]
	v_mov_b32_e32 v100, v120
	v_mov_b32_e32 v101, v121
	ds_read_b128 v[0:3], v78
	ds_read_b128 v[16:19], v78 offset:256
	ds_read_b128 v[32:35], v78 offset:512
	ds_read_b128 v[36:39], v78 offset:768
	v_or_b32_e32 v44, s66, v79
	v_ashrrev_i32_e32 v45, 31, v44
	s_waitcnt lgkmcnt(2)
	v_add_f32_e32 v0, v0, v16
	v_lshlrev_b64 v[44:45], 10, v[44:45]
	s_waitcnt lgkmcnt(0)
	v_add_f32_e32 v16, v32, v36
	v_add_f32_e32 v0, v0, v16
	v_fmamk_f32 v0, v0, 0x3b800000, v93
	v_mul_f32_e32 v16, 0x4f800000, v0
	v_cmp_gt_f32_e32 vcc, s90, v0
	v_lshl_add_u64 v[44:45], v[44:45], 0, v[60:61]
	v_lshlrev_b64 v[44:45], 1, v[44:45]
	v_cndmask_b32_e32 v0, v0, v16, vcc
	v_sqrt_f32_e32 v16, v0
	v_lshl_add_u64 v[46:47], s[50:51], 0, v[44:45]
	v_or_b32_e32 v96, 64, v44
	v_mov_b32_e32 v97, v45
	v_add_u32_e32 v32, -1, v16
	v_add_u32_e32 v36, 1, v16
	v_fma_f32 v98, -v32, v16, v0
	v_fma_f32 v99, -v36, v16, v0
	v_cmp_ge_f32_e64 s[36:37], 0, v98
	v_lshl_add_u64 v[42:43], s[52:53], 0, v[42:43]
	v_add_f32_e32 v33, v33, v37
	v_cndmask_b32_e64 v16, v16, v32, s[36:37]
	v_cmp_lt_f32_e64 s[36:37], 0, v99
	v_lshl_add_u64 v[98:99], s[50:51], 0, v[96:97]
	v_add_f32_e32 v2, v2, v18
	v_cndmask_b32_e64 v16, v16, v36, s[36:37]
	v_mul_f32_e32 v32, 0x37800000, v16
	v_cndmask_b32_e32 v16, v16, v32, vcc
	v_cmp_class_f32_e32 vcc, v0, v94
	v_add_f32_e32 v18, v34, v38
	v_add_f32_e32 v2, v2, v18
	v_cndmask_b32_e32 v0, v16, v0, vcc
	v_div_scale_f32 v16, s[36:37], v0, v0, 1.0
	v_rcp_f32_e32 v32, v16
	v_div_scale_f32 v36, vcc, 1.0, v0, 1.0
	v_fmamk_f32 v2, v2, 0x3b800000, v93
	v_fma_f32 v102, -v16, v32, 1.0
	v_fmac_f32_e32 v32, v102, v32
	v_mul_f32_e32 v102, v36, v32
	v_fma_f32 v103, -v16, v102, v36
	v_fmac_f32_e32 v102, v103, v32
	v_fma_f32 v16, -v16, v102, v36
	v_div_fmas_f32 v16, v16, v32, v102
	v_div_fixup_f32 v0, v16, v0, 1.0
	v_mul_f32_e32 v16, v20, v0
	v_mul_f32_e32 v0, v4, v0
	v_mul_f32_e32 v16, v48, v16
	v_mul_f32_e32 v0, v59, v0
	v_mul_f32_e32 v18, 0x4f800000, v2
	v_lshlrev_b32_e32 v4, 16, v100
	v_lshlrev_b32_e32 v20, 16, v101
	v_mul_f32_e32 v32, 0xbfb8aa3b, v4
	v_mul_f32_e32 v36, 0xbfb8aa3b, v20
	v_exp_f32_e32 v32, v32
	v_exp_f32_e32 v36, v36
	v_mul_f32_e32 v4, v16, v4
	v_mul_f32_e32 v0, v0, v20
	v_add_f32_e32 v32, 1.0, v32
	v_add_f32_e32 v36, 1.0, v36
	v_rcp_f32_e32 v32, v32
	v_rcp_f32_e32 v36, v36
	v_mul_f32_e32 v4, v32, v4
	v_mul_f32_e32 v0, v0, v36
	v_bfe_u32 v16, v4, 16, 1
	v_bfe_u32 v20, v0, 16, 1
	v_add3_u32 v4, v4, v16, s89
	v_add3_u32 v0, v0, v20, s89
	global_store_short_d16_hi v[40:41], v4, off
	global_store_short_d16_hi v[42:43], v0, off
	v_mov_b32_e32 v4, v122
	s_nop 0
	v_mov_b32_e32 v20, v123
	v_add_f32_e32 v32, v1, v17
	v_add_f32_e32 v32, v32, v33
	v_fmamk_f32 v32, v32, 0x3b800000, v93
	v_mul_f32_e32 v33, 0x4f800000, v32
	v_cmp_gt_f32_e32 vcc, s90, v32
	v_lshl_add_u64 v[0:1], s[52:53], 0, v[44:45]
	v_lshl_add_u64 v[36:37], s[52:53], 0, v[96:97]
	v_cndmask_b32_e32 v42, v32, v33, vcc
	v_sqrt_f32_e32 v43, v42
	v_or_b32_e32 v40, s66, v80
	v_ashrrev_i32_e32 v41, 31, v40
	v_lshlrev_b64 v[40:41], 10, v[40:41]
	v_add_u32_e32 v44, -1, v43
	v_add_u32_e32 v45, 1, v43
	v_fma_f32 v46, -v44, v43, v42
	v_fma_f32 v47, -v45, v43, v42
	v_cmp_ge_f32_e64 s[36:37], 0, v46
	v_lshl_add_u64 v[40:41], v[40:41], 0, v[60:61]
	v_lshlrev_b64 v[40:41], 1, v[40:41]
	v_cndmask_b32_e64 v43, v43, v44, s[36:37]
	v_cmp_lt_f32_e64 s[36:37], 0, v47
	v_or_b32_e32 v32, 64, v40
	v_mov_b32_e32 v33, v41
	v_cndmask_b32_e64 v43, v43, v45, s[36:37]
	v_mul_f32_e32 v44, 0x37800000, v43
	v_cndmask_b32_e32 v43, v43, v44, vcc
	v_cmp_class_f32_e32 vcc, v42, v94
	v_lshl_add_u64 v[16:17], s[50:51], 0, v[40:41]
	v_lshlrev_b32_e32 v4, 16, v4
	v_cndmask_b32_e32 v44, v43, v42, vcc
	v_div_scale_f32 v45, s[36:37], v44, v44, 1.0
	v_rcp_f32_e32 v46, v45
	v_div_scale_f32 v47, vcc, 1.0, v44, 1.0
	v_lshlrev_b32_e32 v20, 16, v20
	v_fma_f32 v96, -v45, v46, 1.0
	v_fmac_f32_e32 v46, v96, v46
	v_mul_f32_e32 v96, v47, v46
; __device__ __forceinline__ unsigned f2bf(float f) { unsigned u = __builtin_bit_cast(unsigned, f); return (u + 0x7fffu + ((u >> 16) & 1u)) >> 16; }
; __device__ __forceinline__ int crow(int r, int hi) { return (r & 3) + 8 * (r >> 2) + 4 * hi; }
; __device__ __forceinline__ float sigmoid_f(float x) { return __builtin_amdgcn_rcpf(1.0f + __builtin_amdgcn_exp2f(-x * LOG2E)); }
; __device__ __forceinline__ void gla_out(const Ptrs& A, int l, LAS unsigned char* lds, int c, int G, int wave, int lane_, const int wv0) {
;     ...
;         for (int r = 0; r < 16; ++r) { const int t = 32 * ti + crow(r, hi);
;             const float tot = (red[t] + red[64 + t]) + (red[128 + t] + red[192 + t]); const float rinv = 1.0f / sqrtf(tot * (1.0f / 256.0f) + EPS);
;             const size_t off = (size_t)(t0 + t) * 1024 + hd * 256 + 64 * vq + r32;
;             const float r0 = bf2f(GR[off]), r1 = bf2f(GR[off + 32]);
;             AG[off] = (bf16)f2bf(o0[r] * rinv * g0 * r0 * pg8::sigmoid_f(r0)); AG[off + 32] = (bf16)f2bf(o1[r] * rinv * g1 * r1 * pg8::sigmoid_f(r1)); }
	v_fma_f32 v97, -v45, v96, v47
	v_fmac_f32_e32 v96, v97, v46
	v_fma_f32 v45, -v45, v96, v47
	v_div_fmas_f32 v45, v45, v46, v96
	v_div_fixup_f32 v44, v45, v44, 1.0
	v_mul_f32_e32 v21, v21, v44
	v_mul_f32_e32 v5, v5, v44
	v_mul_f32_e32 v44, 0xbfb8aa3b, v4
	v_mul_f32_e32 v45, 0xbfb8aa3b, v20
	v_exp_f32_e32 v44, v44
	v_exp_f32_e32 v45, v45
	v_mul_f32_e32 v21, v48, v21
	v_mul_f32_e32 v5, v59, v5
	v_add_f32_e32 v44, 1.0, v44
	v_add_f32_e32 v45, 1.0, v45
	v_rcp_f32_e32 v44, v44
	v_rcp_f32_e32 v45, v45
	v_mul_f32_e32 v4, v21, v4
	v_mul_f32_e32 v5, v5, v20
	v_mul_f32_e32 v4, v44, v4
	v_mul_f32_e32 v5, v5, v45
	v_bfe_u32 v20, v4, 16, 1
	v_bfe_u32 v21, v5, 16, 1
	v_add3_u32 v4, v4, v20, s89
	v_lshl_add_u64 v[42:43], s[50:51], 0, v[32:33]
	v_add3_u32 v5, v5, v21, s89
	global_store_short_d16_hi v[0:1], v4, off
	global_store_short_d16_hi v[36:37], v5, off
	v_mov_b32_e32 v44, v124
	s_nop 0
	v_mov_b32_e32 v42, v125
	v_cmp_gt_f32_e32 vcc, s90, v2
	v_lshl_add_u64 v[4:5], s[52:53], 0, v[40:41]
	v_or_b32_e32 v0, s66, v81
	v_cndmask_b32_e32 v2, v2, v18, vcc
	v_sqrt_f32_e32 v18, v2
	v_ashrrev_i32_e32 v1, 31, v0
	v_lshlrev_b64 v[0:1], 10, v[0:1]
	v_lshl_add_u64 v[0:1], v[0:1], 0, v[60:61]
	v_add_u32_e32 v34, -1, v18
	v_add_u32_e32 v36, 1, v18
	v_fma_f32 v37, -v34, v18, v2
	v_fma_f32 v38, -v36, v18, v2
	v_cmp_ge_f32_e64 s[36:37], 0, v37
	v_lshlrev_b64 v[0:1], 1, v[0:1]
	v_lshl_add_u64 v[16:17], s[50:51], 0, v[0:1]
	v_cndmask_b32_e64 v18, v18, v34, s[36:37]
	v_cmp_lt_f32_e64 s[36:37], 0, v38
	v_or_b32_e32 v20, 64, v0
	v_mov_b32_e32 v21, v1
	v_cndmask_b32_e64 v18, v18, v36, s[36:37]
	v_mul_f32_e32 v34, 0x37800000, v18
	v_cndmask_b32_e32 v18, v18, v34, vcc
	v_cmp_class_f32_e32 vcc, v2, v94
	v_lshl_add_u64 v[32:33], s[52:53], 0, v[32:33]
	v_lshl_add_u64 v[36:37], s[50:51], 0, v[20:21]
	v_cndmask_b32_e32 v2, v18, v2, vcc
	v_div_scale_f32 v18, s[36:37], v2, v2, 1.0
	v_rcp_f32_e32 v34, v18
	v_div_scale_f32 v38, vcc, 1.0, v2, 1.0
	v_lshl_add_u64 v[0:1], s[52:53], 0, v[0:1]
	v_fma_f32 v40, -v18, v34, 1.0
	v_fmac_f32_e32 v34, v40, v34
	v_mul_f32_e32 v40, v38, v34
	v_fma_f32 v41, -v18, v40, v38
	v_fmac_f32_e32 v40, v41, v34
	v_fma_f32 v18, -v18, v40, v38
	v_div_fmas_f32 v18, v18, v34, v40
	v_div_fixup_f32 v2, v18, v2, 1.0
	v_mul_f32_e32 v18, v22, v2
	v_mul_f32_e32 v2, v6, v2
	v_mul_f32_e32 v18, v48, v18
	v_mul_f32_e32 v2, v59, v2
	v_lshlrev_b32_e32 v6, 16, v44
	v_lshlrev_b32_e32 v22, 16, v42
	v_mul_f32_e32 v34, 0xbfb8aa3b, v6
	v_mul_f32_e32 v38, 0xbfb8aa3b, v22
	v_exp_f32_e32 v34, v34
	v_exp_f32_e32 v38, v38
	v_mul_f32_e32 v6, v18, v6
	v_mul_f32_e32 v2, v2, v22
	v_add_f32_e32 v34, 1.0, v34
	v_add_f32_e32 v38, 1.0, v38
	v_rcp_f32_e32 v34, v34
	v_rcp_f32_e32 v38, v38
	v_mul_f32_e32 v6, v34, v6
	v_mul_f32_e32 v2, v2, v38
	v_bfe_u32 v18, v6, 16, 1
	v_bfe_u32 v22, v2, 16, 1
	v_add3_u32 v6, v6, v18, s89
	v_add3_u32 v2, v2, v22, s89
	global_store_short_d16_hi v[4:5], v6, off
	global_store_short_d16_hi v[32:33], v2, off
	v_mov_b32_e32 v6, v126
	s_nop 0
	v_mov_b32_e32 v18, v127
	v_or_b32_e32 v4, s66, v82
	v_ashrrev_i32_e32 v5, 31, v4
	v_lshlrev_b64 v[4:5], 10, v[4:5]
	v_lshl_add_u64 v[4:5], v[4:5], 0, v[60:61]
	v_lshlrev_b64 v[32:33], 1, v[4:5]
	v_add_f32_e32 v4, v3, v19
	v_add_f32_e32 v5, v35, v39
	v_add_f32_e32 v4, v4, v5
	v_fmamk_f32 v4, v4, 0x3b800000, v93
	v_mul_f32_e32 v5, 0x4f800000, v4
	v_cmp_gt_f32_e32 vcc, s90, v4
	v_lshl_add_u64 v[2:3], s[50:51], 0, v[32:33]
	v_or_b32_e32 v34, 64, v32
	v_cndmask_b32_e32 v16, v4, v5, vcc
	v_sqrt_f32_e32 v17, v16
	v_lshl_add_u64 v[4:5], s[52:53], 0, v[20:21]
	v_mov_b32_e32 v35, v33
	v_lshl_add_u64 v[32:33], s[52:53], 0, v[32:33]
	v_add_u32_e32 v19, -1, v17
	v_add_u32_e32 v20, 1, v17
	v_fma_f32 v21, -v19, v17, v16
	v_fma_f32 v22, -v20, v17, v16
	v_cmp_ge_f32_e64 s[36:37], 0, v21
	v_lshlrev_b32_e32 v6, 16, v6
	v_cndmask_b32_e64 v17, v17, v19, s[36:37]
	v_cmp_lt_f32_e64 s[36:37], 0, v22
	v_lshlrev_b32_e32 v18, 16, v18
	v_cndmask_b32_e64 v17, v17, v20, s[36:37]
	v_mul_f32_e32 v19, 0x37800000, v17
	v_cndmask_b32_e32 v17, v17, v19, vcc
	v_cmp_class_f32_e32 vcc, v16, v94
	s_nop 1
	v_cndmask_b32_e32 v19, v17, v16, vcc
	v_div_scale_f32 v20, s[36:37], v19, v19, 1.0
	v_rcp_f32_e32 v21, v20
	v_div_scale_f32 v22, vcc, 1.0, v19, 1.0
	v_lshl_add_u64 v[16:17], s[50:51], 0, v[34:35]
	v_fma_f32 v36, -v20, v21, 1.0
	v_fmac_f32_e32 v21, v36, v21
	v_mul_f32_e32 v36, v22, v21
	v_fma_f32 v37, -v20, v36, v22
	v_fmac_f32_e32 v36, v37, v21
	v_fma_f32 v20, -v20, v36, v22
	v_div_fmas_f32 v20, v20, v21, v36
	v_div_fixup_f32 v19, v20, v19, 1.0
	v_mul_f32_e32 v20, v23, v19
	v_mul_f32_e32 v7, v7, v19
	v_mul_f32_e32 v19, 0xbfb8aa3b, v6
	v_mul_f32_e32 v21, 0xbfb8aa3b, v18
	v_exp_f32_e32 v19, v19
	v_exp_f32_e32 v21, v21
	v_mul_f32_e32 v20, v48, v20
	v_mul_f32_e32 v7, v59, v7
	v_add_f32_e32 v19, 1.0, v19
	v_add_f32_e32 v21, 1.0, v21
	v_rcp_f32_e32 v19, v19
	v_rcp_f32_e32 v21, v21
	v_mul_f32_e32 v6, v20, v6
	v_mul_f32_e32 v7, v7, v18
	v_mul_f32_e32 v6, v19, v6
	v_mul_f32_e32 v7, v7, v21
	v_bfe_u32 v18, v6, 16, 1
	v_bfe_u32 v19, v7, 16, 1
	v_add3_u32 v6, v6, v18, s89
	v_add3_u32 v7, v7, v19, s89
	global_store_short_d16_hi v[0:1], v6, off
	global_store_short_d16_hi v[4:5], v7, off
	v_mov_b32_e32 v44, v128
	v_mov_b32_e32 v45, v129
	ds_read_b128 v[0:3], v83
	ds_read_b128 v[4:7], v83 offset:256
	ds_read_b128 v[16:19], v83 offset:512
	ds_read_b128 v[20:23], v83 offset:768
	v_or_b32_e32 v36, s66, v84
	v_ashrrev_i32_e32 v37, 31, v36
	s_waitcnt lgkmcnt(2)
	v_add_f32_e32 v0, v0, v4
	v_lshlrev_b64 v[36:37], 10, v[36:37]
	s_waitcnt lgkmcnt(0)
; __device__ __forceinline__ unsigned f2bf(float f) { unsigned u = __builtin_bit_cast(unsigned, f); return (u + 0x7fffu + ((u >> 16) & 1u)) >> 16; }
; __device__ __forceinline__ int crow(int r, int hi) { return (r & 3) + 8 * (r >> 2) + 4 * hi; }
; __device__ __forceinline__ float sigmoid_f(float x) { return __builtin_amdgcn_rcpf(1.0f + __builtin_amdgcn_exp2f(-x * LOG2E)); }
; __device__ __forceinline__ void gla_out(const Ptrs& A, int l, LAS unsigned char* lds, int c, int G, int wave, int lane_, const int wv0) {
;     ...
;         for (int r = 0; r < 16; ++r) { const int t = 32 * ti + crow(r, hi);
;             const float tot = (red[t] + red[64 + t]) + (red[128 + t] + red[192 + t]); const float rinv = 1.0f / sqrtf(tot * (1.0f / 256.0f) + EPS);
;             const size_t off = (size_t)(t0 + t) * 1024 + hd * 256 + 64 * vq + r32;
;             const float r0 = bf2f(GR[off]), r1 = bf2f(GR[off + 32]);
;             AG[off] = (bf16)f2bf(o0[r] * rinv * g0 * r0 * pg8::sigmoid_f(r0)); AG[off + 32] = (bf16)f2bf(o1[r] * rinv * g1 * r1 * pg8::sigmoid_f(r1)); }
	v_add_f32_e32 v4, v16, v20
	v_add_f32_e32 v0, v0, v4
	v_fmamk_f32 v0, v0, 0x3b800000, v93
	v_mul_f32_e32 v4, 0x4f800000, v0
	v_cmp_gt_f32_e32 vcc, s90, v0
	v_lshl_add_u64 v[36:37], v[36:37], 0, v[60:61]
	v_lshlrev_b64 v[36:37], 1, v[36:37]
	v_cndmask_b32_e32 v0, v0, v4, vcc
	v_sqrt_f32_e32 v4, v0
	v_lshl_add_u64 v[38:39], s[50:51], 0, v[36:37]
	v_or_b32_e32 v40, 64, v36
	v_mov_b32_e32 v41, v37
	v_add_u32_e32 v16, -1, v4
	v_add_u32_e32 v20, 1, v4
	v_fma_f32 v42, -v16, v4, v0
	v_fma_f32 v43, -v20, v4, v0
	v_cmp_ge_f32_e64 s[36:37], 0, v42
	v_lshl_add_u64 v[34:35], s[52:53], 0, v[34:35]
	v_add_f32_e32 v17, v17, v21
	v_cndmask_b32_e64 v4, v4, v16, s[36:37]
	v_cmp_lt_f32_e64 s[36:37], 0, v43
	v_lshl_add_u64 v[42:43], s[50:51], 0, v[40:41]
	v_add_f32_e32 v2, v2, v6
	v_cndmask_b32_e64 v4, v4, v20, s[36:37]
	v_mul_f32_e32 v16, 0x37800000, v4
	v_cndmask_b32_e32 v4, v4, v16, vcc
	v_cmp_class_f32_e32 vcc, v0, v94
	v_add_f32_e32 v6, v18, v22
	v_add_f32_e32 v2, v2, v6
	v_cndmask_b32_e32 v0, v4, v0, vcc
	v_div_scale_f32 v4, s[36:37], v0, v0, 1.0
	v_rcp_f32_e32 v16, v4
	v_div_scale_f32 v20, vcc, 1.0, v0, 1.0
	v_fmamk_f32 v2, v2, 0x3b800000, v93
	v_fma_f32 v46, -v4, v16, 1.0
	v_fmac_f32_e32 v16, v46, v16
	v_mul_f32_e32 v46, v20, v16
	v_fma_f32 v47, -v4, v46, v20
	v_fmac_f32_e32 v46, v47, v16
	v_fma_f32 v4, -v4, v46, v20
	v_div_fmas_f32 v4, v4, v16, v46
	v_div_fixup_f32 v0, v4, v0, 1.0
	v_mul_f32_e32 v4, v24, v0
	v_mul_f32_e32 v0, v8, v0
	v_mul_f32_e32 v4, v48, v4
	v_mul_f32_e32 v0, v59, v0
	v_mul_f32_e32 v6, 0x4f800000, v2
	v_lshlrev_b32_e32 v8, 16, v44
	v_lshlrev_b32_e32 v16, 16, v45
	v_mul_f32_e32 v20, 0xbfb8aa3b, v8
	v_mul_f32_e32 v24, 0xbfb8aa3b, v16
	v_exp_f32_e32 v20, v20
	v_exp_f32_e32 v24, v24
	v_mul_f32_e32 v4, v4, v8
	v_mul_f32_e32 v0, v0, v16
	v_add_f32_e32 v20, 1.0, v20
	v_add_f32_e32 v24, 1.0, v24
	v_rcp_f32_e32 v20, v20
	v_rcp_f32_e32 v24, v24
	v_mul_f32_e32 v4, v20, v4
	v_mul_f32_e32 v0, v0, v24
	v_bfe_u32 v8, v4, 16, 1
	v_bfe_u32 v16, v0, 16, 1
	v_add3_u32 v4, v4, v8, s89
	v_add3_u32 v0, v0, v16, s89
	global_store_short_d16_hi v[32:33], v4, off
	global_store_short_d16_hi v[34:35], v0, off
	v_mov_b32_e32 v8, v130
	v_mov_b32_e32 v24, v131
	v_add_f32_e32 v16, v1, v5
	v_add_f32_e32 v16, v16, v17
	v_fmamk_f32 v16, v16, 0x3b800000, v93
	v_mul_f32_e32 v17, 0x4f800000, v16
	v_cmp_gt_f32_e32 vcc, s90, v16
	v_lshl_add_u64 v[0:1], s[52:53], 0, v[36:37]
	v_lshl_add_u64 v[20:21], s[52:53], 0, v[40:41]
	v_cndmask_b32_e32 v34, v16, v17, vcc
	v_sqrt_f32_e32 v35, v34
	v_or_b32_e32 v32, s66, v85
	v_ashrrev_i32_e32 v33, 31, v32
	v_lshlrev_b64 v[32:33], 10, v[32:33]
	v_add_u32_e32 v36, -1, v35
	v_add_u32_e32 v37, 1, v35
	v_fma_f32 v38, -v36, v35, v34
	v_fma_f32 v39, -v37, v35, v34
	v_cmp_ge_f32_e64 s[36:37], 0, v38
	v_lshl_add_u64 v[32:33], v[32:33], 0, v[60:61]
	v_lshlrev_b64 v[32:33], 1, v[32:33]
	v_cndmask_b32_e64 v35, v35, v36, s[36:37]
	v_cmp_lt_f32_e64 s[36:37], 0, v39
	v_or_b32_e32 v16, 64, v32
	v_mov_b32_e32 v17, v33
	v_cndmask_b32_e64 v35, v35, v37, s[36:37]
	v_mul_f32_e32 v36, 0x37800000, v35
	v_cndmask_b32_e32 v35, v35, v36, vcc
	v_cmp_class_f32_e32 vcc, v34, v94
	v_lshl_add_u64 v[4:5], s[50:51], 0, v[32:33]
	v_lshlrev_b32_e32 v8, 16, v8
	v_cndmask_b32_e32 v36, v35, v34, vcc
	v_div_scale_f32 v37, s[36:37], v36, v36, 1.0
	v_rcp_f32_e32 v38, v37
	v_div_scale_f32 v39, vcc, 1.0, v36, 1.0
	v_lshlrev_b32_e32 v24, 16, v24
	v_fma_f32 v40, -v37, v38, 1.0
	v_fmac_f32_e32 v38, v40, v38
	v_mul_f32_e32 v40, v39, v38
	v_fma_f32 v41, -v37, v40, v39
	v_fmac_f32_e32 v40, v41, v38
	v_fma_f32 v37, -v37, v40, v39
	v_div_fmas_f32 v37, v37, v38, v40
	v_div_fixup_f32 v36, v37, v36, 1.0
	v_mul_f32_e32 v25, v25, v36
	v_mul_f32_e32 v9, v9, v36
	v_mul_f32_e32 v36, 0xbfb8aa3b, v8
	v_mul_f32_e32 v37, 0xbfb8aa3b, v24
	v_exp_f32_e32 v36, v36
	v_exp_f32_e32 v37, v37
	v_mul_f32_e32 v25, v48, v25
	v_mul_f32_e32 v9, v59, v9
	v_add_f32_e32 v36, 1.0, v36
	v_add_f32_e32 v37, 1.0, v37
	v_rcp_f32_e32 v36, v36
	v_rcp_f32_e32 v37, v37
	v_mul_f32_e32 v8, v25, v8
	v_mul_f32_e32 v9, v9, v24
	v_mul_f32_e32 v8, v36, v8
	v_mul_f32_e32 v9, v9, v37
	v_bfe_u32 v24, v8, 16, 1
	v_bfe_u32 v25, v9, 16, 1
	v_add3_u32 v8, v8, v24, s89
	v_lshl_add_u64 v[34:35], s[50:51], 0, v[16:17]
	v_add3_u32 v9, v9, v25, s89
	global_store_short_d16_hi v[0:1], v8, off
	global_store_short_d16_hi v[20:21], v9, off
	v_mov_b32_e32 v36, v132
	s_nop 0
	v_mov_b32_e32 v34, v133
	v_cmp_gt_f32_e32 vcc, s90, v2
	v_lshl_add_u64 v[4:5], s[52:53], 0, v[32:33]
	v_or_b32_e32 v0, s66, v86
	v_cndmask_b32_e32 v2, v2, v6, vcc
	v_sqrt_f32_e32 v6, v2
	v_ashrrev_i32_e32 v1, 31, v0
	v_lshlrev_b64 v[0:1], 10, v[0:1]
	v_lshl_add_u64 v[0:1], v[0:1], 0, v[60:61]
	v_add_u32_e32 v18, -1, v6
	v_add_u32_e32 v22, 1, v6
	v_fma_f32 v24, -v18, v6, v2
	v_fma_f32 v25, -v22, v6, v2
	v_cmp_ge_f32_e64 s[36:37], 0, v24
	v_lshlrev_b64 v[0:1], 1, v[0:1]
	v_lshl_add_u64 v[8:9], s[50:51], 0, v[0:1]
	v_cndmask_b32_e64 v6, v6, v18, s[36:37]
	v_cmp_lt_f32_e64 s[36:37], 0, v25
	v_or_b32_e32 v20, 64, v0
	v_mov_b32_e32 v21, v1
	v_cndmask_b32_e64 v6, v6, v22, s[36:37]
	v_mul_f32_e32 v18, 0x37800000, v6
	v_cndmask_b32_e32 v6, v6, v18, vcc
	v_cmp_class_f32_e32 vcc, v2, v94
	v_lshl_add_u64 v[16:17], s[52:53], 0, v[16:17]
	v_lshl_add_u64 v[24:25], s[50:51], 0, v[20:21]
	v_cndmask_b32_e32 v2, v6, v2, vcc
	v_div_scale_f32 v6, s[36:37], v2, v2, 1.0
	v_rcp_f32_e32 v18, v6
	v_div_scale_f32 v22, vcc, 1.0, v2, 1.0
	v_lshl_add_u64 v[0:1], s[52:53], 0, v[0:1]
	v_fma_f32 v32, -v6, v18, 1.0
	v_fmac_f32_e32 v18, v32, v18
	v_mul_f32_e32 v32, v22, v18
	v_fma_f32 v33, -v6, v32, v22
	v_fmac_f32_e32 v32, v33, v18
	v_fma_f32 v6, -v6, v32, v22
	v_div_fmas_f32 v6, v6, v18, v32
; __device__ __forceinline__ unsigned f2bf(float f) { unsigned u = __builtin_bit_cast(unsigned, f); return (u + 0x7fffu + ((u >> 16) & 1u)) >> 16; }
; __device__ __forceinline__ int crow(int r, int hi) { return (r & 3) + 8 * (r >> 2) + 4 * hi; }
; __device__ __forceinline__ float sigmoid_f(float x) { return __builtin_amdgcn_rcpf(1.0f + __builtin_amdgcn_exp2f(-x * LOG2E)); }
; __device__ __forceinline__ void gla_out(const Ptrs& A, int l, LAS unsigned char* lds, int c, int G, int wave, int lane_, const int wv0) {
;     ...
;         for (int r = 0; r < 16; ++r) { const int t = 32 * ti + crow(r, hi);
;             const float tot = (red[t] + red[64 + t]) + (red[128 + t] + red[192 + t]); const float rinv = 1.0f / sqrtf(tot * (1.0f / 256.0f) + EPS);
;             const size_t off = (size_t)(t0 + t) * 1024 + hd * 256 + 64 * vq + r32;
;             const float r0 = bf2f(GR[off]), r1 = bf2f(GR[off + 32]);
;             AG[off] = (bf16)f2bf(o0[r] * rinv * g0 * r0 * pg8::sigmoid_f(r0)); AG[off + 32] = (bf16)f2bf(o1[r] * rinv * g1 * r1 * pg8::sigmoid_f(r1)); }
	v_div_fixup_f32 v2, v6, v2, 1.0
	v_mul_f32_e32 v6, v26, v2
	v_mul_f32_e32 v2, v10, v2
	v_mul_f32_e32 v6, v48, v6
	v_mul_f32_e32 v2, v59, v2
	v_lshlrev_b32_e32 v10, 16, v36
	v_lshlrev_b32_e32 v18, 16, v34
	v_mul_f32_e32 v22, 0xbfb8aa3b, v10
	v_mul_f32_e32 v26, 0xbfb8aa3b, v18
	v_exp_f32_e32 v22, v22
	v_exp_f32_e32 v26, v26
	v_mul_f32_e32 v6, v6, v10
	v_mul_f32_e32 v2, v2, v18
	v_add_f32_e32 v22, 1.0, v22
	v_add_f32_e32 v26, 1.0, v26
	v_rcp_f32_e32 v22, v22
	v_rcp_f32_e32 v26, v26
	v_mul_f32_e32 v6, v22, v6
	v_mul_f32_e32 v2, v2, v26
	v_bfe_u32 v10, v6, 16, 1
	v_bfe_u32 v18, v2, 16, 1
	v_add3_u32 v6, v6, v10, s89
	v_add3_u32 v2, v2, v18, s89
	global_store_short_d16_hi v[4:5], v6, off
	global_store_short_d16_hi v[16:17], v2, off
	v_mov_b32_e32 v8, v134
	s_nop 0
	v_mov_b32_e32 v9, v135
	v_or_b32_e32 v4, s66, v87
	v_ashrrev_i32_e32 v5, 31, v4
	v_lshlrev_b64 v[4:5], 10, v[4:5]
	v_lshl_add_u64 v[4:5], v[4:5], 0, v[60:61]
	v_lshlrev_b64 v[24:25], 1, v[4:5]
	v_add_f32_e32 v4, v3, v7
	v_add_f32_e32 v5, v19, v23
	v_add_f32_e32 v4, v4, v5
	v_fmamk_f32 v4, v4, 0x3b800000, v93
	v_mul_f32_e32 v5, 0x4f800000, v4
	v_cmp_gt_f32_e32 vcc, s90, v4
	v_lshl_add_u64 v[2:3], s[50:51], 0, v[24:25]
	v_or_b32_e32 v22, 64, v24
	v_cndmask_b32_e32 v6, v4, v5, vcc
	v_sqrt_f32_e32 v7, v6
	v_lshl_add_u64 v[4:5], s[52:53], 0, v[20:21]
	v_mov_b32_e32 v23, v25
	v_lshl_add_u64 v[24:25], s[52:53], 0, v[24:25]
	v_add_u32_e32 v10, -1, v7
	v_add_u32_e32 v16, 1, v7
	v_fma_f32 v17, -v10, v7, v6
	v_fma_f32 v18, -v16, v7, v6
	v_cmp_ge_f32_e64 s[36:37], 0, v17
	v_lshlrev_b32_e32 v8, 16, v8
	v_cndmask_b32_e64 v7, v7, v10, s[36:37]
	v_cmp_lt_f32_e64 s[36:37], 0, v18
	v_lshlrev_b32_e32 v9, 16, v9
	v_cndmask_b32_e64 v7, v7, v16, s[36:37]
	v_mul_f32_e32 v10, 0x37800000, v7
	v_cndmask_b32_e32 v7, v7, v10, vcc
	v_cmp_class_f32_e32 vcc, v6, v94
	s_nop 1
	v_cndmask_b32_e32 v10, v7, v6, vcc
	v_div_scale_f32 v16, s[36:37], v10, v10, 1.0
	v_rcp_f32_e32 v17, v16
	v_div_scale_f32 v18, vcc, 1.0, v10, 1.0
	v_lshl_add_u64 v[6:7], s[50:51], 0, v[22:23]
	v_fma_f32 v19, -v16, v17, 1.0
	v_fmac_f32_e32 v17, v19, v17
	v_mul_f32_e32 v19, v18, v17
	v_fma_f32 v20, -v16, v19, v18
	v_fmac_f32_e32 v19, v20, v17
	v_fma_f32 v16, -v16, v19, v18
	v_div_fmas_f32 v16, v16, v17, v19
	v_div_fixup_f32 v10, v16, v10, 1.0
	v_mul_f32_e32 v16, v27, v10
	v_mul_f32_e32 v10, v11, v10
	v_mul_f32_e32 v11, 0xbfb8aa3b, v8
	v_mul_f32_e32 v17, 0xbfb8aa3b, v9
	v_exp_f32_e32 v11, v11
	v_exp_f32_e32 v17, v17
	v_mul_f32_e32 v16, v48, v16
	v_mul_f32_e32 v10, v59, v10
	v_add_f32_e32 v11, 1.0, v11
	v_add_f32_e32 v17, 1.0, v17
	v_rcp_f32_e32 v11, v11
	v_rcp_f32_e32 v17, v17
	v_mul_f32_e32 v8, v16, v8
	v_mul_f32_e32 v9, v10, v9
	v_mul_f32_e32 v8, v11, v8
	v_mul_f32_e32 v9, v9, v17
	v_bfe_u32 v10, v8, 16, 1
	v_bfe_u32 v11, v9, 16, 1
	v_add3_u32 v8, v8, v10, s89
	v_add3_u32 v9, v9, v11, s89
	global_store_short_d16_hi v[0:1], v8, off
	global_store_short_d16_hi v[4:5], v9, off
	v_mov_b32_e32 v36, v136
	v_mov_b32_e32 v37, v137
	ds_read_b128 v[0:3], v88
	ds_read_b128 v[4:7], v88 offset:256
	ds_read_b128 v[8:11], v88 offset:512
	ds_read_b128 v[16:19], v88 offset:768
	v_or_b32_e32 v20, s66, v89
	v_ashrrev_i32_e32 v21, 31, v20
	s_waitcnt lgkmcnt(2)
	v_add_f32_e32 v0, v0, v4
	v_lshlrev_b64 v[20:21], 10, v[20:21]
	s_waitcnt lgkmcnt(0)
	v_add_f32_e32 v4, v8, v16
	v_add_f32_e32 v0, v0, v4
	v_fmamk_f32 v0, v0, 0x3b800000, v93
	v_mul_f32_e32 v4, 0x4f800000, v0
	v_cmp_gt_f32_e32 vcc, s90, v0
	v_lshl_add_u64 v[20:21], v[20:21], 0, v[60:61]
	v_lshlrev_b64 v[20:21], 1, v[20:21]
	v_cndmask_b32_e32 v0, v0, v4, vcc
	v_sqrt_f32_e32 v4, v0
	v_lshl_add_u64 v[26:27], s[50:51], 0, v[20:21]
	v_or_b32_e32 v32, 64, v20
	v_mov_b32_e32 v33, v21
	v_add_u32_e32 v8, -1, v4
	v_add_u32_e32 v16, 1, v4
	v_fma_f32 v34, -v8, v4, v0
	v_fma_f32 v35, -v16, v4, v0
	v_cmp_ge_f32_e64 s[36:37], 0, v34
	v_lshl_add_u64 v[22:23], s[52:53], 0, v[22:23]
	v_add_f32_e32 v9, v9, v17
	v_cndmask_b32_e64 v4, v4, v8, s[36:37]
	v_cmp_lt_f32_e64 s[36:37], 0, v35
	v_lshl_add_u64 v[34:35], s[50:51], 0, v[32:33]
	v_add_f32_e32 v2, v2, v6
	v_cndmask_b32_e64 v4, v4, v16, s[36:37]
	v_mul_f32_e32 v8, 0x37800000, v4
	v_cndmask_b32_e32 v4, v4, v8, vcc
	v_cmp_class_f32_e32 vcc, v0, v94
	v_add_f32_e32 v6, v10, v18
	v_add_f32_e32 v2, v2, v6
	v_cndmask_b32_e32 v0, v4, v0, vcc
	v_div_scale_f32 v4, s[36:37], v0, v0, 1.0
	v_rcp_f32_e32 v8, v4
	v_div_scale_f32 v16, vcc, 1.0, v0, 1.0
	v_fmamk_f32 v2, v2, 0x3b800000, v93
	v_fma_f32 v38, -v4, v8, 1.0
	v_fmac_f32_e32 v8, v38, v8
	v_mul_f32_e32 v38, v16, v8
	v_fma_f32 v39, -v4, v38, v16
	v_fmac_f32_e32 v38, v39, v8
	v_fma_f32 v4, -v4, v38, v16
	v_div_fmas_f32 v4, v4, v8, v38
	v_div_fixup_f32 v0, v4, v0, 1.0
	v_mul_f32_e32 v4, v28, v0
	v_mul_f32_e32 v0, v12, v0
	v_mul_f32_e32 v4, v48, v4
	v_mul_f32_e32 v0, v59, v0
	v_mul_f32_e32 v6, 0x4f800000, v2
	v_lshlrev_b32_e32 v8, 16, v36
	v_lshlrev_b32_e32 v12, 16, v37
	v_mul_f32_e32 v16, 0xbfb8aa3b, v8
	v_mul_f32_e32 v28, 0xbfb8aa3b, v12
	v_exp_f32_e32 v16, v16
	v_exp_f32_e32 v28, v28
	v_mul_f32_e32 v4, v4, v8
	v_mul_f32_e32 v0, v0, v12
	v_add_f32_e32 v16, 1.0, v16
	v_add_f32_e32 v28, 1.0, v28
	v_rcp_f32_e32 v16, v16
	v_rcp_f32_e32 v28, v28
	v_mul_f32_e32 v4, v16, v4
	v_mul_f32_e32 v0, v0, v28
	v_bfe_u32 v8, v4, 16, 1
	v_bfe_u32 v12, v0, 16, 1
	v_add3_u32 v4, v4, v8, s89
	v_add3_u32 v0, v0, v12, s89
	global_store_short_d16_hi v[24:25], v4, off
	global_store_short_d16_hi v[22:23], v0, off
	v_mov_b32_e32 v12, v138
	s_nop 0
	v_mov_b32_e32 v24, v139
	v_add_f32_e32 v8, v1, v5
	v_add_f32_e32 v8, v8, v9
	v_fmamk_f32 v8, v8, 0x3b800000, v93
	v_mul_f32_e32 v9, 0x4f800000, v8
	v_cmp_gt_f32_e32 vcc, s90, v8
	v_lshl_add_u64 v[0:1], s[52:53], 0, v[20:21]
; __device__ __forceinline__ unsigned f2bf(float f) { unsigned u = __builtin_bit_cast(unsigned, f); return (u + 0x7fffu + ((u >> 16) & 1u)) >> 16; }
; __device__ __forceinline__ int crow(int r, int hi) { return (r & 3) + 8 * (r >> 2) + 4 * hi; }
; __device__ __forceinline__ float sigmoid_f(float x) { return __builtin_amdgcn_rcpf(1.0f + __builtin_amdgcn_exp2f(-x * LOG2E)); }
; __device__ __forceinline__ void gla_out(const Ptrs& A, int l, LAS unsigned char* lds, int c, int G, int wave, int lane_, const int wv0) {
;     ...
;         for (int r = 0; r < 16; ++r) { const int t = 32 * ti + crow(r, hi);
;             const float tot = (red[t] + red[64 + t]) + (red[128 + t] + red[192 + t]); const float rinv = 1.0f / sqrtf(tot * (1.0f / 256.0f) + EPS);
;             const size_t off = (size_t)(t0 + t) * 1024 + hd * 256 + 64 * vq + r32;
;             const float r0 = bf2f(GR[off]), r1 = bf2f(GR[off + 32]);
;             AG[off] = (bf16)f2bf(o0[r] * rinv * g0 * r0 * pg8::sigmoid_f(r0)); AG[off + 32] = (bf16)f2bf(o1[r] * rinv * g1 * r1 * pg8::sigmoid_f(r1)); }
;         __syncthreads();
	v_lshl_add_u64 v[16:17], s[52:53], 0, v[32:33]
	v_cndmask_b32_e32 v20, v8, v9, vcc
	v_sqrt_f32_e32 v21, v20
	v_or_b32_e32 v22, s66, v90
	v_ashrrev_i32_e32 v23, 31, v22
	v_lshlrev_b64 v[22:23], 10, v[22:23]
	v_add_u32_e32 v25, -1, v21
	v_add_u32_e32 v26, 1, v21
	v_fma_f32 v27, -v25, v21, v20
	v_fma_f32 v28, -v26, v21, v20
	v_cmp_ge_f32_e64 s[36:37], 0, v27
	v_lshl_add_u64 v[22:23], v[22:23], 0, v[60:61]
	v_lshlrev_b64 v[22:23], 1, v[22:23]
	v_cndmask_b32_e64 v21, v21, v25, s[36:37]
	v_cmp_lt_f32_e64 s[36:37], 0, v28
	v_lshl_add_u64 v[4:5], s[50:51], 0, v[22:23]
	v_or_b32_e32 v8, 64, v22
	v_cndmask_b32_e64 v21, v21, v26, s[36:37]
	v_mul_f32_e32 v25, 0x37800000, v21
	v_cndmask_b32_e32 v21, v21, v25, vcc
	v_cmp_class_f32_e32 vcc, v20, v94
	v_mov_b32_e32 v9, v23
	v_lshlrev_b32_e32 v12, 16, v12
	v_cndmask_b32_e32 v25, v21, v20, vcc
	v_div_scale_f32 v26, s[36:37], v25, v25, 1.0
	v_rcp_f32_e32 v27, v26
	v_div_scale_f32 v28, vcc, 1.0, v25, 1.0
	v_lshlrev_b32_e32 v24, 16, v24
	v_fma_f32 v32, -v26, v27, 1.0
	v_fmac_f32_e32 v27, v32, v27
	v_mul_f32_e32 v32, v28, v27
	v_fma_f32 v33, -v26, v32, v28
	v_fmac_f32_e32 v32, v33, v27
	v_fma_f32 v26, -v26, v32, v28
	v_div_fmas_f32 v26, v26, v27, v32
	v_div_fixup_f32 v25, v26, v25, 1.0
	v_mul_f32_e32 v26, v29, v25
	v_mul_f32_e32 v13, v13, v25
	v_mul_f32_e32 v25, 0xbfb8aa3b, v12
	v_mul_f32_e32 v27, 0xbfb8aa3b, v24
	v_exp_f32_e32 v25, v25
	v_exp_f32_e32 v27, v27
	v_mul_f32_e32 v26, v48, v26
	v_mul_f32_e32 v13, v59, v13
	v_add_f32_e32 v25, 1.0, v25
	v_add_f32_e32 v27, 1.0, v27
	v_rcp_f32_e32 v25, v25
	v_rcp_f32_e32 v27, v27
	v_mul_f32_e32 v12, v26, v12
	v_mul_f32_e32 v13, v13, v24
	v_mul_f32_e32 v12, v25, v12
	v_mul_f32_e32 v13, v13, v27
	v_bfe_u32 v24, v12, 16, 1
	v_bfe_u32 v25, v13, 16, 1
	v_add3_u32 v12, v12, v24, s89
	v_add3_u32 v13, v13, v25, s89
	global_store_short_d16_hi v[0:1], v12, off
	global_store_short_d16_hi v[16:17], v13, off
	v_lshl_add_u64 v[20:21], s[50:51], 0, v[8:9]
	v_mov_b32_e32 v24, v140
	v_mov_b32_e32 v25, v141
	v_cmp_gt_f32_e32 vcc, s90, v2
	v_lshl_add_u64 v[4:5], s[52:53], 0, v[22:23]
	v_or_b32_e32 v0, s66, v91
	v_cndmask_b32_e32 v2, v2, v6, vcc
	v_sqrt_f32_e32 v6, v2
	v_ashrrev_i32_e32 v1, 31, v0
	v_lshlrev_b64 v[0:1], 10, v[0:1]
	v_lshl_add_u64 v[0:1], v[0:1], 0, v[60:61]
	v_add_u32_e32 v10, -1, v6
	v_add_u32_e32 v18, 1, v6
	v_fma_f32 v20, -v10, v6, v2
	v_fma_f32 v21, -v18, v6, v2
	v_cmp_ge_f32_e64 s[36:37], 0, v20
	v_lshlrev_b64 v[0:1], 1, v[0:1]
	v_lshl_add_u64 v[12:13], s[50:51], 0, v[0:1]
	v_cndmask_b32_e64 v6, v6, v10, s[36:37]
	v_cmp_lt_f32_e64 s[36:37], 0, v21
	v_or_b32_e32 v16, 64, v0
	v_mov_b32_e32 v17, v1
	v_cndmask_b32_e64 v6, v6, v18, s[36:37]
	v_mul_f32_e32 v10, 0x37800000, v6
	v_cndmask_b32_e32 v6, v6, v10, vcc
	v_cmp_class_f32_e32 vcc, v2, v94
	v_lshl_add_u64 v[8:9], s[52:53], 0, v[8:9]
	v_lshl_add_u64 v[20:21], s[50:51], 0, v[16:17]
	v_cndmask_b32_e32 v2, v6, v2, vcc
	v_div_scale_f32 v6, s[36:37], v2, v2, 1.0
	v_rcp_f32_e32 v10, v6
	v_div_scale_f32 v18, vcc, 1.0, v2, 1.0
	v_lshl_add_u64 v[0:1], s[52:53], 0, v[0:1]
	v_fma_f32 v22, -v6, v10, 1.0
	v_fmac_f32_e32 v10, v22, v10
	v_mul_f32_e32 v22, v18, v10
	v_fma_f32 v23, -v6, v22, v18
	v_fmac_f32_e32 v22, v23, v10
	v_fma_f32 v6, -v6, v22, v18
	v_div_fmas_f32 v6, v6, v10, v22
	v_div_fixup_f32 v2, v6, v2, 1.0
	v_mul_f32_e32 v6, v30, v2
	v_mul_f32_e32 v2, v14, v2
	v_mul_f32_e32 v6, v48, v6
	v_mul_f32_e32 v2, v59, v2
	v_lshlrev_b32_e32 v10, 16, v24
	v_lshlrev_b32_e32 v14, 16, v25
	v_mul_f32_e32 v18, 0xbfb8aa3b, v10
	v_mul_f32_e32 v22, 0xbfb8aa3b, v14
	v_exp_f32_e32 v18, v18
	v_exp_f32_e32 v22, v22
	v_mul_f32_e32 v6, v6, v10
	v_mul_f32_e32 v2, v2, v14
	v_add_f32_e32 v18, 1.0, v18
	v_add_f32_e32 v22, 1.0, v22
	v_rcp_f32_e32 v18, v18
	v_rcp_f32_e32 v22, v22
	v_mul_f32_e32 v6, v18, v6
	v_mul_f32_e32 v2, v2, v22
	v_bfe_u32 v10, v6, 16, 1
	v_bfe_u32 v14, v2, 16, 1
	v_add3_u32 v6, v6, v10, s89
	v_add3_u32 v2, v2, v14, s89
	global_store_short_d16_hi v[4:5], v6, off
	global_store_short_d16_hi v[8:9], v2, off
	v_mov_b32_e32 v4, v142
	s_nop 0
	v_mov_b32_e32 v5, v143
	v_add_f32_e32 v2, v3, v7
	v_add_f32_e32 v3, v11, v19
	v_add_f32_e32 v2, v2, v3
	v_fmamk_f32 v2, v2, 0x3b800000, v93
	v_mul_f32_e32 v3, 0x4f800000, v2
	v_cmp_gt_f32_e32 vcc, s90, v2
	v_lshlrev_b32_e32 v4, 16, v4
	v_cndmask_b32_e32 v2, v2, v3, vcc
	v_sqrt_f32_e32 v3, v2
	v_lshlrev_b32_e32 v5, 16, v5
	v_add_u32_e32 v6, -1, v3
	v_add_u32_e32 v7, 1, v3
	v_fma_f32 v8, -v6, v3, v2
	v_fma_f32 v9, -v7, v3, v2
	v_cmp_ge_f32_e64 s[36:37], 0, v8
	s_nop 1
	v_cndmask_b32_e64 v3, v3, v6, s[36:37]
	v_cmp_lt_f32_e64 s[36:37], 0, v9
	s_nop 1
	v_cndmask_b32_e64 v3, v3, v7, s[36:37]
	v_mul_f32_e32 v6, 0x37800000, v3
	v_cndmask_b32_e32 v3, v3, v6, vcc
	v_cmp_class_f32_e32 vcc, v2, v94
	s_nop 1
	v_cndmask_b32_e32 v6, v3, v2, vcc
	v_div_scale_f32 v7, s[36:37], v6, v6, 1.0
	v_rcp_f32_e32 v8, v7
	v_div_scale_f32 v9, vcc, 1.0, v6, 1.0
	v_lshl_add_u64 v[2:3], s[52:53], 0, v[16:17]
	v_fma_f32 v10, -v7, v8, 1.0
	v_fmac_f32_e32 v8, v10, v8
	v_mul_f32_e32 v10, v9, v8
	v_fma_f32 v11, -v7, v10, v9
	v_fmac_f32_e32 v10, v11, v8
	v_fma_f32 v7, -v7, v10, v9
	v_div_fmas_f32 v7, v7, v8, v10
	v_mul_f32_e32 v8, 0xbfb8aa3b, v4
	v_mul_f32_e32 v9, 0xbfb8aa3b, v5
	v_exp_f32_e32 v8, v8
	v_exp_f32_e32 v9, v9
	v_div_fixup_f32 v6, v7, v6, 1.0
	v_mul_f32_e32 v7, v31, v6
	v_add_f32_e32 v8, 1.0, v8
	v_add_f32_e32 v9, 1.0, v9
	v_rcp_f32_e32 v8, v8
	v_rcp_f32_e32 v9, v9
	v_mul_f32_e32 v6, v15, v6
	v_mul_f32_e32 v7, v48, v7
	v_mul_f32_e32 v6, v59, v6
	v_mul_f32_e32 v4, v7, v4
	v_mul_f32_e32 v5, v6, v5
	v_mul_f32_e32 v4, v8, v4
	v_mul_f32_e32 v5, v5, v9
	v_bfe_u32 v6, v4, 16, 1
	v_bfe_u32 v7, v5, 16, 1
	v_add3_u32 v4, v4, v6, s89
	v_add3_u32 v5, v5, v7, s89
	global_store_short_d16_hi v[0:1], v4, off
	global_store_short_d16_hi v[2:3], v5, off
	s_barrier
	s_cbranch_scc0 .LBB0_427
; #define LAS __attribute__((address_space(3)))
; #define TID() (wv0 * 64 + (int)__builtin_amdgcn_mbcnt_hi(~0u, __builtin_amdgcn_mbcnt_lo(~0u, 0u)))
; __device__ __forceinline__ int opaque(int x) { asm volatile("" : "+v"(x)); return x; }
;     __device__ __forceinline__ const float* in(int k) const { return (const float*)(const __attribute__((address_space(1))) float*)get(k); }
;     __device__ __forceinline__ unsigned char* ws() const { return (unsigned char*)(__attribute__((address_space(1))) unsigned char*)get(21); }
; __device__ __forceinline__ void gla_cumdecay(const Ptrs& A, int l, int n, int hd, LAS float* bl, const int wv0) {
;     const int tid = opaque(TID()), d = tid & 127, tq = __builtin_amdgcn_readfirstlane(tid >> 7);
;     const float* wa2 = A.in(4) + (size_t)l * 16 * 512 + hd * 128 + d;
;     float w[16];
; #pragma unroll
;     for (int r = 0; r < 16; ++r) w[r] = wa2[r * 512];
;     const float bias = A.in(5)[(size_t)l * 512 + hd * 128 + d];
;     LAS float* gal = bl + 29184;
;     *(LAS f32x2*)(gal + 2 * tid) = *(const f32x2*)((const float*)(A.ws() + WS_GA1) + (size_t)n * 64 * 16 + 2 * tid);
;     __syncthreads();
;     const LAS float* ga = gal + 16 * tq * 16;
;     float run = 0.f;
;     for (int tt = 0; tt < 16; ++tt) {
;         float pre = bias;
;         const f32x4 g0 = *(const LAS f32x4*)(ga + tt * 16), g1 = *(const LAS f32x4*)(ga + tt * 16 + 4), g2 = *(const LAS f32x4*)(ga + tt * 16 + 8), g3 = *(const LAS f32x4*)(ga + tt * 16 + 12);
;         pre += (g0.x * w[0] + g0.y * w[1]) + (g0.z * w[2] + g0.w * w[3]); pre += (g1.x * w[4] + g1.y * w[5]) + (g1.z * w[6] + g1.w * w[7]);
;         pre += (g2.x * w[8] + g2.y * w[9]) + (g2.z * w[10] + g2.w * w[11]); pre += (g3.x * w[12] + g3.y * w[13]) + (g3.z * w[14] + g3.w * w[15]);
;         const float la = (fminf(pre, 0.f) - __logf(1.0f + __expf(-fabsf(pre)))) * (1.0f / 16.0f);
;         run += la; bl[(16 * tq + tt) * BLS + d] = run;
; __device__ __forceinline__ void gla_out(const Ptrs& A, int l, LAS unsigned char* lds, int c, int G, int wave, int lane_, const int wv0) {
;     ...
;         for (int i = 0; i < 2; ++i) { qq[i] = *(const u32x4*)(GQ + (size_t)(t0 + lane) * 512 + hd * 128 + (wave + 8 * i) * 8); kk[i] = *(const u32x4*)(GK + (size_t)(t0 + lane) * 512 + hd * 128 + (wave + 8 * i) * 8); }
;         gla_cumdecay(A, l, n, hd, bl, wv0);
.LBB0_383:
	s_ashr_i32 s36, s44, 2
	s_lshl_b32 s66, s36, 6
	v_or_b32_e32 v0, s66, v62
	v_ashrrev_i32_e32 v1, 31, v0
	s_and_b32 s37, s44, 3
	v_lshlrev_b64 v[0:1], 10, v[0:1]
	v_lshl_add_u64 v[2:3], s[46:47], 0, v[0:1]
	s_lshl_b32 s56, s37, 8
	v_lshl_add_u64 v[0:1], s[48:49], 0, v[0:1]
	v_lshl_add_u64 v[2:3], v[2:3], 0, s[56:57]
	v_lshl_add_u64 v[0:1], v[0:1], 0, s[56:57]
	s_lshl_b64 s[40:41], s[54:55], 1
	v_lshl_add_u64 v[2:3], v[2:3], 0, s[40:41]
	v_lshl_add_u64 v[0:1], v[0:1], 0, s[40:41]
	v_mov_b32_e32 v23, v204
	global_load_dwordx4 v[12:15], v[2:3], off
	global_load_dwordx4 v[4:7], v[2:3], off offset:128
	global_load_dwordx4 v[8:11], v[0:1], off
	s_nop 0
	global_load_dwordx4 v[0:3], v[0:1], off offset:128
	v_mov_b32 v16, s77
	ds_read_b64 v[16:17], v16 offset:32
	s_lshl_b32 s40, s37, 9
	v_readfirstlane_b32 s37, v23
	s_waitcnt lgkmcnt(0)
	v_readfirstlane_b32 s67, v16
	v_readfirstlane_b32 s41, v17
	s_add_u32 s92, s67, s40
	v_lshlrev_b32_e32 v16, 2, v23
	s_addc_u32 s93, s41, 0
	v_and_b32_e32 v48, 0x1fc, v16
	v_lshl_add_u64 v[26:27], s[92:93], 0, v[48:49]
	v_add_co_u32_e32 v34, vcc, s39, v26
	s_ashr_i32 s41, s37, 7
	s_nop 0
	v_addc_co_u32_e32 v35, vcc, 0, v27, vcc
	v_add_co_u32_e32 v28, vcc, s45, v26
	s_nop 1
	v_addc_co_u32_e32 v29, vcc, 0, v27, vcc
	v_add_co_u32_e32 v36, vcc, s72, v26
	s_nop 1
	v_addc_co_u32_e32 v37, vcc, 0, v27, vcc
	v_add_co_u32_e32 v18, vcc, s73, v26
	s_nop 1
	v_addc_co_u32_e32 v19, vcc, 0, v27, vcc
	v_add_co_u32_e32 v38, vcc, s74, v26
	s_nop 1
	v_addc_co_u32_e32 v39, vcc, 0, v27, vcc
	v_add_co_u32_e32 v30, vcc, s75, v26
	s_nop 1
	v_addc_co_u32_e32 v31, vcc, 0, v27, vcc
	v_add_co_u32_e32 v40, vcc, s80, v26
	global_load_dword v22, v[28:29], off
	global_load_dword v25, v[28:29], off offset:2048
	global_load_dword v21, v[18:19], off offset:-4096
	global_load_dword v17, v[18:19], off
	global_load_dword v20, v[18:19], off offset:2048
	s_nop 0
	global_load_dword v18, v[30:31], off offset:-4096
	global_load_dword v16, v[30:31], off
	global_load_dword v19, v[30:31], off offset:2048
	v_addc_co_u32_e32 v41, vcc, 0, v27, vcc
	global_load_dword v30, v48, s[92:93]
	global_load_dword v32, v48, s[92:93] offset:2048
	s_nop 0
	global_load_dword v29, v[28:29], off offset:-4096
	s_nop 0
	global_load_dword v31, v[34:35], off offset:2048
	global_load_dword v28, v[36:37], off offset:2048
	global_load_dword v27, v[38:39], off offset:2048
	global_load_dword v24, v[40:41], off
	global_load_dword v26, v[40:41], off offset:2048
	v_mov_b32 v33, s77
	ds_read_b64 v[34:35], v33 offset:40
	s_waitcnt lgkmcnt(0)
	v_readfirstlane_b32 s67, v34
	v_readfirstlane_b32 s37, v35
	s_add_u32 s92, s67, s40
	s_addc_u32 s93, s37, 0
	global_load_dword v33, v48, s[92:93]
	v_mov_b32 v34, s77
	ds_read_b64 v[34:35], v34 offset:168
	s_ashr_i32 s37, s36, 31
	s_lshl_b64 s[36:37], s[36:37], 12
	s_waitcnt lgkmcnt(0)
	v_readfirstlane_b32 s79, v34
	v_readfirstlane_b32 s67, v35
	s_add_u32 s36, s79, s36
	v_lshlrev_b32_e32 v34, 1, v23
	s_addc_u32 s37, s67, s37
	v_ashrrev_i32_e32 v35, 31, v34
	v_lshl_add_u64 v[34:35], v[34:35], 2, s[36:37]
	v_add_co_u32_e32 v34, vcc, s81, v34
	s_lshl_b32 s36, s41, 10
	s_nop 0
	v_addc_co_u32_e32 v35, vcc, 0, v35, vcc
	global_load_dwordx2 v[36:37], v[34:35], off
	s_add_i32 s36, s82, s36
	v_lshl_add_u32 v23, v23, 3, s82
	v_mov_b32_e32 v35, s36
	s_cmp_gt_i32 s41, 0
	s_waitcnt vmcnt(0)
	ds_write_b64 v23, v[36:37]
	s_waitcnt lgkmcnt(0)
	s_barrier
	ds_read_b128 v[36:39], v35
	ds_read_b128 v[40:43], v35 offset:16
	ds_read_b128 v[44:47], v35 offset:32
	ds_read_b128 v[96:99], v35 offset:48
	s_waitcnt lgkmcnt(3)
	v_mul_f32_e32 v23, v32, v37
	v_mul_f32_e32 v34, v31, v39
	s_waitcnt lgkmcnt(2)
	v_mul_f32_e32 v37, v25, v41
	v_mul_f32_e32 v39, v28, v43
	v_fmac_f32_e32 v23, v30, v36
	v_fmac_f32_e32 v34, v29, v38
	v_fmac_f32_e32 v37, v22, v40
	v_fmac_f32_e32 v39, v21, v42
	v_add_f32_e32 v23, v23, v34
	s_waitcnt lgkmcnt(1)
	v_mul_f32_e32 v41, v20, v45
	v_mul_f32_e32 v43, v27, v47
	v_add_f32_e32 v34, v37, v39
	v_add_f32_e32 v23, v33, v23
	s_waitcnt lgkmcnt(0)
	ds_read_b128 v[166:169], v35 offset:64
	ds_read_b128 v[170:173], v35 offset:80
	ds_read_b128 v[174:177], v35 offset:96
	ds_read_b128 v[178:181], v35 offset:112
	v_mul_f32_e32 v45, v19, v97
	v_fmac_f32_e32 v41, v17, v44
	v_fmac_f32_e32 v43, v18, v46
	v_add_f32_e32 v23, v23, v34
	v_mul_f32_e32 v34, v26, v99
	v_add_f32_e32 v36, v41, v43
	v_fmac_f32_e32 v45, v16, v96
	v_fmac_f32_e32 v34, v24, v98
	v_add_f32_e32 v23, v23, v36
	v_add_f32_e32 v34, v45, v34
	v_add_f32_e32 v23, v23, v34
	v_mul_f32_e64 v34, |v23|, s83
	v_exp_f32_e32 v34, v34
	v_min_f32_e32 v23, 0, v23
	v_add_f32_e32 v34, 1.0, v34
	v_cmp_gt_f32_e32 vcc, s84, v34
	s_nop 1
	v_cndmask_b32_e64 v36, 0, 32, vcc
	v_ldexp_f32 v34, v34, v36
	v_log_f32_e32 v36, v34
	v_add_u32_e32 v34, 0, v48
	v_mul_f32_e32 v37, 0x3f317217, v36
	v_fma_f32 v37, v36, s85, -v37
	v_fmac_f32_e32 v37, 0x3377d1cf, v36
	v_fmac_f32_e32 v37, 0x3f317217, v36
	v_cmp_lt_f32_e64 s[36:37], |v36|, s86
	s_nop 1
	v_cndmask_b32_e64 v36, v36, v37, s[36:37]
	v_cndmask_b32_e32 v37, 0, v95, vcc
	v_sub_f32_e32 v36, v36, v37
	v_sub_f32_e32 v23, v23, v36
	s_mul_i32 s36, s41, 0x2100
	v_fma_f32 v36, v23, s87, 0
	v_add_u32_e32 v23, s36, v34
	ds_write_b32 v23, v36
	s_waitcnt lgkmcnt(3)
	v_mul_f32_e32 v37, v32, v167
	v_fmac_f32_e32 v37, v30, v166
	v_mul_f32_e32 v38, v31, v169
	v_fmac_f32_e32 v38, v29, v168
	v_add_f32_e32 v37, v37, v38
	s_waitcnt lgkmcnt(2)
	v_mul_f32_e32 v38, v25, v171
	v_mul_f32_e32 v39, v28, v173
	v_fmac_f32_e32 v38, v22, v170
	v_fmac_f32_e32 v39, v21, v172
	v_add_f32_e32 v37, v33, v37
	v_add_f32_e32 v38, v38, v39
	v_add_f32_e32 v37, v37, v38
	s_waitcnt lgkmcnt(1)
; #define LAS __attribute__((address_space(3)))
; __device__ __forceinline__ void gla_cumdecay(const Ptrs& A, int l, int n, int hd, LAS float* bl, const int wv0) {
;     ...
;     for (int tt = 0; tt < 16; ++tt) {
;         float pre = bias;
;         const f32x4 g0 = *(const LAS f32x4*)(ga + tt * 16), g1 = *(const LAS f32x4*)(ga + tt * 16 + 4), g2 = *(const LAS f32x4*)(ga + tt * 16 + 8), g3 = *(const LAS f32x4*)(ga + tt * 16 + 12);
;         pre += (g0.x * w[0] + g0.y * w[1]) + (g0.z * w[2] + g0.w * w[3]); pre += (g1.x * w[4] + g1.y * w[5]) + (g1.z * w[6] + g1.w * w[7]);
;         pre += (g2.x * w[8] + g2.y * w[9]) + (g2.z * w[10] + g2.w * w[11]); pre += (g3.x * w[12] + g3.y * w[13]) + (g3.z * w[14] + g3.w * w[15]);
;         const float la = (fminf(pre, 0.f) - __logf(1.0f + __expf(-fabsf(pre)))) * (1.0f / 16.0f);
;         run += la; bl[(16 * tq + tt) * BLS + d] = run;
	v_mul_f32_e32 v38, v20, v175
	v_mul_f32_e32 v39, v27, v177
	v_fmac_f32_e32 v38, v17, v174
	v_fmac_f32_e32 v39, v18, v176
	v_add_f32_e32 v38, v38, v39
	v_add_f32_e32 v37, v37, v38
	s_waitcnt lgkmcnt(0)
	ds_read_b128 v[150:153], v35 offset:128
	ds_read_b128 v[154:157], v35 offset:144
	ds_read_b128 v[158:161], v35 offset:160
	ds_read_b128 v[162:165], v35 offset:176
	v_mul_f32_e32 v38, v19, v179
	v_mul_f32_e32 v39, v26, v181
	v_fmac_f32_e32 v38, v16, v178
	v_fmac_f32_e32 v39, v24, v180
	v_add_f32_e32 v38, v38, v39
	v_add_f32_e32 v37, v37, v38
	v_mul_f32_e64 v38, |v37|, s83
	v_exp_f32_e32 v38, v38
	v_min_f32_e32 v37, 0, v37
	v_add_f32_e32 v38, 1.0, v38
	v_cmp_gt_f32_e32 vcc, s84, v38
	s_nop 1
	v_cndmask_b32_e64 v39, 0, 32, vcc
	v_ldexp_f32 v38, v38, v39
	v_log_f32_e32 v38, v38
	s_nop 0
	v_mul_f32_e32 v39, 0x3f317217, v38
	v_fma_f32 v39, v38, s85, -v39
	v_fmac_f32_e32 v39, 0x3377d1cf, v38
	v_fmac_f32_e32 v39, 0x3f317217, v38
	v_cmp_lt_f32_e64 s[36:37], |v38|, s86
	s_nop 1
	v_cndmask_b32_e64 v38, v38, v39, s[36:37]
	v_cndmask_b32_e32 v39, 0, v95, vcc
	v_sub_f32_e32 v38, v38, v39
	v_sub_f32_e32 v37, v37, v38
	v_fmac_f32_e32 v36, 0x3d800000, v37
	ds_write_b32 v23, v36 offset:528
	s_waitcnt lgkmcnt(3)
	v_mul_f32_e32 v37, v32, v151
	v_fmac_f32_e32 v37, v30, v150
	v_mul_f32_e32 v38, v31, v153
	v_fmac_f32_e32 v38, v29, v152
	v_add_f32_e32 v37, v37, v38
	s_waitcnt lgkmcnt(2)
	v_mul_f32_e32 v38, v25, v155
	v_mul_f32_e32 v39, v28, v157
	v_fmac_f32_e32 v38, v22, v154
	v_fmac_f32_e32 v39, v21, v156
	v_add_f32_e32 v37, v33, v37
	v_add_f32_e32 v38, v38, v39
	v_add_f32_e32 v37, v37, v38
	s_waitcnt lgkmcnt(1)
	v_mul_f32_e32 v38, v20, v159
	v_mul_f32_e32 v39, v27, v161
	v_fmac_f32_e32 v38, v17, v158
	v_fmac_f32_e32 v39, v18, v160
	v_add_f32_e32 v38, v38, v39
	v_add_f32_e32 v37, v37, v38
	s_waitcnt lgkmcnt(0)
	ds_read_b128 v[166:169], v35 offset:192
	ds_read_b128 v[170:173], v35 offset:208
	ds_read_b128 v[174:177], v35 offset:224
	ds_read_b128 v[178:181], v35 offset:240
	v_mul_f32_e32 v38, v19, v163
	v_mul_f32_e32 v39, v26, v165
	v_fmac_f32_e32 v38, v16, v162
	v_fmac_f32_e32 v39, v24, v164
	v_add_f32_e32 v38, v38, v39
	v_add_f32_e32 v37, v37, v38
	v_mul_f32_e64 v38, |v37|, s83
	v_exp_f32_e32 v38, v38
	v_min_f32_e32 v37, 0, v37
	v_add_f32_e32 v38, 1.0, v38
	v_cmp_gt_f32_e32 vcc, s84, v38
	s_nop 1
	v_cndmask_b32_e64 v39, 0, 32, vcc
	v_ldexp_f32 v38, v38, v39
	v_log_f32_e32 v38, v38
	s_nop 0
	v_mul_f32_e32 v39, 0x3f317217, v38
	v_fma_f32 v39, v38, s85, -v39
	v_fmac_f32_e32 v39, 0x3377d1cf, v38
	v_fmac_f32_e32 v39, 0x3f317217, v38
	v_cmp_lt_f32_e64 s[36:37], |v38|, s86
	s_nop 1
	v_cndmask_b32_e64 v38, v38, v39, s[36:37]
	v_cndmask_b32_e32 v39, 0, v95, vcc
	v_sub_f32_e32 v38, v38, v39
	v_sub_f32_e32 v37, v37, v38
	v_fmac_f32_e32 v36, 0x3d800000, v37
	ds_write_b32 v23, v36 offset:1056
	s_waitcnt lgkmcnt(3)
	v_mul_f32_e32 v37, v32, v167
	v_fmac_f32_e32 v37, v30, v166
	v_mul_f32_e32 v38, v31, v169
	v_fmac_f32_e32 v38, v29, v168
	v_add_f32_e32 v37, v37, v38
	s_waitcnt lgkmcnt(2)
	v_mul_f32_e32 v38, v25, v171
	v_mul_f32_e32 v39, v28, v173
	v_fmac_f32_e32 v38, v22, v170
	v_fmac_f32_e32 v39, v21, v172
	v_add_f32_e32 v37, v33, v37
	v_add_f32_e32 v38, v38, v39
	v_add_f32_e32 v37, v37, v38
	s_waitcnt lgkmcnt(1)
	v_mul_f32_e32 v38, v20, v175
	v_mul_f32_e32 v39, v27, v177
	v_fmac_f32_e32 v38, v17, v174
	v_fmac_f32_e32 v39, v18, v176
	v_add_f32_e32 v38, v38, v39
	v_add_f32_e32 v37, v37, v38
	s_waitcnt lgkmcnt(0)
	ds_read_b128 v[150:153], v35 offset:256
	ds_read_b128 v[154:157], v35 offset:272
	ds_read_b128 v[158:161], v35 offset:288
	ds_read_b128 v[162:165], v35 offset:304
	v_mul_f32_e32 v38, v19, v179
	v_mul_f32_e32 v39, v26, v181
	v_fmac_f32_e32 v38, v16, v178
	v_fmac_f32_e32 v39, v24, v180
	v_add_f32_e32 v38, v38, v39
	v_add_f32_e32 v37, v37, v38
	v_mul_f32_e64 v38, |v37|, s83
	v_exp_f32_e32 v38, v38
	v_min_f32_e32 v37, 0, v37
	v_add_f32_e32 v38, 1.0, v38
	v_cmp_gt_f32_e32 vcc, s84, v38
	s_nop 1
	v_cndmask_b32_e64 v39, 0, 32, vcc
	v_ldexp_f32 v38, v38, v39
	v_log_f32_e32 v38, v38
	s_nop 0
	v_mul_f32_e32 v39, 0x3f317217, v38
	v_fma_f32 v39, v38, s85, -v39
	v_fmac_f32_e32 v39, 0x3377d1cf, v38
	v_fmac_f32_e32 v39, 0x3f317217, v38
	v_cmp_lt_f32_e64 s[36:37], |v38|, s86
	s_nop 1
	v_cndmask_b32_e64 v38, v38, v39, s[36:37]
	v_cndmask_b32_e32 v39, 0, v95, vcc
	v_sub_f32_e32 v38, v38, v39
	v_sub_f32_e32 v37, v37, v38
	v_fmac_f32_e32 v36, 0x3d800000, v37
	ds_write_b32 v23, v36 offset:1584
	s_waitcnt lgkmcnt(3)
	v_mul_f32_e32 v37, v32, v151
	v_fmac_f32_e32 v37, v30, v150
	v_mul_f32_e32 v38, v31, v153
	v_fmac_f32_e32 v38, v29, v152
	v_add_f32_e32 v37, v37, v38
	s_waitcnt lgkmcnt(2)
	v_mul_f32_e32 v38, v25, v155
	v_mul_f32_e32 v39, v28, v157
	v_fmac_f32_e32 v38, v22, v154
	v_fmac_f32_e32 v39, v21, v156
	v_add_f32_e32 v37, v33, v37
	v_add_f32_e32 v38, v38, v39
	v_add_f32_e32 v37, v37, v38
	s_waitcnt lgkmcnt(1)
	v_mul_f32_e32 v38, v20, v159
	v_mul_f32_e32 v39, v27, v161
	v_fmac_f32_e32 v38, v17, v158
	v_fmac_f32_e32 v39, v18, v160
	v_add_f32_e32 v38, v38, v39
	v_add_f32_e32 v37, v37, v38
	s_waitcnt lgkmcnt(0)
	ds_read_b128 v[166:169], v35 offset:320
	ds_read_b128 v[170:173], v35 offset:336
	ds_read_b128 v[174:177], v35 offset:352
	ds_read_b128 v[178:181], v35 offset:368
	v_mul_f32_e32 v38, v19, v163
	v_mul_f32_e32 v39, v26, v165
	v_fmac_f32_e32 v38, v16, v162
	v_fmac_f32_e32 v39, v24, v164
	v_add_f32_e32 v38, v38, v39
	v_add_f32_e32 v37, v37, v38
	v_mul_f32_e64 v38, |v37|, s83
	v_exp_f32_e32 v38, v38
	v_min_f32_e32 v37, 0, v37
	v_add_f32_e32 v38, 1.0, v38
	v_cmp_gt_f32_e32 vcc, s84, v38
	s_nop 1
	v_cndmask_b32_e64 v39, 0, 32, vcc
	v_ldexp_f32 v38, v38, v39
	v_log_f32_e32 v38, v38
	s_nop 0
	v_mul_f32_e32 v39, 0x3f317217, v38
	v_fma_f32 v39, v38, s85, -v39
	v_fmac_f32_e32 v39, 0x3377d1cf, v38
	v_fmac_f32_e32 v39, 0x3f317217, v38
	v_cmp_lt_f32_e64 s[36:37], |v38|, s86
	s_nop 1
	v_cndmask_b32_e64 v38, v38, v39, s[36:37]
	v_cndmask_b32_e32 v39, 0, v95, vcc
	v_sub_f32_e32 v38, v38, v39
	v_sub_f32_e32 v37, v37, v38
	v_fmac_f32_e32 v36, 0x3d800000, v37
	ds_write_b32 v23, v36 offset:2112
	s_waitcnt lgkmcnt(3)
; #define LAS __attribute__((address_space(3)))
; __device__ __forceinline__ void gla_cumdecay(const Ptrs& A, int l, int n, int hd, LAS float* bl, const int wv0) {
;     ...
;     for (int tt = 0; tt < 16; ++tt) {
;         float pre = bias;
;         const f32x4 g0 = *(const LAS f32x4*)(ga + tt * 16), g1 = *(const LAS f32x4*)(ga + tt * 16 + 4), g2 = *(const LAS f32x4*)(ga + tt * 16 + 8), g3 = *(const LAS f32x4*)(ga + tt * 16 + 12);
;         pre += (g0.x * w[0] + g0.y * w[1]) + (g0.z * w[2] + g0.w * w[3]); pre += (g1.x * w[4] + g1.y * w[5]) + (g1.z * w[6] + g1.w * w[7]);
;         pre += (g2.x * w[8] + g2.y * w[9]) + (g2.z * w[10] + g2.w * w[11]); pre += (g3.x * w[12] + g3.y * w[13]) + (g3.z * w[14] + g3.w * w[15]);
;         const float la = (fminf(pre, 0.f) - __logf(1.0f + __expf(-fabsf(pre)))) * (1.0f / 16.0f);
;         run += la; bl[(16 * tq + tt) * BLS + d] = run;
	v_mul_f32_e32 v37, v32, v167
	v_fmac_f32_e32 v37, v30, v166
	v_mul_f32_e32 v38, v31, v169
	v_fmac_f32_e32 v38, v29, v168
	v_add_f32_e32 v37, v37, v38
	s_waitcnt lgkmcnt(2)
	v_mul_f32_e32 v38, v25, v171
	v_mul_f32_e32 v39, v28, v173
	v_fmac_f32_e32 v38, v22, v170
	v_fmac_f32_e32 v39, v21, v172
	v_add_f32_e32 v37, v33, v37
	v_add_f32_e32 v38, v38, v39
	v_add_f32_e32 v37, v37, v38
	s_waitcnt lgkmcnt(1)
	v_mul_f32_e32 v38, v20, v175
	v_mul_f32_e32 v39, v27, v177
	v_fmac_f32_e32 v38, v17, v174
	v_fmac_f32_e32 v39, v18, v176
	v_add_f32_e32 v38, v38, v39
	v_add_f32_e32 v37, v37, v38
	s_waitcnt lgkmcnt(0)
	ds_read_b128 v[150:153], v35 offset:384
	ds_read_b128 v[154:157], v35 offset:400
	ds_read_b128 v[158:161], v35 offset:416
	ds_read_b128 v[162:165], v35 offset:432
	v_mul_f32_e32 v38, v19, v179
	v_mul_f32_e32 v39, v26, v181
	v_fmac_f32_e32 v38, v16, v178
	v_fmac_f32_e32 v39, v24, v180
	v_add_f32_e32 v38, v38, v39
	v_add_f32_e32 v37, v37, v38
	v_mul_f32_e64 v38, |v37|, s83
	v_exp_f32_e32 v38, v38
	v_min_f32_e32 v37, 0, v37
	v_add_f32_e32 v38, 1.0, v38
	v_cmp_gt_f32_e32 vcc, s84, v38
	s_nop 1
	v_cndmask_b32_e64 v39, 0, 32, vcc
	v_ldexp_f32 v38, v38, v39
	v_log_f32_e32 v38, v38
	s_nop 0
	v_mul_f32_e32 v39, 0x3f317217, v38
	v_fma_f32 v39, v38, s85, -v39
	v_fmac_f32_e32 v39, 0x3377d1cf, v38
	v_fmac_f32_e32 v39, 0x3f317217, v38
	v_cmp_lt_f32_e64 s[36:37], |v38|, s86
	s_nop 1
	v_cndmask_b32_e64 v38, v38, v39, s[36:37]
	v_cndmask_b32_e32 v39, 0, v95, vcc
	v_sub_f32_e32 v38, v38, v39
	v_sub_f32_e32 v37, v37, v38
	v_fmac_f32_e32 v36, 0x3d800000, v37
	ds_write_b32 v23, v36 offset:2640
	s_waitcnt lgkmcnt(3)
	v_mul_f32_e32 v37, v32, v151
	v_fmac_f32_e32 v37, v30, v150
	v_mul_f32_e32 v38, v31, v153
	v_fmac_f32_e32 v38, v29, v152
	v_add_f32_e32 v37, v37, v38
	s_waitcnt lgkmcnt(2)
	v_mul_f32_e32 v38, v25, v155
	v_mul_f32_e32 v39, v28, v157
	v_fmac_f32_e32 v38, v22, v154
	v_fmac_f32_e32 v39, v21, v156
	v_add_f32_e32 v37, v33, v37
	v_add_f32_e32 v38, v38, v39
	v_add_f32_e32 v37, v37, v38
	s_waitcnt lgkmcnt(1)
	v_mul_f32_e32 v38, v20, v159
	v_mul_f32_e32 v39, v27, v161
	v_fmac_f32_e32 v38, v17, v158
	v_fmac_f32_e32 v39, v18, v160
	v_add_f32_e32 v38, v38, v39
	v_add_f32_e32 v37, v37, v38
	s_waitcnt lgkmcnt(0)
	ds_read_b128 v[166:169], v35 offset:448
	ds_read_b128 v[170:173], v35 offset:464
	ds_read_b128 v[174:177], v35 offset:480
	ds_read_b128 v[178:181], v35 offset:496
	v_mul_f32_e32 v38, v19, v163
	v_mul_f32_e32 v39, v26, v165
	v_fmac_f32_e32 v38, v16, v162
	v_fmac_f32_e32 v39, v24, v164
	v_add_f32_e32 v38, v38, v39
	v_add_f32_e32 v37, v37, v38
	v_mul_f32_e64 v38, |v37|, s83
	v_exp_f32_e32 v38, v38
	v_min_f32_e32 v37, 0, v37
	v_add_f32_e32 v38, 1.0, v38
	v_cmp_gt_f32_e32 vcc, s84, v38
	s_nop 1
	v_cndmask_b32_e64 v39, 0, 32, vcc
	v_ldexp_f32 v38, v38, v39
	v_log_f32_e32 v38, v38
	s_nop 0
	v_mul_f32_e32 v39, 0x3f317217, v38
	v_fma_f32 v39, v38, s85, -v39
	v_fmac_f32_e32 v39, 0x3377d1cf, v38
	v_fmac_f32_e32 v39, 0x3f317217, v38
	v_cmp_lt_f32_e64 s[36:37], |v38|, s86
	s_nop 1
	v_cndmask_b32_e64 v38, v38, v39, s[36:37]
	v_cndmask_b32_e32 v39, 0, v95, vcc
	v_sub_f32_e32 v38, v38, v39
	v_sub_f32_e32 v37, v37, v38
	v_fmac_f32_e32 v36, 0x3d800000, v37
	ds_write_b32 v23, v36 offset:3168
	s_waitcnt lgkmcnt(3)
	v_mul_f32_e32 v37, v32, v167
	v_fmac_f32_e32 v37, v30, v166
	v_mul_f32_e32 v38, v31, v169
	v_fmac_f32_e32 v38, v29, v168
	v_add_f32_e32 v37, v37, v38
	s_waitcnt lgkmcnt(2)
	v_mul_f32_e32 v38, v25, v171
	v_mul_f32_e32 v39, v28, v173
	v_fmac_f32_e32 v38, v22, v170
	v_fmac_f32_e32 v39, v21, v172
	v_add_f32_e32 v37, v33, v37
	v_add_f32_e32 v38, v38, v39
	v_add_f32_e32 v37, v37, v38
	s_waitcnt lgkmcnt(1)
	v_mul_f32_e32 v38, v20, v175
	v_mul_f32_e32 v39, v27, v177
	v_fmac_f32_e32 v38, v17, v174
	v_fmac_f32_e32 v39, v18, v176
	v_add_f32_e32 v38, v38, v39
	v_add_f32_e32 v37, v37, v38
	s_waitcnt lgkmcnt(0)
	ds_read_b128 v[150:153], v35 offset:512
	ds_read_b128 v[154:157], v35 offset:528
	ds_read_b128 v[158:161], v35 offset:544
	ds_read_b128 v[162:165], v35 offset:560
	v_mul_f32_e32 v38, v19, v179
	v_mul_f32_e32 v39, v26, v181
	v_fmac_f32_e32 v38, v16, v178
	v_fmac_f32_e32 v39, v24, v180
	v_add_f32_e32 v38, v38, v39
	v_add_f32_e32 v37, v37, v38
	v_mul_f32_e64 v38, |v37|, s83
	v_exp_f32_e32 v38, v38
	v_min_f32_e32 v37, 0, v37
	v_add_f32_e32 v38, 1.0, v38
	v_cmp_gt_f32_e32 vcc, s84, v38
	s_nop 1
	v_cndmask_b32_e64 v39, 0, 32, vcc
	v_ldexp_f32 v38, v38, v39
	v_log_f32_e32 v38, v38
	s_nop 0
	v_mul_f32_e32 v39, 0x3f317217, v38
	v_fma_f32 v39, v38, s85, -v39
	v_fmac_f32_e32 v39, 0x3377d1cf, v38
	v_fmac_f32_e32 v39, 0x3f317217, v38
	v_cmp_lt_f32_e64 s[36:37], |v38|, s86
	s_nop 1
	v_cndmask_b32_e64 v38, v38, v39, s[36:37]
	v_cndmask_b32_e32 v39, 0, v95, vcc
	v_sub_f32_e32 v38, v38, v39
	v_sub_f32_e32 v37, v37, v38
	v_fmac_f32_e32 v36, 0x3d800000, v37
	ds_write_b32 v23, v36 offset:3696
	s_waitcnt lgkmcnt(3)
	v_mul_f32_e32 v37, v32, v151
	v_fmac_f32_e32 v37, v30, v150
	v_mul_f32_e32 v38, v31, v153
	v_fmac_f32_e32 v38, v29, v152
	v_add_f32_e32 v37, v37, v38
	s_waitcnt lgkmcnt(2)
	v_mul_f32_e32 v38, v25, v155
	v_mul_f32_e32 v39, v28, v157
	v_fmac_f32_e32 v38, v22, v154
	v_fmac_f32_e32 v39, v21, v156
	v_add_f32_e32 v37, v33, v37
	v_add_f32_e32 v38, v38, v39
	v_add_f32_e32 v37, v37, v38
	s_waitcnt lgkmcnt(1)
	v_mul_f32_e32 v38, v20, v159
	v_mul_f32_e32 v39, v27, v161
	v_fmac_f32_e32 v38, v17, v158
	v_fmac_f32_e32 v39, v18, v160
	v_add_f32_e32 v38, v38, v39
	v_add_f32_e32 v37, v37, v38
	s_waitcnt lgkmcnt(0)
; #define LAS __attribute__((address_space(3)))
; __device__ __forceinline__ void gla_cumdecay(const Ptrs& A, int l, int n, int hd, LAS float* bl, const int wv0) {
;     ...
;     for (int tt = 0; tt < 16; ++tt) {
;         float pre = bias;
;         const f32x4 g0 = *(const LAS f32x4*)(ga + tt * 16), g1 = *(const LAS f32x4*)(ga + tt * 16 + 4), g2 = *(const LAS f32x4*)(ga + tt * 16 + 8), g3 = *(const LAS f32x4*)(ga + tt * 16 + 12);
;         pre += (g0.x * w[0] + g0.y * w[1]) + (g0.z * w[2] + g0.w * w[3]); pre += (g1.x * w[4] + g1.y * w[5]) + (g1.z * w[6] + g1.w * w[7]);
;         pre += (g2.x * w[8] + g2.y * w[9]) + (g2.z * w[10] + g2.w * w[11]); pre += (g3.x * w[12] + g3.y * w[13]) + (g3.z * w[14] + g3.w * w[15]);
;         const float la = (fminf(pre, 0.f) - __logf(1.0f + __expf(-fabsf(pre)))) * (1.0f / 16.0f);
;         run += la; bl[(16 * tq + tt) * BLS + d] = run;
	ds_read_b128 v[166:169], v35 offset:576
	ds_read_b128 v[170:173], v35 offset:592
	ds_read_b128 v[174:177], v35 offset:608
	ds_read_b128 v[178:181], v35 offset:624
	v_mul_f32_e32 v38, v19, v163
	v_mul_f32_e32 v39, v26, v165
	v_fmac_f32_e32 v38, v16, v162
	v_fmac_f32_e32 v39, v24, v164
	v_add_f32_e32 v38, v38, v39
	v_add_f32_e32 v37, v37, v38
	v_mul_f32_e64 v38, |v37|, s83
	v_exp_f32_e32 v38, v38
	v_min_f32_e32 v37, 0, v37
	v_add_f32_e32 v38, 1.0, v38
	v_cmp_gt_f32_e32 vcc, s84, v38
	s_nop 1
	v_cndmask_b32_e64 v39, 0, 32, vcc
	v_ldexp_f32 v38, v38, v39
	v_log_f32_e32 v38, v38
	s_nop 0
	v_mul_f32_e32 v39, 0x3f317217, v38
	v_fma_f32 v39, v38, s85, -v39
	v_fmac_f32_e32 v39, 0x3377d1cf, v38
	v_fmac_f32_e32 v39, 0x3f317217, v38
	v_cmp_lt_f32_e64 s[36:37], |v38|, s86
	s_nop 1
	v_cndmask_b32_e64 v38, v38, v39, s[36:37]
	v_cndmask_b32_e32 v39, 0, v95, vcc
	v_sub_f32_e32 v38, v38, v39
	v_sub_f32_e32 v37, v37, v38
	v_fmac_f32_e32 v36, 0x3d800000, v37
	ds_write_b32 v23, v36 offset:4224
	s_waitcnt lgkmcnt(3)
	v_mul_f32_e32 v37, v32, v167
	v_fmac_f32_e32 v37, v30, v166
	v_mul_f32_e32 v38, v31, v169
	v_fmac_f32_e32 v38, v29, v168
	v_add_f32_e32 v37, v37, v38
	s_waitcnt lgkmcnt(2)
	v_mul_f32_e32 v38, v25, v171
	v_mul_f32_e32 v39, v28, v173
	v_fmac_f32_e32 v38, v22, v170
	v_fmac_f32_e32 v39, v21, v172
	v_add_f32_e32 v37, v33, v37
	v_add_f32_e32 v38, v38, v39
	v_add_f32_e32 v37, v37, v38
	s_waitcnt lgkmcnt(1)
	v_mul_f32_e32 v38, v20, v175
	v_mul_f32_e32 v39, v27, v177
	v_fmac_f32_e32 v38, v17, v174
	v_fmac_f32_e32 v39, v18, v176
	v_add_f32_e32 v38, v38, v39
	v_add_f32_e32 v37, v37, v38
	s_waitcnt lgkmcnt(0)
	ds_read_b128 v[150:153], v35 offset:640
	ds_read_b128 v[154:157], v35 offset:656
	ds_read_b128 v[158:161], v35 offset:672
	ds_read_b128 v[162:165], v35 offset:688
	v_mul_f32_e32 v38, v19, v179
	v_mul_f32_e32 v39, v26, v181
	v_fmac_f32_e32 v38, v16, v178
	v_fmac_f32_e32 v39, v24, v180
	v_add_f32_e32 v38, v38, v39
	v_add_f32_e32 v37, v37, v38
	v_mul_f32_e64 v38, |v37|, s83
	v_exp_f32_e32 v38, v38
	v_min_f32_e32 v37, 0, v37
	v_add_f32_e32 v38, 1.0, v38
	v_cmp_gt_f32_e32 vcc, s84, v38
	s_nop 1
	v_cndmask_b32_e64 v39, 0, 32, vcc
	v_ldexp_f32 v38, v38, v39
	v_log_f32_e32 v38, v38
	s_nop 0
	v_mul_f32_e32 v39, 0x3f317217, v38
	v_fma_f32 v39, v38, s85, -v39
	v_fmac_f32_e32 v39, 0x3377d1cf, v38
	v_fmac_f32_e32 v39, 0x3f317217, v38
	v_cmp_lt_f32_e64 s[36:37], |v38|, s86
	s_nop 1
	v_cndmask_b32_e64 v38, v38, v39, s[36:37]
	v_cndmask_b32_e32 v39, 0, v95, vcc
	v_sub_f32_e32 v38, v38, v39
	v_sub_f32_e32 v37, v37, v38
	v_fmac_f32_e32 v36, 0x3d800000, v37
	ds_write_b32 v23, v36 offset:4752
	s_waitcnt lgkmcnt(3)
	v_mul_f32_e32 v37, v32, v151
	v_fmac_f32_e32 v37, v30, v150
	v_mul_f32_e32 v38, v31, v153
	v_fmac_f32_e32 v38, v29, v152
	v_add_f32_e32 v37, v37, v38
	s_waitcnt lgkmcnt(2)
	v_mul_f32_e32 v38, v25, v155
	v_mul_f32_e32 v39, v28, v157
	v_fmac_f32_e32 v38, v22, v154
	v_fmac_f32_e32 v39, v21, v156
	v_add_f32_e32 v37, v33, v37
	v_add_f32_e32 v38, v38, v39
	v_add_f32_e32 v37, v37, v38
	s_waitcnt lgkmcnt(1)
	v_mul_f32_e32 v38, v20, v159
	v_mul_f32_e32 v39, v27, v161
	v_fmac_f32_e32 v38, v17, v158
	v_fmac_f32_e32 v39, v18, v160
	v_add_f32_e32 v38, v38, v39
	v_add_f32_e32 v37, v37, v38
	s_waitcnt lgkmcnt(0)
	ds_read_b128 v[166:169], v35 offset:704
	ds_read_b128 v[170:173], v35 offset:720
	ds_read_b128 v[174:177], v35 offset:736
	ds_read_b128 v[178:181], v35 offset:752
	v_mul_f32_e32 v38, v19, v163
	v_mul_f32_e32 v39, v26, v165
	v_fmac_f32_e32 v38, v16, v162
	v_fmac_f32_e32 v39, v24, v164
	v_add_f32_e32 v38, v38, v39
	v_add_f32_e32 v37, v37, v38
	v_mul_f32_e64 v38, |v37|, s83
	v_exp_f32_e32 v38, v38
	v_min_f32_e32 v37, 0, v37
	v_add_f32_e32 v38, 1.0, v38
	v_cmp_gt_f32_e32 vcc, s84, v38
	s_nop 1
	v_cndmask_b32_e64 v39, 0, 32, vcc
	v_ldexp_f32 v38, v38, v39
	v_log_f32_e32 v38, v38
	s_nop 0
	v_mul_f32_e32 v39, 0x3f317217, v38
	v_fma_f32 v39, v38, s85, -v39
	v_fmac_f32_e32 v39, 0x3377d1cf, v38
	v_fmac_f32_e32 v39, 0x3f317217, v38
	v_cmp_lt_f32_e64 s[36:37], |v38|, s86
	s_nop 1
	v_cndmask_b32_e64 v38, v38, v39, s[36:37]
	v_cndmask_b32_e32 v39, 0, v95, vcc
	v_sub_f32_e32 v38, v38, v39
	v_sub_f32_e32 v37, v37, v38
	v_fmac_f32_e32 v36, 0x3d800000, v37
	ds_write_b32 v23, v36 offset:5280
	s_waitcnt lgkmcnt(3)
	v_mul_f32_e32 v37, v32, v167
	v_fmac_f32_e32 v37, v30, v166
	v_mul_f32_e32 v38, v31, v169
	v_fmac_f32_e32 v38, v29, v168
	v_add_f32_e32 v37, v37, v38
	s_waitcnt lgkmcnt(2)
	v_mul_f32_e32 v38, v25, v171
	v_mul_f32_e32 v39, v28, v173
	v_fmac_f32_e32 v38, v22, v170
	v_fmac_f32_e32 v39, v21, v172
	v_add_f32_e32 v37, v33, v37
	v_add_f32_e32 v38, v38, v39
	v_add_f32_e32 v37, v37, v38
	s_waitcnt lgkmcnt(1)
	v_mul_f32_e32 v38, v20, v175
	v_mul_f32_e32 v39, v27, v177
	v_fmac_f32_e32 v38, v17, v174
	v_fmac_f32_e32 v39, v18, v176
	v_add_f32_e32 v38, v38, v39
	v_add_f32_e32 v37, v37, v38
	s_waitcnt lgkmcnt(0)
	ds_read_b128 v[150:153], v35 offset:768
	ds_read_b128 v[154:157], v35 offset:784
	ds_read_b128 v[158:161], v35 offset:800
	ds_read_b128 v[162:165], v35 offset:816
	v_mul_f32_e32 v38, v19, v179
	v_mul_f32_e32 v39, v26, v181
	v_fmac_f32_e32 v38, v16, v178
	v_fmac_f32_e32 v39, v24, v180
	v_add_f32_e32 v38, v38, v39
	v_add_f32_e32 v37, v37, v38
	v_mul_f32_e64 v38, |v37|, s83
	v_exp_f32_e32 v38, v38
	v_min_f32_e32 v37, 0, v37
	v_add_f32_e32 v38, 1.0, v38
	v_cmp_gt_f32_e32 vcc, s84, v38
	s_nop 1
	v_cndmask_b32_e64 v39, 0, 32, vcc
	v_ldexp_f32 v38, v38, v39
	v_log_f32_e32 v38, v38
	s_nop 0
	v_mul_f32_e32 v39, 0x3f317217, v38
	v_fma_f32 v39, v38, s85, -v39
	v_fmac_f32_e32 v39, 0x3377d1cf, v38
	v_fmac_f32_e32 v39, 0x3f317217, v38
	v_cmp_lt_f32_e64 s[36:37], |v38|, s86
	s_nop 1
	v_cndmask_b32_e64 v38, v38, v39, s[36:37]
	v_cndmask_b32_e32 v39, 0, v95, vcc
	v_sub_f32_e32 v38, v38, v39
	v_sub_f32_e32 v37, v37, v38
	v_fmac_f32_e32 v36, 0x3d800000, v37
	ds_write_b32 v23, v36 offset:5808
	s_waitcnt lgkmcnt(3)
; #define LAS __attribute__((address_space(3)))
; __device__ __forceinline__ void gla_cumdecay(const Ptrs& A, int l, int n, int hd, LAS float* bl, const int wv0) {
;     ...
;     for (int tt = 0; tt < 16; ++tt) {
;         float pre = bias;
;         const f32x4 g0 = *(const LAS f32x4*)(ga + tt * 16), g1 = *(const LAS f32x4*)(ga + tt * 16 + 4), g2 = *(const LAS f32x4*)(ga + tt * 16 + 8), g3 = *(const LAS f32x4*)(ga + tt * 16 + 12);
;         pre += (g0.x * w[0] + g0.y * w[1]) + (g0.z * w[2] + g0.w * w[3]); pre += (g1.x * w[4] + g1.y * w[5]) + (g1.z * w[6] + g1.w * w[7]);
;         pre += (g2.x * w[8] + g2.y * w[9]) + (g2.z * w[10] + g2.w * w[11]); pre += (g3.x * w[12] + g3.y * w[13]) + (g3.z * w[14] + g3.w * w[15]);
;         const float la = (fminf(pre, 0.f) - __logf(1.0f + __expf(-fabsf(pre)))) * (1.0f / 16.0f);
;         run += la; bl[(16 * tq + tt) * BLS + d] = run;
;     }
;     __syncthreads();
;     float add = 0.f;
; #pragma unroll
;     for (int q = 0; q < 3; ++q) if (q < tq) add += bl[(16 * q + 15) * BLS + d];
	v_mul_f32_e32 v37, v32, v151
	v_fmac_f32_e32 v37, v30, v150
	v_mul_f32_e32 v38, v31, v153
	v_fmac_f32_e32 v38, v29, v152
	v_add_f32_e32 v37, v37, v38
	s_waitcnt lgkmcnt(2)
	v_mul_f32_e32 v38, v25, v155
	v_mul_f32_e32 v39, v28, v157
	v_fmac_f32_e32 v38, v22, v154
	v_fmac_f32_e32 v39, v21, v156
	v_add_f32_e32 v37, v33, v37
	v_add_f32_e32 v38, v38, v39
	v_add_f32_e32 v37, v37, v38
	s_waitcnt lgkmcnt(1)
	v_mul_f32_e32 v38, v20, v159
	v_mul_f32_e32 v39, v27, v161
	v_fmac_f32_e32 v38, v17, v158
	v_fmac_f32_e32 v39, v18, v160
	v_add_f32_e32 v38, v38, v39
	v_add_f32_e32 v37, v37, v38
	s_waitcnt lgkmcnt(0)
	ds_read_b128 v[166:169], v35 offset:832
	ds_read_b128 v[170:173], v35 offset:848
	ds_read_b128 v[174:177], v35 offset:864
	ds_read_b128 v[178:181], v35 offset:880
	v_mul_f32_e32 v38, v19, v163
	v_mul_f32_e32 v39, v26, v165
	v_fmac_f32_e32 v38, v16, v162
	v_fmac_f32_e32 v39, v24, v164
	v_add_f32_e32 v38, v38, v39
	v_add_f32_e32 v37, v37, v38
	v_mul_f32_e64 v38, |v37|, s83
	v_exp_f32_e32 v38, v38
	v_min_f32_e32 v37, 0, v37
	v_add_f32_e32 v38, 1.0, v38
	v_cmp_gt_f32_e32 vcc, s84, v38
	s_nop 1
	v_cndmask_b32_e64 v39, 0, 32, vcc
	v_ldexp_f32 v38, v38, v39
	v_log_f32_e32 v38, v38
	s_nop 0
	v_mul_f32_e32 v39, 0x3f317217, v38
	v_fma_f32 v39, v38, s85, -v39
	v_fmac_f32_e32 v39, 0x3377d1cf, v38
	v_fmac_f32_e32 v39, 0x3f317217, v38
	v_cmp_lt_f32_e64 s[36:37], |v38|, s86
	s_nop 1
	v_cndmask_b32_e64 v38, v38, v39, s[36:37]
	v_cndmask_b32_e32 v39, 0, v95, vcc
	v_sub_f32_e32 v38, v38, v39
	v_sub_f32_e32 v37, v37, v38
	v_fmac_f32_e32 v36, 0x3d800000, v37
	ds_write_b32 v23, v36 offset:6336
	s_waitcnt lgkmcnt(3)
	v_mul_f32_e32 v37, v32, v167
	v_fmac_f32_e32 v37, v30, v166
	v_mul_f32_e32 v38, v31, v169
	v_fmac_f32_e32 v38, v29, v168
	v_add_f32_e32 v37, v37, v38
	s_waitcnt lgkmcnt(2)
	v_mul_f32_e32 v38, v25, v171
	v_mul_f32_e32 v39, v28, v173
	v_fmac_f32_e32 v38, v22, v170
	v_fmac_f32_e32 v39, v21, v172
	v_add_f32_e32 v37, v33, v37
	v_add_f32_e32 v38, v38, v39
	v_add_f32_e32 v37, v37, v38
	s_waitcnt lgkmcnt(1)
	v_mul_f32_e32 v38, v20, v175
	v_mul_f32_e32 v39, v27, v177
	v_fmac_f32_e32 v38, v17, v174
	v_fmac_f32_e32 v39, v18, v176
	v_add_f32_e32 v38, v38, v39
	v_add_f32_e32 v37, v37, v38
	s_waitcnt lgkmcnt(0)
	ds_read_b128 v[150:153], v35 offset:896
	ds_read_b128 v[154:157], v35 offset:912
	ds_read_b128 v[158:161], v35 offset:928
	ds_read_b128 v[162:165], v35 offset:944
	v_mul_f32_e32 v38, v19, v179
	v_mul_f32_e32 v39, v26, v181
	v_fmac_f32_e32 v38, v16, v178
	v_fmac_f32_e32 v39, v24, v180
	v_add_f32_e32 v38, v38, v39
	v_add_f32_e32 v37, v37, v38
	v_mul_f32_e64 v38, |v37|, s83
	v_exp_f32_e32 v38, v38
	v_min_f32_e32 v37, 0, v37
	v_add_f32_e32 v38, 1.0, v38
	v_cmp_gt_f32_e32 vcc, s84, v38
	s_nop 1
	v_cndmask_b32_e64 v39, 0, 32, vcc
	v_ldexp_f32 v38, v38, v39
	v_log_f32_e32 v38, v38
	s_nop 0
	v_mul_f32_e32 v39, 0x3f317217, v38
	v_fma_f32 v39, v38, s85, -v39
	v_fmac_f32_e32 v39, 0x3377d1cf, v38
	v_fmac_f32_e32 v39, 0x3f317217, v38
	v_cmp_lt_f32_e64 s[36:37], |v38|, s86
	s_nop 1
	v_cndmask_b32_e64 v38, v38, v39, s[36:37]
	v_cndmask_b32_e32 v39, 0, v95, vcc
	v_sub_f32_e32 v38, v38, v39
	v_sub_f32_e32 v37, v37, v38
	v_fmac_f32_e32 v36, 0x3d800000, v37
	ds_write_b32 v23, v36 offset:6864
	s_waitcnt lgkmcnt(3)
	v_mul_f32_e32 v37, v32, v151
	v_fmac_f32_e32 v37, v30, v150
	v_mul_f32_e32 v38, v31, v153
	v_fmac_f32_e32 v38, v29, v152
	v_add_f32_e32 v37, v37, v38
	s_waitcnt lgkmcnt(2)
	v_mul_f32_e32 v38, v25, v155
	v_mul_f32_e32 v39, v28, v157
	v_fmac_f32_e32 v38, v22, v154
	v_fmac_f32_e32 v39, v21, v156
	v_add_f32_e32 v37, v33, v37
	v_add_f32_e32 v38, v38, v39
	v_add_f32_e32 v37, v37, v38
	s_waitcnt lgkmcnt(1)
	v_mul_f32_e32 v38, v20, v159
	v_mul_f32_e32 v39, v27, v161
	v_fmac_f32_e32 v38, v17, v158
	v_fmac_f32_e32 v39, v18, v160
	v_add_f32_e32 v38, v38, v39
	v_add_f32_e32 v37, v37, v38
	s_waitcnt lgkmcnt(0)
	ds_read_b128 v[166:169], v35 offset:960
	ds_read_b128 v[170:173], v35 offset:976
	ds_read_b128 v[174:177], v35 offset:992
	ds_read_b128 v[178:181], v35 offset:1008
	v_mul_f32_e32 v38, v19, v163
	v_mul_f32_e32 v39, v26, v165
	v_fmac_f32_e32 v38, v16, v162
	v_fmac_f32_e32 v39, v24, v164
	v_add_f32_e32 v38, v38, v39
	v_add_f32_e32 v37, v37, v38
	v_mul_f32_e64 v38, |v37|, s83
	v_exp_f32_e32 v38, v38
	v_min_f32_e32 v37, 0, v37
	v_add_f32_e32 v38, 1.0, v38
	v_cmp_gt_f32_e32 vcc, s84, v38
	s_nop 1
	v_cndmask_b32_e64 v39, 0, 32, vcc
	v_ldexp_f32 v38, v38, v39
	v_log_f32_e32 v38, v38
	s_nop 0
	v_mul_f32_e32 v39, 0x3f317217, v38
	v_fma_f32 v39, v38, s85, -v39
	v_fmac_f32_e32 v39, 0x3377d1cf, v38
	v_fmac_f32_e32 v39, 0x3f317217, v38
	v_cmp_lt_f32_e64 s[36:37], |v38|, s86
	s_nop 1
	v_cndmask_b32_e64 v38, v38, v39, s[36:37]
	v_cndmask_b32_e32 v39, 0, v95, vcc
	v_sub_f32_e32 v38, v38, v39
	v_sub_f32_e32 v37, v37, v38
	v_fmac_f32_e32 v36, 0x3d800000, v37
	ds_write_b32 v23, v36 offset:7392
	s_waitcnt lgkmcnt(3)
	v_mul_f32_e32 v32, v32, v167
	v_fmac_f32_e32 v32, v30, v166
	v_mul_f32_e32 v30, v31, v169
	s_waitcnt lgkmcnt(2)
	v_mul_f32_e32 v25, v25, v171
	s_waitcnt lgkmcnt(1)
	v_mul_f32_e32 v20, v20, v175
	v_fmac_f32_e32 v30, v29, v168
	v_fmac_f32_e32 v25, v22, v170
	v_mul_f32_e32 v22, v28, v173
	v_fmac_f32_e32 v20, v17, v174
	v_mul_f32_e32 v17, v27, v177
	v_add_f32_e32 v29, v32, v30
	v_fmac_f32_e32 v22, v21, v172
	v_fmac_f32_e32 v17, v18, v176
	s_waitcnt lgkmcnt(0)
	v_mul_f32_e32 v18, v19, v179
	v_add_f32_e32 v29, v33, v29
	v_add_f32_e32 v21, v25, v22
	v_fmac_f32_e32 v18, v16, v178
	v_mul_f32_e32 v16, v26, v181
	v_add_f32_e32 v21, v29, v21
	v_add_f32_e32 v17, v20, v17
	v_fmac_f32_e32 v16, v24, v180
	v_add_f32_e32 v17, v21, v17
	v_add_f32_e32 v16, v18, v16
	v_add_f32_e32 v16, v17, v16
	v_mul_f32_e64 v17, |v16|, s83
	v_exp_f32_e32 v17, v17
	v_min_f32_e32 v16, 0, v16
	v_add_f32_e32 v17, 1.0, v17
	v_cmp_gt_f32_e32 vcc, s84, v17
	s_nop 1
	v_cndmask_b32_e64 v18, 0, 32, vcc
	v_ldexp_f32 v17, v17, v18
	v_log_f32_e32 v17, v17
	s_nop 0
	v_mul_f32_e32 v18, 0x3f317217, v17
	v_fma_f32 v18, v17, s85, -v18
	v_fmac_f32_e32 v18, 0x3377d1cf, v17
	v_fmac_f32_e32 v18, 0x3f317217, v17
	v_cmp_lt_f32_e64 s[36:37], |v17|, s86
	s_nop 1
	v_cndmask_b32_e64 v17, v17, v18, s[36:37]
	v_cndmask_b32_e32 v18, 0, v95, vcc
	v_sub_f32_e32 v17, v17, v18
	v_sub_f32_e32 v16, v16, v17
	s_cselect_b64 s[36:37], -1, 0
	v_fmac_f32_e32 v36, 0x3d800000, v16
	s_and_b64 vcc, exec, s[36:37]
	v_mov_b32_e32 v16, 0
	ds_write_b32 v23, v36 offset:7920
	s_waitcnt lgkmcnt(0)
	s_barrier
	s_cbranch_vccz .LBB0_385
	ds_read_b32 v16, v34 offset:7920
	s_waitcnt lgkmcnt(0)
	v_add_f32_e32 v16, 0, v16

; __device__ __forceinline__ float wave_sum(float v) { return swap32_sum(red32(v)); }
; template <bool GA, bool XBF = false>
; __device__ __forceinline__ void norm_rows(const float* X, const float* gain, bf16* H, float* GA1, const LAS float* waT, int nrows, int gw, int NGW, int lane_) {
;     ...
;     for (int m = gw; m < nrows; m += NGW) {
;         f32x4 v[8]; float s = 0.f;
;         if constexpr (XBF) { const u32x2* xb = (const u32x2*)((const bf16*)X + (size_t)m * DM) + lane;
; #pragma unroll
;             for (int j = 0; j < 8; ++j) { const u32x2 w = xb[64 * j]; v[j] = (f32x4){bflo(w.x), bfhi(w.x), bflo(w.y), bfhi(w.y)}; }
;         } else { const f32x4* xr = (const f32x4*)(X + (size_t)m * DM) + lane;
; #pragma unroll
;             for (int j = 0; j < 8; ++j) v[j] = __builtin_nontemporal_load(xr + 64 * j); }
; #pragma unroll
;         for (int j = 0; j < 8; ++j) s += (v[j].x * v[j].x + v[j].y * v[j].y) + (v[j].z * v[j].z + v[j].w * v[j].w);
;         const float rinv = 1.0f / sqrtf(wave_sum(s) * (1.0f / DM) + EPS);
;         unsigned long long* o8 = (unsigned long long*)(H + (size_t)m * DM) + lane;
; #pragma unroll
;         for (int j = 0; j < 8; ++j) { const f32x4 g = ((const f32x4*)gain)[lane + 64 * j]; v[j] = v[j] * rinv * g;
.LBB0_726:
	s_or_b64 exec, exec, s[0:1]
	s_waitcnt lgkmcnt(0)
	s_barrier
	v_mov_b32 v0, s77
	ds_read_b64 v[0:1], v0 offset:168
	v_mov_b32_e32 v2, v204
	s_mov_b32 s0, s76
	s_mov_b32 s1, s33
	s_waitcnt lgkmcnt(0)
	v_readfirstlane_b32 s3, v1
	v_readfirstlane_b32 s2, v0
	v_mov_b32 v0, s77
	ds_read_b64 v[0:1], v0 offset:136
	v_readfirstlane_b32 s4, v2
	s_ashr_i32 s4, s4, 6
	s_lshl_b32 s1, s1, 3
	s_add_i32 s4, s1, s4
	v_and_b32_e32 v10, 63, v2
	s_waitcnt lgkmcnt(0)
	v_readfirstlane_b32 s9, v1
	v_readfirstlane_b32 s8, v0
	s_cmpk_gt_i32 s4, 0x3fff
	s_cbranch_scc1 .LBB0_729
	v_ashrrev_i32_e32 v11, 31, v10
	v_lshl_add_u64 v[0:1], v[10:11], 4, s[8:9]
	s_mov_b64 s[8:9], 0x1000
	v_lshl_add_u64 v[2:3], v[0:1], 0, s[8:9]
	s_mov_b64 s[8:9], 0x1400
	v_lshl_add_u64 v[4:5], v[0:1], 0, s[8:9]
	s_mov_b64 s[8:9], 0x1800
	v_lshl_add_u64 v[6:7], v[0:1], 0, s[8:9]
	s_mov_b64 s[8:9], 0x1c00
	s_ashr_i32 s5, s4, 31
	s_lshl_b32 s6, s0, 3
	v_lshl_add_u64 v[8:9], v[0:1], 0, s[8:9]
	s_lshl_b64 s[8:9], s[4:5], 12
	s_add_u32 s2, s2, s8
	s_addc_u32 s3, s3, s9
	v_lshl_add_u64 v[10:11], v[10:11], 3, s[2:3]
	s_mov_b64 s[2:3], 0x2e500e00
	s_ashr_i32 s7, s6, 31
	v_cmp_eq_u32_e64 s[0:1], 32, v205
	v_lshl_add_u64 v[10:11], v[10:11], 0, s[2:3]
	s_lshl_b64 s[8:9], s[6:7], 12
	s_mov_b32 s5, 0xffff0000
	v_mov_b32_e32 v24, 0x358637bd
	s_mov_b32 s7, 0xf800000
	v_mov_b32_e32 v25, 0x260
	s_movk_i32 s10, 0x7fff
	s_mov_b32 s11, 0xdb500000
	global_load_dwordx4 v[208:211], v[0:1], off
	global_load_dwordx4 v[212:215], v[0:1], off offset:1024
	global_load_dwordx4 v[216:219], v[0:1], off offset:2048
	global_load_dwordx4 v[220:223], v[0:1], off offset:3072
	global_load_dwordx4 v[224:227], v[2:3], off
	global_load_dwordx4 v[228:231], v[4:5], off
	global_load_dwordx4 v[232:235], v[6:7], off
	global_load_dwordx4 v[236:239], v[8:9], off
	s_waitcnt vmcnt(0)
.LBB0_728:
	global_load_dwordx2 v[14:15], v[10:11], off offset:-2048
	global_load_dwordx2 v[20:21], v[10:11], off
	global_load_dwordx2 v[22:23], v[10:11], off offset:-3584
	global_load_dwordx2 v[30:31], v[10:11], off offset:-3072
	global_load_dwordx2 v[32:33], v[10:11], off offset:-2560
	global_load_dwordx2 v[34:35], v[10:11], off offset:-1536
	global_load_dwordx2 v[36:37], v[10:11], off offset:-1024
	global_load_dwordx2 v[38:39], v[10:11], off offset:-512
	v_mov_b32_e32 v26, v208
	v_mov_b32_e32 v27, v209
	v_mov_b32_e32 v28, v210
	v_mov_b32_e32 v29, v211
	v_add_co_u32_e32 v12, vcc, s11, v10
	s_add_i32 s4, s4, s6
	s_nop 0
	v_addc_co_u32_e32 v13, vcc, -1, v11, vcc
	v_lshl_add_u64 v[10:11], v[10:11], 0, s[8:9]
	s_cmpk_lt_i32 s4, 0x4000
	s_waitcnt vmcnt(7)
	v_lshlrev_b32_e32 v41, 16, v14
	v_and_b32_e32 v43, 0xffff0000, v14
	s_waitcnt vmcnt(5)
	v_and_b32_e32 v47, 0xffff0000, v22
	v_and_b32_e32 v49, 0xffff0000, v23
	v_lshlrev_b32_e32 v44, 16, v15
	v_and_b32_e32 v45, 0xffff0000, v15
	v_lshlrev_b32_e32 v19, 16, v20
	v_and_b32_e32 v17, 0xffff0000, v20
	v_lshlrev_b32_e32 v14, 16, v21
	v_and_b32_e32 v15, 0xffff0000, v21
	v_lshlrev_b32_e32 v46, 16, v22
	v_lshlrev_b32_e32 v48, 16, v23
	s_waitcnt vmcnt(4)
	v_lshlrev_b32_e32 v51, 16, v31
	v_lshlrev_b32_e32 v50, 16, v30
	v_and_b32_e32 v31, 0xffff0000, v31
	v_and_b32_e32 v30, 0xffff0000, v30
	s_waitcnt vmcnt(3)
	v_and_b32_e32 v53, 0xffff0000, v32
	s_waitcnt vmcnt(0)
	v_and_b32_e32 v21, 0xffff0000, v38
	v_mul_f32_e32 v16, v49, v49
	v_mul_f32_e32 v18, v47, v47
	v_lshlrev_b32_e32 v52, 16, v32
	v_lshlrev_b32_e32 v32, 16, v33
	v_and_b32_e32 v33, 0xffff0000, v33
	v_lshlrev_b32_e32 v20, 16, v38
	v_lshlrev_b32_e32 v22, 16, v39
	v_and_b32_e32 v23, 0xffff0000, v39
	v_pk_mul_f32 v[38:39], v[30:31], v[30:31]
	v_mov_b32_e32 v59, v41
	v_mul_f32_e32 v40, v53, v53
	v_mul_f32_e32 v58, v21, v21
	v_pk_fma_f32 v[66:67], v[48:49], v[48:49], v[16:17] op_sel_hi:[1,1,0]
	v_pk_fma_f32 v[68:69], v[46:47], v[46:47], v[18:19] op_sel_hi:[1,1,0]
	v_mul_f32_e32 v42, v33, v33
	v_pk_fma_f32 v[38:39], v[50:51], v[50:51], v[38:39]
	v_pk_fma_f32 v[70:71], v[52:53], v[52:53], v[40:41] op_sel_hi:[1,1,0]
	v_pk_fma_f32 v[74:75], v[20:21], v[20:21], v[58:59] op_sel_hi:[1,1,0]
	v_mov_b32_e32 v40, v68
	v_mov_b32_e32 v58, v66
	v_mul_f32_e32 v78, v43, v43
	v_mul_f32_e32 v79, v44, v44
	v_mul_f32_e32 v80, v45, v45
	v_pk_fma_f32 v[72:73], v[32:33], v[32:33], v[42:43] op_sel_hi:[1,1,0]
	v_pk_add_f32 v[66:67], v[68:69], v[66:67]
	v_pk_add_f32 v[38:39], v[38:39], v[38:39] op_sel:[0,1] op_sel_hi:[1,0]
	v_pk_mul_f32 v[58:59], v[40:41], v[58:59]
	v_lshlrev_b32_e32 v55, 16, v35
	v_lshlrev_b32_e32 v54, 16, v34
	v_and_b32_e32 v35, 0xffff0000, v35
	v_and_b32_e32 v34, 0xffff0000, v34
	v_mov_b32_e32 v71, v79
	v_mov_b32_e32 v73, v80
	v_mov_b32_e32 v39, v78
	v_mov_b32_e32 v67, v59
	v_pk_mul_f32 v[60:61], v[34:35], v[34:35]
	v_pk_add_f32 v[68:69], v[70:71], v[72:73]
	v_pk_add_f32 v[38:39], v[66:67], v[38:39]
	v_lshlrev_b32_e32 v57, 16, v37
	v_lshlrev_b32_e32 v56, 16, v36
	v_and_b32_e32 v37, 0xffff0000, v37
	v_and_b32_e32 v36, 0xffff0000, v36
	v_pk_fma_f32 v[60:61], v[54:55], v[54:55], v[60:61]
	v_pk_add_f32 v[38:39], v[38:39], v[68:69]
	v_pk_mul_f32 v[62:63], v[36:37], v[36:37]
	v_mov_b32_e32 v65, v19
	v_mul_f32_e32 v64, v23, v23
	v_pk_add_f32 v[60:61], v[60:61], v[60:61] op_sel:[0,1] op_sel_hi:[1,0]
	v_pk_add_f32 v[38:39], v[38:39], v[38:39] op_sel:[0,1] op_sel_hi:[1,0]
	v_pk_fma_f32 v[62:63], v[56:57], v[56:57], v[62:63]
	v_pk_fma_f32 v[76:77], v[22:23], v[22:23], v[64:65] op_sel_hi:[1,1,0]
	v_mov_b32_e32 v64, v60
	v_mov_b32_e32 v18, v38
	v_mul_f32_e32 v81, v17, v17
	v_mul_f32_e32 v82, v14, v14
	v_mul_f32_e32 v83, v15, v15
	v_pk_add_f32 v[62:63], v[62:63], v[62:63] op_sel:[0,1] op_sel_hi:[1,0]
	v_pk_add_f32 v[38:39], v[38:39], v[60:61]
	v_pk_mul_f32 v[58:59], v[18:19], v[64:65]
	v_mov_b32_e32 v75, v82
	v_mov_b32_e32 v77, v83
	v_mov_b32_e32 v63, v81
	v_mov_b32_e32 v39, v59
	v_pk_add_f32 v[70:71], v[74:75], v[76:77]
	v_pk_add_f32 v[38:39], v[38:39], v[62:63]
	s_nop 0
	v_pk_add_f32 v[38:39], v[38:39], v[70:71]
	s_nop 0
	v_add_f32_e32 v16, v38, v39
	s_nop 1
	v_add_f32_dpp v16, v16, v16 quad_perm:[1,0,3,2] row_mask:0xf bank_mask:0xf bound_ctrl:1
	s_nop 1
	v_add_f32_dpp v16, v16, v16 quad_perm:[2,3,0,1] row_mask:0xf bank_mask:0xf bound_ctrl:1
	s_nop 1
	v_add_f32_dpp v16, v16, v16 row_half_mirror row_mask:0xf bank_mask:0xf bound_ctrl:1
	s_nop 1
	v_add_f32_dpp v16, v16, v16 row_mirror row_mask:0xf bank_mask:0xf bound_ctrl:1
	ds_swizzle_b32 v18, v16 offset:swizzle(SWAP,16)
	s_waitcnt lgkmcnt(0)
; __device__ __forceinline__ float wave_sum(float v) { return swap32_sum(red32(v)); }
; template <bool GA, bool XBF = false>
; __device__ __forceinline__ void norm_rows(const float* X, const float* gain, bf16* H, float* GA1, const LAS float* waT, int nrows, int gw, int NGW, int lane_) {
;     ...
;         for (int j = 0; j < 8; ++j) s += (v[j].x * v[j].x + v[j].y * v[j].y) + (v[j].z * v[j].z + v[j].w * v[j].w);
;         const float rinv = 1.0f / sqrtf(wave_sum(s) * (1.0f / DM) + EPS);
	v_add_f32_e32 v16, v16, v18
	v_mov_b32_e32 v18, v16
	v_mov_b32_e32 v38, v16
	s_nop 1
	v_permlane32_swap_b32_e32 v18, v38
	v_cndmask_b32_e64 v18, v38, v18, s[0:1]
	v_add_f32_e32 v16, v16, v18
	v_fmamk_f32 v16, v16, 0x3a000000, v24
	v_mul_f32_e32 v18, 0x4f800000, v16
	v_cmp_gt_f32_e32 vcc, s7, v16
	s_nop 1
	v_cndmask_b32_e32 v16, v16, v18, vcc
	v_sqrt_f32_e32 v18, v16
	s_nop 0
	v_add_u32_e32 v38, -1, v18
	v_add_u32_e32 v39, 1, v18
	v_fma_f32 v40, -v38, v18, v16
	v_fma_f32 v42, -v39, v18, v16
	v_cmp_ge_f32_e64 s[2:3], 0, v40
	s_nop 1
	v_cndmask_b32_e64 v18, v18, v38, s[2:3]
	v_cmp_lt_f32_e64 s[2:3], 0, v42
	s_nop 1
	v_cndmask_b32_e64 v18, v18, v39, s[2:3]
	v_mul_f32_e32 v38, 0x37800000, v18
	v_cndmask_b32_e32 v18, v18, v38, vcc
	v_cmp_class_f32_e32 vcc, v16, v25
	s_nop 1
	v_cndmask_b32_e32 v16, v18, v16, vcc
	v_div_scale_f32 v18, s[2:3], v16, v16, 1.0
	v_rcp_f32_e32 v39, v18
	v_div_scale_f32 v38, vcc, 1.0, v16, 1.0
	v_fma_f32 v40, -v18, v39, 1.0
	v_fmac_f32_e32 v39, v40, v39
	v_mul_f32_e32 v40, v38, v39
	v_fma_f32 v42, -v18, v40, v38
	v_fmac_f32_e32 v40, v42, v39
	v_fma_f32 v18, -v18, v40, v38
	v_div_fmas_f32 v18, v18, v39, v40
	v_div_fixup_f32 v18, v18, v16, 1.0
	v_pk_mul_f32 v[38:39], v[18:19], v[46:47] op_sel_hi:[0,1]
	v_pk_mul_f32 v[46:47], v[18:19], v[48:49] op_sel_hi:[0,1]
	s_waitcnt vmcnt(0)
; __device__ __forceinline__ unsigned pk2(float lo, float hi) { return f2bf(lo) | (f2bf(hi) << 16); }
; template <bool GA, bool XBF = false>
; __device__ __forceinline__ void norm_rows(const float* X, const float* gain, bf16* H, float* GA1, const LAS float* waT, int nrows, int gw, int NGW, int lane_) {
;     ...
;         unsigned long long* o8 = (unsigned long long*)(H + (size_t)m * DM) + lane;
; #pragma unroll
;         for (int j = 0; j < 8; ++j) { const f32x4 g = ((const f32x4*)gain)[lane + 64 * j]; v[j] = v[j] * rinv * g;
;             o8[64 * j] = (unsigned long long)pk2(v[j].x, v[j].y) | ((unsigned long long)pk2(v[j].z, v[j].w) << 32); }
	v_pk_mul_f32 v[28:29], v[28:29], v[46:47]
	v_pk_mul_f32 v[26:27], v[26:27], v[38:39]
	v_bfe_u32 v39, v28, 16, 1
	v_bfe_u32 v16, v26, 16, 1
	v_bfe_u32 v38, v27, 16, 1
	v_bfe_u32 v40, v29, 16, 1
	v_add3_u32 v16, v26, v16, s10
	v_add3_u32 v26, v27, v38, s10
	v_add3_u32 v27, v28, v39, s10
	v_add3_u32 v28, v29, v40, s10
	v_lshrrev_b32_e32 v16, 16, v16
	v_lshrrev_b32_e32 v27, 16, v27
	v_and_or_b32 v26, v26, s5, v16
	v_and_or_b32 v27, v28, s5, v27
	global_store_dwordx2 v[12:13], v[26:27], off offset:-3584
	v_mov_b32_e32 v26, v212
	v_mov_b32_e32 v27, v213
	v_mov_b32_e32 v28, v214
	v_mov_b32_e32 v29, v215
	v_mov_b32_e32 v38, v50
	v_mov_b32_e32 v39, v30
	v_mov_b32_e32 v30, v51
	v_pk_mul_f32 v[38:39], v[18:19], v[38:39] op_sel_hi:[0,1]
	v_pk_mul_f32 v[30:31], v[18:19], v[30:31] op_sel_hi:[0,1]
	v_pk_mul_f32 v[32:33], v[18:19], v[32:33] op_sel_hi:[0,1]
	v_mov_b32_e32 v42, v41
	v_pk_mul_f32 v[20:21], v[18:19], v[20:21] op_sel_hi:[0,1]
	v_pk_mul_f32 v[22:23], v[18:19], v[22:23] op_sel_hi:[0,1]
	v_pk_mul_f32 v[14:15], v[14:15], v[18:19] op_sel_hi:[1,0]
	v_pk_mul_f32 v[28:29], v[28:29], v[30:31]
	v_pk_mul_f32 v[26:27], v[26:27], v[38:39]
	v_bfe_u32 v31, v28, 16, 1
	v_bfe_u32 v16, v26, 16, 1
	v_bfe_u32 v30, v27, 16, 1
	v_bfe_u32 v38, v29, 16, 1
	v_add3_u32 v16, v26, v16, s10
	v_add3_u32 v26, v27, v30, s10
	v_add3_u32 v27, v28, v31, s10
	v_add3_u32 v28, v29, v38, s10
	v_lshrrev_b32_e32 v16, 16, v16
	v_lshrrev_b32_e32 v27, 16, v27
	v_and_or_b32 v26, v26, s5, v16
	v_and_or_b32 v27, v28, s5, v27
	global_store_dwordx2 v[12:13], v[26:27], off offset:-3072
	v_mov_b32_e32 v26, v216
	v_mov_b32_e32 v27, v217
	v_mov_b32_e32 v28, v218
	v_mov_b32_e32 v29, v219
	v_pk_mul_f32 v[30:31], v[18:19], v[52:53] op_sel_hi:[0,1]
	v_pk_mul_f32 v[28:29], v[28:29], v[32:33]
	v_pk_mul_f32 v[26:27], v[26:27], v[30:31]
	v_bfe_u32 v31, v28, 16, 1
	v_bfe_u32 v16, v26, 16, 1
	v_bfe_u32 v30, v27, 16, 1
	v_bfe_u32 v32, v29, 16, 1
	v_add3_u32 v16, v26, v16, s10
	v_add3_u32 v26, v27, v30, s10
	v_add3_u32 v27, v28, v31, s10
	v_add3_u32 v28, v29, v32, s10
	v_lshrrev_b32_e32 v16, 16, v16
	v_lshrrev_b32_e32 v27, 16, v27
	v_and_or_b32 v26, v26, s5, v16
	v_and_or_b32 v27, v28, s5, v27
	global_store_dwordx2 v[12:13], v[26:27], off offset:-2560
	v_mov_b32_e32 v26, v220
	v_mov_b32_e32 v27, v221
	v_mov_b32_e32 v28, v222
	v_mov_b32_e32 v29, v223
	v_pk_mul_f32 v[30:31], v[42:43], v[18:19] op_sel_hi:[1,0]
	v_pk_mul_f32 v[32:33], v[44:45], v[18:19] op_sel_hi:[1,0]
	v_pk_mul_f32 v[26:27], v[26:27], v[30:31]
	v_pk_mul_f32 v[28:29], v[28:29], v[32:33]
	v_bfe_u32 v16, v26, 16, 1
	v_bfe_u32 v30, v27, 16, 1
	v_bfe_u32 v31, v28, 16, 1
	v_bfe_u32 v32, v29, 16, 1
	v_add3_u32 v16, v26, v16, s10
	v_add3_u32 v26, v27, v30, s10
	v_add3_u32 v27, v28, v31, s10
	v_add3_u32 v28, v29, v32, s10
	v_lshrrev_b32_e32 v16, 16, v16
	v_lshrrev_b32_e32 v27, 16, v27
	v_and_or_b32 v26, v26, s5, v16
	v_and_or_b32 v27, v28, s5, v27
	global_store_dwordx2 v[12:13], v[26:27], off offset:-2048
	v_mov_b32_e32 v26, v224
	v_mov_b32_e32 v27, v225
	v_mov_b32_e32 v28, v226
	v_mov_b32_e32 v29, v227
	v_mov_b32_e32 v30, v54
	v_mov_b32_e32 v31, v34
	v_mov_b32_e32 v34, v55
	v_pk_mul_f32 v[30:31], v[18:19], v[30:31] op_sel_hi:[0,1]
	v_pk_mul_f32 v[32:33], v[18:19], v[34:35] op_sel_hi:[0,1]
	v_pk_mul_f32 v[28:29], v[28:29], v[32:33]
	v_pk_mul_f32 v[26:27], v[26:27], v[30:31]
	v_bfe_u32 v31, v28, 16, 1
	v_bfe_u32 v16, v26, 16, 1
	v_bfe_u32 v30, v27, 16, 1
	v_bfe_u32 v32, v29, 16, 1
	v_add3_u32 v16, v26, v16, s10
	v_add3_u32 v26, v27, v30, s10
	v_add3_u32 v27, v28, v31, s10
	v_add3_u32 v28, v29, v32, s10
	v_lshrrev_b32_e32 v16, 16, v16
	v_lshrrev_b32_e32 v27, 16, v27
	v_and_or_b32 v26, v26, s5, v16
	v_and_or_b32 v27, v28, s5, v27
	global_store_dwordx2 v[12:13], v[26:27], off offset:-1536
	v_mov_b32_e32 v26, v228
	v_mov_b32_e32 v27, v229
	v_mov_b32_e32 v28, v230
	v_mov_b32_e32 v29, v231
	v_mov_b32_e32 v30, v56
	v_mov_b32_e32 v31, v36
	v_mov_b32_e32 v36, v57
	v_pk_mul_f32 v[30:31], v[18:19], v[30:31] op_sel_hi:[0,1]
	v_pk_mul_f32 v[32:33], v[18:19], v[36:37] op_sel_hi:[0,1]
	v_pk_mul_f32 v[28:29], v[28:29], v[32:33]
	v_pk_mul_f32 v[26:27], v[26:27], v[30:31]
	v_bfe_u32 v31, v28, 16, 1
	v_bfe_u32 v16, v26, 16, 1
	v_bfe_u32 v30, v27, 16, 1
	v_bfe_u32 v32, v29, 16, 1
	v_add3_u32 v16, v26, v16, s10
	v_add3_u32 v26, v27, v30, s10
	v_add3_u32 v27, v28, v31, s10
	v_add3_u32 v28, v29, v32, s10
	v_lshrrev_b32_e32 v16, 16, v16
	v_lshrrev_b32_e32 v27, 16, v27
	v_and_or_b32 v26, v26, s5, v16
	v_and_or_b32 v27, v28, s5, v27
	global_store_dwordx2 v[12:13], v[26:27], off offset:-1024
	v_mov_b32_e32 v26, v232
	v_mov_b32_e32 v27, v233
	v_mov_b32_e32 v28, v234
	v_mov_b32_e32 v29, v235
	v_pk_mul_f32 v[22:23], v[28:29], v[22:23]
	v_pk_mul_f32 v[20:21], v[26:27], v[20:21]
	v_bfe_u32 v27, v22, 16, 1
	v_bfe_u32 v16, v20, 16, 1
	v_bfe_u32 v26, v21, 16, 1
	v_bfe_u32 v28, v23, 16, 1
	v_add3_u32 v16, v20, v16, s10
	v_add3_u32 v20, v21, v26, s10
	v_add3_u32 v21, v22, v27, s10
	v_add3_u32 v22, v23, v28, s10
	v_lshrrev_b32_e32 v16, 16, v16
	v_lshrrev_b32_e32 v21, 16, v21
	v_and_or_b32 v20, v20, s5, v16
	v_and_or_b32 v21, v22, s5, v21
	global_store_dwordx2 v[12:13], v[20:21], off offset:-512
	v_mov_b32_e32 v20, v236
	v_mov_b32_e32 v21, v237
	v_mov_b32_e32 v22, v238
	v_mov_b32_e32 v23, v239
	v_mov_b32_e32 v16, v19
	v_pk_mul_f32 v[16:17], v[16:17], v[18:19] op_sel_hi:[1,0]
	v_pk_mul_f32 v[14:15], v[14:15], v[22:23]
	v_pk_mul_f32 v[16:17], v[16:17], v[20:21]
	v_bfe_u32 v20, v14, 16, 1
	v_bfe_u32 v18, v16, 16, 1
	v_bfe_u32 v19, v17, 16, 1
	v_bfe_u32 v21, v15, 16, 1
	v_add3_u32 v16, v16, v18, s10
	v_add3_u32 v14, v14, v20, s10
	v_add3_u32 v17, v17, v19, s10
	v_add3_u32 v15, v15, v21, s10
	v_lshrrev_b32_e32 v16, 16, v16
	v_lshrrev_b32_e32 v18, 16, v14
	v_and_or_b32 v14, v17, s5, v16
	v_and_or_b32 v15, v15, s5, v18
	global_store_dwordx2 v[12:13], v[14:15], off
	s_cbranch_scc1 .LBB0_728

; __device__ __forceinline__ float wave_sum(float v) { return swap32_sum(red32(v)); }
; template <bool GA, bool XBF = false>
; __device__ __forceinline__ void norm_rows(const float* X, const float* gain, bf16* H, float* GA1, const LAS float* waT, int nrows, int gw, int NGW, int lane_) {
;     ...
;     for (int m = gw; m < nrows; m += NGW) {
;         f32x4 v[8]; float s = 0.f;
;         if constexpr (XBF) { const u32x2* xb = (const u32x2*)((const bf16*)X + (size_t)m * DM) + lane;
; #pragma unroll
;             for (int j = 0; j < 8; ++j) { const u32x2 w = xb[64 * j]; v[j] = (f32x4){bflo(w.x), bfhi(w.x), bflo(w.y), bfhi(w.y)}; }
;         } else { const f32x4* xr = (const f32x4*)(X + (size_t)m * DM) + lane;
; #pragma unroll
;             for (int j = 0; j < 8; ++j) v[j] = __builtin_nontemporal_load(xr + 64 * j); }
; #pragma unroll
;         for (int j = 0; j < 8; ++j) s += (v[j].x * v[j].x + v[j].y * v[j].y) + (v[j].z * v[j].z + v[j].w * v[j].w);
;         const float rinv = 1.0f / sqrtf(wave_sum(s) * (1.0f / DM) + EPS);
;         unsigned long long* o8 = (unsigned long long*)(H + (size_t)m * DM) + lane;
; #pragma unroll
;         for (int j = 0; j < 8; ++j) { const f32x4 g = ((const f32x4*)gain)[lane + 64 * j]; v[j] = v[j] * rinv * g;
.LBB0_966:
	s_or_b64 exec, exec, s[0:1]
	s_waitcnt lgkmcnt(0)
	s_barrier
	v_mov_b32 v1, s77
	ds_read_b64 v[2:3], v1 offset:16
	s_cmpk_gt_i32 s6, 0x3fff
	s_waitcnt lgkmcnt(0)
	v_readfirstlane_b32 s9, v3
	v_readfirstlane_b32 s8, v2
	s_cbranch_scc1 .LBB0_973
	v_ashrrev_i32_e32 v1, 31, v0
	v_lshl_add_u64 v[4:5], v[0:1], 3, s[4:5]
	v_lshl_add_u64 v[6:7], v[0:1], 2, s[4:5]
	s_mov_b64 s[4:5], 0x2da00000
	v_lshl_add_u64 v[6:7], v[6:7], 0, s[4:5]
	v_lshl_add_u64 v[16:17], v[0:1], 4, s[8:9]
	s_mov_b64 s[4:5], 0x2000
	v_lshl_add_u64 v[8:9], v[16:17], 0, s[4:5]
	s_mov_b64 s[4:5], 0x3000
	v_lshl_add_u64 v[10:11], v[16:17], 0, s[4:5]
	s_mov_b64 s[4:5], 0x3400
	v_lshl_add_u64 v[12:13], v[16:17], 0, s[4:5]
	s_mov_b64 s[4:5], 0x3800
	s_mov_b64 s[0:1], 0x2e500000
	s_mov_b64 s[2:3], 0x9a00000
	v_lshl_add_u64 v[14:15], v[16:17], 0, s[4:5]
	s_mov_b64 s[4:5], 0x3c00
	v_lshl_add_u64 v[2:3], v[4:5], 0, s[0:1]
	v_cmp_eq_u32_e64 s[0:1], 32, v205
	v_lshl_add_u64 v[4:5], v[4:5], 0, s[2:3]
	v_lshl_add_u32 v54, v0, 4, 0
	v_cmp_gt_i32_e64 s[2:3], 16, v0
	v_lshl_add_u64 v[16:17], v[16:17], 0, s[4:5]
	s_mov_b32 s10, 0xffff0000
	v_mov_b32_e32 v1, 0x358637bd
	s_mov_b32 s11, 0xf800000
	v_mov_b32_e32 v55, 0x260
	s_movk_i32 s12, 0x7fff
	global_load_dwordx4 v[208:211], v[8:9], off
	global_load_dwordx4 v[212:215], v[8:9], off offset:1024
	global_load_dwordx4 v[216:219], v[8:9], off offset:2048
	global_load_dwordx4 v[220:223], v[8:9], off offset:3072
	global_load_dwordx4 v[224:227], v[10:11], off
	global_load_dwordx4 v[228:231], v[12:13], off
	global_load_dwordx4 v[232:235], v[14:15], off
	global_load_dwordx4 v[236:239], v[16:17], off
	s_waitcnt vmcnt(0)
	s_branch .LBB0_969

; __device__ __forceinline__ float wave_sum(float v) { return swap32_sum(red32(v)); }
; template <bool GA, bool XBF = false>
; __device__ __forceinline__ void norm_rows(const float* X, const float* gain, bf16* H, float* GA1, const LAS float* waT, int nrows, int gw, int NGW, int lane_) {
;     ...
;         if constexpr (XBF) { const u32x2* xb = (const u32x2*)((const bf16*)X + (size_t)m * DM) + lane;
; #pragma unroll
;             for (int j = 0; j < 8; ++j) { const u32x2 w = xb[64 * j]; v[j] = (f32x4){bflo(w.x), bfhi(w.x), bflo(w.y), bfhi(w.y)}; }
;         } else { const f32x4* xr = (const f32x4*)(X + (size_t)m * DM) + lane;
; #pragma unroll
;             for (int j = 0; j < 8; ++j) v[j] = __builtin_nontemporal_load(xr + 64 * j); }
; #pragma unroll
;         for (int j = 0; j < 8; ++j) s += (v[j].x * v[j].x + v[j].y * v[j].y) + (v[j].z * v[j].z + v[j].w * v[j].w);
;         const float rinv = 1.0f / sqrtf(wave_sum(s) * (1.0f / DM) + EPS);
;         unsigned long long* o8 = (unsigned long long*)(H + (size_t)m * DM) + lane;
; #pragma unroll
;         for (int j = 0; j < 8; ++j) { const f32x4 g = ((const f32x4*)gain)[lane + 64 * j]; v[j] = v[j] * rinv * g;
.LBB0_969:
	s_ashr_i32 s7, s6, 31
	s_lshl_b64 s[8:9], s[6:7], 12
	v_lshl_add_u64 v[22:23], v[2:3], 0, s[8:9]
	global_load_dwordx2 v[24:25], v[22:23], off offset:1536
	global_load_dwordx2 v[26:27], v[22:23], off offset:3584
	global_load_dwordx2 v[34:35], v[22:23], off
	global_load_dwordx2 v[36:37], v[22:23], off offset:512
	global_load_dwordx2 v[38:39], v[22:23], off offset:1024
	global_load_dwordx2 v[40:41], v[22:23], off offset:2048
	global_load_dwordx2 v[42:43], v[22:23], off offset:2560
	global_load_dwordx2 v[46:47], v[22:23], off offset:3072
	v_mov_b32_e32 v18, v208
	v_mov_b32_e32 v19, v209
	v_mov_b32_e32 v20, v210
	v_mov_b32_e32 v21, v211
	s_waitcnt vmcnt(7)
	v_lshlrev_b32_e32 v60, 16, v25
	v_and_b32_e32 v61, 0xffff0000, v25
	s_waitcnt vmcnt(5)
	v_and_b32_e32 v23, 0xffff0000, v34
	v_and_b32_e32 v25, 0xffff0000, v35
	v_lshlrev_b32_e32 v57, 16, v24
	v_and_b32_e32 v59, 0xffff0000, v24
	v_lshlrev_b32_e32 v33, 16, v26
	v_and_b32_e32 v31, 0xffff0000, v26
	v_lshlrev_b32_e32 v28, 16, v27
	v_and_b32_e32 v29, 0xffff0000, v27
	v_lshlrev_b32_e32 v22, 16, v34
	v_lshlrev_b32_e32 v24, 16, v35
	s_waitcnt vmcnt(4)
	v_lshlrev_b32_e32 v27, 16, v37
	v_and_b32_e32 v35, 0xffff0000, v37
	v_and_b32_e32 v34, 0xffff0000, v36
	s_waitcnt vmcnt(3)
	v_and_b32_e32 v37, 0xffff0000, v38
	s_waitcnt vmcnt(0)
	v_and_b32_e32 v45, 0xffff0000, v46
	v_mul_f32_e32 v30, v25, v25
	v_mul_f32_e32 v32, v23, v23
	v_lshlrev_b32_e32 v26, 16, v36
	v_lshlrev_b32_e32 v36, 16, v38
	v_lshlrev_b32_e32 v38, 16, v39
	v_and_b32_e32 v39, 0xffff0000, v39
	v_lshlrev_b32_e32 v44, 16, v46
	v_pk_mul_f32 v[48:49], v[34:35], v[34:35]
	v_mov_b32_e32 v51, v57
	v_mul_f32_e32 v50, v37, v37
	v_mul_f32_e32 v56, v45, v45
	v_pk_fma_f32 v[70:71], v[24:25], v[24:25], v[30:31] op_sel_hi:[1,1,0]
	v_pk_fma_f32 v[72:73], v[22:23], v[22:23], v[32:33] op_sel_hi:[1,1,0]
	v_mul_f32_e32 v52, v39, v39
	v_mov_b32_e32 v53, v33
	v_pk_fma_f32 v[48:49], v[26:27], v[26:27], v[48:49]
	v_pk_fma_f32 v[74:75], v[36:37], v[36:37], v[50:51] op_sel_hi:[1,1,0]
	v_pk_fma_f32 v[78:79], v[44:45], v[44:45], v[56:57] op_sel_hi:[1,1,0]
	v_mov_b32_e32 v56, v72
	v_mov_b32_e32 v50, v70
	v_mul_f32_e32 v82, v59, v59
	v_mul_f32_e32 v83, v60, v60
	v_mul_f32_e32 v84, v61, v61
	v_pk_fma_f32 v[76:77], v[38:39], v[38:39], v[52:53] op_sel_hi:[1,1,0]
	v_pk_add_f32 v[70:71], v[72:73], v[70:71]
	v_pk_add_f32 v[48:49], v[48:49], v[48:49] op_sel:[0,1] op_sel_hi:[1,0]
	v_pk_mul_f32 v[50:51], v[56:57], v[50:51]
	v_and_b32_e32 v65, 0xffff0000, v41
	v_and_b32_e32 v64, 0xffff0000, v40
	v_mov_b32_e32 v75, v83
	v_mov_b32_e32 v77, v84
	v_mov_b32_e32 v49, v82
	v_mov_b32_e32 v71, v51
	v_lshlrev_b32_e32 v63, 16, v41
	v_lshlrev_b32_e32 v62, 16, v40
	v_pk_mul_f32 v[66:67], v[64:65], v[64:65]
	v_pk_add_f32 v[72:73], v[74:75], v[76:77]
	v_pk_add_f32 v[48:49], v[70:71], v[48:49]
	v_lshlrev_b32_e32 v41, 16, v43
	v_lshlrev_b32_e32 v40, 16, v42
	v_and_b32_e32 v43, 0xffff0000, v43
	v_and_b32_e32 v42, 0xffff0000, v42
	v_pk_fma_f32 v[66:67], v[62:63], v[62:63], v[66:67]
	v_pk_add_f32 v[48:49], v[48:49], v[72:73]
	v_lshlrev_b32_e32 v46, 16, v47
	v_and_b32_e32 v47, 0xffff0000, v47
	v_pk_mul_f32 v[68:69], v[42:43], v[42:43]
	v_pk_add_f32 v[66:67], v[66:67], v[66:67] op_sel:[0,1] op_sel_hi:[1,0]
	v_pk_add_f32 v[48:49], v[48:49], v[48:49] op_sel:[0,1] op_sel_hi:[1,0]
	v_mul_f32_e32 v58, v47, v47
	v_pk_fma_f32 v[68:69], v[40:41], v[40:41], v[68:69]
	v_mov_b32_e32 v52, v66
	v_mov_b32_e32 v32, v48
	v_mul_f32_e32 v85, v31, v31
	v_mul_f32_e32 v86, v28, v28
	v_mul_f32_e32 v87, v29, v29
	v_pk_fma_f32 v[80:81], v[46:47], v[46:47], v[58:59] op_sel_hi:[1,1,0]
	v_pk_add_f32 v[68:69], v[68:69], v[68:69] op_sel:[0,1] op_sel_hi:[1,0]
	v_pk_add_f32 v[48:49], v[48:49], v[66:67]
	v_pk_mul_f32 v[50:51], v[32:33], v[52:53]
	v_mov_b32_e32 v79, v86
	v_mov_b32_e32 v81, v87
	v_mov_b32_e32 v69, v85
	v_mov_b32_e32 v49, v51
	v_pk_add_f32 v[74:75], v[78:79], v[80:81]
	v_pk_add_f32 v[48:49], v[48:49], v[68:69]
	v_mov_b32_e32 v58, v57
	v_pk_add_f32 v[48:49], v[48:49], v[74:75]
	s_nop 0
	v_add_f32_e32 v30, v48, v49
	s_nop 1
	v_add_f32_dpp v30, v30, v30 quad_perm:[1,0,3,2] row_mask:0xf bank_mask:0xf bound_ctrl:1
	s_nop 1
	v_add_f32_dpp v30, v30, v30 quad_perm:[2,3,0,1] row_mask:0xf bank_mask:0xf bound_ctrl:1
	s_nop 1
	v_add_f32_dpp v30, v30, v30 row_half_mirror row_mask:0xf bank_mask:0xf bound_ctrl:1
	s_nop 1
	v_add_f32_dpp v30, v30, v30 row_mirror row_mask:0xf bank_mask:0xf bound_ctrl:1
	ds_swizzle_b32 v32, v30 offset:swizzle(SWAP,16)
	s_waitcnt lgkmcnt(0)
	v_add_f32_e32 v30, v30, v32
	v_mov_b32_e32 v32, v30
	v_mov_b32_e32 v48, v30
	s_nop 1
	v_permlane32_swap_b32_e32 v32, v48
	v_cndmask_b32_e64 v32, v48, v32, s[0:1]
	v_add_f32_e32 v30, v30, v32
	v_fmamk_f32 v30, v30, 0x3a000000, v1
	v_mul_f32_e32 v32, 0x4f800000, v30
	v_cmp_gt_f32_e32 vcc, s11, v30
	s_nop 1
	v_cndmask_b32_e32 v30, v30, v32, vcc
	v_sqrt_f32_e32 v32, v30
	s_nop 0
	v_add_u32_e32 v48, -1, v32
	v_add_u32_e32 v49, 1, v32
	v_fma_f32 v50, -v48, v32, v30
	v_fma_f32 v51, -v49, v32, v30
	v_cmp_ge_f32_e64 s[4:5], 0, v50
	s_nop 1
	v_cndmask_b32_e64 v32, v32, v48, s[4:5]
	v_cmp_lt_f32_e64 s[4:5], 0, v51
	s_nop 1
	v_cndmask_b32_e64 v32, v32, v49, s[4:5]
	v_mul_f32_e32 v48, 0x37800000, v32
	v_cndmask_b32_e32 v32, v32, v48, vcc
	v_cmp_class_f32_e32 vcc, v30, v55
	s_nop 1
	v_cndmask_b32_e32 v30, v32, v30, vcc
	v_div_scale_f32 v32, s[4:5], v30, v30, 1.0
	v_rcp_f32_e32 v48, v32
	v_div_scale_f32 v49, vcc, 1.0, v30, 1.0
	s_mov_b32 s4, 0
	v_fma_f32 v50, -v32, v48, 1.0
	v_fmac_f32_e32 v48, v50, v48
	v_mul_f32_e32 v50, v49, v48
	v_fma_f32 v51, -v32, v50, v49
	v_fmac_f32_e32 v50, v51, v48
	v_fma_f32 v32, -v32, v50, v49
	v_div_fmas_f32 v32, v32, v48, v50
	v_div_fixup_f32 v32, v32, v30, 1.0
	v_pk_mul_f32 v[22:23], v[32:33], v[22:23] op_sel_hi:[0,1]
	s_waitcnt vmcnt(0)
; __device__ __forceinline__ unsigned pk2(float lo, float hi) { return f2bf(lo) | (f2bf(hi) << 16); }
; template <bool GA, bool XBF = false>
; __device__ __forceinline__ void norm_rows(const float* X, const float* gain, bf16* H, float* GA1, const LAS float* waT, int nrows, int gw, int NGW, int lane_) {
;     ...
;         unsigned long long* o8 = (unsigned long long*)(H + (size_t)m * DM) + lane;
; #pragma unroll
;         for (int j = 0; j < 8; ++j) { const f32x4 g = ((const f32x4*)gain)[lane + 64 * j]; v[j] = v[j] * rinv * g;
;             o8[64 * j] = (unsigned long long)pk2(v[j].x, v[j].y) | ((unsigned long long)pk2(v[j].z, v[j].w) << 32); }
	v_pk_mul_f32 v[52:53], v[18:19], v[22:23]
	v_pk_mul_f32 v[24:25], v[32:33], v[24:25] op_sel_hi:[0,1]
	v_bfe_u32 v18, v52, 16, 1
	v_add3_u32 v18, v52, v18, s12
	v_bfe_u32 v19, v53, 16, 1
	v_pk_mul_f32 v[50:51], v[20:21], v[24:25]
	v_lshrrev_b32_e32 v18, 16, v18
	v_add3_u32 v19, v53, v19, s12
	v_and_or_b32 v18, v19, s10, v18
	v_bfe_u32 v19, v50, 16, 1
	v_add3_u32 v19, v50, v19, s12
	v_bfe_u32 v20, v51, 16, 1
	v_lshrrev_b32_e32 v19, 16, v19
	v_add3_u32 v20, v51, v20, s12
	v_lshl_add_u64 v[48:49], v[4:5], 0, s[8:9]
	v_and_or_b32 v19, v20, s10, v19
	global_store_dwordx2 v[48:49], v[18:19], off
	v_mov_b32_e32 v20, v212
	v_mov_b32_e32 v21, v213
	v_mov_b32_e32 v22, v214
	v_mov_b32_e32 v23, v215
	v_mov_b32_e32 v18, v26
	v_mov_b32_e32 v19, v34
	v_mov_b32_e32 v34, v27
	v_pk_mul_f32 v[24:25], v[32:33], v[18:19] op_sel_hi:[0,1]
	v_pk_mul_f32 v[18:19], v[32:33], v[34:35] op_sel_hi:[0,1]
	v_pk_mul_f32 v[26:27], v[32:33], v[38:39] op_sel_hi:[0,1]
	v_pk_mul_f32 v[34:35], v[32:33], v[36:37] op_sel_hi:[0,1]
	v_pk_mul_f32 v[38:39], v[60:61], v[32:33] op_sel_hi:[1,0]
	v_mov_b32_e32 v60, v41
	v_mov_b32_e32 v61, v43
	v_mov_b32_e32 v41, v42
	v_pk_mul_f32 v[42:43], v[32:33], v[60:61] op_sel_hi:[0,1]
	v_pk_mul_f32 v[40:41], v[32:33], v[40:41] op_sel_hi:[0,1]
	v_pk_mul_f32 v[46:47], v[32:33], v[46:47] op_sel_hi:[0,1]
	v_pk_mul_f32 v[44:45], v[32:33], v[44:45] op_sel_hi:[0,1]
	v_pk_mul_f32 v[18:19], v[22:23], v[18:19]
	v_pk_mul_f32 v[20:21], v[20:21], v[24:25]
	v_bfe_u32 v24, v18, 16, 1
	v_bfe_u32 v22, v20, 16, 1
	v_bfe_u32 v23, v21, 16, 1
	v_bfe_u32 v25, v19, 16, 1
	v_add3_u32 v22, v20, v22, s12
	v_add3_u32 v24, v18, v24, s12
	v_add3_u32 v23, v21, v23, s12
	v_add3_u32 v25, v19, v25, s12
	v_lshrrev_b32_e32 v22, 16, v22
	v_lshrrev_b32_e32 v24, 16, v24
	v_and_or_b32 v22, v23, s10, v22
	v_and_or_b32 v23, v25, s10, v24
	global_store_dwordx2 v[48:49], v[22:23], off offset:512
	v_mov_b32_e32 v22, v216
	v_mov_b32_e32 v23, v217
	v_mov_b32_e32 v24, v218
	v_mov_b32_e32 v25, v219
	v_pk_mul_f32 v[22:23], v[22:23], v[34:35]
	v_pk_mul_f32 v[24:25], v[24:25], v[26:27]
	v_bfe_u32 v26, v22, 16, 1
	v_bfe_u32 v30, v24, 16, 1
	v_bfe_u32 v27, v23, 16, 1
	v_bfe_u32 v34, v25, 16, 1
	v_add3_u32 v26, v22, v26, s12
	v_add3_u32 v30, v24, v30, s12
	v_add3_u32 v27, v23, v27, s12
	v_add3_u32 v34, v25, v34, s12
	v_lshrrev_b32_e32 v26, 16, v26
	v_lshrrev_b32_e32 v30, 16, v30
	v_and_or_b32 v26, v27, s10, v26
	v_and_or_b32 v27, v34, s10, v30
	global_store_dwordx2 v[48:49], v[26:27], off offset:1024
	v_mov_b32_e32 v34, v220
	v_mov_b32_e32 v35, v221
	v_mov_b32_e32 v36, v222
	v_mov_b32_e32 v37, v223
	v_pk_mul_f32 v[26:27], v[58:59], v[32:33] op_sel_hi:[1,0]
	v_pk_mul_f32 v[26:27], v[34:35], v[26:27]
	v_pk_mul_f32 v[34:35], v[36:37], v[38:39]
	v_bfe_u32 v30, v26, 16, 1
	v_bfe_u32 v37, v34, 16, 1
	v_bfe_u32 v36, v27, 16, 1
	v_bfe_u32 v38, v35, 16, 1
	v_add3_u32 v30, v26, v30, s12
	v_add3_u32 v37, v34, v37, s12
	v_add3_u32 v36, v27, v36, s12
	v_add3_u32 v38, v35, v38, s12
	v_lshrrev_b32_e32 v30, 16, v30
	v_lshrrev_b32_e32 v37, 16, v37
	v_and_or_b32 v36, v36, s10, v30
	v_and_or_b32 v37, v38, s10, v37
	global_store_dwordx2 v[48:49], v[36:37], off offset:1536
	v_mov_b32_e32 v56, v224
	v_mov_b32_e32 v57, v225
	v_mov_b32_e32 v58, v226
	v_mov_b32_e32 v59, v227
	v_mov_b32_e32 v36, v62
	v_mov_b32_e32 v37, v64
	v_mov_b32_e32 v64, v63
	v_pk_mul_f32 v[38:39], v[32:33], v[36:37] op_sel_hi:[0,1]
	v_pk_mul_f32 v[36:37], v[32:33], v[64:65] op_sel_hi:[0,1]
	v_pk_mul_f32 v[36:37], v[58:59], v[36:37]
	v_pk_mul_f32 v[38:39], v[56:57], v[38:39]
	v_bfe_u32 v57, v36, 16, 1
	v_bfe_u32 v30, v38, 16, 1
	v_bfe_u32 v56, v39, 16, 1
	v_bfe_u32 v58, v37, 16, 1
	v_add3_u32 v30, v38, v30, s12
	v_add3_u32 v57, v36, v57, s12
	v_add3_u32 v56, v39, v56, s12
	v_add3_u32 v58, v37, v58, s12
	v_lshrrev_b32_e32 v30, 16, v30
	v_lshrrev_b32_e32 v57, 16, v57
	v_and_or_b32 v56, v56, s10, v30
	v_and_or_b32 v57, v58, s10, v57
	global_store_dwordx2 v[48:49], v[56:57], off offset:2048
	v_mov_b32_e32 v56, v228
	v_mov_b32_e32 v57, v229
	v_mov_b32_e32 v58, v230
	v_mov_b32_e32 v59, v231
	v_pk_mul_f32 v[40:41], v[56:57], v[40:41]
	v_pk_mul_f32 v[42:43], v[58:59], v[42:43]
	v_bfe_u32 v30, v40, 16, 1
	v_bfe_u32 v57, v42, 16, 1
	v_bfe_u32 v56, v41, 16, 1
	v_bfe_u32 v58, v43, 16, 1
	v_add3_u32 v30, v40, v30, s12
	v_add3_u32 v57, v42, v57, s12
	v_add3_u32 v56, v41, v56, s12
	v_add3_u32 v58, v43, v58, s12
	v_lshrrev_b32_e32 v30, 16, v30
	v_lshrrev_b32_e32 v57, 16, v57
	v_and_or_b32 v56, v56, s10, v30
	v_and_or_b32 v57, v58, s10, v57
	global_store_dwordx2 v[48:49], v[56:57], off offset:2560
	v_mov_b32_e32 v56, v232
	v_mov_b32_e32 v57, v233
	v_mov_b32_e32 v58, v234
	v_mov_b32_e32 v59, v235
	v_pk_mul_f32 v[44:45], v[56:57], v[44:45]
	v_pk_mul_f32 v[46:47], v[58:59], v[46:47]
	v_bfe_u32 v30, v44, 16, 1
	v_bfe_u32 v57, v46, 16, 1
	v_bfe_u32 v56, v45, 16, 1
	v_bfe_u32 v58, v47, 16, 1
	v_add3_u32 v30, v44, v30, s12
	v_add3_u32 v57, v46, v57, s12
	v_add3_u32 v56, v45, v56, s12
	v_add3_u32 v58, v47, v58, s12
	v_lshrrev_b32_e32 v30, 16, v30
	v_lshrrev_b32_e32 v57, 16, v57
	v_and_or_b32 v56, v56, s10, v30
	v_and_or_b32 v57, v58, s10, v57
	global_store_dwordx2 v[48:49], v[56:57], off offset:3072
	v_mov_b32_e32 v58, v236
	v_mov_b32_e32 v59, v237
	v_mov_b32_e32 v60, v238
	v_mov_b32_e32 v61, v239
	v_mov_b32_e32 v30, v33
	v_pk_mul_f32 v[62:63], v[30:31], v[32:33] op_sel_hi:[1,0]
	v_pk_mul_f32 v[32:33], v[28:29], v[32:33] op_sel_hi:[1,0]
	v_mov_b32_e32 v30, v50
	v_mov_b32_e32 v31, v18
	v_mov_b32_e32 v18, v51
	v_mov_b32_e32 v28, v52
	v_mov_b32_e32 v29, v20
	v_mov_b32_e32 v20, v53
	v_mov_b32_e32 v56, 0
	v_pk_mul_f32 v[32:33], v[32:33], v[60:61]
	v_pk_mul_f32 v[50:51], v[62:63], v[58:59]
	v_bfe_u32 v57, v32, 16, 1
	v_bfe_u32 v52, v50, 16, 1
	v_bfe_u32 v53, v51, 16, 1
	v_bfe_u32 v58, v33, 16, 1
	v_add3_u32 v52, v50, v52, s12
	v_add3_u32 v57, v32, v57, s12
	v_add3_u32 v53, v51, v53, s12
	v_add3_u32 v58, v33, v58, s12
	v_lshrrev_b32_e32 v52, 16, v52
	v_lshrrev_b32_e32 v57, 16, v57
	v_and_or_b32 v52, v53, s10, v52
	v_and_or_b32 v53, v58, s10, v57
	global_store_dwordx2 v[48:49], v[52:53], off offset:3584
	v_mov_b32_e32 v48, v54

; #define LAS __attribute__((address_space(3)))
; #define TID() (wv0 * 64 + (int)__builtin_amdgcn_mbcnt_hi(~0u, __builtin_amdgcn_mbcnt_lo(~0u, 0u)))
; __device__ __forceinline__ int opaque(int x) { asm volatile("" : "+v"(x)); return x; }
;     __device__ __forceinline__ const float* in(int k) const { return (const float*)(const __attribute__((address_space(1))) float*)get(k); }
;     __device__ __forceinline__ unsigned char* ws() const { return (unsigned char*)(__attribute__((address_space(1))) unsigned char*)get(21); }
; __device__ __forceinline__ void gla_cumdecay(const Ptrs& A, int l, int n, int hd, LAS float* bl, const int wv0) {
;     const int tid = opaque(TID()), d = tid & 127, tq = __builtin_amdgcn_readfirstlane(tid >> 7);
;     const float* wa2 = A.in(4) + (size_t)l * 16 * 512 + hd * 128 + d;
;     float w[16];
; #pragma unroll
;     for (int r = 0; r < 16; ++r) w[r] = wa2[r * 512];
;     const float bias = A.in(5)[(size_t)l * 512 + hd * 128 + d];
;     LAS float* gal = bl + 29184;
;     *(LAS f32x2*)(gal + 2 * tid) = *(const f32x2*)((const float*)(A.ws() + WS_GA1) + (size_t)n * 64 * 16 + 2 * tid);
;     __syncthreads();
;     const LAS float* ga = gal + 16 * tq * 16;
;     float run = 0.f;
;     for (int tt = 0; tt < 16; ++tt) {
;         float pre = bias;
;         const f32x4 g0 = *(const LAS f32x4*)(ga + tt * 16), g1 = *(const LAS f32x4*)(ga + tt * 16 + 4), g2 = *(const LAS f32x4*)(ga + tt * 16 + 8), g3 = *(const LAS f32x4*)(ga + tt * 16 + 12);
;         pre += (g0.x * w[0] + g0.y * w[1]) + (g0.z * w[2] + g0.w * w[3]); pre += (g1.x * w[4] + g1.y * w[5]) + (g1.z * w[6] + g1.w * w[7]);
;         pre += (g2.x * w[8] + g2.y * w[9]) + (g2.z * w[10] + g2.w * w[11]); pre += (g3.x * w[12] + g3.y * w[13]) + (g3.z * w[14] + g3.w * w[15]);
;         const float la = (fminf(pre, 0.f) - __logf(1.0f + __expf(-fabsf(pre)))) * (1.0f / 16.0f);
;         run += la; bl[(16 * tq + tt) * BLS + d] = run;
;     }
.LBB0_1158:
	s_ashr_i32 s2, s6, 2
	s_lshl_b32 s22, s2, 6
	v_or_b32_e32 v0, s22, v64
	v_ashrrev_i32_e32 v1, 31, v0
	s_and_b32 s3, s6, 3
	v_lshlrev_b64 v[0:1], 10, v[0:1]
	v_lshl_add_u64 v[0:1], s[10:11], 0, v[0:1]
	s_lshl_b32 s14, s3, 8
	v_lshl_add_u64 v[0:1], v[0:1], 0, s[14:15]
	v_lshl_add_u64 v[0:1], s[12:13], 1, v[0:1]
	v_mov_b32_e32 v34, v204
	global_load_dwordx4 v[4:7], v[0:1], off
	s_nop 0
	global_load_dwordx4 v[0:3], v[0:1], off offset:128
	v_mov_b32 v8, s77
	ds_read_b64 v[8:9], v8 offset:32
	s_lshl_b32 s14, s3, 9
	v_readfirstlane_b32 s3, v34
	s_waitcnt lgkmcnt(0)
	v_readfirstlane_b32 s49, v8
	v_readfirstlane_b32 s23, v9
	s_add_u32 s50, s49, s14
	v_lshlrev_b32_e32 v8, 2, v34
	s_addc_u32 s51, s23, 0
	v_and_b32_e32 v48, 0x1fc, v8
	v_lshl_add_u64 v[8:9], s[50:51], 0, v[48:49]
	v_add_co_u32_e32 v12, vcc, s5, v8
	v_lshl_add_u64 v[10:11], v[8:9], 0, s[20:21]
	s_nop 0
	v_addc_co_u32_e32 v13, vcc, 0, v9, vcc
	v_add_co_u32_e32 v16, vcc, s7, v8
	s_ashr_i32 s23, s3, 7
	s_nop 0
	v_addc_co_u32_e32 v17, vcc, 0, v9, vcc
	v_add_co_u32_e32 v24, vcc, s30, v8
	s_nop 1
	v_addc_co_u32_e32 v25, vcc, 0, v9, vcc
	v_add_co_u32_e32 v26, vcc, s31, v8
	s_nop 1
	v_addc_co_u32_e32 v27, vcc, 0, v9, vcc
	v_add_co_u32_e32 v28, vcc, s34, v8
	s_nop 1
	v_addc_co_u32_e32 v29, vcc, 0, v9, vcc
	v_add_co_u32_e32 v30, vcc, s35, v8
	s_nop 1
	v_addc_co_u32_e32 v31, vcc, 0, v9, vcc
	v_add_co_u32_e32 v32, vcc, s36, v8
	s_nop 1
	v_addc_co_u32_e32 v33, vcc, 0, v9, vcc
	global_load_dword v20, v[12:13], off offset:-4096
	global_load_dword v23, v[10:11], off offset:2048
	global_load_dword v18, v[12:13], off
	global_load_dword v22, v[12:13], off offset:2048
	global_load_dword v15, v[24:25], off offset:-4096
	global_load_dword v19, v[16:17], off offset:2048
	s_nop 0
	global_load_dword v10, v[26:27], off offset:2048
	global_load_dword v8, v[30:31], off offset:2048
	global_load_dword v21, v[24:25], off
	s_nop 0
	global_load_dword v24, v[24:25], off offset:2048
	s_nop 0
	global_load_dword v16, v[28:29], off offset:-4096
	global_load_dword v14, v[28:29], off
	global_load_dword v17, v[28:29], off offset:2048
	global_load_dword v11, v[32:33], off offset:-4096
	global_load_dword v9, v[32:33], off
	global_load_dword v12, v[32:33], off offset:2048
	v_mov_b32 v13, s77
	ds_read_b64 v[26:27], v13 offset:40
	s_waitcnt lgkmcnt(0)
	v_readfirstlane_b32 s49, v26
	v_readfirstlane_b32 s3, v27
	s_add_u32 s50, s49, s14
	s_addc_u32 s51, s3, 0
	global_load_dword v25, v48, s[50:51] offset:2048
	v_mov_b32 v13, s77
	ds_read_b64 v[26:27], v13 offset:168
	s_ashr_i32 s3, s2, 31
	s_lshl_b64 s[2:3], s[2:3], 12
	v_lshl_add_u32 v13, v34, 3, s38
	s_waitcnt lgkmcnt(0)
	v_readfirstlane_b32 s50, v26
	v_readfirstlane_b32 s49, v27
	s_add_u32 s2, s50, s2
	v_lshlrev_b32_e32 v26, 1, v34
	s_addc_u32 s3, s49, s3
	v_ashrrev_i32_e32 v27, 31, v26
	v_lshl_add_u64 v[26:27], v[26:27], 2, s[2:3]
	v_add_co_u32_e32 v26, vcc, s37, v26
	s_lshl_b32 s2, s23, 10
	s_nop 0
	v_addc_co_u32_e32 v27, vcc, 0, v27, vcc
	global_load_dwordx2 v[28:29], v[26:27], off
	s_add_i32 s2, s38, s2
	v_mov_b32_e32 v27, s2
	s_mul_i32 s2, s23, 0x2100
	s_cmp_gt_i32 s23, 0
	s_waitcnt vmcnt(0)
	ds_write_b64 v13, v[28:29]
	s_waitcnt lgkmcnt(0)
	s_barrier
	ds_read_b128 v[28:31], v27
	ds_read_b128 v[32:35], v27 offset:16
	ds_read_b128 v[36:39], v27 offset:32
	ds_read_b128 v[40:43], v27 offset:48
	s_waitcnt lgkmcnt(3)
	v_mul_f32_e32 v13, v23, v29
	v_mul_f32_e32 v26, v22, v31
	s_waitcnt lgkmcnt(2)
	v_mul_f32_e32 v29, v19, v33
	v_mul_f32_e32 v31, v24, v35
	v_fmac_f32_e32 v13, v20, v28
	v_fmac_f32_e32 v26, v18, v30
	s_waitcnt lgkmcnt(1)
	v_mul_f32_e32 v33, v10, v37
	v_mul_f32_e32 v35, v17, v39
	v_fmac_f32_e32 v29, v15, v32
	v_fmac_f32_e32 v31, v21, v34
	v_add_f32_e32 v13, v13, v26
	s_waitcnt lgkmcnt(0)
	ds_read_b128 v[166:169], v27 offset:64
	ds_read_b128 v[170:173], v27 offset:80
	ds_read_b128 v[174:177], v27 offset:96
	ds_read_b128 v[178:181], v27 offset:112
	v_mul_f32_e32 v37, v8, v41
	v_mul_f32_e32 v39, v12, v43
	v_fmac_f32_e32 v33, v16, v36
	v_fmac_f32_e32 v35, v14, v38
	v_add_f32_e32 v26, v29, v31
	v_add_f32_e32 v13, v25, v13
	v_fmac_f32_e32 v37, v11, v40
	v_fmac_f32_e32 v39, v9, v42
	v_add_f32_e32 v28, v33, v35
	v_add_f32_e32 v13, v13, v26
	v_add_f32_e32 v29, v37, v39
	v_add_f32_e32 v13, v13, v28
	v_add_f32_e32 v28, v13, v29
	v_mul_f32_e64 v13, |v28|, s39
	v_exp_f32_e32 v13, v13
	v_min_f32_e32 v28, 0, v28
	v_add_u32_e32 v26, 0, v48
	v_add_f32_e32 v13, 1.0, v13
	v_cmp_gt_f32_e32 vcc, s40, v13
	s_nop 1
	v_cndmask_b32_e64 v29, 0, 32, vcc
	v_ldexp_f32 v13, v13, v29
	v_log_f32_e32 v29, v13
	v_cndmask_b32_e32 v30, 0, v69, vcc
	v_add_u32_e32 v13, s2, v26
	v_mul_f32_e32 v31, 0x3f317217, v29
	v_fma_f32 v31, v29, s41, -v31
	v_fmac_f32_e32 v31, 0x3377d1cf, v29
	v_fmac_f32_e32 v31, 0x3f317217, v29
	v_cmp_lt_f32_e64 vcc, |v29|, s44
	s_nop 1
	v_cndmask_b32_e32 v29, v29, v31, vcc
	v_sub_f32_e32 v29, v29, v30
	v_sub_f32_e32 v28, v28, v29
	v_fma_f32 v28, v28, s45, 0
	ds_write_b32 v13, v28
	s_waitcnt lgkmcnt(3)
	v_mul_f32_e32 v29, v23, v167
	v_mul_f32_e32 v31, v22, v169
	v_fmac_f32_e32 v29, v20, v166
	v_fmac_f32_e32 v31, v18, v168
	v_add_f32_e32 v29, v29, v31
	s_waitcnt lgkmcnt(2)
	v_mul_f32_e32 v30, v19, v171
	v_mul_f32_e32 v31, v24, v173
	v_fmac_f32_e32 v30, v15, v170
	v_fmac_f32_e32 v31, v21, v172
	v_add_f32_e32 v29, v25, v29
	v_add_f32_e32 v30, v30, v31
	v_add_f32_e32 v29, v29, v30
	s_waitcnt lgkmcnt(1)
	v_mul_f32_e32 v30, v10, v175
	v_mul_f32_e32 v31, v17, v177
	v_fmac_f32_e32 v30, v16, v174
	v_fmac_f32_e32 v31, v14, v176
	v_add_f32_e32 v30, v30, v31
	v_add_f32_e32 v29, v29, v30
	s_waitcnt lgkmcnt(0)
; #define LAS __attribute__((address_space(3)))
; __device__ __forceinline__ void gla_cumdecay(const Ptrs& A, int l, int n, int hd, LAS float* bl, const int wv0) {
;     ...
;     for (int tt = 0; tt < 16; ++tt) {
;         float pre = bias;
;         const f32x4 g0 = *(const LAS f32x4*)(ga + tt * 16), g1 = *(const LAS f32x4*)(ga + tt * 16 + 4), g2 = *(const LAS f32x4*)(ga + tt * 16 + 8), g3 = *(const LAS f32x4*)(ga + tt * 16 + 12);
;         pre += (g0.x * w[0] + g0.y * w[1]) + (g0.z * w[2] + g0.w * w[3]); pre += (g1.x * w[4] + g1.y * w[5]) + (g1.z * w[6] + g1.w * w[7]);
;         pre += (g2.x * w[8] + g2.y * w[9]) + (g2.z * w[10] + g2.w * w[11]); pre += (g3.x * w[12] + g3.y * w[13]) + (g3.z * w[14] + g3.w * w[15]);
;         const float la = (fminf(pre, 0.f) - __logf(1.0f + __expf(-fabsf(pre)))) * (1.0f / 16.0f);
;         run += la; bl[(16 * tq + tt) * BLS + d] = run;
;     }
	ds_read_b128 v[150:153], v27 offset:128
	ds_read_b128 v[154:157], v27 offset:144
	ds_read_b128 v[158:161], v27 offset:160
	ds_read_b128 v[162:165], v27 offset:176
	v_mul_f32_e32 v30, v8, v179
	v_mul_f32_e32 v31, v12, v181
	v_fmac_f32_e32 v30, v11, v178
	v_fmac_f32_e32 v31, v9, v180
	v_add_f32_e32 v30, v30, v31
	v_add_f32_e32 v29, v29, v30
	v_mul_f32_e64 v30, |v29|, s39
	v_exp_f32_e32 v30, v30
	v_min_f32_e32 v29, 0, v29
	v_add_f32_e32 v30, 1.0, v30
	v_cmp_gt_f32_e32 vcc, s40, v30
	s_nop 1
	v_cndmask_b32_e64 v31, 0, 32, vcc
	v_ldexp_f32 v30, v30, v31
	v_log_f32_e32 v30, v30
	s_nop 0
	v_mul_f32_e32 v31, 0x3f317217, v30
	v_fma_f32 v31, v30, s41, -v31
	v_fmac_f32_e32 v31, 0x3377d1cf, v30
	v_fmac_f32_e32 v31, 0x3f317217, v30
	v_cmp_lt_f32_e64 s[2:3], |v30|, s44
	s_nop 1
	v_cndmask_b32_e64 v30, v30, v31, s[2:3]
	v_cndmask_b32_e32 v31, 0, v69, vcc
	v_sub_f32_e32 v30, v30, v31
	v_sub_f32_e32 v29, v29, v30
	v_fmac_f32_e32 v28, 0x3d800000, v29
	ds_write_b32 v13, v28 offset:528
	s_waitcnt lgkmcnt(3)
	v_mul_f32_e32 v29, v23, v151
	v_fmac_f32_e32 v29, v20, v150
	v_mul_f32_e32 v30, v22, v153
	v_fmac_f32_e32 v30, v18, v152
	v_add_f32_e32 v29, v29, v30
	s_waitcnt lgkmcnt(2)
	v_mul_f32_e32 v30, v19, v155
	v_mul_f32_e32 v31, v24, v157
	v_fmac_f32_e32 v30, v15, v154
	v_fmac_f32_e32 v31, v21, v156
	v_add_f32_e32 v29, v25, v29
	v_add_f32_e32 v30, v30, v31
	v_add_f32_e32 v29, v29, v30
	s_waitcnt lgkmcnt(1)
	v_mul_f32_e32 v30, v10, v159
	v_mul_f32_e32 v31, v17, v161
	v_fmac_f32_e32 v30, v16, v158
	v_fmac_f32_e32 v31, v14, v160
	v_add_f32_e32 v30, v30, v31
	v_add_f32_e32 v29, v29, v30
	s_waitcnt lgkmcnt(0)
	ds_read_b128 v[166:169], v27 offset:192
	ds_read_b128 v[170:173], v27 offset:208
	ds_read_b128 v[174:177], v27 offset:224
	ds_read_b128 v[178:181], v27 offset:240
	v_mul_f32_e32 v30, v8, v163
	v_mul_f32_e32 v31, v12, v165
	v_fmac_f32_e32 v30, v11, v162
	v_fmac_f32_e32 v31, v9, v164
	v_add_f32_e32 v30, v30, v31
	v_add_f32_e32 v29, v29, v30
	v_mul_f32_e64 v30, |v29|, s39
	v_exp_f32_e32 v30, v30
	v_min_f32_e32 v29, 0, v29
	v_add_f32_e32 v30, 1.0, v30
	v_cmp_gt_f32_e32 vcc, s40, v30
	s_nop 1
	v_cndmask_b32_e64 v31, 0, 32, vcc
	v_ldexp_f32 v30, v30, v31
	v_log_f32_e32 v30, v30
	s_nop 0
	v_mul_f32_e32 v31, 0x3f317217, v30
	v_fma_f32 v31, v30, s41, -v31
	v_fmac_f32_e32 v31, 0x3377d1cf, v30
	v_fmac_f32_e32 v31, 0x3f317217, v30
	v_cmp_lt_f32_e64 s[2:3], |v30|, s44
	s_nop 1
	v_cndmask_b32_e64 v30, v30, v31, s[2:3]
	v_cndmask_b32_e32 v31, 0, v69, vcc
	v_sub_f32_e32 v30, v30, v31
	v_sub_f32_e32 v29, v29, v30
	v_fmac_f32_e32 v28, 0x3d800000, v29
	ds_write_b32 v13, v28 offset:1056
	s_waitcnt lgkmcnt(3)
	v_mul_f32_e32 v29, v23, v167
	v_fmac_f32_e32 v29, v20, v166
	v_mul_f32_e32 v30, v22, v169
	v_fmac_f32_e32 v30, v18, v168
	v_add_f32_e32 v29, v29, v30
	s_waitcnt lgkmcnt(2)
	v_mul_f32_e32 v30, v19, v171
	v_mul_f32_e32 v31, v24, v173
	v_fmac_f32_e32 v30, v15, v170
	v_fmac_f32_e32 v31, v21, v172
	v_add_f32_e32 v29, v25, v29
	v_add_f32_e32 v30, v30, v31
	v_add_f32_e32 v29, v29, v30
	s_waitcnt lgkmcnt(1)
	v_mul_f32_e32 v30, v10, v175
	v_mul_f32_e32 v31, v17, v177
	v_fmac_f32_e32 v30, v16, v174
	v_fmac_f32_e32 v31, v14, v176
	v_add_f32_e32 v30, v30, v31
	v_add_f32_e32 v29, v29, v30
	s_waitcnt lgkmcnt(0)
	ds_read_b128 v[150:153], v27 offset:256
	ds_read_b128 v[154:157], v27 offset:272
	ds_read_b128 v[158:161], v27 offset:288
	ds_read_b128 v[162:165], v27 offset:304
	v_mul_f32_e32 v30, v8, v179
	v_mul_f32_e32 v31, v12, v181
	v_fmac_f32_e32 v30, v11, v178
	v_fmac_f32_e32 v31, v9, v180
	v_add_f32_e32 v30, v30, v31
	v_add_f32_e32 v29, v29, v30
	v_mul_f32_e64 v30, |v29|, s39
	v_exp_f32_e32 v30, v30
	v_min_f32_e32 v29, 0, v29
	v_add_f32_e32 v30, 1.0, v30
	v_cmp_gt_f32_e32 vcc, s40, v30
	s_nop 1
	v_cndmask_b32_e64 v31, 0, 32, vcc
	v_ldexp_f32 v30, v30, v31
	v_log_f32_e32 v30, v30
	s_nop 0
	v_mul_f32_e32 v31, 0x3f317217, v30
	v_fma_f32 v31, v30, s41, -v31
	v_fmac_f32_e32 v31, 0x3377d1cf, v30
	v_fmac_f32_e32 v31, 0x3f317217, v30
	v_cmp_lt_f32_e64 s[2:3], |v30|, s44
	s_nop 1
	v_cndmask_b32_e64 v30, v30, v31, s[2:3]
	v_cndmask_b32_e32 v31, 0, v69, vcc
	v_sub_f32_e32 v30, v30, v31
	v_sub_f32_e32 v29, v29, v30
	v_fmac_f32_e32 v28, 0x3d800000, v29
	ds_write_b32 v13, v28 offset:1584
	s_waitcnt lgkmcnt(3)
	v_mul_f32_e32 v29, v23, v151
	v_fmac_f32_e32 v29, v20, v150
	v_mul_f32_e32 v30, v22, v153
	v_fmac_f32_e32 v30, v18, v152
	v_add_f32_e32 v29, v29, v30
	s_waitcnt lgkmcnt(2)
	v_mul_f32_e32 v30, v19, v155
	v_mul_f32_e32 v31, v24, v157
	v_fmac_f32_e32 v30, v15, v154
	v_fmac_f32_e32 v31, v21, v156
	v_add_f32_e32 v29, v25, v29
	v_add_f32_e32 v30, v30, v31
	v_add_f32_e32 v29, v29, v30
	s_waitcnt lgkmcnt(1)
	v_mul_f32_e32 v30, v10, v159
	v_mul_f32_e32 v31, v17, v161
	v_fmac_f32_e32 v30, v16, v158
	v_fmac_f32_e32 v31, v14, v160
	v_add_f32_e32 v30, v30, v31
	v_add_f32_e32 v29, v29, v30
	s_waitcnt lgkmcnt(0)
	ds_read_b128 v[166:169], v27 offset:320
	ds_read_b128 v[170:173], v27 offset:336
	ds_read_b128 v[174:177], v27 offset:352
	ds_read_b128 v[178:181], v27 offset:368
	v_mul_f32_e32 v30, v8, v163
	v_mul_f32_e32 v31, v12, v165
	v_fmac_f32_e32 v30, v11, v162
	v_fmac_f32_e32 v31, v9, v164
	v_add_f32_e32 v30, v30, v31
	v_add_f32_e32 v29, v29, v30
	v_mul_f32_e64 v30, |v29|, s39
	v_exp_f32_e32 v30, v30
	v_min_f32_e32 v29, 0, v29
	v_add_f32_e32 v30, 1.0, v30
	v_cmp_gt_f32_e32 vcc, s40, v30
	s_nop 1
	v_cndmask_b32_e64 v31, 0, 32, vcc
	v_ldexp_f32 v30, v30, v31
	v_log_f32_e32 v30, v30
	s_nop 0
	v_mul_f32_e32 v31, 0x3f317217, v30
	v_fma_f32 v31, v30, s41, -v31
	v_fmac_f32_e32 v31, 0x3377d1cf, v30
	v_fmac_f32_e32 v31, 0x3f317217, v30
	v_cmp_lt_f32_e64 s[2:3], |v30|, s44
	s_nop 1
	v_cndmask_b32_e64 v30, v30, v31, s[2:3]
	v_cndmask_b32_e32 v31, 0, v69, vcc
	v_sub_f32_e32 v30, v30, v31
	v_sub_f32_e32 v29, v29, v30
	v_fmac_f32_e32 v28, 0x3d800000, v29
	ds_write_b32 v13, v28 offset:2112
	s_waitcnt lgkmcnt(3)
; #define LAS __attribute__((address_space(3)))
; __device__ __forceinline__ void gla_cumdecay(const Ptrs& A, int l, int n, int hd, LAS float* bl, const int wv0) {
;     ...
;     for (int tt = 0; tt < 16; ++tt) {
;         float pre = bias;
;         const f32x4 g0 = *(const LAS f32x4*)(ga + tt * 16), g1 = *(const LAS f32x4*)(ga + tt * 16 + 4), g2 = *(const LAS f32x4*)(ga + tt * 16 + 8), g3 = *(const LAS f32x4*)(ga + tt * 16 + 12);
;         pre += (g0.x * w[0] + g0.y * w[1]) + (g0.z * w[2] + g0.w * w[3]); pre += (g1.x * w[4] + g1.y * w[5]) + (g1.z * w[6] + g1.w * w[7]);
;         pre += (g2.x * w[8] + g2.y * w[9]) + (g2.z * w[10] + g2.w * w[11]); pre += (g3.x * w[12] + g3.y * w[13]) + (g3.z * w[14] + g3.w * w[15]);
;         const float la = (fminf(pre, 0.f) - __logf(1.0f + __expf(-fabsf(pre)))) * (1.0f / 16.0f);
;         run += la; bl[(16 * tq + tt) * BLS + d] = run;
;     }
	v_mul_f32_e32 v29, v23, v167
	v_fmac_f32_e32 v29, v20, v166
	v_mul_f32_e32 v30, v22, v169
	v_fmac_f32_e32 v30, v18, v168
	v_add_f32_e32 v29, v29, v30
	s_waitcnt lgkmcnt(2)
	v_mul_f32_e32 v30, v19, v171
	v_mul_f32_e32 v31, v24, v173
	v_fmac_f32_e32 v30, v15, v170
	v_fmac_f32_e32 v31, v21, v172
	v_add_f32_e32 v29, v25, v29
	v_add_f32_e32 v30, v30, v31
	v_add_f32_e32 v29, v29, v30
	s_waitcnt lgkmcnt(1)
	v_mul_f32_e32 v30, v10, v175
	v_mul_f32_e32 v31, v17, v177
	v_fmac_f32_e32 v30, v16, v174
	v_fmac_f32_e32 v31, v14, v176
	v_add_f32_e32 v30, v30, v31
	v_add_f32_e32 v29, v29, v30
	s_waitcnt lgkmcnt(0)
	ds_read_b128 v[150:153], v27 offset:384
	ds_read_b128 v[154:157], v27 offset:400
	ds_read_b128 v[158:161], v27 offset:416
	ds_read_b128 v[162:165], v27 offset:432
	v_mul_f32_e32 v30, v8, v179
	v_mul_f32_e32 v31, v12, v181
	v_fmac_f32_e32 v30, v11, v178
	v_fmac_f32_e32 v31, v9, v180
	v_add_f32_e32 v30, v30, v31
	v_add_f32_e32 v29, v29, v30
	v_mul_f32_e64 v30, |v29|, s39
	v_exp_f32_e32 v30, v30
	v_min_f32_e32 v29, 0, v29
	v_add_f32_e32 v30, 1.0, v30
	v_cmp_gt_f32_e32 vcc, s40, v30
	s_nop 1
	v_cndmask_b32_e64 v31, 0, 32, vcc
	v_ldexp_f32 v30, v30, v31
	v_log_f32_e32 v30, v30
	s_nop 0
	v_mul_f32_e32 v31, 0x3f317217, v30
	v_fma_f32 v31, v30, s41, -v31
	v_fmac_f32_e32 v31, 0x3377d1cf, v30
	v_fmac_f32_e32 v31, 0x3f317217, v30
	v_cmp_lt_f32_e64 s[2:3], |v30|, s44
	s_nop 1
	v_cndmask_b32_e64 v30, v30, v31, s[2:3]
	v_cndmask_b32_e32 v31, 0, v69, vcc
	v_sub_f32_e32 v30, v30, v31
	v_sub_f32_e32 v29, v29, v30
	v_fmac_f32_e32 v28, 0x3d800000, v29
	ds_write_b32 v13, v28 offset:2640
	s_waitcnt lgkmcnt(3)
	v_mul_f32_e32 v29, v23, v151
	v_fmac_f32_e32 v29, v20, v150
	v_mul_f32_e32 v30, v22, v153
	v_fmac_f32_e32 v30, v18, v152
	v_add_f32_e32 v29, v29, v30
	s_waitcnt lgkmcnt(2)
	v_mul_f32_e32 v30, v19, v155
	v_mul_f32_e32 v31, v24, v157
	v_fmac_f32_e32 v30, v15, v154
	v_fmac_f32_e32 v31, v21, v156
	v_add_f32_e32 v29, v25, v29
	v_add_f32_e32 v30, v30, v31
	v_add_f32_e32 v29, v29, v30
	s_waitcnt lgkmcnt(1)
	v_mul_f32_e32 v30, v10, v159
	v_mul_f32_e32 v31, v17, v161
	v_fmac_f32_e32 v30, v16, v158
	v_fmac_f32_e32 v31, v14, v160
	v_add_f32_e32 v30, v30, v31
	v_add_f32_e32 v29, v29, v30
	s_waitcnt lgkmcnt(0)
	ds_read_b128 v[166:169], v27 offset:448
	ds_read_b128 v[170:173], v27 offset:464
	ds_read_b128 v[174:177], v27 offset:480
	ds_read_b128 v[178:181], v27 offset:496
	v_mul_f32_e32 v30, v8, v163
	v_mul_f32_e32 v31, v12, v165
	v_fmac_f32_e32 v30, v11, v162
	v_fmac_f32_e32 v31, v9, v164
	v_add_f32_e32 v30, v30, v31
	v_add_f32_e32 v29, v29, v30
	v_mul_f32_e64 v30, |v29|, s39
	v_exp_f32_e32 v30, v30
	v_min_f32_e32 v29, 0, v29
	v_add_f32_e32 v30, 1.0, v30
	v_cmp_gt_f32_e32 vcc, s40, v30
	s_nop 1
	v_cndmask_b32_e64 v31, 0, 32, vcc
	v_ldexp_f32 v30, v30, v31
	v_log_f32_e32 v30, v30
	s_nop 0
	v_mul_f32_e32 v31, 0x3f317217, v30
	v_fma_f32 v31, v30, s41, -v31
	v_fmac_f32_e32 v31, 0x3377d1cf, v30
	v_fmac_f32_e32 v31, 0x3f317217, v30
	v_cmp_lt_f32_e64 s[2:3], |v30|, s44
	s_nop 1
	v_cndmask_b32_e64 v30, v30, v31, s[2:3]
	v_cndmask_b32_e32 v31, 0, v69, vcc
	v_sub_f32_e32 v30, v30, v31
	v_sub_f32_e32 v29, v29, v30
	v_fmac_f32_e32 v28, 0x3d800000, v29
	ds_write_b32 v13, v28 offset:3168
	s_waitcnt lgkmcnt(3)
	v_mul_f32_e32 v29, v23, v167
	v_fmac_f32_e32 v29, v20, v166
	v_mul_f32_e32 v30, v22, v169
	v_fmac_f32_e32 v30, v18, v168
	v_add_f32_e32 v29, v29, v30
	s_waitcnt lgkmcnt(2)
	v_mul_f32_e32 v30, v19, v171
	v_mul_f32_e32 v31, v24, v173
	v_fmac_f32_e32 v30, v15, v170
	v_fmac_f32_e32 v31, v21, v172
	v_add_f32_e32 v29, v25, v29
	v_add_f32_e32 v30, v30, v31
	v_add_f32_e32 v29, v29, v30
	s_waitcnt lgkmcnt(1)
	v_mul_f32_e32 v30, v10, v175
	v_mul_f32_e32 v31, v17, v177
	v_fmac_f32_e32 v30, v16, v174
	v_fmac_f32_e32 v31, v14, v176
	v_add_f32_e32 v30, v30, v31
	v_add_f32_e32 v29, v29, v30
	s_waitcnt lgkmcnt(0)
	ds_read_b128 v[150:153], v27 offset:512
	ds_read_b128 v[154:157], v27 offset:528
	ds_read_b128 v[158:161], v27 offset:544
	ds_read_b128 v[162:165], v27 offset:560
	v_mul_f32_e32 v30, v8, v179
	v_mul_f32_e32 v31, v12, v181
	v_fmac_f32_e32 v30, v11, v178
	v_fmac_f32_e32 v31, v9, v180
	v_add_f32_e32 v30, v30, v31
	v_add_f32_e32 v29, v29, v30
	v_mul_f32_e64 v30, |v29|, s39
	v_exp_f32_e32 v30, v30
	v_min_f32_e32 v29, 0, v29
	v_add_f32_e32 v30, 1.0, v30
	v_cmp_gt_f32_e32 vcc, s40, v30
	s_nop 1
	v_cndmask_b32_e64 v31, 0, 32, vcc
	v_ldexp_f32 v30, v30, v31
	v_log_f32_e32 v30, v30
	s_nop 0
	v_mul_f32_e32 v31, 0x3f317217, v30
	v_fma_f32 v31, v30, s41, -v31
	v_fmac_f32_e32 v31, 0x3377d1cf, v30
	v_fmac_f32_e32 v31, 0x3f317217, v30
	v_cmp_lt_f32_e64 s[2:3], |v30|, s44
	s_nop 1
	v_cndmask_b32_e64 v30, v30, v31, s[2:3]
	v_cndmask_b32_e32 v31, 0, v69, vcc
	v_sub_f32_e32 v30, v30, v31
	v_sub_f32_e32 v29, v29, v30
	v_fmac_f32_e32 v28, 0x3d800000, v29
	ds_write_b32 v13, v28 offset:3696
	s_waitcnt lgkmcnt(3)
	v_mul_f32_e32 v29, v23, v151
	v_fmac_f32_e32 v29, v20, v150
	v_mul_f32_e32 v30, v22, v153
	v_fmac_f32_e32 v30, v18, v152
	v_add_f32_e32 v29, v29, v30
	s_waitcnt lgkmcnt(2)
	v_mul_f32_e32 v30, v19, v155
	v_mul_f32_e32 v31, v24, v157
	v_fmac_f32_e32 v30, v15, v154
	v_fmac_f32_e32 v31, v21, v156
	v_add_f32_e32 v29, v25, v29
	v_add_f32_e32 v30, v30, v31
	v_add_f32_e32 v29, v29, v30
	s_waitcnt lgkmcnt(1)
	v_mul_f32_e32 v30, v10, v159
	v_mul_f32_e32 v31, v17, v161
	v_fmac_f32_e32 v30, v16, v158
	v_fmac_f32_e32 v31, v14, v160
	v_add_f32_e32 v30, v30, v31
	v_add_f32_e32 v29, v29, v30
	s_waitcnt lgkmcnt(0)
; #define LAS __attribute__((address_space(3)))
; __device__ __forceinline__ void gla_cumdecay(const Ptrs& A, int l, int n, int hd, LAS float* bl, const int wv0) {
;     ...
;     for (int tt = 0; tt < 16; ++tt) {
;         float pre = bias;
;         const f32x4 g0 = *(const LAS f32x4*)(ga + tt * 16), g1 = *(const LAS f32x4*)(ga + tt * 16 + 4), g2 = *(const LAS f32x4*)(ga + tt * 16 + 8), g3 = *(const LAS f32x4*)(ga + tt * 16 + 12);
;         pre += (g0.x * w[0] + g0.y * w[1]) + (g0.z * w[2] + g0.w * w[3]); pre += (g1.x * w[4] + g1.y * w[5]) + (g1.z * w[6] + g1.w * w[7]);
;         pre += (g2.x * w[8] + g2.y * w[9]) + (g2.z * w[10] + g2.w * w[11]); pre += (g3.x * w[12] + g3.y * w[13]) + (g3.z * w[14] + g3.w * w[15]);
;         const float la = (fminf(pre, 0.f) - __logf(1.0f + __expf(-fabsf(pre)))) * (1.0f / 16.0f);
;         run += la; bl[(16 * tq + tt) * BLS + d] = run;
;     }
	ds_read_b128 v[166:169], v27 offset:576
	ds_read_b128 v[170:173], v27 offset:592
	ds_read_b128 v[174:177], v27 offset:608
	ds_read_b128 v[178:181], v27 offset:624
	v_mul_f32_e32 v30, v8, v163
	v_mul_f32_e32 v31, v12, v165
	v_fmac_f32_e32 v30, v11, v162
	v_fmac_f32_e32 v31, v9, v164
	v_add_f32_e32 v30, v30, v31
	v_add_f32_e32 v29, v29, v30
	v_mul_f32_e64 v30, |v29|, s39
	v_exp_f32_e32 v30, v30
	v_min_f32_e32 v29, 0, v29
	v_add_f32_e32 v30, 1.0, v30
	v_cmp_gt_f32_e32 vcc, s40, v30
	s_nop 1
	v_cndmask_b32_e64 v31, 0, 32, vcc
	v_ldexp_f32 v30, v30, v31
	v_log_f32_e32 v30, v30
	s_nop 0
	v_mul_f32_e32 v31, 0x3f317217, v30
	v_fma_f32 v31, v30, s41, -v31
	v_fmac_f32_e32 v31, 0x3377d1cf, v30
	v_fmac_f32_e32 v31, 0x3f317217, v30
	v_cmp_lt_f32_e64 s[2:3], |v30|, s44
	s_nop 1
	v_cndmask_b32_e64 v30, v30, v31, s[2:3]
	v_cndmask_b32_e32 v31, 0, v69, vcc
	v_sub_f32_e32 v30, v30, v31
	v_sub_f32_e32 v29, v29, v30
	v_fmac_f32_e32 v28, 0x3d800000, v29
	ds_write_b32 v13, v28 offset:4224
	s_waitcnt lgkmcnt(3)
	v_mul_f32_e32 v29, v23, v167
	v_fmac_f32_e32 v29, v20, v166
	v_mul_f32_e32 v30, v22, v169
	v_fmac_f32_e32 v30, v18, v168
	v_add_f32_e32 v29, v29, v30
	s_waitcnt lgkmcnt(2)
	v_mul_f32_e32 v30, v19, v171
	v_mul_f32_e32 v31, v24, v173
	v_fmac_f32_e32 v30, v15, v170
	v_fmac_f32_e32 v31, v21, v172
	v_add_f32_e32 v29, v25, v29
	v_add_f32_e32 v30, v30, v31
	v_add_f32_e32 v29, v29, v30
	s_waitcnt lgkmcnt(1)
	v_mul_f32_e32 v30, v10, v175
	v_mul_f32_e32 v31, v17, v177
	v_fmac_f32_e32 v30, v16, v174
	v_fmac_f32_e32 v31, v14, v176
	v_add_f32_e32 v30, v30, v31
	v_add_f32_e32 v29, v29, v30
	s_waitcnt lgkmcnt(0)
	ds_read_b128 v[150:153], v27 offset:640
	ds_read_b128 v[154:157], v27 offset:656
	ds_read_b128 v[158:161], v27 offset:672
	ds_read_b128 v[162:165], v27 offset:688
	v_mul_f32_e32 v30, v8, v179
	v_mul_f32_e32 v31, v12, v181
	v_fmac_f32_e32 v30, v11, v178
	v_fmac_f32_e32 v31, v9, v180
	v_add_f32_e32 v30, v30, v31
	v_add_f32_e32 v29, v29, v30
	v_mul_f32_e64 v30, |v29|, s39
	v_exp_f32_e32 v30, v30
	v_min_f32_e32 v29, 0, v29
	v_add_f32_e32 v30, 1.0, v30
	v_cmp_gt_f32_e32 vcc, s40, v30
	s_nop 1
	v_cndmask_b32_e64 v31, 0, 32, vcc
	v_ldexp_f32 v30, v30, v31
	v_log_f32_e32 v30, v30
	s_nop 0
	v_mul_f32_e32 v31, 0x3f317217, v30
	v_fma_f32 v31, v30, s41, -v31
	v_fmac_f32_e32 v31, 0x3377d1cf, v30
	v_fmac_f32_e32 v31, 0x3f317217, v30
	v_cmp_lt_f32_e64 s[2:3], |v30|, s44
	s_nop 1
	v_cndmask_b32_e64 v30, v30, v31, s[2:3]
	v_cndmask_b32_e32 v31, 0, v69, vcc
	v_sub_f32_e32 v30, v30, v31
	v_sub_f32_e32 v29, v29, v30
	v_fmac_f32_e32 v28, 0x3d800000, v29
	ds_write_b32 v13, v28 offset:4752
	s_waitcnt lgkmcnt(3)
	v_mul_f32_e32 v29, v23, v151
	v_fmac_f32_e32 v29, v20, v150
	v_mul_f32_e32 v30, v22, v153
	v_fmac_f32_e32 v30, v18, v152
	v_add_f32_e32 v29, v29, v30
	s_waitcnt lgkmcnt(2)
	v_mul_f32_e32 v30, v19, v155
	v_mul_f32_e32 v31, v24, v157
	v_fmac_f32_e32 v30, v15, v154
	v_fmac_f32_e32 v31, v21, v156
	v_add_f32_e32 v29, v25, v29
	v_add_f32_e32 v30, v30, v31
	v_add_f32_e32 v29, v29, v30
	s_waitcnt lgkmcnt(1)
	v_mul_f32_e32 v30, v10, v159
	v_mul_f32_e32 v31, v17, v161
	v_fmac_f32_e32 v30, v16, v158
	v_fmac_f32_e32 v31, v14, v160
	v_add_f32_e32 v30, v30, v31
	v_add_f32_e32 v29, v29, v30
	s_waitcnt lgkmcnt(0)
	ds_read_b128 v[166:169], v27 offset:704
	ds_read_b128 v[170:173], v27 offset:720
	ds_read_b128 v[174:177], v27 offset:736
	ds_read_b128 v[178:181], v27 offset:752
	v_mul_f32_e32 v30, v8, v163
	v_mul_f32_e32 v31, v12, v165
	v_fmac_f32_e32 v30, v11, v162
	v_fmac_f32_e32 v31, v9, v164
	v_add_f32_e32 v30, v30, v31
	v_add_f32_e32 v29, v29, v30
	v_mul_f32_e64 v30, |v29|, s39
	v_exp_f32_e32 v30, v30
	v_min_f32_e32 v29, 0, v29
	v_add_f32_e32 v30, 1.0, v30
	v_cmp_gt_f32_e32 vcc, s40, v30
	s_nop 1
	v_cndmask_b32_e64 v31, 0, 32, vcc
	v_ldexp_f32 v30, v30, v31
	v_log_f32_e32 v30, v30
	s_nop 0
	v_mul_f32_e32 v31, 0x3f317217, v30
	v_fma_f32 v31, v30, s41, -v31
	v_fmac_f32_e32 v31, 0x3377d1cf, v30
	v_fmac_f32_e32 v31, 0x3f317217, v30
	v_cmp_lt_f32_e64 s[2:3], |v30|, s44
	s_nop 1
	v_cndmask_b32_e64 v30, v30, v31, s[2:3]
	v_cndmask_b32_e32 v31, 0, v69, vcc
	v_sub_f32_e32 v30, v30, v31
	v_sub_f32_e32 v29, v29, v30
	v_fmac_f32_e32 v28, 0x3d800000, v29
	ds_write_b32 v13, v28 offset:5280
	s_waitcnt lgkmcnt(3)
	v_mul_f32_e32 v29, v23, v167
	v_fmac_f32_e32 v29, v20, v166
	v_mul_f32_e32 v30, v22, v169
	v_fmac_f32_e32 v30, v18, v168
	v_add_f32_e32 v29, v29, v30
	s_waitcnt lgkmcnt(2)
	v_mul_f32_e32 v30, v19, v171
	v_mul_f32_e32 v31, v24, v173
	v_fmac_f32_e32 v30, v15, v170
	v_fmac_f32_e32 v31, v21, v172
	v_add_f32_e32 v29, v25, v29
	v_add_f32_e32 v30, v30, v31
	v_add_f32_e32 v29, v29, v30
	s_waitcnt lgkmcnt(1)
	v_mul_f32_e32 v30, v10, v175
	v_mul_f32_e32 v31, v17, v177
	v_fmac_f32_e32 v30, v16, v174
	v_fmac_f32_e32 v31, v14, v176
	v_add_f32_e32 v30, v30, v31
	v_add_f32_e32 v29, v29, v30
	s_waitcnt lgkmcnt(0)
	ds_read_b128 v[150:153], v27 offset:768
	ds_read_b128 v[154:157], v27 offset:784
	ds_read_b128 v[158:161], v27 offset:800
	ds_read_b128 v[162:165], v27 offset:816
	v_mul_f32_e32 v30, v8, v179
	v_mul_f32_e32 v31, v12, v181
	v_fmac_f32_e32 v30, v11, v178
	v_fmac_f32_e32 v31, v9, v180
	v_add_f32_e32 v30, v30, v31
	v_add_f32_e32 v29, v29, v30
	v_mul_f32_e64 v30, |v29|, s39
	v_exp_f32_e32 v30, v30
	v_min_f32_e32 v29, 0, v29
	v_add_f32_e32 v30, 1.0, v30
	v_cmp_gt_f32_e32 vcc, s40, v30
	s_nop 1
	v_cndmask_b32_e64 v31, 0, 32, vcc
	v_ldexp_f32 v30, v30, v31
	v_log_f32_e32 v30, v30
	s_nop 0
	v_mul_f32_e32 v31, 0x3f317217, v30
	v_fma_f32 v31, v30, s41, -v31
	v_fmac_f32_e32 v31, 0x3377d1cf, v30
	v_fmac_f32_e32 v31, 0x3f317217, v30
	v_cmp_lt_f32_e64 s[2:3], |v30|, s44
	s_nop 1
	v_cndmask_b32_e64 v30, v30, v31, s[2:3]
	v_cndmask_b32_e32 v31, 0, v69, vcc
	v_sub_f32_e32 v30, v30, v31
	v_sub_f32_e32 v29, v29, v30
	v_fmac_f32_e32 v28, 0x3d800000, v29
	ds_write_b32 v13, v28 offset:5808
	s_waitcnt lgkmcnt(3)
; #define LAS __attribute__((address_space(3)))
; __device__ __forceinline__ void gla_cumdecay(const Ptrs& A, int l, int n, int hd, LAS float* bl, const int wv0) {
;     ...
;     for (int tt = 0; tt < 16; ++tt) {
;         float pre = bias;
;         const f32x4 g0 = *(const LAS f32x4*)(ga + tt * 16), g1 = *(const LAS f32x4*)(ga + tt * 16 + 4), g2 = *(const LAS f32x4*)(ga + tt * 16 + 8), g3 = *(const LAS f32x4*)(ga + tt * 16 + 12);
;         pre += (g0.x * w[0] + g0.y * w[1]) + (g0.z * w[2] + g0.w * w[3]); pre += (g1.x * w[4] + g1.y * w[5]) + (g1.z * w[6] + g1.w * w[7]);
;         pre += (g2.x * w[8] + g2.y * w[9]) + (g2.z * w[10] + g2.w * w[11]); pre += (g3.x * w[12] + g3.y * w[13]) + (g3.z * w[14] + g3.w * w[15]);
;         const float la = (fminf(pre, 0.f) - __logf(1.0f + __expf(-fabsf(pre)))) * (1.0f / 16.0f);
;         run += la; bl[(16 * tq + tt) * BLS + d] = run;
;     }
;     __syncthreads();
;     float add = 0.f;
; #pragma unroll
;     for (int q = 0; q < 3; ++q) if (q < tq) add += bl[(16 * q + 15) * BLS + d];
	v_mul_f32_e32 v29, v23, v151
	v_fmac_f32_e32 v29, v20, v150
	v_mul_f32_e32 v30, v22, v153
	v_fmac_f32_e32 v30, v18, v152
	v_add_f32_e32 v29, v29, v30
	s_waitcnt lgkmcnt(2)
	v_mul_f32_e32 v30, v19, v155
	v_mul_f32_e32 v31, v24, v157
	v_fmac_f32_e32 v30, v15, v154
	v_fmac_f32_e32 v31, v21, v156
	v_add_f32_e32 v29, v25, v29
	v_add_f32_e32 v30, v30, v31
	v_add_f32_e32 v29, v29, v30
	s_waitcnt lgkmcnt(1)
	v_mul_f32_e32 v30, v10, v159
	v_mul_f32_e32 v31, v17, v161
	v_fmac_f32_e32 v30, v16, v158
	v_fmac_f32_e32 v31, v14, v160
	v_add_f32_e32 v30, v30, v31
	v_add_f32_e32 v29, v29, v30
	s_waitcnt lgkmcnt(0)
	ds_read_b128 v[166:169], v27 offset:832
	ds_read_b128 v[170:173], v27 offset:848
	ds_read_b128 v[174:177], v27 offset:864
	ds_read_b128 v[178:181], v27 offset:880
	v_mul_f32_e32 v30, v8, v163
	v_mul_f32_e32 v31, v12, v165
	v_fmac_f32_e32 v30, v11, v162
	v_fmac_f32_e32 v31, v9, v164
	v_add_f32_e32 v30, v30, v31
	v_add_f32_e32 v29, v29, v30
	v_mul_f32_e64 v30, |v29|, s39
	v_exp_f32_e32 v30, v30
	v_min_f32_e32 v29, 0, v29
	v_add_f32_e32 v30, 1.0, v30
	v_cmp_gt_f32_e32 vcc, s40, v30
	s_nop 1
	v_cndmask_b32_e64 v31, 0, 32, vcc
	v_ldexp_f32 v30, v30, v31
	v_log_f32_e32 v30, v30
	s_nop 0
	v_mul_f32_e32 v31, 0x3f317217, v30
	v_fma_f32 v31, v30, s41, -v31
	v_fmac_f32_e32 v31, 0x3377d1cf, v30
	v_fmac_f32_e32 v31, 0x3f317217, v30
	v_cmp_lt_f32_e64 s[2:3], |v30|, s44
	s_nop 1
	v_cndmask_b32_e64 v30, v30, v31, s[2:3]
	v_cndmask_b32_e32 v31, 0, v69, vcc
	v_sub_f32_e32 v30, v30, v31
	v_sub_f32_e32 v29, v29, v30
	v_fmac_f32_e32 v28, 0x3d800000, v29
	ds_write_b32 v13, v28 offset:6336
	s_waitcnt lgkmcnt(3)
	v_mul_f32_e32 v29, v23, v167
	v_fmac_f32_e32 v29, v20, v166
	v_mul_f32_e32 v30, v22, v169
	v_fmac_f32_e32 v30, v18, v168
	v_add_f32_e32 v29, v29, v30
	s_waitcnt lgkmcnt(2)
	v_mul_f32_e32 v30, v19, v171
	v_mul_f32_e32 v31, v24, v173
	v_fmac_f32_e32 v30, v15, v170
	v_fmac_f32_e32 v31, v21, v172
	v_add_f32_e32 v29, v25, v29
	v_add_f32_e32 v30, v30, v31
	v_add_f32_e32 v29, v29, v30
	s_waitcnt lgkmcnt(1)
	v_mul_f32_e32 v30, v10, v175
	v_mul_f32_e32 v31, v17, v177
	v_fmac_f32_e32 v30, v16, v174
	v_fmac_f32_e32 v31, v14, v176
	v_add_f32_e32 v30, v30, v31
	v_add_f32_e32 v29, v29, v30
	s_waitcnt lgkmcnt(0)
	ds_read_b128 v[150:153], v27 offset:896
	ds_read_b128 v[154:157], v27 offset:912
	ds_read_b128 v[158:161], v27 offset:928
	ds_read_b128 v[162:165], v27 offset:944
	v_mul_f32_e32 v30, v8, v179
	v_mul_f32_e32 v31, v12, v181
	v_fmac_f32_e32 v30, v11, v178
	v_fmac_f32_e32 v31, v9, v180
	v_add_f32_e32 v30, v30, v31
	v_add_f32_e32 v29, v29, v30
	v_mul_f32_e64 v30, |v29|, s39
	v_exp_f32_e32 v30, v30
	v_min_f32_e32 v29, 0, v29
	v_add_f32_e32 v30, 1.0, v30
	v_cmp_gt_f32_e32 vcc, s40, v30
	s_nop 1
	v_cndmask_b32_e64 v31, 0, 32, vcc
	v_ldexp_f32 v30, v30, v31
	v_log_f32_e32 v30, v30
	s_nop 0
	v_mul_f32_e32 v31, 0x3f317217, v30
	v_fma_f32 v31, v30, s41, -v31
	v_fmac_f32_e32 v31, 0x3377d1cf, v30
	v_fmac_f32_e32 v31, 0x3f317217, v30
	v_cmp_lt_f32_e64 s[2:3], |v30|, s44
	s_nop 1
	v_cndmask_b32_e64 v30, v30, v31, s[2:3]
	v_cndmask_b32_e32 v31, 0, v69, vcc
	v_sub_f32_e32 v30, v30, v31
	v_sub_f32_e32 v29, v29, v30
	v_fmac_f32_e32 v28, 0x3d800000, v29
	ds_write_b32 v13, v28 offset:6864
	s_waitcnt lgkmcnt(3)
	v_mul_f32_e32 v29, v23, v151
	v_fmac_f32_e32 v29, v20, v150
	v_mul_f32_e32 v30, v22, v153
	v_fmac_f32_e32 v30, v18, v152
	v_add_f32_e32 v29, v29, v30
	s_waitcnt lgkmcnt(2)
	v_mul_f32_e32 v30, v19, v155
	v_mul_f32_e32 v31, v24, v157
	v_fmac_f32_e32 v30, v15, v154
	v_fmac_f32_e32 v31, v21, v156
	v_add_f32_e32 v29, v25, v29
	v_add_f32_e32 v30, v30, v31
	v_add_f32_e32 v29, v29, v30
	s_waitcnt lgkmcnt(1)
	v_mul_f32_e32 v30, v10, v159
	v_mul_f32_e32 v31, v17, v161
	v_fmac_f32_e32 v30, v16, v158
	v_fmac_f32_e32 v31, v14, v160
	v_add_f32_e32 v30, v30, v31
	v_add_f32_e32 v29, v29, v30
	s_waitcnt lgkmcnt(0)
	ds_read_b128 v[166:169], v27 offset:960
	ds_read_b128 v[170:173], v27 offset:976
	ds_read_b128 v[174:177], v27 offset:992
	ds_read_b128 v[178:181], v27 offset:1008
	v_mul_f32_e32 v30, v8, v163
	v_mul_f32_e32 v31, v12, v165
	v_fmac_f32_e32 v30, v11, v162
	v_fmac_f32_e32 v31, v9, v164
	v_add_f32_e32 v30, v30, v31
	v_add_f32_e32 v29, v29, v30
	v_mul_f32_e64 v30, |v29|, s39
	v_exp_f32_e32 v30, v30
	v_min_f32_e32 v29, 0, v29
	v_add_f32_e32 v30, 1.0, v30
	v_cmp_gt_f32_e32 vcc, s40, v30
	s_nop 1
	v_cndmask_b32_e64 v31, 0, 32, vcc
	v_ldexp_f32 v30, v30, v31
	v_log_f32_e32 v30, v30
	s_nop 0
	v_mul_f32_e32 v31, 0x3f317217, v30
	v_fma_f32 v31, v30, s41, -v31
	v_fmac_f32_e32 v31, 0x3377d1cf, v30
	v_fmac_f32_e32 v31, 0x3f317217, v30
	v_cmp_lt_f32_e64 s[2:3], |v30|, s44
	s_nop 1
	v_cndmask_b32_e64 v30, v30, v31, s[2:3]
	v_cndmask_b32_e32 v31, 0, v69, vcc
	v_sub_f32_e32 v30, v30, v31
	v_sub_f32_e32 v29, v29, v30
	v_fmac_f32_e32 v28, 0x3d800000, v29
	ds_write_b32 v13, v28 offset:7392
	s_waitcnt lgkmcnt(3)
	v_mul_f32_e32 v23, v23, v167
	v_fmac_f32_e32 v23, v20, v166
	v_mul_f32_e32 v20, v22, v169
	s_waitcnt lgkmcnt(2)
	v_mul_f32_e32 v19, v19, v171
	v_fmac_f32_e32 v20, v18, v168
	v_fmac_f32_e32 v19, v15, v170
	v_mul_f32_e32 v15, v24, v173
	s_waitcnt lgkmcnt(1)
	v_mul_f32_e32 v10, v10, v175
	v_add_f32_e32 v18, v23, v20
	v_fmac_f32_e32 v15, v21, v172
	v_fmac_f32_e32 v10, v16, v174
	v_mul_f32_e32 v16, v17, v177
	s_waitcnt lgkmcnt(0)
	v_mul_f32_e32 v8, v8, v179
	v_add_f32_e32 v18, v25, v18
	v_add_f32_e32 v15, v19, v15
	v_fmac_f32_e32 v16, v14, v176
	v_fmac_f32_e32 v8, v11, v178
	v_mul_f32_e32 v11, v12, v181
	v_add_f32_e32 v15, v18, v15
	v_add_f32_e32 v10, v10, v16
	v_fmac_f32_e32 v11, v9, v180
	v_add_f32_e32 v10, v15, v10
	v_add_f32_e32 v8, v8, v11
	v_add_f32_e32 v8, v10, v8
	v_mul_f32_e64 v9, |v8|, s39
	v_exp_f32_e32 v9, v9
	v_min_f32_e32 v8, 0, v8
	v_add_f32_e32 v9, 1.0, v9
	v_cmp_gt_f32_e32 vcc, s40, v9
	s_nop 1
	v_cndmask_b32_e64 v10, 0, 32, vcc
	v_ldexp_f32 v9, v9, v10
	v_log_f32_e32 v9, v9
	s_nop 0
	v_mul_f32_e32 v10, 0x3f317217, v9
	v_fma_f32 v10, v9, s41, -v10
	v_fmac_f32_e32 v10, 0x3377d1cf, v9
	v_fmac_f32_e32 v10, 0x3f317217, v9
	v_cmp_lt_f32_e64 s[2:3], |v9|, s44
	s_nop 1
	v_cndmask_b32_e64 v9, v9, v10, s[2:3]
	v_cndmask_b32_e32 v10, 0, v69, vcc
	v_sub_f32_e32 v9, v9, v10
	v_sub_f32_e32 v8, v8, v9
	s_cselect_b64 s[2:3], -1, 0
	v_fmac_f32_e32 v28, 0x3d800000, v8
	s_and_b64 vcc, exec, s[2:3]
	v_mov_b32_e32 v8, 0
	ds_write_b32 v13, v28 offset:7920
	s_waitcnt lgkmcnt(0)
	s_barrier
	s_cbranch_vccz .LBB0_1160
	ds_read_b32 v8, v26 offset:7920
	s_waitcnt lgkmcnt(0)
	v_add_f32_e32 v8, 0, v8

; __device__ __forceinline__ unsigned f2bf(float f) { unsigned u = __builtin_bit_cast(unsigned, f); return (u + 0x7fffu + ((u >> 16) & 1u)) >> 16; }
; __device__ __forceinline__ int crow(int r, int hi) { return (r & 3) + 8 * (r >> 2) + 4 * hi; }
; __device__ __forceinline__ float sigmoid_f(float x) { return __builtin_amdgcn_rcpf(1.0f + __builtin_amdgcn_exp2f(-x * LOG2E)); }
; __device__ __forceinline__ void gla_out(const Ptrs& A, int l, LAS unsigned char* lds, int c, int G, int wave, int lane_, const int wv0) {
;     ...
;         const float g0 = gout[64 * vq + r32], g1 = gout[64 * vq + 32 + r32];
; #pragma unroll
;         for (int r = 0; r < 16; ++r) { const int t = 32 * ti + crow(r, hi);
;             const float tot = (red[t] + red[64 + t]) + (red[128 + t] + red[192 + t]); const float rinv = 1.0f / sqrtf(tot * (1.0f / 256.0f) + EPS);
;             const size_t off = (size_t)(t0 + t) * 1024 + hd * 256 + 64 * vq + r32;
;             const float r0 = bf2f(GR[off]), r1 = bf2f(GR[off + 32]);
;             AG[off] = (bf16)f2bf(o0[r] * rinv * g0 * r0 * pg8::sigmoid_f(r0)); AG[off + 32] = (bf16)f2bf(o1[r] * rinv * g1 * r1 * pg8::sigmoid_f(r1)); }
.LBB0_1323:
	s_or_b64 exec, exec, s[36:37]
	v_or_b32_e32 v32, s68, v70
	v_ashrrev_i32_e32 v33, 31, v32
	v_lshl_add_u64 v[60:61], v[50:51], 0, s[56:57]
	v_lshlrev_b64 v[32:33], 10, v[32:33]
	v_lshl_add_u64 v[32:33], v[32:33], 0, v[60:61]
	v_lshlrev_b64 v[96:97], 1, v[32:33]
	v_lshl_add_u64 v[32:33], s[50:51], 0, v[96:97]
	v_or_b32_e32 v98, 64, v96
	v_mov_b32_e32 v99, v97
	s_waitcnt lgkmcnt(0)
	s_barrier
	v_or_b32_e32 v144, s68, v70
	v_lshl_add_u32 v144, v144, 10, v60
	v_lshlrev_b32_e32 v144, 1, v144
	global_load_ushort v108, v144, s[50:51]
	global_load_ushort v109, v144, s[50:51] offset:64
	v_or_b32_e32 v144, s68, v74
	v_lshl_add_u32 v144, v144, 10, v60
	v_lshlrev_b32_e32 v144, 1, v144
	global_load_ushort v114, v144, s[50:51]
	global_load_ushort v115, v144, s[50:51] offset:64
	v_or_b32_e32 v144, s68, v75
	v_lshl_add_u32 v144, v144, 10, v60
	v_lshlrev_b32_e32 v144, 1, v144
	global_load_ushort v116, v144, s[50:51]
	global_load_ushort v117, v144, s[50:51] offset:64
	v_or_b32_e32 v144, s68, v76
	v_lshl_add_u32 v144, v144, 10, v60
	v_lshlrev_b32_e32 v144, 1, v144
	global_load_ushort v118, v144, s[50:51]
	global_load_ushort v119, v144, s[50:51] offset:64
	v_or_b32_e32 v144, s68, v77
	v_lshl_add_u32 v144, v144, 10, v60
	v_lshlrev_b32_e32 v144, 1, v144
	global_load_ushort v120, v144, s[50:51]
	global_load_ushort v121, v144, s[50:51] offset:64
	v_or_b32_e32 v144, s68, v79
	v_lshl_add_u32 v144, v144, 10, v60
	v_lshlrev_b32_e32 v144, 1, v144
	global_load_ushort v122, v144, s[50:51]
	global_load_ushort v123, v144, s[50:51] offset:64
	v_or_b32_e32 v144, s68, v80
	v_lshl_add_u32 v144, v144, 10, v60
	v_lshlrev_b32_e32 v144, 1, v144
	global_load_ushort v124, v144, s[50:51]
	global_load_ushort v125, v144, s[50:51] offset:64
	v_or_b32_e32 v144, s68, v81
	v_lshl_add_u32 v144, v144, 10, v60
	v_lshlrev_b32_e32 v144, 1, v144
	global_load_ushort v126, v144, s[50:51]
	global_load_ushort v127, v144, s[50:51] offset:64
	v_or_b32_e32 v144, s68, v82
	v_lshl_add_u32 v144, v144, 10, v60
	v_lshlrev_b32_e32 v144, 1, v144
	global_load_ushort v128, v144, s[50:51]
	global_load_ushort v129, v144, s[50:51] offset:64
	v_or_b32_e32 v144, s68, v84
	v_lshl_add_u32 v144, v144, 10, v60
	v_lshlrev_b32_e32 v144, 1, v144
	global_load_ushort v130, v144, s[50:51]
	global_load_ushort v131, v144, s[50:51] offset:64
	v_or_b32_e32 v144, s68, v85
	v_lshl_add_u32 v144, v144, 10, v60
	v_lshlrev_b32_e32 v144, 1, v144
	global_load_ushort v132, v144, s[50:51]
	global_load_ushort v133, v144, s[50:51] offset:64
	v_or_b32_e32 v144, s68, v86
	v_lshl_add_u32 v144, v144, 10, v60
	v_lshlrev_b32_e32 v144, 1, v144
	global_load_ushort v134, v144, s[50:51]
	global_load_ushort v135, v144, s[50:51] offset:64
	v_or_b32_e32 v144, s68, v87
	v_lshl_add_u32 v144, v144, 10, v60
	v_lshlrev_b32_e32 v144, 1, v144
	global_load_ushort v136, v144, s[50:51]
	global_load_ushort v137, v144, s[50:51] offset:64
	v_or_b32_e32 v144, s68, v89
	v_lshl_add_u32 v144, v144, 10, v60
	v_lshlrev_b32_e32 v144, 1, v144
	global_load_ushort v138, v144, s[50:51]
	global_load_ushort v139, v144, s[50:51] offset:64
	v_or_b32_e32 v144, s68, v90
	v_lshl_add_u32 v144, v144, 10, v60
	v_lshlrev_b32_e32 v144, 1, v144
	global_load_ushort v140, v144, s[50:51]
	global_load_ushort v141, v144, s[50:51] offset:64
	v_or_b32_e32 v144, s68, v91
	v_lshl_add_u32 v144, v144, 10, v60
	v_lshlrev_b32_e32 v144, 1, v144
	global_load_ushort v142, v144, s[50:51]
	global_load_ushort v143, v144, s[50:51] offset:64
	global_load_dword v48, v[52:53], off offset:1024
	global_load_dword v59, v[54:55], off offset:1024
	v_lshl_add_u64 v[34:35], s[50:51], 0, v[98:99]
	ds_read_b128 v[32:35], v71
	ds_read_b128 v[36:39], v71 offset:256
	ds_read_b128 v[40:43], v71 offset:512
	ds_read_b128 v[44:47], v71 offset:768
	v_or_b32_e32 v100, s68, v74
	v_ashrrev_i32_e32 v101, 31, v100
	s_waitcnt lgkmcnt(2)
	v_add_f32_e32 v32, v32, v36
	v_lshlrev_b64 v[100:101], 10, v[100:101]
	s_waitcnt lgkmcnt(0)
	v_add_f32_e32 v36, v40, v44
	v_add_f32_e32 v32, v32, v36
	v_fmamk_f32 v32, v32, 0x3b800000, v93
	v_mul_f32_e32 v36, 0x4f800000, v32
	v_cmp_gt_f32_e32 vcc, s91, v32
	v_lshl_add_u64 v[100:101], v[100:101], 0, v[60:61]
	v_lshlrev_b64 v[100:101], 1, v[100:101]
	v_cndmask_b32_e32 v32, v32, v36, vcc
	v_sqrt_f32_e32 v36, v32
	v_lshl_add_u64 v[96:97], s[52:53], 0, v[96:97]
	v_lshl_add_u64 v[98:99], s[52:53], 0, v[98:99]
	v_lshl_add_u64 v[102:103], s[50:51], 0, v[100:101]
	v_add_u32_e32 v40, -1, v36
	v_add_u32_e32 v44, 1, v36
	v_fma_f32 v106, -v40, v36, v32
	v_fma_f32 v107, -v44, v36, v32
	v_cmp_ge_f32_e64 s[36:37], 0, v106
	v_or_b32_e32 v104, 64, v100
	v_mov_b32_e32 v105, v101
	v_cndmask_b32_e64 v36, v36, v40, s[36:37]
	v_cmp_lt_f32_e64 s[36:37], 0, v107
	v_lshl_add_u64 v[106:107], s[50:51], 0, v[104:105]
	v_add_f32_e32 v41, v41, v45
	v_cndmask_b32_e64 v36, v36, v44, s[36:37]
	v_mul_f32_e32 v40, 0x37800000, v36
	v_cndmask_b32_e32 v36, v36, v40, vcc
	v_cmp_class_f32_e32 vcc, v32, v94
	v_add_f32_e32 v34, v34, v38
	s_add_i32 s44, s44, s38
	v_cndmask_b32_e32 v32, v36, v32, vcc
	v_div_scale_f32 v36, s[36:37], v32, v32, 1.0
	v_rcp_f32_e32 v40, v36
	v_div_scale_f32 v44, vcc, 1.0, v32, 1.0
	s_cmpk_lt_i32 s44, 0x400
	v_fma_f32 v110, -v36, v40, 1.0
	v_fmac_f32_e32 v40, v110, v40
	v_mul_f32_e32 v110, v44, v40
	v_fma_f32 v111, -v36, v110, v44
	v_fmac_f32_e32 v110, v111, v40
	v_fma_f32 v36, -v36, v110, v44
	v_div_fmas_f32 v36, v36, v40, v110
	v_div_fixup_f32 v32, v36, v32, 1.0
	v_mul_f32_e32 v16, v16, v32
	v_mul_f32_e32 v0, v0, v32
	v_lshl_add_u64 v[56:57], v[56:57], 0, s[62:63]
	s_waitcnt vmcnt(0)
; __device__ __forceinline__ unsigned f2bf(float f) { unsigned u = __builtin_bit_cast(unsigned, f); return (u + 0x7fffu + ((u >> 16) & 1u)) >> 16; }
; __device__ __forceinline__ int crow(int r, int hi) { return (r & 3) + 8 * (r >> 2) + 4 * hi; }
; __device__ __forceinline__ float sigmoid_f(float x) { return __builtin_amdgcn_rcpf(1.0f + __builtin_amdgcn_exp2f(-x * LOG2E)); }
; __device__ __forceinline__ void gla_out(const Ptrs& A, int l, LAS unsigned char* lds, int c, int G, int wave, int lane_, const int wv0) {
;     ...
;         for (int r = 0; r < 16; ++r) { const int t = 32 * ti + crow(r, hi);
;             const float tot = (red[t] + red[64 + t]) + (red[128 + t] + red[192 + t]); const float rinv = 1.0f / sqrtf(tot * (1.0f / 256.0f) + EPS);
;             const size_t off = (size_t)(t0 + t) * 1024 + hd * 256 + 64 * vq + r32;
;             const float r0 = bf2f(GR[off]), r1 = bf2f(GR[off + 32]);
;             AG[off] = (bf16)f2bf(o0[r] * rinv * g0 * r0 * pg8::sigmoid_f(r0)); AG[off + 32] = (bf16)f2bf(o1[r] * rinv * g1 * r1 * pg8::sigmoid_f(r1)); }
	v_mul_f32_e32 v16, v48, v16
	v_mul_f32_e32 v0, v59, v0
	v_lshlrev_b32_e32 v32, 16, v108
	v_lshlrev_b32_e32 v36, 16, v109
	v_mul_f32_e32 v40, 0xbfb8aa3b, v32
	v_exp_f32_e32 v40, v40
	v_mul_f32_e32 v44, 0xbfb8aa3b, v36
	v_exp_f32_e32 v44, v44
	v_mul_f32_e32 v16, v16, v32
	v_add_f32_e32 v32, 1.0, v40
	v_rcp_f32_e32 v32, v32
	v_add_f32_e32 v40, 1.0, v44
	v_rcp_f32_e32 v40, v40
	v_mul_f32_e32 v0, v0, v36
	v_mul_f32_e32 v16, v32, v16
	v_bfe_u32 v32, v16, 16, 1
	v_mul_f32_e32 v0, v0, v40
	v_add3_u32 v16, v16, v32, s90
	v_bfe_u32 v32, v0, 16, 1
	v_add3_u32 v0, v0, v32, s90
	global_store_short_d16_hi v[96:97], v16, off
	global_store_short_d16_hi v[98:99], v0, off
	v_mov_b32_e32 v0, v114
	s_nop 0
	v_mov_b32_e32 v16, v115
	v_add_f32_e32 v40, v33, v37
	v_add_f32_e32 v40, v40, v41
	v_fmamk_f32 v40, v40, 0x3b800000, v93
	v_mul_f32_e32 v41, 0x4f800000, v40
	v_cmp_gt_f32_e32 vcc, s91, v40
	v_lshl_add_u64 v[32:33], s[52:53], 0, v[100:101]
	v_lshl_add_u64 v[44:45], s[52:53], 0, v[104:105]
	v_cndmask_b32_e32 v98, v40, v41, vcc
	v_sqrt_f32_e32 v99, v98
	v_or_b32_e32 v96, s68, v75
	v_ashrrev_i32_e32 v97, 31, v96
	v_lshlrev_b64 v[96:97], 10, v[96:97]
	v_add_u32_e32 v100, -1, v99
	v_add_u32_e32 v101, 1, v99
	v_fma_f32 v102, -v100, v99, v98
	v_fma_f32 v103, -v101, v99, v98
	v_cmp_ge_f32_e64 s[36:37], 0, v102
	v_lshl_add_u64 v[96:97], v[96:97], 0, v[60:61]
	v_lshlrev_b64 v[96:97], 1, v[96:97]
	v_cndmask_b32_e64 v99, v99, v100, s[36:37]
	v_cmp_lt_f32_e64 s[36:37], 0, v103
	v_or_b32_e32 v40, 64, v96
	v_mov_b32_e32 v41, v97
	v_cndmask_b32_e64 v99, v99, v101, s[36:37]
	v_mul_f32_e32 v100, 0x37800000, v99
	v_cndmask_b32_e32 v99, v99, v100, vcc
	v_cmp_class_f32_e32 vcc, v98, v94
	v_lshl_add_u64 v[36:37], s[50:51], 0, v[96:97]
	v_lshlrev_b32_e32 v0, 16, v0
	v_cndmask_b32_e32 v100, v99, v98, vcc
	v_div_scale_f32 v101, s[36:37], v100, v100, 1.0
	v_rcp_f32_e32 v102, v101
	v_div_scale_f32 v103, vcc, 1.0, v100, 1.0
	v_lshlrev_b32_e32 v16, 16, v16
	v_fma_f32 v104, -v101, v102, 1.0
	v_fmac_f32_e32 v102, v104, v102
	v_mul_f32_e32 v104, v103, v102
	v_fma_f32 v105, -v101, v104, v103
	v_fmac_f32_e32 v104, v105, v102
	v_fma_f32 v101, -v101, v104, v103
	v_div_fmas_f32 v101, v101, v102, v104
	v_div_fixup_f32 v100, v101, v100, 1.0
	v_mul_f32_e32 v17, v17, v100
	v_mul_f32_e32 v1, v1, v100
	v_mul_f32_e32 v100, 0xbfb8aa3b, v0
	v_mul_f32_e32 v101, 0xbfb8aa3b, v16
	v_exp_f32_e32 v100, v100
	v_exp_f32_e32 v101, v101
	v_mul_f32_e32 v17, v48, v17
	v_mul_f32_e32 v1, v59, v1
	v_add_f32_e32 v100, 1.0, v100
	v_add_f32_e32 v101, 1.0, v101
	v_rcp_f32_e32 v100, v100
	v_rcp_f32_e32 v101, v101
	v_mul_f32_e32 v0, v17, v0
	v_mul_f32_e32 v1, v1, v16
	v_mul_f32_e32 v0, v100, v0
	v_mul_f32_e32 v1, v1, v101
	v_bfe_u32 v16, v0, 16, 1
	v_bfe_u32 v17, v1, 16, 1
	v_add3_u32 v0, v0, v16, s90
	v_lshl_add_u64 v[98:99], s[50:51], 0, v[40:41]
	v_add3_u32 v1, v1, v17, s90
	global_store_short_d16_hi v[32:33], v0, off
	global_store_short_d16_hi v[44:45], v1, off
	v_mov_b32_e32 v100, v116
	s_nop 0
	v_mov_b32_e32 v98, v117
	v_add_f32_e32 v36, v42, v46
	v_add_f32_e32 v34, v34, v36
	v_fmamk_f32 v34, v34, 0x3b800000, v93
	v_mul_f32_e32 v36, 0x4f800000, v34
	v_cmp_gt_f32_e32 vcc, s91, v34
	v_lshl_add_u64 v[16:17], s[52:53], 0, v[96:97]
	v_or_b32_e32 v0, s68, v76
	v_cndmask_b32_e32 v34, v34, v36, vcc
	v_sqrt_f32_e32 v38, v34
	v_ashrrev_i32_e32 v1, 31, v0
	v_lshlrev_b64 v[0:1], 10, v[0:1]
	v_lshl_add_u64 v[0:1], v[0:1], 0, v[60:61]
	v_add_u32_e32 v42, -1, v38
	v_add_u32_e32 v44, 1, v38
	v_fma_f32 v45, -v42, v38, v34
	v_fma_f32 v46, -v44, v38, v34
	v_cmp_ge_f32_e64 s[36:37], 0, v45
	v_lshlrev_b64 v[0:1], 1, v[0:1]
	v_lshl_add_u64 v[32:33], s[50:51], 0, v[0:1]
	v_cndmask_b32_e64 v38, v38, v42, s[36:37]
	v_cmp_lt_f32_e64 s[36:37], 0, v46
	v_or_b32_e32 v36, 64, v0
	v_mov_b32_e32 v37, v1
	v_cndmask_b32_e64 v38, v38, v44, s[36:37]
	v_mul_f32_e32 v42, 0x37800000, v38
	v_cndmask_b32_e32 v38, v38, v42, vcc
	v_cmp_class_f32_e32 vcc, v34, v94
	v_lshl_add_u64 v[40:41], s[52:53], 0, v[40:41]
	v_lshl_add_u64 v[44:45], s[50:51], 0, v[36:37]
	v_cndmask_b32_e32 v34, v38, v34, vcc
	v_div_scale_f32 v38, s[36:37], v34, v34, 1.0
	v_rcp_f32_e32 v42, v38
	v_div_scale_f32 v46, vcc, 1.0, v34, 1.0
	v_lshl_add_u64 v[0:1], s[52:53], 0, v[0:1]
	v_fma_f32 v96, -v38, v42, 1.0
	v_fmac_f32_e32 v42, v96, v42
	v_mul_f32_e32 v96, v46, v42
	v_fma_f32 v97, -v38, v96, v46
	v_fmac_f32_e32 v96, v97, v42
	v_fma_f32 v38, -v38, v96, v46
	v_div_fmas_f32 v38, v38, v42, v96
	v_div_fixup_f32 v34, v38, v34, 1.0
	v_mul_f32_e32 v18, v18, v34
	v_mul_f32_e32 v2, v2, v34
	v_mul_f32_e32 v18, v48, v18
	v_mul_f32_e32 v2, v59, v2
	v_lshlrev_b32_e32 v34, 16, v100
	v_lshlrev_b32_e32 v38, 16, v98
	v_mul_f32_e32 v42, 0xbfb8aa3b, v34
	v_mul_f32_e32 v46, 0xbfb8aa3b, v38
	v_exp_f32_e32 v42, v42
	v_exp_f32_e32 v46, v46
	v_mul_f32_e32 v18, v18, v34
	v_mul_f32_e32 v2, v2, v38
	v_add_f32_e32 v42, 1.0, v42
	v_add_f32_e32 v46, 1.0, v46
	v_rcp_f32_e32 v42, v42
	v_rcp_f32_e32 v46, v46
	v_mul_f32_e32 v18, v42, v18
	v_mul_f32_e32 v2, v2, v46
	v_bfe_u32 v34, v18, 16, 1
	v_bfe_u32 v38, v2, 16, 1
	v_add3_u32 v18, v18, v34, s90
	v_add3_u32 v2, v2, v38, s90
	global_store_short_d16_hi v[16:17], v18, off
	global_store_short_d16_hi v[40:41], v2, off
	v_mov_b32_e32 v2, v118
	s_nop 0
	v_mov_b32_e32 v18, v119
	v_add_f32_e32 v32, v35, v39
	v_add_f32_e32 v33, v43, v47
	v_add_f32_e32 v32, v32, v33
	v_fmamk_f32 v32, v32, 0x3b800000, v93
	v_mul_f32_e32 v33, 0x4f800000, v32
	v_cmp_gt_f32_e32 vcc, s91, v32
	v_or_b32_e32 v16, s68, v77
	v_ashrrev_i32_e32 v17, 31, v16
	v_cndmask_b32_e32 v34, v32, v33, vcc
	v_sqrt_f32_e32 v35, v34
	v_lshl_add_u64 v[32:33], s[52:53], 0, v[36:37]
	v_lshlrev_b64 v[16:17], 10, v[16:17]
; __device__ __forceinline__ unsigned f2bf(float f) { unsigned u = __builtin_bit_cast(unsigned, f); return (u + 0x7fffu + ((u >> 16) & 1u)) >> 16; }
; __device__ __forceinline__ int crow(int r, int hi) { return (r & 3) + 8 * (r >> 2) + 4 * hi; }
; __device__ __forceinline__ float sigmoid_f(float x) { return __builtin_amdgcn_rcpf(1.0f + __builtin_amdgcn_exp2f(-x * LOG2E)); }
; __device__ __forceinline__ void gla_out(const Ptrs& A, int l, LAS unsigned char* lds, int c, int G, int wave, int lane_, const int wv0) {
;     ...
;         for (int r = 0; r < 16; ++r) { const int t = 32 * ti + crow(r, hi);
;             const float tot = (red[t] + red[64 + t]) + (red[128 + t] + red[192 + t]); const float rinv = 1.0f / sqrtf(tot * (1.0f / 256.0f) + EPS);
;             const size_t off = (size_t)(t0 + t) * 1024 + hd * 256 + 64 * vq + r32;
;             const float r0 = bf2f(GR[off]), r1 = bf2f(GR[off + 32]);
;             AG[off] = (bf16)f2bf(o0[r] * rinv * g0 * r0 * pg8::sigmoid_f(r0)); AG[off + 32] = (bf16)f2bf(o1[r] * rinv * g1 * r1 * pg8::sigmoid_f(r1)); }
	v_lshl_add_u64 v[16:17], v[16:17], 0, v[60:61]
	v_add_u32_e32 v36, -1, v35
	v_add_u32_e32 v37, 1, v35
	v_fma_f32 v38, -v36, v35, v34
	v_fma_f32 v39, -v37, v35, v34
	v_cmp_ge_f32_e64 s[36:37], 0, v38
	v_lshlrev_b64 v[40:41], 1, v[16:17]
	v_lshl_add_u64 v[16:17], s[50:51], 0, v[40:41]
	v_cndmask_b32_e64 v35, v35, v36, s[36:37]
	v_cmp_lt_f32_e64 s[36:37], 0, v39
	v_or_b32_e32 v42, 64, v40
	v_mov_b32_e32 v43, v41
	v_cndmask_b32_e64 v35, v35, v37, s[36:37]
	v_mul_f32_e32 v36, 0x37800000, v35
	v_cndmask_b32_e32 v35, v35, v36, vcc
	v_cmp_class_f32_e32 vcc, v34, v94
	v_lshl_add_u64 v[40:41], s[52:53], 0, v[40:41]
	v_lshlrev_b32_e32 v2, 16, v2
	v_cndmask_b32_e32 v36, v35, v34, vcc
	v_div_scale_f32 v37, s[36:37], v36, v36, 1.0
	v_rcp_f32_e32 v38, v37
	v_div_scale_f32 v39, vcc, 1.0, v36, 1.0
	v_lshlrev_b32_e32 v18, 16, v18
	v_fma_f32 v44, -v37, v38, 1.0
	v_fmac_f32_e32 v38, v44, v38
	v_mul_f32_e32 v44, v39, v38
	v_fma_f32 v45, -v37, v44, v39
	v_fmac_f32_e32 v44, v45, v38
	v_fma_f32 v37, -v37, v44, v39
	v_div_fmas_f32 v37, v37, v38, v44
	v_div_fixup_f32 v36, v37, v36, 1.0
	v_mul_f32_e32 v19, v19, v36
	v_mul_f32_e32 v3, v3, v36
	v_mul_f32_e32 v36, 0xbfb8aa3b, v2
	v_mul_f32_e32 v37, 0xbfb8aa3b, v18
	v_exp_f32_e32 v36, v36
	v_exp_f32_e32 v37, v37
	v_mul_f32_e32 v19, v48, v19
	v_mul_f32_e32 v3, v59, v3
	v_add_f32_e32 v36, 1.0, v36
	v_add_f32_e32 v37, 1.0, v37
	v_rcp_f32_e32 v36, v36
	v_rcp_f32_e32 v37, v37
	v_mul_f32_e32 v2, v19, v2
	v_mul_f32_e32 v3, v3, v18
	v_mul_f32_e32 v2, v36, v2
	v_mul_f32_e32 v3, v3, v37
	v_bfe_u32 v18, v2, 16, 1
	v_bfe_u32 v19, v3, 16, 1
	v_add3_u32 v2, v2, v18, s90
	v_add3_u32 v3, v3, v19, s90
	global_store_short_d16_hi v[0:1], v2, off
	global_store_short_d16_hi v[32:33], v3, off
	v_lshl_add_u64 v[34:35], s[50:51], 0, v[42:43]
	v_mov_b32_e32 v100, v120
	v_mov_b32_e32 v101, v121
	ds_read_b128 v[0:3], v78
	ds_read_b128 v[16:19], v78 offset:256
	ds_read_b128 v[32:35], v78 offset:512
	ds_read_b128 v[36:39], v78 offset:768
	v_or_b32_e32 v44, s68, v79
	v_ashrrev_i32_e32 v45, 31, v44
	s_waitcnt lgkmcnt(2)
	v_add_f32_e32 v0, v0, v16
	v_lshlrev_b64 v[44:45], 10, v[44:45]
	s_waitcnt lgkmcnt(0)
	v_add_f32_e32 v16, v32, v36
	v_add_f32_e32 v0, v0, v16
	v_fmamk_f32 v0, v0, 0x3b800000, v93
	v_mul_f32_e32 v16, 0x4f800000, v0
	v_cmp_gt_f32_e32 vcc, s91, v0
	v_lshl_add_u64 v[44:45], v[44:45], 0, v[60:61]
	v_lshlrev_b64 v[44:45], 1, v[44:45]
	v_cndmask_b32_e32 v0, v0, v16, vcc
	v_sqrt_f32_e32 v16, v0
	v_lshl_add_u64 v[46:47], s[50:51], 0, v[44:45]
	v_or_b32_e32 v96, 64, v44
	v_mov_b32_e32 v97, v45
	v_add_u32_e32 v32, -1, v16
	v_add_u32_e32 v36, 1, v16
	v_fma_f32 v98, -v32, v16, v0
	v_fma_f32 v99, -v36, v16, v0
	v_cmp_ge_f32_e64 s[36:37], 0, v98
	v_lshl_add_u64 v[42:43], s[52:53], 0, v[42:43]
	v_add_f32_e32 v33, v33, v37
	v_cndmask_b32_e64 v16, v16, v32, s[36:37]
	v_cmp_lt_f32_e64 s[36:37], 0, v99
	v_lshl_add_u64 v[98:99], s[50:51], 0, v[96:97]
	v_add_f32_e32 v2, v2, v18
	v_cndmask_b32_e64 v16, v16, v36, s[36:37]
	v_mul_f32_e32 v32, 0x37800000, v16
	v_cndmask_b32_e32 v16, v16, v32, vcc
	v_cmp_class_f32_e32 vcc, v0, v94
	v_add_f32_e32 v18, v34, v38
	v_add_f32_e32 v2, v2, v18
	v_cndmask_b32_e32 v0, v16, v0, vcc
	v_div_scale_f32 v16, s[36:37], v0, v0, 1.0
	v_rcp_f32_e32 v32, v16
	v_div_scale_f32 v36, vcc, 1.0, v0, 1.0
	v_fmamk_f32 v2, v2, 0x3b800000, v93
	v_fma_f32 v102, -v16, v32, 1.0
	v_fmac_f32_e32 v32, v102, v32
	v_mul_f32_e32 v102, v36, v32
	v_fma_f32 v103, -v16, v102, v36
	v_fmac_f32_e32 v102, v103, v32
	v_fma_f32 v16, -v16, v102, v36
	v_div_fmas_f32 v16, v16, v32, v102
	v_div_fixup_f32 v0, v16, v0, 1.0
	v_mul_f32_e32 v16, v20, v0
	v_mul_f32_e32 v0, v4, v0
	v_mul_f32_e32 v16, v48, v16
	v_mul_f32_e32 v0, v59, v0
	v_mul_f32_e32 v18, 0x4f800000, v2
	v_lshlrev_b32_e32 v4, 16, v100
	v_lshlrev_b32_e32 v20, 16, v101
	v_mul_f32_e32 v32, 0xbfb8aa3b, v4
	v_mul_f32_e32 v36, 0xbfb8aa3b, v20
	v_exp_f32_e32 v32, v32
	v_exp_f32_e32 v36, v36
	v_mul_f32_e32 v4, v16, v4
	v_mul_f32_e32 v0, v0, v20
	v_add_f32_e32 v32, 1.0, v32
	v_add_f32_e32 v36, 1.0, v36
	v_rcp_f32_e32 v32, v32
	v_rcp_f32_e32 v36, v36
	v_mul_f32_e32 v4, v32, v4
	v_mul_f32_e32 v0, v0, v36
	v_bfe_u32 v16, v4, 16, 1
	v_bfe_u32 v20, v0, 16, 1
	v_add3_u32 v4, v4, v16, s90
	v_add3_u32 v0, v0, v20, s90
	global_store_short_d16_hi v[40:41], v4, off
	global_store_short_d16_hi v[42:43], v0, off
	v_mov_b32_e32 v4, v122
	s_nop 0
	v_mov_b32_e32 v20, v123
	v_add_f32_e32 v32, v1, v17
	v_add_f32_e32 v32, v32, v33
	v_fmamk_f32 v32, v32, 0x3b800000, v93
	v_mul_f32_e32 v33, 0x4f800000, v32
	v_cmp_gt_f32_e32 vcc, s91, v32
	v_lshl_add_u64 v[0:1], s[52:53], 0, v[44:45]
	v_lshl_add_u64 v[36:37], s[52:53], 0, v[96:97]
	v_cndmask_b32_e32 v42, v32, v33, vcc
	v_sqrt_f32_e32 v43, v42
	v_or_b32_e32 v40, s68, v80
	v_ashrrev_i32_e32 v41, 31, v40
	v_lshlrev_b64 v[40:41], 10, v[40:41]
	v_add_u32_e32 v44, -1, v43
	v_add_u32_e32 v45, 1, v43
	v_fma_f32 v46, -v44, v43, v42
	v_fma_f32 v47, -v45, v43, v42
	v_cmp_ge_f32_e64 s[36:37], 0, v46
	v_lshl_add_u64 v[40:41], v[40:41], 0, v[60:61]
	v_lshlrev_b64 v[40:41], 1, v[40:41]
	v_cndmask_b32_e64 v43, v43, v44, s[36:37]
	v_cmp_lt_f32_e64 s[36:37], 0, v47
	v_or_b32_e32 v32, 64, v40
	v_mov_b32_e32 v33, v41
	v_cndmask_b32_e64 v43, v43, v45, s[36:37]
	v_mul_f32_e32 v44, 0x37800000, v43
	v_cndmask_b32_e32 v43, v43, v44, vcc
	v_cmp_class_f32_e32 vcc, v42, v94
	v_lshl_add_u64 v[16:17], s[50:51], 0, v[40:41]
	v_lshlrev_b32_e32 v4, 16, v4
	v_cndmask_b32_e32 v44, v43, v42, vcc
	v_div_scale_f32 v45, s[36:37], v44, v44, 1.0
	v_rcp_f32_e32 v46, v45
	v_div_scale_f32 v47, vcc, 1.0, v44, 1.0
	v_lshlrev_b32_e32 v20, 16, v20
	v_fma_f32 v96, -v45, v46, 1.0
	v_fmac_f32_e32 v46, v96, v46
	v_mul_f32_e32 v96, v47, v46
; __device__ __forceinline__ unsigned f2bf(float f) { unsigned u = __builtin_bit_cast(unsigned, f); return (u + 0x7fffu + ((u >> 16) & 1u)) >> 16; }
; __device__ __forceinline__ int crow(int r, int hi) { return (r & 3) + 8 * (r >> 2) + 4 * hi; }
; __device__ __forceinline__ float sigmoid_f(float x) { return __builtin_amdgcn_rcpf(1.0f + __builtin_amdgcn_exp2f(-x * LOG2E)); }
; __device__ __forceinline__ void gla_out(const Ptrs& A, int l, LAS unsigned char* lds, int c, int G, int wave, int lane_, const int wv0) {
;     ...
;         for (int r = 0; r < 16; ++r) { const int t = 32 * ti + crow(r, hi);
;             const float tot = (red[t] + red[64 + t]) + (red[128 + t] + red[192 + t]); const float rinv = 1.0f / sqrtf(tot * (1.0f / 256.0f) + EPS);
;             const size_t off = (size_t)(t0 + t) * 1024 + hd * 256 + 64 * vq + r32;
;             const float r0 = bf2f(GR[off]), r1 = bf2f(GR[off + 32]);
;             AG[off] = (bf16)f2bf(o0[r] * rinv * g0 * r0 * pg8::sigmoid_f(r0)); AG[off + 32] = (bf16)f2bf(o1[r] * rinv * g1 * r1 * pg8::sigmoid_f(r1)); }
	v_fma_f32 v97, -v45, v96, v47
	v_fmac_f32_e32 v96, v97, v46
	v_fma_f32 v45, -v45, v96, v47
	v_div_fmas_f32 v45, v45, v46, v96
	v_div_fixup_f32 v44, v45, v44, 1.0
	v_mul_f32_e32 v21, v21, v44
	v_mul_f32_e32 v5, v5, v44
	v_mul_f32_e32 v44, 0xbfb8aa3b, v4
	v_mul_f32_e32 v45, 0xbfb8aa3b, v20
	v_exp_f32_e32 v44, v44
	v_exp_f32_e32 v45, v45
	v_mul_f32_e32 v21, v48, v21
	v_mul_f32_e32 v5, v59, v5
	v_add_f32_e32 v44, 1.0, v44
	v_add_f32_e32 v45, 1.0, v45
	v_rcp_f32_e32 v44, v44
	v_rcp_f32_e32 v45, v45
	v_mul_f32_e32 v4, v21, v4
	v_mul_f32_e32 v5, v5, v20
	v_mul_f32_e32 v4, v44, v4
	v_mul_f32_e32 v5, v5, v45
	v_bfe_u32 v20, v4, 16, 1
	v_bfe_u32 v21, v5, 16, 1
	v_add3_u32 v4, v4, v20, s90
	v_lshl_add_u64 v[42:43], s[50:51], 0, v[32:33]
	v_add3_u32 v5, v5, v21, s90
	global_store_short_d16_hi v[0:1], v4, off
	global_store_short_d16_hi v[36:37], v5, off
	v_mov_b32_e32 v44, v124
	s_nop 0
	v_mov_b32_e32 v42, v125
	v_cmp_gt_f32_e32 vcc, s91, v2
	v_lshl_add_u64 v[4:5], s[52:53], 0, v[40:41]
	v_or_b32_e32 v0, s68, v81
	v_cndmask_b32_e32 v2, v2, v18, vcc
	v_sqrt_f32_e32 v18, v2
	v_ashrrev_i32_e32 v1, 31, v0
	v_lshlrev_b64 v[0:1], 10, v[0:1]
	v_lshl_add_u64 v[0:1], v[0:1], 0, v[60:61]
	v_add_u32_e32 v34, -1, v18
	v_add_u32_e32 v36, 1, v18
	v_fma_f32 v37, -v34, v18, v2
	v_fma_f32 v38, -v36, v18, v2
	v_cmp_ge_f32_e64 s[36:37], 0, v37
	v_lshlrev_b64 v[0:1], 1, v[0:1]
	v_lshl_add_u64 v[16:17], s[50:51], 0, v[0:1]
	v_cndmask_b32_e64 v18, v18, v34, s[36:37]
	v_cmp_lt_f32_e64 s[36:37], 0, v38
	v_or_b32_e32 v20, 64, v0
	v_mov_b32_e32 v21, v1
	v_cndmask_b32_e64 v18, v18, v36, s[36:37]
	v_mul_f32_e32 v34, 0x37800000, v18
	v_cndmask_b32_e32 v18, v18, v34, vcc
	v_cmp_class_f32_e32 vcc, v2, v94
	v_lshl_add_u64 v[32:33], s[52:53], 0, v[32:33]
	v_lshl_add_u64 v[36:37], s[50:51], 0, v[20:21]
	v_cndmask_b32_e32 v2, v18, v2, vcc
	v_div_scale_f32 v18, s[36:37], v2, v2, 1.0
	v_rcp_f32_e32 v34, v18
	v_div_scale_f32 v38, vcc, 1.0, v2, 1.0
	v_lshl_add_u64 v[0:1], s[52:53], 0, v[0:1]
	v_fma_f32 v40, -v18, v34, 1.0
	v_fmac_f32_e32 v34, v40, v34
	v_mul_f32_e32 v40, v38, v34
	v_fma_f32 v41, -v18, v40, v38
	v_fmac_f32_e32 v40, v41, v34
	v_fma_f32 v18, -v18, v40, v38
	v_div_fmas_f32 v18, v18, v34, v40
	v_div_fixup_f32 v2, v18, v2, 1.0
	v_mul_f32_e32 v18, v22, v2
	v_mul_f32_e32 v2, v6, v2
	v_mul_f32_e32 v18, v48, v18
	v_mul_f32_e32 v2, v59, v2
	v_lshlrev_b32_e32 v6, 16, v44
	v_lshlrev_b32_e32 v22, 16, v42
	v_mul_f32_e32 v34, 0xbfb8aa3b, v6
	v_mul_f32_e32 v38, 0xbfb8aa3b, v22
	v_exp_f32_e32 v34, v34
	v_exp_f32_e32 v38, v38
	v_mul_f32_e32 v6, v18, v6
	v_mul_f32_e32 v2, v2, v22
	v_add_f32_e32 v34, 1.0, v34
	v_add_f32_e32 v38, 1.0, v38
	v_rcp_f32_e32 v34, v34
	v_rcp_f32_e32 v38, v38
	v_mul_f32_e32 v6, v34, v6
	v_mul_f32_e32 v2, v2, v38
	v_bfe_u32 v18, v6, 16, 1
	v_bfe_u32 v22, v2, 16, 1
	v_add3_u32 v6, v6, v18, s90
	v_add3_u32 v2, v2, v22, s90
	global_store_short_d16_hi v[4:5], v6, off
	global_store_short_d16_hi v[32:33], v2, off
	v_mov_b32_e32 v6, v126
	s_nop 0
	v_mov_b32_e32 v18, v127
	v_or_b32_e32 v4, s68, v82
	v_ashrrev_i32_e32 v5, 31, v4
	v_lshlrev_b64 v[4:5], 10, v[4:5]
	v_lshl_add_u64 v[4:5], v[4:5], 0, v[60:61]
	v_lshlrev_b64 v[32:33], 1, v[4:5]
	v_add_f32_e32 v4, v3, v19
	v_add_f32_e32 v5, v35, v39
	v_add_f32_e32 v4, v4, v5
	v_fmamk_f32 v4, v4, 0x3b800000, v93
	v_mul_f32_e32 v5, 0x4f800000, v4
	v_cmp_gt_f32_e32 vcc, s91, v4
	v_lshl_add_u64 v[2:3], s[50:51], 0, v[32:33]
	v_or_b32_e32 v34, 64, v32
	v_cndmask_b32_e32 v16, v4, v5, vcc
	v_sqrt_f32_e32 v17, v16
	v_lshl_add_u64 v[4:5], s[52:53], 0, v[20:21]
	v_mov_b32_e32 v35, v33
	v_lshl_add_u64 v[32:33], s[52:53], 0, v[32:33]
	v_add_u32_e32 v19, -1, v17
	v_add_u32_e32 v20, 1, v17
	v_fma_f32 v21, -v19, v17, v16
	v_fma_f32 v22, -v20, v17, v16
	v_cmp_ge_f32_e64 s[36:37], 0, v21
	v_lshlrev_b32_e32 v6, 16, v6
	v_cndmask_b32_e64 v17, v17, v19, s[36:37]
	v_cmp_lt_f32_e64 s[36:37], 0, v22
	v_lshlrev_b32_e32 v18, 16, v18
	v_cndmask_b32_e64 v17, v17, v20, s[36:37]
	v_mul_f32_e32 v19, 0x37800000, v17
	v_cndmask_b32_e32 v17, v17, v19, vcc
	v_cmp_class_f32_e32 vcc, v16, v94
	s_nop 1
	v_cndmask_b32_e32 v19, v17, v16, vcc
	v_div_scale_f32 v20, s[36:37], v19, v19, 1.0
	v_rcp_f32_e32 v21, v20
	v_div_scale_f32 v22, vcc, 1.0, v19, 1.0
	v_lshl_add_u64 v[16:17], s[50:51], 0, v[34:35]
	v_fma_f32 v36, -v20, v21, 1.0
	v_fmac_f32_e32 v21, v36, v21
	v_mul_f32_e32 v36, v22, v21
	v_fma_f32 v37, -v20, v36, v22
	v_fmac_f32_e32 v36, v37, v21
	v_fma_f32 v20, -v20, v36, v22
	v_div_fmas_f32 v20, v20, v21, v36
	v_div_fixup_f32 v19, v20, v19, 1.0
	v_mul_f32_e32 v20, v23, v19
	v_mul_f32_e32 v7, v7, v19
	v_mul_f32_e32 v19, 0xbfb8aa3b, v6
	v_mul_f32_e32 v21, 0xbfb8aa3b, v18
	v_exp_f32_e32 v19, v19
	v_exp_f32_e32 v21, v21
	v_mul_f32_e32 v20, v48, v20
	v_mul_f32_e32 v7, v59, v7
	v_add_f32_e32 v19, 1.0, v19
	v_add_f32_e32 v21, 1.0, v21
	v_rcp_f32_e32 v19, v19
	v_rcp_f32_e32 v21, v21
	v_mul_f32_e32 v6, v20, v6
	v_mul_f32_e32 v7, v7, v18
	v_mul_f32_e32 v6, v19, v6
	v_mul_f32_e32 v7, v7, v21
	v_bfe_u32 v18, v6, 16, 1
	v_bfe_u32 v19, v7, 16, 1
	v_add3_u32 v6, v6, v18, s90
	v_add3_u32 v7, v7, v19, s90
	global_store_short_d16_hi v[0:1], v6, off
	global_store_short_d16_hi v[4:5], v7, off
	v_mov_b32_e32 v44, v128
	v_mov_b32_e32 v45, v129
	ds_read_b128 v[0:3], v83
	ds_read_b128 v[4:7], v83 offset:256
	ds_read_b128 v[16:19], v83 offset:512
	ds_read_b128 v[20:23], v83 offset:768
	v_or_b32_e32 v36, s68, v84
	v_ashrrev_i32_e32 v37, 31, v36
	s_waitcnt lgkmcnt(2)
	v_add_f32_e32 v0, v0, v4
	v_lshlrev_b64 v[36:37], 10, v[36:37]
	s_waitcnt lgkmcnt(0)
; __device__ __forceinline__ unsigned f2bf(float f) { unsigned u = __builtin_bit_cast(unsigned, f); return (u + 0x7fffu + ((u >> 16) & 1u)) >> 16; }
; __device__ __forceinline__ int crow(int r, int hi) { return (r & 3) + 8 * (r >> 2) + 4 * hi; }
; __device__ __forceinline__ float sigmoid_f(float x) { return __builtin_amdgcn_rcpf(1.0f + __builtin_amdgcn_exp2f(-x * LOG2E)); }
; __device__ __forceinline__ void gla_out(const Ptrs& A, int l, LAS unsigned char* lds, int c, int G, int wave, int lane_, const int wv0) {
;     ...
;         for (int r = 0; r < 16; ++r) { const int t = 32 * ti + crow(r, hi);
;             const float tot = (red[t] + red[64 + t]) + (red[128 + t] + red[192 + t]); const float rinv = 1.0f / sqrtf(tot * (1.0f / 256.0f) + EPS);
;             const size_t off = (size_t)(t0 + t) * 1024 + hd * 256 + 64 * vq + r32;
;             const float r0 = bf2f(GR[off]), r1 = bf2f(GR[off + 32]);
;             AG[off] = (bf16)f2bf(o0[r] * rinv * g0 * r0 * pg8::sigmoid_f(r0)); AG[off + 32] = (bf16)f2bf(o1[r] * rinv * g1 * r1 * pg8::sigmoid_f(r1)); }
	v_add_f32_e32 v4, v16, v20
	v_add_f32_e32 v0, v0, v4
	v_fmamk_f32 v0, v0, 0x3b800000, v93
	v_mul_f32_e32 v4, 0x4f800000, v0
	v_cmp_gt_f32_e32 vcc, s91, v0
	v_lshl_add_u64 v[36:37], v[36:37], 0, v[60:61]
	v_lshlrev_b64 v[36:37], 1, v[36:37]
	v_cndmask_b32_e32 v0, v0, v4, vcc
	v_sqrt_f32_e32 v4, v0
	v_lshl_add_u64 v[38:39], s[50:51], 0, v[36:37]
	v_or_b32_e32 v40, 64, v36
	v_mov_b32_e32 v41, v37
	v_add_u32_e32 v16, -1, v4
	v_add_u32_e32 v20, 1, v4
	v_fma_f32 v42, -v16, v4, v0
	v_fma_f32 v43, -v20, v4, v0
	v_cmp_ge_f32_e64 s[36:37], 0, v42
	v_lshl_add_u64 v[34:35], s[52:53], 0, v[34:35]
	v_add_f32_e32 v17, v17, v21
	v_cndmask_b32_e64 v4, v4, v16, s[36:37]
	v_cmp_lt_f32_e64 s[36:37], 0, v43
	v_lshl_add_u64 v[42:43], s[50:51], 0, v[40:41]
	v_add_f32_e32 v2, v2, v6
	v_cndmask_b32_e64 v4, v4, v20, s[36:37]
	v_mul_f32_e32 v16, 0x37800000, v4
	v_cndmask_b32_e32 v4, v4, v16, vcc
	v_cmp_class_f32_e32 vcc, v0, v94
	v_add_f32_e32 v6, v18, v22
	v_add_f32_e32 v2, v2, v6
	v_cndmask_b32_e32 v0, v4, v0, vcc
	v_div_scale_f32 v4, s[36:37], v0, v0, 1.0
	v_rcp_f32_e32 v16, v4
	v_div_scale_f32 v20, vcc, 1.0, v0, 1.0
	v_fmamk_f32 v2, v2, 0x3b800000, v93
	v_fma_f32 v46, -v4, v16, 1.0
	v_fmac_f32_e32 v16, v46, v16
	v_mul_f32_e32 v46, v20, v16
	v_fma_f32 v47, -v4, v46, v20
	v_fmac_f32_e32 v46, v47, v16
	v_fma_f32 v4, -v4, v46, v20
	v_div_fmas_f32 v4, v4, v16, v46
	v_div_fixup_f32 v0, v4, v0, 1.0
	v_mul_f32_e32 v4, v24, v0
	v_mul_f32_e32 v0, v8, v0
	v_mul_f32_e32 v4, v48, v4
	v_mul_f32_e32 v0, v59, v0
	v_mul_f32_e32 v6, 0x4f800000, v2
	v_lshlrev_b32_e32 v8, 16, v44
	v_lshlrev_b32_e32 v16, 16, v45
	v_mul_f32_e32 v20, 0xbfb8aa3b, v8
	v_mul_f32_e32 v24, 0xbfb8aa3b, v16
	v_exp_f32_e32 v20, v20
	v_exp_f32_e32 v24, v24
	v_mul_f32_e32 v4, v4, v8
	v_mul_f32_e32 v0, v0, v16
	v_add_f32_e32 v20, 1.0, v20
	v_add_f32_e32 v24, 1.0, v24
	v_rcp_f32_e32 v20, v20
	v_rcp_f32_e32 v24, v24
	v_mul_f32_e32 v4, v20, v4
	v_mul_f32_e32 v0, v0, v24
	v_bfe_u32 v8, v4, 16, 1
	v_bfe_u32 v16, v0, 16, 1
	v_add3_u32 v4, v4, v8, s90
	v_add3_u32 v0, v0, v16, s90
	global_store_short_d16_hi v[32:33], v4, off
	global_store_short_d16_hi v[34:35], v0, off
	v_mov_b32_e32 v8, v130
	v_mov_b32_e32 v24, v131
	v_add_f32_e32 v16, v1, v5
	v_add_f32_e32 v16, v16, v17
	v_fmamk_f32 v16, v16, 0x3b800000, v93
	v_mul_f32_e32 v17, 0x4f800000, v16
	v_cmp_gt_f32_e32 vcc, s91, v16
	v_lshl_add_u64 v[0:1], s[52:53], 0, v[36:37]
	v_lshl_add_u64 v[20:21], s[52:53], 0, v[40:41]
	v_cndmask_b32_e32 v34, v16, v17, vcc
	v_sqrt_f32_e32 v35, v34
	v_or_b32_e32 v32, s68, v85
	v_ashrrev_i32_e32 v33, 31, v32
	v_lshlrev_b64 v[32:33], 10, v[32:33]
	v_add_u32_e32 v36, -1, v35
	v_add_u32_e32 v37, 1, v35
	v_fma_f32 v38, -v36, v35, v34
	v_fma_f32 v39, -v37, v35, v34
	v_cmp_ge_f32_e64 s[36:37], 0, v38
	v_lshl_add_u64 v[32:33], v[32:33], 0, v[60:61]
	v_lshlrev_b64 v[32:33], 1, v[32:33]
	v_cndmask_b32_e64 v35, v35, v36, s[36:37]
	v_cmp_lt_f32_e64 s[36:37], 0, v39
	v_or_b32_e32 v16, 64, v32
	v_mov_b32_e32 v17, v33
	v_cndmask_b32_e64 v35, v35, v37, s[36:37]
	v_mul_f32_e32 v36, 0x37800000, v35
	v_cndmask_b32_e32 v35, v35, v36, vcc
	v_cmp_class_f32_e32 vcc, v34, v94
	v_lshl_add_u64 v[4:5], s[50:51], 0, v[32:33]
	v_lshlrev_b32_e32 v8, 16, v8
	v_cndmask_b32_e32 v36, v35, v34, vcc
	v_div_scale_f32 v37, s[36:37], v36, v36, 1.0
	v_rcp_f32_e32 v38, v37
	v_div_scale_f32 v39, vcc, 1.0, v36, 1.0
	v_lshlrev_b32_e32 v24, 16, v24
	v_fma_f32 v40, -v37, v38, 1.0
	v_fmac_f32_e32 v38, v40, v38
	v_mul_f32_e32 v40, v39, v38
	v_fma_f32 v41, -v37, v40, v39
	v_fmac_f32_e32 v40, v41, v38
	v_fma_f32 v37, -v37, v40, v39
	v_div_fmas_f32 v37, v37, v38, v40
	v_div_fixup_f32 v36, v37, v36, 1.0
	v_mul_f32_e32 v25, v25, v36
	v_mul_f32_e32 v9, v9, v36
	v_mul_f32_e32 v36, 0xbfb8aa3b, v8
	v_mul_f32_e32 v37, 0xbfb8aa3b, v24
	v_exp_f32_e32 v36, v36
	v_exp_f32_e32 v37, v37
	v_mul_f32_e32 v25, v48, v25
	v_mul_f32_e32 v9, v59, v9
	v_add_f32_e32 v36, 1.0, v36
	v_add_f32_e32 v37, 1.0, v37
	v_rcp_f32_e32 v36, v36
	v_rcp_f32_e32 v37, v37
	v_mul_f32_e32 v8, v25, v8
	v_mul_f32_e32 v9, v9, v24
	v_mul_f32_e32 v8, v36, v8
	v_mul_f32_e32 v9, v9, v37
	v_bfe_u32 v24, v8, 16, 1
	v_bfe_u32 v25, v9, 16, 1
	v_add3_u32 v8, v8, v24, s90
	v_lshl_add_u64 v[34:35], s[50:51], 0, v[16:17]
	v_add3_u32 v9, v9, v25, s90
	global_store_short_d16_hi v[0:1], v8, off
	global_store_short_d16_hi v[20:21], v9, off
	v_mov_b32_e32 v36, v132
	s_nop 0
	v_mov_b32_e32 v34, v133
	v_cmp_gt_f32_e32 vcc, s91, v2
	v_lshl_add_u64 v[4:5], s[52:53], 0, v[32:33]
	v_or_b32_e32 v0, s68, v86
	v_cndmask_b32_e32 v2, v2, v6, vcc
	v_sqrt_f32_e32 v6, v2
	v_ashrrev_i32_e32 v1, 31, v0
	v_lshlrev_b64 v[0:1], 10, v[0:1]
	v_lshl_add_u64 v[0:1], v[0:1], 0, v[60:61]
	v_add_u32_e32 v18, -1, v6
	v_add_u32_e32 v22, 1, v6
	v_fma_f32 v24, -v18, v6, v2
	v_fma_f32 v25, -v22, v6, v2
	v_cmp_ge_f32_e64 s[36:37], 0, v24
	v_lshlrev_b64 v[0:1], 1, v[0:1]
	v_lshl_add_u64 v[8:9], s[50:51], 0, v[0:1]
	v_cndmask_b32_e64 v6, v6, v18, s[36:37]
	v_cmp_lt_f32_e64 s[36:37], 0, v25
	v_or_b32_e32 v20, 64, v0
	v_mov_b32_e32 v21, v1
	v_cndmask_b32_e64 v6, v6, v22, s[36:37]
	v_mul_f32_e32 v18, 0x37800000, v6
	v_cndmask_b32_e32 v6, v6, v18, vcc
	v_cmp_class_f32_e32 vcc, v2, v94
	v_lshl_add_u64 v[16:17], s[52:53], 0, v[16:17]
	v_lshl_add_u64 v[24:25], s[50:51], 0, v[20:21]
	v_cndmask_b32_e32 v2, v6, v2, vcc
	v_div_scale_f32 v6, s[36:37], v2, v2, 1.0
	v_rcp_f32_e32 v18, v6
	v_div_scale_f32 v22, vcc, 1.0, v2, 1.0
	v_lshl_add_u64 v[0:1], s[52:53], 0, v[0:1]
	v_fma_f32 v32, -v6, v18, 1.0
	v_fmac_f32_e32 v18, v32, v18
	v_mul_f32_e32 v32, v22, v18
	v_fma_f32 v33, -v6, v32, v22
	v_fmac_f32_e32 v32, v33, v18
	v_fma_f32 v6, -v6, v32, v22
	v_div_fmas_f32 v6, v6, v18, v32
; __device__ __forceinline__ unsigned f2bf(float f) { unsigned u = __builtin_bit_cast(unsigned, f); return (u + 0x7fffu + ((u >> 16) & 1u)) >> 16; }
; __device__ __forceinline__ int crow(int r, int hi) { return (r & 3) + 8 * (r >> 2) + 4 * hi; }
; __device__ __forceinline__ float sigmoid_f(float x) { return __builtin_amdgcn_rcpf(1.0f + __builtin_amdgcn_exp2f(-x * LOG2E)); }
; __device__ __forceinline__ void gla_out(const Ptrs& A, int l, LAS unsigned char* lds, int c, int G, int wave, int lane_, const int wv0) {
;     ...
;         for (int r = 0; r < 16; ++r) { const int t = 32 * ti + crow(r, hi);
;             const float tot = (red[t] + red[64 + t]) + (red[128 + t] + red[192 + t]); const float rinv = 1.0f / sqrtf(tot * (1.0f / 256.0f) + EPS);
;             const size_t off = (size_t)(t0 + t) * 1024 + hd * 256 + 64 * vq + r32;
;             const float r0 = bf2f(GR[off]), r1 = bf2f(GR[off + 32]);
;             AG[off] = (bf16)f2bf(o0[r] * rinv * g0 * r0 * pg8::sigmoid_f(r0)); AG[off + 32] = (bf16)f2bf(o1[r] * rinv * g1 * r1 * pg8::sigmoid_f(r1)); }
	v_div_fixup_f32 v2, v6, v2, 1.0
	v_mul_f32_e32 v6, v26, v2
	v_mul_f32_e32 v2, v10, v2
	v_mul_f32_e32 v6, v48, v6
	v_mul_f32_e32 v2, v59, v2
	v_lshlrev_b32_e32 v10, 16, v36
	v_lshlrev_b32_e32 v18, 16, v34
	v_mul_f32_e32 v22, 0xbfb8aa3b, v10
	v_mul_f32_e32 v26, 0xbfb8aa3b, v18
	v_exp_f32_e32 v22, v22
	v_exp_f32_e32 v26, v26
	v_mul_f32_e32 v6, v6, v10
	v_mul_f32_e32 v2, v2, v18
	v_add_f32_e32 v22, 1.0, v22
	v_add_f32_e32 v26, 1.0, v26
	v_rcp_f32_e32 v22, v22
	v_rcp_f32_e32 v26, v26
	v_mul_f32_e32 v6, v22, v6
	v_mul_f32_e32 v2, v2, v26
	v_bfe_u32 v10, v6, 16, 1
	v_bfe_u32 v18, v2, 16, 1
	v_add3_u32 v6, v6, v10, s90
	v_add3_u32 v2, v2, v18, s90
	global_store_short_d16_hi v[4:5], v6, off
	global_store_short_d16_hi v[16:17], v2, off
	v_mov_b32_e32 v8, v134
	s_nop 0
	v_mov_b32_e32 v9, v135
	v_or_b32_e32 v4, s68, v87
	v_ashrrev_i32_e32 v5, 31, v4
	v_lshlrev_b64 v[4:5], 10, v[4:5]
	v_lshl_add_u64 v[4:5], v[4:5], 0, v[60:61]
	v_lshlrev_b64 v[24:25], 1, v[4:5]
	v_add_f32_e32 v4, v3, v7
	v_add_f32_e32 v5, v19, v23
	v_add_f32_e32 v4, v4, v5
	v_fmamk_f32 v4, v4, 0x3b800000, v93
	v_mul_f32_e32 v5, 0x4f800000, v4
	v_cmp_gt_f32_e32 vcc, s91, v4
	v_lshl_add_u64 v[2:3], s[50:51], 0, v[24:25]
	v_or_b32_e32 v22, 64, v24
	v_cndmask_b32_e32 v6, v4, v5, vcc
	v_sqrt_f32_e32 v7, v6
	v_lshl_add_u64 v[4:5], s[52:53], 0, v[20:21]
	v_mov_b32_e32 v23, v25
	v_lshl_add_u64 v[24:25], s[52:53], 0, v[24:25]
	v_add_u32_e32 v10, -1, v7
	v_add_u32_e32 v16, 1, v7
	v_fma_f32 v17, -v10, v7, v6
	v_fma_f32 v18, -v16, v7, v6
	v_cmp_ge_f32_e64 s[36:37], 0, v17
	v_lshlrev_b32_e32 v8, 16, v8
	v_cndmask_b32_e64 v7, v7, v10, s[36:37]
	v_cmp_lt_f32_e64 s[36:37], 0, v18
	v_lshlrev_b32_e32 v9, 16, v9
	v_cndmask_b32_e64 v7, v7, v16, s[36:37]
	v_mul_f32_e32 v10, 0x37800000, v7
	v_cndmask_b32_e32 v7, v7, v10, vcc
	v_cmp_class_f32_e32 vcc, v6, v94
	s_nop 1
	v_cndmask_b32_e32 v10, v7, v6, vcc
	v_div_scale_f32 v16, s[36:37], v10, v10, 1.0
	v_rcp_f32_e32 v17, v16
	v_div_scale_f32 v18, vcc, 1.0, v10, 1.0
	v_lshl_add_u64 v[6:7], s[50:51], 0, v[22:23]
	v_fma_f32 v19, -v16, v17, 1.0
	v_fmac_f32_e32 v17, v19, v17
	v_mul_f32_e32 v19, v18, v17
	v_fma_f32 v20, -v16, v19, v18
	v_fmac_f32_e32 v19, v20, v17
	v_fma_f32 v16, -v16, v19, v18
	v_div_fmas_f32 v16, v16, v17, v19
	v_div_fixup_f32 v10, v16, v10, 1.0
	v_mul_f32_e32 v16, v27, v10
	v_mul_f32_e32 v10, v11, v10
	v_mul_f32_e32 v11, 0xbfb8aa3b, v8
	v_mul_f32_e32 v17, 0xbfb8aa3b, v9
	v_exp_f32_e32 v11, v11
	v_exp_f32_e32 v17, v17
	v_mul_f32_e32 v16, v48, v16
	v_mul_f32_e32 v10, v59, v10
	v_add_f32_e32 v11, 1.0, v11
	v_add_f32_e32 v17, 1.0, v17
	v_rcp_f32_e32 v11, v11
	v_rcp_f32_e32 v17, v17
	v_mul_f32_e32 v8, v16, v8
	v_mul_f32_e32 v9, v10, v9
	v_mul_f32_e32 v8, v11, v8
	v_mul_f32_e32 v9, v9, v17
	v_bfe_u32 v10, v8, 16, 1
	v_bfe_u32 v11, v9, 16, 1
	v_add3_u32 v8, v8, v10, s90
	v_add3_u32 v9, v9, v11, s90
	global_store_short_d16_hi v[0:1], v8, off
	global_store_short_d16_hi v[4:5], v9, off
	v_mov_b32_e32 v36, v136
	v_mov_b32_e32 v37, v137
	ds_read_b128 v[0:3], v88
	ds_read_b128 v[4:7], v88 offset:256
	ds_read_b128 v[8:11], v88 offset:512
	ds_read_b128 v[16:19], v88 offset:768
	v_or_b32_e32 v20, s68, v89
	v_ashrrev_i32_e32 v21, 31, v20
	s_waitcnt lgkmcnt(2)
	v_add_f32_e32 v0, v0, v4
	v_lshlrev_b64 v[20:21], 10, v[20:21]
	s_waitcnt lgkmcnt(0)
	v_add_f32_e32 v4, v8, v16
	v_add_f32_e32 v0, v0, v4
	v_fmamk_f32 v0, v0, 0x3b800000, v93
	v_mul_f32_e32 v4, 0x4f800000, v0
	v_cmp_gt_f32_e32 vcc, s91, v0
	v_lshl_add_u64 v[20:21], v[20:21], 0, v[60:61]
	v_lshlrev_b64 v[20:21], 1, v[20:21]
	v_cndmask_b32_e32 v0, v0, v4, vcc
	v_sqrt_f32_e32 v4, v0
	v_lshl_add_u64 v[26:27], s[50:51], 0, v[20:21]
	v_or_b32_e32 v32, 64, v20
	v_mov_b32_e32 v33, v21
	v_add_u32_e32 v8, -1, v4
	v_add_u32_e32 v16, 1, v4
	v_fma_f32 v34, -v8, v4, v0
	v_fma_f32 v35, -v16, v4, v0
	v_cmp_ge_f32_e64 s[36:37], 0, v34
	v_lshl_add_u64 v[22:23], s[52:53], 0, v[22:23]
	v_add_f32_e32 v9, v9, v17
	v_cndmask_b32_e64 v4, v4, v8, s[36:37]
	v_cmp_lt_f32_e64 s[36:37], 0, v35
	v_lshl_add_u64 v[34:35], s[50:51], 0, v[32:33]
	v_add_f32_e32 v2, v2, v6
	v_cndmask_b32_e64 v4, v4, v16, s[36:37]
	v_mul_f32_e32 v8, 0x37800000, v4
	v_cndmask_b32_e32 v4, v4, v8, vcc
	v_cmp_class_f32_e32 vcc, v0, v94
	v_add_f32_e32 v6, v10, v18
	v_add_f32_e32 v2, v2, v6
	v_cndmask_b32_e32 v0, v4, v0, vcc
	v_div_scale_f32 v4, s[36:37], v0, v0, 1.0
	v_rcp_f32_e32 v8, v4
	v_div_scale_f32 v16, vcc, 1.0, v0, 1.0
	v_fmamk_f32 v2, v2, 0x3b800000, v93
	v_fma_f32 v38, -v4, v8, 1.0
	v_fmac_f32_e32 v8, v38, v8
	v_mul_f32_e32 v38, v16, v8
	v_fma_f32 v39, -v4, v38, v16
	v_fmac_f32_e32 v38, v39, v8
	v_fma_f32 v4, -v4, v38, v16
	v_div_fmas_f32 v4, v4, v8, v38
	v_div_fixup_f32 v0, v4, v0, 1.0
	v_mul_f32_e32 v4, v28, v0
	v_mul_f32_e32 v0, v12, v0
	v_mul_f32_e32 v4, v48, v4
	v_mul_f32_e32 v0, v59, v0
	v_mul_f32_e32 v6, 0x4f800000, v2
	v_lshlrev_b32_e32 v8, 16, v36
	v_lshlrev_b32_e32 v12, 16, v37
	v_mul_f32_e32 v16, 0xbfb8aa3b, v8
	v_mul_f32_e32 v28, 0xbfb8aa3b, v12
	v_exp_f32_e32 v16, v16
	v_exp_f32_e32 v28, v28
	v_mul_f32_e32 v4, v4, v8
	v_mul_f32_e32 v0, v0, v12
	v_add_f32_e32 v16, 1.0, v16
	v_add_f32_e32 v28, 1.0, v28
	v_rcp_f32_e32 v16, v16
	v_rcp_f32_e32 v28, v28
	v_mul_f32_e32 v4, v16, v4
	v_mul_f32_e32 v0, v0, v28
	v_bfe_u32 v8, v4, 16, 1
	v_bfe_u32 v12, v0, 16, 1
	v_add3_u32 v4, v4, v8, s90
	v_add3_u32 v0, v0, v12, s90
	global_store_short_d16_hi v[24:25], v4, off
	global_store_short_d16_hi v[22:23], v0, off
	v_mov_b32_e32 v12, v138
	s_nop 0
	v_mov_b32_e32 v24, v139
	v_add_f32_e32 v8, v1, v5
	v_add_f32_e32 v8, v8, v9
	v_fmamk_f32 v8, v8, 0x3b800000, v93
	v_mul_f32_e32 v9, 0x4f800000, v8
	v_cmp_gt_f32_e32 vcc, s91, v8
	v_lshl_add_u64 v[0:1], s[52:53], 0, v[20:21]
; __device__ __forceinline__ unsigned f2bf(float f) { unsigned u = __builtin_bit_cast(unsigned, f); return (u + 0x7fffu + ((u >> 16) & 1u)) >> 16; }
; __device__ __forceinline__ int crow(int r, int hi) { return (r & 3) + 8 * (r >> 2) + 4 * hi; }
; __device__ __forceinline__ float sigmoid_f(float x) { return __builtin_amdgcn_rcpf(1.0f + __builtin_amdgcn_exp2f(-x * LOG2E)); }
; __device__ __forceinline__ void gla_out(const Ptrs& A, int l, LAS unsigned char* lds, int c, int G, int wave, int lane_, const int wv0) {
;     ...
;         for (int r = 0; r < 16; ++r) { const int t = 32 * ti + crow(r, hi);
;             const float tot = (red[t] + red[64 + t]) + (red[128 + t] + red[192 + t]); const float rinv = 1.0f / sqrtf(tot * (1.0f / 256.0f) + EPS);
;             const size_t off = (size_t)(t0 + t) * 1024 + hd * 256 + 64 * vq + r32;
;             const float r0 = bf2f(GR[off]), r1 = bf2f(GR[off + 32]);
;             AG[off] = (bf16)f2bf(o0[r] * rinv * g0 * r0 * pg8::sigmoid_f(r0)); AG[off + 32] = (bf16)f2bf(o1[r] * rinv * g1 * r1 * pg8::sigmoid_f(r1)); }
	v_lshl_add_u64 v[16:17], s[52:53], 0, v[32:33]
	v_cndmask_b32_e32 v20, v8, v9, vcc
	v_sqrt_f32_e32 v21, v20
	v_or_b32_e32 v22, s68, v90
	v_ashrrev_i32_e32 v23, 31, v22
	v_lshlrev_b64 v[22:23], 10, v[22:23]
	v_add_u32_e32 v25, -1, v21
	v_add_u32_e32 v26, 1, v21
	v_fma_f32 v27, -v25, v21, v20
	v_fma_f32 v28, -v26, v21, v20
	v_cmp_ge_f32_e64 s[36:37], 0, v27
	v_lshl_add_u64 v[22:23], v[22:23], 0, v[60:61]
	v_lshlrev_b64 v[22:23], 1, v[22:23]
	v_cndmask_b32_e64 v21, v21, v25, s[36:37]
	v_cmp_lt_f32_e64 s[36:37], 0, v28
	v_lshl_add_u64 v[4:5], s[50:51], 0, v[22:23]
	v_or_b32_e32 v8, 64, v22
	v_cndmask_b32_e64 v21, v21, v26, s[36:37]
	v_mul_f32_e32 v25, 0x37800000, v21
	v_cndmask_b32_e32 v21, v21, v25, vcc
	v_cmp_class_f32_e32 vcc, v20, v94
	v_mov_b32_e32 v9, v23
	v_lshlrev_b32_e32 v12, 16, v12
	v_cndmask_b32_e32 v25, v21, v20, vcc
	v_div_scale_f32 v26, s[36:37], v25, v25, 1.0
	v_rcp_f32_e32 v27, v26
	v_div_scale_f32 v28, vcc, 1.0, v25, 1.0
	v_lshlrev_b32_e32 v24, 16, v24
	v_fma_f32 v32, -v26, v27, 1.0
	v_fmac_f32_e32 v27, v32, v27
	v_mul_f32_e32 v32, v28, v27
	v_fma_f32 v33, -v26, v32, v28
	v_fmac_f32_e32 v32, v33, v27
	v_fma_f32 v26, -v26, v32, v28
	v_div_fmas_f32 v26, v26, v27, v32
	v_div_fixup_f32 v25, v26, v25, 1.0
	v_mul_f32_e32 v26, v29, v25
	v_mul_f32_e32 v13, v13, v25
	v_mul_f32_e32 v25, 0xbfb8aa3b, v12
	v_mul_f32_e32 v27, 0xbfb8aa3b, v24
	v_exp_f32_e32 v25, v25
	v_exp_f32_e32 v27, v27
	v_mul_f32_e32 v26, v48, v26
	v_mul_f32_e32 v13, v59, v13
	v_add_f32_e32 v25, 1.0, v25
	v_add_f32_e32 v27, 1.0, v27
	v_rcp_f32_e32 v25, v25
	v_rcp_f32_e32 v27, v27
	v_mul_f32_e32 v12, v26, v12
	v_mul_f32_e32 v13, v13, v24
	v_mul_f32_e32 v12, v25, v12
	v_mul_f32_e32 v13, v13, v27
	v_bfe_u32 v24, v12, 16, 1
	v_bfe_u32 v25, v13, 16, 1
	v_add3_u32 v12, v12, v24, s90
	v_add3_u32 v13, v13, v25, s90
	global_store_short_d16_hi v[0:1], v12, off
	global_store_short_d16_hi v[16:17], v13, off
	v_lshl_add_u64 v[20:21], s[50:51], 0, v[8:9]
	v_mov_b32_e32 v24, v140
	v_mov_b32_e32 v25, v141
	v_cmp_gt_f32_e32 vcc, s91, v2
	v_lshl_add_u64 v[4:5], s[52:53], 0, v[22:23]
	v_or_b32_e32 v0, s68, v91
	v_cndmask_b32_e32 v2, v2, v6, vcc
	v_sqrt_f32_e32 v6, v2
	v_ashrrev_i32_e32 v1, 31, v0
	v_lshlrev_b64 v[0:1], 10, v[0:1]
	v_lshl_add_u64 v[0:1], v[0:1], 0, v[60:61]
	v_add_u32_e32 v10, -1, v6
	v_add_u32_e32 v18, 1, v6
	v_fma_f32 v20, -v10, v6, v2
	v_fma_f32 v21, -v18, v6, v2
	v_cmp_ge_f32_e64 s[36:37], 0, v20
	v_lshlrev_b64 v[0:1], 1, v[0:1]
	v_lshl_add_u64 v[12:13], s[50:51], 0, v[0:1]
	v_cndmask_b32_e64 v6, v6, v10, s[36:37]
	v_cmp_lt_f32_e64 s[36:37], 0, v21
	v_or_b32_e32 v16, 64, v0
	v_mov_b32_e32 v17, v1
	v_cndmask_b32_e64 v6, v6, v18, s[36:37]
	v_mul_f32_e32 v10, 0x37800000, v6
	v_cndmask_b32_e32 v6, v6, v10, vcc
	v_cmp_class_f32_e32 vcc, v2, v94
	v_lshl_add_u64 v[8:9], s[52:53], 0, v[8:9]
	v_lshl_add_u64 v[20:21], s[50:51], 0, v[16:17]
	v_cndmask_b32_e32 v2, v6, v2, vcc
	v_div_scale_f32 v6, s[36:37], v2, v2, 1.0
	v_rcp_f32_e32 v10, v6
	v_div_scale_f32 v18, vcc, 1.0, v2, 1.0
	v_lshl_add_u64 v[0:1], s[52:53], 0, v[0:1]
	v_fma_f32 v22, -v6, v10, 1.0
	v_fmac_f32_e32 v10, v22, v10
	v_mul_f32_e32 v22, v18, v10
	v_fma_f32 v23, -v6, v22, v18
	v_fmac_f32_e32 v22, v23, v10
	v_fma_f32 v6, -v6, v22, v18
	v_div_fmas_f32 v6, v6, v10, v22
	v_div_fixup_f32 v2, v6, v2, 1.0
	v_mul_f32_e32 v6, v30, v2
	v_mul_f32_e32 v2, v14, v2
	v_mul_f32_e32 v6, v48, v6
	v_mul_f32_e32 v2, v59, v2
	v_lshlrev_b32_e32 v10, 16, v24
	v_lshlrev_b32_e32 v14, 16, v25
	v_mul_f32_e32 v18, 0xbfb8aa3b, v10
	v_mul_f32_e32 v22, 0xbfb8aa3b, v14
	v_exp_f32_e32 v18, v18
	v_exp_f32_e32 v22, v22
	v_mul_f32_e32 v6, v6, v10
	v_mul_f32_e32 v2, v2, v14
	v_add_f32_e32 v18, 1.0, v18
	v_add_f32_e32 v22, 1.0, v22
	v_rcp_f32_e32 v18, v18
	v_rcp_f32_e32 v22, v22
	v_mul_f32_e32 v6, v18, v6
	v_mul_f32_e32 v2, v2, v22
	v_bfe_u32 v10, v6, 16, 1
	v_bfe_u32 v14, v2, 16, 1
	v_add3_u32 v6, v6, v10, s90
	v_add3_u32 v2, v2, v14, s90
	global_store_short_d16_hi v[4:5], v6, off
	global_store_short_d16_hi v[8:9], v2, off
	v_mov_b32_e32 v4, v142
	s_nop 0
	v_mov_b32_e32 v5, v143
	v_add_f32_e32 v2, v3, v7
	v_add_f32_e32 v3, v11, v19
	v_add_f32_e32 v2, v2, v3
	v_fmamk_f32 v2, v2, 0x3b800000, v93
	v_mul_f32_e32 v3, 0x4f800000, v2
	v_cmp_gt_f32_e32 vcc, s91, v2
	v_lshlrev_b32_e32 v4, 16, v4
	v_cndmask_b32_e32 v2, v2, v3, vcc
	v_sqrt_f32_e32 v3, v2
	v_lshlrev_b32_e32 v5, 16, v5
	v_add_u32_e32 v6, -1, v3
	v_add_u32_e32 v7, 1, v3
	v_fma_f32 v8, -v6, v3, v2
	v_fma_f32 v9, -v7, v3, v2
	v_cmp_ge_f32_e64 s[36:37], 0, v8
	s_nop 1
	v_cndmask_b32_e64 v3, v3, v6, s[36:37]
	v_cmp_lt_f32_e64 s[36:37], 0, v9
	s_nop 1
	v_cndmask_b32_e64 v3, v3, v7, s[36:37]
	v_mul_f32_e32 v6, 0x37800000, v3
	v_cndmask_b32_e32 v3, v3, v6, vcc
	v_cmp_class_f32_e32 vcc, v2, v94
	s_nop 1
	v_cndmask_b32_e32 v6, v3, v2, vcc
	v_div_scale_f32 v7, s[36:37], v6, v6, 1.0
	v_rcp_f32_e32 v8, v7
	v_div_scale_f32 v9, vcc, 1.0, v6, 1.0
	v_lshl_add_u64 v[2:3], s[52:53], 0, v[16:17]
	v_fma_f32 v10, -v7, v8, 1.0
	v_fmac_f32_e32 v8, v10, v8
	v_mul_f32_e32 v10, v9, v8
	v_fma_f32 v11, -v7, v10, v9
	v_fmac_f32_e32 v10, v11, v8
	v_fma_f32 v7, -v7, v10, v9
	v_div_fmas_f32 v7, v7, v8, v10
	v_mul_f32_e32 v8, 0xbfb8aa3b, v4
	v_mul_f32_e32 v9, 0xbfb8aa3b, v5
	v_exp_f32_e32 v8, v8
	v_exp_f32_e32 v9, v9
	v_div_fixup_f32 v6, v7, v6, 1.0
	v_mul_f32_e32 v7, v31, v6
	v_add_f32_e32 v8, 1.0, v8
	v_add_f32_e32 v9, 1.0, v9
	v_rcp_f32_e32 v8, v8
	v_rcp_f32_e32 v9, v9
	v_mul_f32_e32 v6, v15, v6
	v_mul_f32_e32 v7, v48, v7
	v_mul_f32_e32 v6, v59, v6
	v_mul_f32_e32 v4, v7, v4
	v_mul_f32_e32 v5, v6, v5
	v_mul_f32_e32 v4, v8, v4
	v_mul_f32_e32 v5, v5, v9
	v_bfe_u32 v6, v4, 16, 1
	v_bfe_u32 v7, v5, 16, 1
	v_add3_u32 v4, v4, v6, s90
	v_add3_u32 v5, v5, v7, s90
	global_store_short_d16_hi v[0:1], v4, off
	global_store_short_d16_hi v[2:3], v5, off
	s_barrier
	s_cbranch_scc0 .LBB0_1368
; #define LAS __attribute__((address_space(3)))
; #define TID() (wv0 * 64 + (int)__builtin_amdgcn_mbcnt_hi(~0u, __builtin_amdgcn_mbcnt_lo(~0u, 0u)))
; __device__ __forceinline__ int opaque(int x) { asm volatile("" : "+v"(x)); return x; }
;     __device__ __forceinline__ const float* in(int k) const { return (const float*)(const __attribute__((address_space(1))) float*)get(k); }
; __device__ __forceinline__ void gla_cumdecay(const Ptrs& A, int l, int n, int hd, LAS float* bl, const int wv0) {
;     const int tid = opaque(TID()), d = tid & 127, tq = __builtin_amdgcn_readfirstlane(tid >> 7);
;     const float* wa2 = A.in(4) + (size_t)l * 16 * 512 + hd * 128 + d;
;     float w[16];
; #pragma unroll
;     for (int r = 0; r < 16; ++r) w[r] = wa2[r * 512];
;     const float bias = A.in(5)[(size_t)l * 512 + hd * 128 + d];
;     LAS float* gal = bl + 29184;
;     *(LAS f32x2*)(gal + 2 * tid) = *(const f32x2*)((const float*)(A.ws() + WS_GA1) + (size_t)n * 64 * 16 + 2 * tid);
;     __syncthreads();
;     const LAS float* ga = gal + 16 * tq * 16;
;     float run = 0.f;
;     for (int tt = 0; tt < 16; ++tt) {
;         float pre = bias;
;         const f32x4 g0 = *(const LAS f32x4*)(ga + tt * 16), g1 = *(const LAS f32x4*)(ga + tt * 16 + 4), g2 = *(const LAS f32x4*)(ga + tt * 16 + 8), g3 = *(const LAS f32x4*)(ga + tt * 16 + 12);
;         pre += (g0.x * w[0] + g0.y * w[1]) + (g0.z * w[2] + g0.w * w[3]); pre += (g1.x * w[4] + g1.y * w[5]) + (g1.z * w[6] + g1.w * w[7]);
;         pre += (g2.x * w[8] + g2.y * w[9]) + (g2.z * w[10] + g2.w * w[11]); pre += (g3.x * w[12] + g3.y * w[13]) + (g3.z * w[14] + g3.w * w[15]);
;         const float la = (fminf(pre, 0.f) - __logf(1.0f + __expf(-fabsf(pre)))) * (1.0f / 16.0f);
;         run += la; bl[(16 * tq + tt) * BLS + d] = run;
; __device__ __forceinline__ void gla_out(const Ptrs& A, int l, LAS unsigned char* lds, int c, int G, int wave, int lane_, const int wv0) {
;     ...
;         const int n = it >> 2, hd = it & 3, t0 = n * 64;
;         u32x4 qq[2], kk[2];
; #pragma unroll
;         for (int i = 0; i < 2; ++i) { qq[i] = *(const u32x4*)(GQ + (size_t)(t0 + lane) * 512 + hd * 128 + (wave + 8 * i) * 8); kk[i] = *(const u32x4*)(GK + (size_t)(t0 + lane) * 512 + hd * 128 + (wave + 8 * i) * 8); }
;         gla_cumdecay(A, l, n, hd, bl, wv0);
;         gla_load_vt(GV + (size_t)t0 * 1024 + hd * 256, VTl, wave, lane);
.LBB0_1324:
	s_ashr_i32 s36, s44, 2
	s_lshl_b32 s68, s36, 6
	v_or_b32_e32 v0, s68, v62
	v_ashrrev_i32_e32 v1, 31, v0
	s_and_b32 s37, s44, 3
	v_lshlrev_b64 v[0:1], 10, v[0:1]
	v_lshl_add_u64 v[2:3], s[46:47], 0, v[0:1]
	s_lshl_b32 s56, s37, 8
	v_lshl_add_u64 v[0:1], s[48:49], 0, v[0:1]
	v_lshl_add_u64 v[2:3], v[2:3], 0, s[56:57]
	v_lshl_add_u64 v[0:1], v[0:1], 0, s[56:57]
	s_lshl_b64 s[40:41], s[54:55], 1
	v_lshl_add_u64 v[2:3], v[2:3], 0, s[40:41]
	v_lshl_add_u64 v[0:1], v[0:1], 0, s[40:41]
	v_mov_b32_e32 v42, v204
	global_load_dwordx4 v[12:15], v[2:3], off
	global_load_dwordx4 v[4:7], v[2:3], off offset:128
	global_load_dwordx4 v[8:11], v[0:1], off
	s_nop 0
	global_load_dwordx4 v[0:3], v[0:1], off offset:128
	v_mov_b32 v16, s77
	ds_read_b64 v[16:17], v16 offset:32
	s_lshl_b32 s40, s37, 9
	v_readfirstlane_b32 s37, v42
	s_waitcnt lgkmcnt(0)
	v_readfirstlane_b32 s69, v16
	v_readfirstlane_b32 s41, v17
	s_add_u32 s92, s69, s40
	v_lshlrev_b32_e32 v16, 2, v42
	s_addc_u32 s93, s41, 0
	v_and_b32_e32 v48, 0x1fc, v16
	v_lshl_add_u64 v[16:17], s[92:93], 0, v[48:49]
	v_add_co_u32_e32 v20, vcc, s39, v16
	v_lshl_add_u64 v[18:19], v[16:17], 0, s[64:65]
	s_nop 0
	v_addc_co_u32_e32 v21, vcc, 0, v17, vcc
	v_add_co_u32_e32 v24, vcc, s45, v16
	s_ashr_i32 s41, s37, 7
	s_nop 0
	v_addc_co_u32_e32 v25, vcc, 0, v17, vcc
	v_add_co_u32_e32 v32, vcc, s74, v16
	s_nop 1
	v_addc_co_u32_e32 v33, vcc, 0, v17, vcc
	v_add_co_u32_e32 v34, vcc, s75, v16
	s_nop 1
	v_addc_co_u32_e32 v35, vcc, 0, v17, vcc
	v_add_co_u32_e32 v36, vcc, s79, v16
	s_nop 1
	v_addc_co_u32_e32 v37, vcc, 0, v17, vcc
	v_add_co_u32_e32 v38, vcc, s80, v16
	s_nop 1
	v_addc_co_u32_e32 v39, vcc, 0, v17, vcc
	v_add_co_u32_e32 v40, vcc, s81, v16
	s_nop 1
	v_addc_co_u32_e32 v41, vcc, 0, v17, vcc
	global_load_dword v28, v[20:21], off offset:-4096
	global_load_dword v31, v[18:19], off offset:2048
	global_load_dword v26, v[20:21], off
	global_load_dword v30, v[20:21], off offset:2048
	global_load_dword v23, v[32:33], off offset:-4096
	global_load_dword v27, v[24:25], off offset:2048
	s_nop 0
	global_load_dword v19, v[34:35], off offset:2048
	global_load_dword v17, v[38:39], off offset:2048
	global_load_dword v29, v[32:33], off
	s_nop 0
	global_load_dword v32, v[32:33], off offset:2048
	s_nop 0
	global_load_dword v24, v[36:37], off offset:-4096
	global_load_dword v22, v[36:37], off
	global_load_dword v25, v[36:37], off offset:2048
	global_load_dword v20, v[40:41], off offset:-4096
	global_load_dword v18, v[40:41], off
	global_load_dword v21, v[40:41], off offset:2048
	v_mov_b32 v16, s77
	ds_read_b64 v[34:35], v16 offset:40
	s_waitcnt lgkmcnt(0)
	v_readfirstlane_b32 s69, v34
	v_readfirstlane_b32 s37, v35
	s_add_u32 s92, s69, s40
	s_addc_u32 s93, s37, 0
	global_load_dword v33, v48, s[92:93] offset:2048
	v_mov_b32 v16, s77
	ds_read_b64 v[34:35], v16 offset:168
	s_ashr_i32 s37, s36, 31
	s_lshl_b64 s[36:37], s[36:37], 12
	v_lshl_add_u32 v16, v42, 3, s83
	s_waitcnt lgkmcnt(0)
	v_readfirstlane_b32 s92, v34
	v_readfirstlane_b32 s69, v35
	s_add_u32 s36, s92, s36
	v_lshlrev_b32_e32 v34, 1, v42
	s_addc_u32 s37, s69, s37
	v_ashrrev_i32_e32 v35, 31, v34
	v_lshl_add_u64 v[34:35], v[34:35], 2, s[36:37]
	v_add_co_u32_e32 v34, vcc, s82, v34
	s_lshl_b32 s36, s41, 10
	s_nop 0
	v_addc_co_u32_e32 v35, vcc, 0, v35, vcc
	global_load_dwordx2 v[36:37], v[34:35], off
	s_add_i32 s36, s83, s36
	v_mov_b32_e32 v35, s36
	s_cmp_gt_i32 s41, 0
	s_waitcnt vmcnt(0)
	ds_write_b64 v16, v[36:37]
	s_waitcnt lgkmcnt(0)
	s_barrier
	ds_read_b128 v[36:39], v35
	ds_read_b128 v[40:43], v35 offset:16
	ds_read_b128 v[44:47], v35 offset:32
	ds_read_b128 v[96:99], v35 offset:48
	s_waitcnt lgkmcnt(3)
	v_mul_f32_e32 v16, v31, v37
	v_mul_f32_e32 v34, v30, v39
	s_waitcnt lgkmcnt(2)
	v_mul_f32_e32 v37, v27, v41
	v_mul_f32_e32 v39, v32, v43
	v_fmac_f32_e32 v16, v28, v36
	v_fmac_f32_e32 v34, v26, v38
	s_waitcnt lgkmcnt(1)
	v_mul_f32_e32 v41, v19, v45
	v_mul_f32_e32 v43, v25, v47
	v_fmac_f32_e32 v37, v23, v40
	v_fmac_f32_e32 v39, v29, v42
	v_add_f32_e32 v16, v16, v34
	v_fmac_f32_e32 v41, v24, v44
	v_fmac_f32_e32 v43, v22, v46
	v_add_f32_e32 v34, v37, v39
	v_add_f32_e32 v16, v33, v16
	v_add_f32_e32 v36, v41, v43
	v_add_f32_e32 v16, v16, v34
	v_add_f32_e32 v16, v16, v36
	s_waitcnt lgkmcnt(0)
	ds_read_b128 v[166:169], v35 offset:64
	ds_read_b128 v[170:173], v35 offset:80
	ds_read_b128 v[174:177], v35 offset:96
	ds_read_b128 v[178:181], v35 offset:112
	v_mul_f32_e32 v34, v17, v97
	v_mul_f32_e32 v36, v21, v99
	v_fmac_f32_e32 v34, v20, v96
	v_fmac_f32_e32 v36, v18, v98
	v_add_f32_e32 v34, v34, v36
	v_add_f32_e32 v16, v16, v34
	v_mul_f32_e64 v34, |v16|, s84
	v_exp_f32_e32 v34, v34
	v_min_f32_e32 v16, 0, v16
	v_add_f32_e32 v34, 1.0, v34
	v_cmp_gt_f32_e32 vcc, s85, v34
	s_nop 1
	v_cndmask_b32_e64 v36, 0, 32, vcc
	v_ldexp_f32 v34, v34, v36
	v_log_f32_e32 v36, v34
	v_add_u32_e32 v34, 0, v48
	v_mul_f32_e32 v37, 0x3f317217, v36
	v_fma_f32 v37, v36, s86, -v37
	v_fmac_f32_e32 v37, 0x3377d1cf, v36
	v_fmac_f32_e32 v37, 0x3f317217, v36
	v_cmp_lt_f32_e64 s[36:37], |v36|, s87
	s_nop 1
	v_cndmask_b32_e64 v36, v36, v37, s[36:37]
	v_cndmask_b32_e32 v37, 0, v95, vcc
	v_sub_f32_e32 v36, v36, v37
	v_sub_f32_e32 v16, v16, v36
	s_mul_i32 s36, s41, 0x2100
	v_fma_f32 v36, v16, s88, 0
	v_add_u32_e32 v16, s36, v34
	ds_write_b32 v16, v36
	s_waitcnt lgkmcnt(3)
	v_mul_f32_e32 v37, v31, v167
	v_fmac_f32_e32 v37, v28, v166
	v_mul_f32_e32 v38, v30, v169
	v_fmac_f32_e32 v38, v26, v168
	v_add_f32_e32 v37, v37, v38
	s_waitcnt lgkmcnt(2)
	v_mul_f32_e32 v38, v27, v171
	v_mul_f32_e32 v39, v32, v173
	v_fmac_f32_e32 v38, v23, v170
	v_fmac_f32_e32 v39, v29, v172
	v_add_f32_e32 v37, v33, v37
	v_add_f32_e32 v38, v38, v39
	v_add_f32_e32 v37, v37, v38
	s_waitcnt lgkmcnt(1)
; #define LAS __attribute__((address_space(3)))
; __device__ __forceinline__ void gla_cumdecay(const Ptrs& A, int l, int n, int hd, LAS float* bl, const int wv0) {
;     ...
;     for (int tt = 0; tt < 16; ++tt) {
;         float pre = bias;
;         const f32x4 g0 = *(const LAS f32x4*)(ga + tt * 16), g1 = *(const LAS f32x4*)(ga + tt * 16 + 4), g2 = *(const LAS f32x4*)(ga + tt * 16 + 8), g3 = *(const LAS f32x4*)(ga + tt * 16 + 12);
;         pre += (g0.x * w[0] + g0.y * w[1]) + (g0.z * w[2] + g0.w * w[3]); pre += (g1.x * w[4] + g1.y * w[5]) + (g1.z * w[6] + g1.w * w[7]);
;         pre += (g2.x * w[8] + g2.y * w[9]) + (g2.z * w[10] + g2.w * w[11]); pre += (g3.x * w[12] + g3.y * w[13]) + (g3.z * w[14] + g3.w * w[15]);
;         const float la = (fminf(pre, 0.f) - __logf(1.0f + __expf(-fabsf(pre)))) * (1.0f / 16.0f);
;         run += la; bl[(16 * tq + tt) * BLS + d] = run;
	v_mul_f32_e32 v38, v19, v175
	v_mul_f32_e32 v39, v25, v177
	v_fmac_f32_e32 v38, v24, v174
	v_fmac_f32_e32 v39, v22, v176
	v_add_f32_e32 v38, v38, v39
	v_add_f32_e32 v37, v37, v38
	s_waitcnt lgkmcnt(0)
	ds_read_b128 v[150:153], v35 offset:128
	ds_read_b128 v[154:157], v35 offset:144
	ds_read_b128 v[158:161], v35 offset:160
	ds_read_b128 v[162:165], v35 offset:176
	v_mul_f32_e32 v38, v17, v179
	v_mul_f32_e32 v39, v21, v181
	v_fmac_f32_e32 v38, v20, v178
	v_fmac_f32_e32 v39, v18, v180
	v_add_f32_e32 v38, v38, v39
	v_add_f32_e32 v37, v37, v38
	v_mul_f32_e64 v38, |v37|, s84
	v_exp_f32_e32 v38, v38
	v_min_f32_e32 v37, 0, v37
	v_add_f32_e32 v38, 1.0, v38
	v_cmp_gt_f32_e32 vcc, s85, v38
	s_nop 1
	v_cndmask_b32_e64 v39, 0, 32, vcc
	v_ldexp_f32 v38, v38, v39
	v_log_f32_e32 v38, v38
	s_nop 0
	v_mul_f32_e32 v39, 0x3f317217, v38
	v_fma_f32 v39, v38, s86, -v39
	v_fmac_f32_e32 v39, 0x3377d1cf, v38
	v_fmac_f32_e32 v39, 0x3f317217, v38
	v_cmp_lt_f32_e64 s[36:37], |v38|, s87
	s_nop 1
	v_cndmask_b32_e64 v38, v38, v39, s[36:37]
	v_cndmask_b32_e32 v39, 0, v95, vcc
	v_sub_f32_e32 v38, v38, v39
	v_sub_f32_e32 v37, v37, v38
	v_fmac_f32_e32 v36, 0x3d800000, v37
	ds_write_b32 v16, v36 offset:528
	s_waitcnt lgkmcnt(3)
	v_mul_f32_e32 v37, v31, v151
	v_fmac_f32_e32 v37, v28, v150
	v_mul_f32_e32 v38, v30, v153
	v_fmac_f32_e32 v38, v26, v152
	v_add_f32_e32 v37, v37, v38
	s_waitcnt lgkmcnt(2)
	v_mul_f32_e32 v38, v27, v155
	v_mul_f32_e32 v39, v32, v157
	v_fmac_f32_e32 v38, v23, v154
	v_fmac_f32_e32 v39, v29, v156
	v_add_f32_e32 v37, v33, v37
	v_add_f32_e32 v38, v38, v39
	v_add_f32_e32 v37, v37, v38
	s_waitcnt lgkmcnt(1)
	v_mul_f32_e32 v38, v19, v159
	v_mul_f32_e32 v39, v25, v161
	v_fmac_f32_e32 v38, v24, v158
	v_fmac_f32_e32 v39, v22, v160
	v_add_f32_e32 v38, v38, v39
	v_add_f32_e32 v37, v37, v38
	s_waitcnt lgkmcnt(0)
	ds_read_b128 v[166:169], v35 offset:192
	ds_read_b128 v[170:173], v35 offset:208
	ds_read_b128 v[174:177], v35 offset:224
	ds_read_b128 v[178:181], v35 offset:240
	v_mul_f32_e32 v38, v17, v163
	v_mul_f32_e32 v39, v21, v165
	v_fmac_f32_e32 v38, v20, v162
	v_fmac_f32_e32 v39, v18, v164
	v_add_f32_e32 v38, v38, v39
	v_add_f32_e32 v37, v37, v38
	v_mul_f32_e64 v38, |v37|, s84
	v_exp_f32_e32 v38, v38
	v_min_f32_e32 v37, 0, v37
	v_add_f32_e32 v38, 1.0, v38
	v_cmp_gt_f32_e32 vcc, s85, v38
	s_nop 1
	v_cndmask_b32_e64 v39, 0, 32, vcc
	v_ldexp_f32 v38, v38, v39
	v_log_f32_e32 v38, v38
	s_nop 0
	v_mul_f32_e32 v39, 0x3f317217, v38
	v_fma_f32 v39, v38, s86, -v39
	v_fmac_f32_e32 v39, 0x3377d1cf, v38
	v_fmac_f32_e32 v39, 0x3f317217, v38
	v_cmp_lt_f32_e64 s[36:37], |v38|, s87
	s_nop 1
	v_cndmask_b32_e64 v38, v38, v39, s[36:37]
	v_cndmask_b32_e32 v39, 0, v95, vcc
	v_sub_f32_e32 v38, v38, v39
	v_sub_f32_e32 v37, v37, v38
	v_fmac_f32_e32 v36, 0x3d800000, v37
	ds_write_b32 v16, v36 offset:1056
	s_waitcnt lgkmcnt(3)
	v_mul_f32_e32 v37, v31, v167
	v_fmac_f32_e32 v37, v28, v166
	v_mul_f32_e32 v38, v30, v169
	v_fmac_f32_e32 v38, v26, v168
	v_add_f32_e32 v37, v37, v38
	s_waitcnt lgkmcnt(2)
	v_mul_f32_e32 v38, v27, v171
	v_mul_f32_e32 v39, v32, v173
	v_fmac_f32_e32 v38, v23, v170
	v_fmac_f32_e32 v39, v29, v172
	v_add_f32_e32 v37, v33, v37
	v_add_f32_e32 v38, v38, v39
	v_add_f32_e32 v37, v37, v38
	s_waitcnt lgkmcnt(1)
	v_mul_f32_e32 v38, v19, v175
	v_mul_f32_e32 v39, v25, v177
	v_fmac_f32_e32 v38, v24, v174
	v_fmac_f32_e32 v39, v22, v176
	v_add_f32_e32 v38, v38, v39
	v_add_f32_e32 v37, v37, v38
	s_waitcnt lgkmcnt(0)
	ds_read_b128 v[150:153], v35 offset:256
	ds_read_b128 v[154:157], v35 offset:272
	ds_read_b128 v[158:161], v35 offset:288
	ds_read_b128 v[162:165], v35 offset:304
	v_mul_f32_e32 v38, v17, v179
	v_mul_f32_e32 v39, v21, v181
	v_fmac_f32_e32 v38, v20, v178
	v_fmac_f32_e32 v39, v18, v180
	v_add_f32_e32 v38, v38, v39
	v_add_f32_e32 v37, v37, v38
	v_mul_f32_e64 v38, |v37|, s84
	v_exp_f32_e32 v38, v38
	v_min_f32_e32 v37, 0, v37
	v_add_f32_e32 v38, 1.0, v38
	v_cmp_gt_f32_e32 vcc, s85, v38
	s_nop 1
	v_cndmask_b32_e64 v39, 0, 32, vcc
	v_ldexp_f32 v38, v38, v39
	v_log_f32_e32 v38, v38
	s_nop 0
	v_mul_f32_e32 v39, 0x3f317217, v38
	v_fma_f32 v39, v38, s86, -v39
	v_fmac_f32_e32 v39, 0x3377d1cf, v38
	v_fmac_f32_e32 v39, 0x3f317217, v38
	v_cmp_lt_f32_e64 s[36:37], |v38|, s87
	s_nop 1
	v_cndmask_b32_e64 v38, v38, v39, s[36:37]
	v_cndmask_b32_e32 v39, 0, v95, vcc
	v_sub_f32_e32 v38, v38, v39
	v_sub_f32_e32 v37, v37, v38
	v_fmac_f32_e32 v36, 0x3d800000, v37
	ds_write_b32 v16, v36 offset:1584
	s_waitcnt lgkmcnt(3)
	v_mul_f32_e32 v37, v31, v151
	v_fmac_f32_e32 v37, v28, v150
	v_mul_f32_e32 v38, v30, v153
	v_fmac_f32_e32 v38, v26, v152
	v_add_f32_e32 v37, v37, v38
	s_waitcnt lgkmcnt(2)
	v_mul_f32_e32 v38, v27, v155
	v_mul_f32_e32 v39, v32, v157
	v_fmac_f32_e32 v38, v23, v154
	v_fmac_f32_e32 v39, v29, v156
	v_add_f32_e32 v37, v33, v37
	v_add_f32_e32 v38, v38, v39
	v_add_f32_e32 v37, v37, v38
	s_waitcnt lgkmcnt(1)
	v_mul_f32_e32 v38, v19, v159
	v_mul_f32_e32 v39, v25, v161
	v_fmac_f32_e32 v38, v24, v158
	v_fmac_f32_e32 v39, v22, v160
	v_add_f32_e32 v38, v38, v39
	v_add_f32_e32 v37, v37, v38
	s_waitcnt lgkmcnt(0)
	ds_read_b128 v[166:169], v35 offset:320
	ds_read_b128 v[170:173], v35 offset:336
	ds_read_b128 v[174:177], v35 offset:352
	ds_read_b128 v[178:181], v35 offset:368
	v_mul_f32_e32 v38, v17, v163
	v_mul_f32_e32 v39, v21, v165
	v_fmac_f32_e32 v38, v20, v162
	v_fmac_f32_e32 v39, v18, v164
	v_add_f32_e32 v38, v38, v39
	v_add_f32_e32 v37, v37, v38
	v_mul_f32_e64 v38, |v37|, s84
	v_exp_f32_e32 v38, v38
	v_min_f32_e32 v37, 0, v37
	v_add_f32_e32 v38, 1.0, v38
	v_cmp_gt_f32_e32 vcc, s85, v38
	s_nop 1
	v_cndmask_b32_e64 v39, 0, 32, vcc
	v_ldexp_f32 v38, v38, v39
	v_log_f32_e32 v38, v38
	s_nop 0
	v_mul_f32_e32 v39, 0x3f317217, v38
	v_fma_f32 v39, v38, s86, -v39
	v_fmac_f32_e32 v39, 0x3377d1cf, v38
	v_fmac_f32_e32 v39, 0x3f317217, v38
	v_cmp_lt_f32_e64 s[36:37], |v38|, s87
	s_nop 1
	v_cndmask_b32_e64 v38, v38, v39, s[36:37]
	v_cndmask_b32_e32 v39, 0, v95, vcc
	v_sub_f32_e32 v38, v38, v39
	v_sub_f32_e32 v37, v37, v38
	v_fmac_f32_e32 v36, 0x3d800000, v37
	ds_write_b32 v16, v36 offset:2112
	s_waitcnt lgkmcnt(3)
; #define LAS __attribute__((address_space(3)))
; __device__ __forceinline__ void gla_cumdecay(const Ptrs& A, int l, int n, int hd, LAS float* bl, const int wv0) {
;     ...
;     for (int tt = 0; tt < 16; ++tt) {
;         float pre = bias;
;         const f32x4 g0 = *(const LAS f32x4*)(ga + tt * 16), g1 = *(const LAS f32x4*)(ga + tt * 16 + 4), g2 = *(const LAS f32x4*)(ga + tt * 16 + 8), g3 = *(const LAS f32x4*)(ga + tt * 16 + 12);
;         pre += (g0.x * w[0] + g0.y * w[1]) + (g0.z * w[2] + g0.w * w[3]); pre += (g1.x * w[4] + g1.y * w[5]) + (g1.z * w[6] + g1.w * w[7]);
;         pre += (g2.x * w[8] + g2.y * w[9]) + (g2.z * w[10] + g2.w * w[11]); pre += (g3.x * w[12] + g3.y * w[13]) + (g3.z * w[14] + g3.w * w[15]);
;         const float la = (fminf(pre, 0.f) - __logf(1.0f + __expf(-fabsf(pre)))) * (1.0f / 16.0f);
;         run += la; bl[(16 * tq + tt) * BLS + d] = run;
	v_mul_f32_e32 v37, v31, v167
	v_fmac_f32_e32 v37, v28, v166
	v_mul_f32_e32 v38, v30, v169
	v_fmac_f32_e32 v38, v26, v168
	v_add_f32_e32 v37, v37, v38
	s_waitcnt lgkmcnt(2)
	v_mul_f32_e32 v38, v27, v171
	v_mul_f32_e32 v39, v32, v173
	v_fmac_f32_e32 v38, v23, v170
	v_fmac_f32_e32 v39, v29, v172
	v_add_f32_e32 v37, v33, v37
	v_add_f32_e32 v38, v38, v39
	v_add_f32_e32 v37, v37, v38
	s_waitcnt lgkmcnt(1)
	v_mul_f32_e32 v38, v19, v175
	v_mul_f32_e32 v39, v25, v177
	v_fmac_f32_e32 v38, v24, v174
	v_fmac_f32_e32 v39, v22, v176
	v_add_f32_e32 v38, v38, v39
	v_add_f32_e32 v37, v37, v38
	s_waitcnt lgkmcnt(0)
	ds_read_b128 v[150:153], v35 offset:384
	ds_read_b128 v[154:157], v35 offset:400
	ds_read_b128 v[158:161], v35 offset:416
	ds_read_b128 v[162:165], v35 offset:432
	v_mul_f32_e32 v38, v17, v179
	v_mul_f32_e32 v39, v21, v181
	v_fmac_f32_e32 v38, v20, v178
	v_fmac_f32_e32 v39, v18, v180
	v_add_f32_e32 v38, v38, v39
	v_add_f32_e32 v37, v37, v38
	v_mul_f32_e64 v38, |v37|, s84
	v_exp_f32_e32 v38, v38
	v_min_f32_e32 v37, 0, v37
	v_add_f32_e32 v38, 1.0, v38
	v_cmp_gt_f32_e32 vcc, s85, v38
	s_nop 1
	v_cndmask_b32_e64 v39, 0, 32, vcc
	v_ldexp_f32 v38, v38, v39
	v_log_f32_e32 v38, v38
	s_nop 0
	v_mul_f32_e32 v39, 0x3f317217, v38
	v_fma_f32 v39, v38, s86, -v39
	v_fmac_f32_e32 v39, 0x3377d1cf, v38
	v_fmac_f32_e32 v39, 0x3f317217, v38
	v_cmp_lt_f32_e64 s[36:37], |v38|, s87
	s_nop 1
	v_cndmask_b32_e64 v38, v38, v39, s[36:37]
	v_cndmask_b32_e32 v39, 0, v95, vcc
	v_sub_f32_e32 v38, v38, v39
	v_sub_f32_e32 v37, v37, v38
	v_fmac_f32_e32 v36, 0x3d800000, v37
	ds_write_b32 v16, v36 offset:2640
	s_waitcnt lgkmcnt(3)
	v_mul_f32_e32 v37, v31, v151
	v_fmac_f32_e32 v37, v28, v150
	v_mul_f32_e32 v38, v30, v153
	v_fmac_f32_e32 v38, v26, v152
	v_add_f32_e32 v37, v37, v38
	s_waitcnt lgkmcnt(2)
	v_mul_f32_e32 v38, v27, v155
	v_mul_f32_e32 v39, v32, v157
	v_fmac_f32_e32 v38, v23, v154
	v_fmac_f32_e32 v39, v29, v156
	v_add_f32_e32 v37, v33, v37
	v_add_f32_e32 v38, v38, v39
	v_add_f32_e32 v37, v37, v38
	s_waitcnt lgkmcnt(1)
	v_mul_f32_e32 v38, v19, v159
	v_mul_f32_e32 v39, v25, v161
	v_fmac_f32_e32 v38, v24, v158
	v_fmac_f32_e32 v39, v22, v160
	v_add_f32_e32 v38, v38, v39
	v_add_f32_e32 v37, v37, v38
	s_waitcnt lgkmcnt(0)
	ds_read_b128 v[166:169], v35 offset:448
	ds_read_b128 v[170:173], v35 offset:464
	ds_read_b128 v[174:177], v35 offset:480
	ds_read_b128 v[178:181], v35 offset:496
	v_mul_f32_e32 v38, v17, v163
	v_mul_f32_e32 v39, v21, v165
	v_fmac_f32_e32 v38, v20, v162
	v_fmac_f32_e32 v39, v18, v164
	v_add_f32_e32 v38, v38, v39
	v_add_f32_e32 v37, v37, v38
	v_mul_f32_e64 v38, |v37|, s84
	v_exp_f32_e32 v38, v38
	v_min_f32_e32 v37, 0, v37
	v_add_f32_e32 v38, 1.0, v38
	v_cmp_gt_f32_e32 vcc, s85, v38
	s_nop 1
	v_cndmask_b32_e64 v39, 0, 32, vcc
	v_ldexp_f32 v38, v38, v39
	v_log_f32_e32 v38, v38
	s_nop 0
	v_mul_f32_e32 v39, 0x3f317217, v38
	v_fma_f32 v39, v38, s86, -v39
	v_fmac_f32_e32 v39, 0x3377d1cf, v38
	v_fmac_f32_e32 v39, 0x3f317217, v38
	v_cmp_lt_f32_e64 s[36:37], |v38|, s87
	s_nop 1
	v_cndmask_b32_e64 v38, v38, v39, s[36:37]
	v_cndmask_b32_e32 v39, 0, v95, vcc
	v_sub_f32_e32 v38, v38, v39
	v_sub_f32_e32 v37, v37, v38
	v_fmac_f32_e32 v36, 0x3d800000, v37
	ds_write_b32 v16, v36 offset:3168
	s_waitcnt lgkmcnt(3)
	v_mul_f32_e32 v37, v31, v167
	v_fmac_f32_e32 v37, v28, v166
	v_mul_f32_e32 v38, v30, v169
	v_fmac_f32_e32 v38, v26, v168
	v_add_f32_e32 v37, v37, v38
	s_waitcnt lgkmcnt(2)
	v_mul_f32_e32 v38, v27, v171
	v_mul_f32_e32 v39, v32, v173
	v_fmac_f32_e32 v38, v23, v170
	v_fmac_f32_e32 v39, v29, v172
	v_add_f32_e32 v37, v33, v37
	v_add_f32_e32 v38, v38, v39
	v_add_f32_e32 v37, v37, v38
	s_waitcnt lgkmcnt(1)
	v_mul_f32_e32 v38, v19, v175
	v_mul_f32_e32 v39, v25, v177
	v_fmac_f32_e32 v38, v24, v174
	v_fmac_f32_e32 v39, v22, v176
	v_add_f32_e32 v38, v38, v39
	v_add_f32_e32 v37, v37, v38
	s_waitcnt lgkmcnt(0)
	ds_read_b128 v[150:153], v35 offset:512
	ds_read_b128 v[154:157], v35 offset:528
	ds_read_b128 v[158:161], v35 offset:544
	ds_read_b128 v[162:165], v35 offset:560
	v_mul_f32_e32 v38, v17, v179
	v_mul_f32_e32 v39, v21, v181
	v_fmac_f32_e32 v38, v20, v178
	v_fmac_f32_e32 v39, v18, v180
	v_add_f32_e32 v38, v38, v39
	v_add_f32_e32 v37, v37, v38
	v_mul_f32_e64 v38, |v37|, s84
	v_exp_f32_e32 v38, v38
	v_min_f32_e32 v37, 0, v37
	v_add_f32_e32 v38, 1.0, v38
	v_cmp_gt_f32_e32 vcc, s85, v38
	s_nop 1
	v_cndmask_b32_e64 v39, 0, 32, vcc
	v_ldexp_f32 v38, v38, v39
	v_log_f32_e32 v38, v38
	s_nop 0
	v_mul_f32_e32 v39, 0x3f317217, v38
	v_fma_f32 v39, v38, s86, -v39
	v_fmac_f32_e32 v39, 0x3377d1cf, v38
	v_fmac_f32_e32 v39, 0x3f317217, v38
	v_cmp_lt_f32_e64 s[36:37], |v38|, s87
	s_nop 1
	v_cndmask_b32_e64 v38, v38, v39, s[36:37]
	v_cndmask_b32_e32 v39, 0, v95, vcc
	v_sub_f32_e32 v38, v38, v39
	v_sub_f32_e32 v37, v37, v38
	v_fmac_f32_e32 v36, 0x3d800000, v37
	ds_write_b32 v16, v36 offset:3696
	s_waitcnt lgkmcnt(3)
	v_mul_f32_e32 v37, v31, v151
	v_fmac_f32_e32 v37, v28, v150
	v_mul_f32_e32 v38, v30, v153
	v_fmac_f32_e32 v38, v26, v152
	v_add_f32_e32 v37, v37, v38
	s_waitcnt lgkmcnt(2)
	v_mul_f32_e32 v38, v27, v155
	v_mul_f32_e32 v39, v32, v157
	v_fmac_f32_e32 v38, v23, v154
	v_fmac_f32_e32 v39, v29, v156
	v_add_f32_e32 v37, v33, v37
	v_add_f32_e32 v38, v38, v39
	v_add_f32_e32 v37, v37, v38
	s_waitcnt lgkmcnt(1)
	v_mul_f32_e32 v38, v19, v159
	v_mul_f32_e32 v39, v25, v161
	v_fmac_f32_e32 v38, v24, v158
	v_fmac_f32_e32 v39, v22, v160
	v_add_f32_e32 v38, v38, v39
	v_add_f32_e32 v37, v37, v38
	s_waitcnt lgkmcnt(0)
; #define LAS __attribute__((address_space(3)))
; __device__ __forceinline__ void gla_cumdecay(const Ptrs& A, int l, int n, int hd, LAS float* bl, const int wv0) {
;     ...
;     for (int tt = 0; tt < 16; ++tt) {
;         float pre = bias;
;         const f32x4 g0 = *(const LAS f32x4*)(ga + tt * 16), g1 = *(const LAS f32x4*)(ga + tt * 16 + 4), g2 = *(const LAS f32x4*)(ga + tt * 16 + 8), g3 = *(const LAS f32x4*)(ga + tt * 16 + 12);
;         pre += (g0.x * w[0] + g0.y * w[1]) + (g0.z * w[2] + g0.w * w[3]); pre += (g1.x * w[4] + g1.y * w[5]) + (g1.z * w[6] + g1.w * w[7]);
;         pre += (g2.x * w[8] + g2.y * w[9]) + (g2.z * w[10] + g2.w * w[11]); pre += (g3.x * w[12] + g3.y * w[13]) + (g3.z * w[14] + g3.w * w[15]);
;         const float la = (fminf(pre, 0.f) - __logf(1.0f + __expf(-fabsf(pre)))) * (1.0f / 16.0f);
;         run += la; bl[(16 * tq + tt) * BLS + d] = run;
	ds_read_b128 v[166:169], v35 offset:576
	ds_read_b128 v[170:173], v35 offset:592
	ds_read_b128 v[174:177], v35 offset:608
	ds_read_b128 v[178:181], v35 offset:624
	v_mul_f32_e32 v38, v17, v163
	v_mul_f32_e32 v39, v21, v165
	v_fmac_f32_e32 v38, v20, v162
	v_fmac_f32_e32 v39, v18, v164
	v_add_f32_e32 v38, v38, v39
	v_add_f32_e32 v37, v37, v38
	v_mul_f32_e64 v38, |v37|, s84
	v_exp_f32_e32 v38, v38
	v_min_f32_e32 v37, 0, v37
	v_add_f32_e32 v38, 1.0, v38
	v_cmp_gt_f32_e32 vcc, s85, v38
	s_nop 1
	v_cndmask_b32_e64 v39, 0, 32, vcc
	v_ldexp_f32 v38, v38, v39
	v_log_f32_e32 v38, v38
	s_nop 0
	v_mul_f32_e32 v39, 0x3f317217, v38
	v_fma_f32 v39, v38, s86, -v39
	v_fmac_f32_e32 v39, 0x3377d1cf, v38
	v_fmac_f32_e32 v39, 0x3f317217, v38
	v_cmp_lt_f32_e64 s[36:37], |v38|, s87
	s_nop 1
	v_cndmask_b32_e64 v38, v38, v39, s[36:37]
	v_cndmask_b32_e32 v39, 0, v95, vcc
	v_sub_f32_e32 v38, v38, v39
	v_sub_f32_e32 v37, v37, v38
	v_fmac_f32_e32 v36, 0x3d800000, v37
	ds_write_b32 v16, v36 offset:4224
	s_waitcnt lgkmcnt(3)
	v_mul_f32_e32 v37, v31, v167
	v_fmac_f32_e32 v37, v28, v166
	v_mul_f32_e32 v38, v30, v169
	v_fmac_f32_e32 v38, v26, v168
	v_add_f32_e32 v37, v37, v38
	s_waitcnt lgkmcnt(2)
	v_mul_f32_e32 v38, v27, v171
	v_mul_f32_e32 v39, v32, v173
	v_fmac_f32_e32 v38, v23, v170
	v_fmac_f32_e32 v39, v29, v172
	v_add_f32_e32 v37, v33, v37
	v_add_f32_e32 v38, v38, v39
	v_add_f32_e32 v37, v37, v38
	s_waitcnt lgkmcnt(1)
	v_mul_f32_e32 v38, v19, v175
	v_mul_f32_e32 v39, v25, v177
	v_fmac_f32_e32 v38, v24, v174
	v_fmac_f32_e32 v39, v22, v176
	v_add_f32_e32 v38, v38, v39
	v_add_f32_e32 v37, v37, v38
	s_waitcnt lgkmcnt(0)
	ds_read_b128 v[150:153], v35 offset:640
	ds_read_b128 v[154:157], v35 offset:656
	ds_read_b128 v[158:161], v35 offset:672
	ds_read_b128 v[162:165], v35 offset:688
	v_mul_f32_e32 v38, v17, v179
	v_mul_f32_e32 v39, v21, v181
	v_fmac_f32_e32 v38, v20, v178
	v_fmac_f32_e32 v39, v18, v180
	v_add_f32_e32 v38, v38, v39
	v_add_f32_e32 v37, v37, v38
	v_mul_f32_e64 v38, |v37|, s84
	v_exp_f32_e32 v38, v38
	v_min_f32_e32 v37, 0, v37
	v_add_f32_e32 v38, 1.0, v38
	v_cmp_gt_f32_e32 vcc, s85, v38
	s_nop 1
	v_cndmask_b32_e64 v39, 0, 32, vcc
	v_ldexp_f32 v38, v38, v39
	v_log_f32_e32 v38, v38
	s_nop 0
	v_mul_f32_e32 v39, 0x3f317217, v38
	v_fma_f32 v39, v38, s86, -v39
	v_fmac_f32_e32 v39, 0x3377d1cf, v38
	v_fmac_f32_e32 v39, 0x3f317217, v38
	v_cmp_lt_f32_e64 s[36:37], |v38|, s87
	s_nop 1
	v_cndmask_b32_e64 v38, v38, v39, s[36:37]
	v_cndmask_b32_e32 v39, 0, v95, vcc
	v_sub_f32_e32 v38, v38, v39
	v_sub_f32_e32 v37, v37, v38
	v_fmac_f32_e32 v36, 0x3d800000, v37
	ds_write_b32 v16, v36 offset:4752
	s_waitcnt lgkmcnt(3)
	v_mul_f32_e32 v37, v31, v151
	v_fmac_f32_e32 v37, v28, v150
	v_mul_f32_e32 v38, v30, v153
	v_fmac_f32_e32 v38, v26, v152
	v_add_f32_e32 v37, v37, v38
	s_waitcnt lgkmcnt(2)
	v_mul_f32_e32 v38, v27, v155
	v_mul_f32_e32 v39, v32, v157
	v_fmac_f32_e32 v38, v23, v154
	v_fmac_f32_e32 v39, v29, v156
	v_add_f32_e32 v37, v33, v37
	v_add_f32_e32 v38, v38, v39
	v_add_f32_e32 v37, v37, v38
	s_waitcnt lgkmcnt(1)
	v_mul_f32_e32 v38, v19, v159
	v_mul_f32_e32 v39, v25, v161
	v_fmac_f32_e32 v38, v24, v158
	v_fmac_f32_e32 v39, v22, v160
	v_add_f32_e32 v38, v38, v39
	v_add_f32_e32 v37, v37, v38
	s_waitcnt lgkmcnt(0)
	ds_read_b128 v[166:169], v35 offset:704
	ds_read_b128 v[170:173], v35 offset:720
	ds_read_b128 v[174:177], v35 offset:736
	ds_read_b128 v[178:181], v35 offset:752
	v_mul_f32_e32 v38, v17, v163
	v_mul_f32_e32 v39, v21, v165
	v_fmac_f32_e32 v38, v20, v162
	v_fmac_f32_e32 v39, v18, v164
	v_add_f32_e32 v38, v38, v39
	v_add_f32_e32 v37, v37, v38
	v_mul_f32_e64 v38, |v37|, s84
	v_exp_f32_e32 v38, v38
	v_min_f32_e32 v37, 0, v37
	v_add_f32_e32 v38, 1.0, v38
	v_cmp_gt_f32_e32 vcc, s85, v38
	s_nop 1
	v_cndmask_b32_e64 v39, 0, 32, vcc
	v_ldexp_f32 v38, v38, v39
	v_log_f32_e32 v38, v38
	s_nop 0
	v_mul_f32_e32 v39, 0x3f317217, v38
	v_fma_f32 v39, v38, s86, -v39
	v_fmac_f32_e32 v39, 0x3377d1cf, v38
	v_fmac_f32_e32 v39, 0x3f317217, v38
	v_cmp_lt_f32_e64 s[36:37], |v38|, s87
	s_nop 1
	v_cndmask_b32_e64 v38, v38, v39, s[36:37]
	v_cndmask_b32_e32 v39, 0, v95, vcc
	v_sub_f32_e32 v38, v38, v39
	v_sub_f32_e32 v37, v37, v38
	v_fmac_f32_e32 v36, 0x3d800000, v37
	ds_write_b32 v16, v36 offset:5280
	s_waitcnt lgkmcnt(3)
	v_mul_f32_e32 v37, v31, v167
	v_fmac_f32_e32 v37, v28, v166
	v_mul_f32_e32 v38, v30, v169
	v_fmac_f32_e32 v38, v26, v168
	v_add_f32_e32 v37, v37, v38
	s_waitcnt lgkmcnt(2)
	v_mul_f32_e32 v38, v27, v171
	v_mul_f32_e32 v39, v32, v173
	v_fmac_f32_e32 v38, v23, v170
	v_fmac_f32_e32 v39, v29, v172
	v_add_f32_e32 v37, v33, v37
	v_add_f32_e32 v38, v38, v39
	v_add_f32_e32 v37, v37, v38
	s_waitcnt lgkmcnt(1)
	v_mul_f32_e32 v38, v19, v175
	v_mul_f32_e32 v39, v25, v177
	v_fmac_f32_e32 v38, v24, v174
	v_fmac_f32_e32 v39, v22, v176
	v_add_f32_e32 v38, v38, v39
	v_add_f32_e32 v37, v37, v38
	s_waitcnt lgkmcnt(0)
	ds_read_b128 v[150:153], v35 offset:768
	ds_read_b128 v[154:157], v35 offset:784
	ds_read_b128 v[158:161], v35 offset:800
	ds_read_b128 v[162:165], v35 offset:816
	v_mul_f32_e32 v38, v17, v179
	v_mul_f32_e32 v39, v21, v181
	v_fmac_f32_e32 v38, v20, v178
	v_fmac_f32_e32 v39, v18, v180
	v_add_f32_e32 v38, v38, v39
	v_add_f32_e32 v37, v37, v38
	v_mul_f32_e64 v38, |v37|, s84
	v_exp_f32_e32 v38, v38
	v_min_f32_e32 v37, 0, v37
	v_add_f32_e32 v38, 1.0, v38
	v_cmp_gt_f32_e32 vcc, s85, v38
	s_nop 1
	v_cndmask_b32_e64 v39, 0, 32, vcc
	v_ldexp_f32 v38, v38, v39
	v_log_f32_e32 v38, v38
	s_nop 0
	v_mul_f32_e32 v39, 0x3f317217, v38
	v_fma_f32 v39, v38, s86, -v39
	v_fmac_f32_e32 v39, 0x3377d1cf, v38
	v_fmac_f32_e32 v39, 0x3f317217, v38
	v_cmp_lt_f32_e64 s[36:37], |v38|, s87
	s_nop 1
	v_cndmask_b32_e64 v38, v38, v39, s[36:37]
	v_cndmask_b32_e32 v39, 0, v95, vcc
	v_sub_f32_e32 v38, v38, v39
	v_sub_f32_e32 v37, v37, v38
	v_fmac_f32_e32 v36, 0x3d800000, v37
	ds_write_b32 v16, v36 offset:5808
	s_waitcnt lgkmcnt(3)
; #define LAS __attribute__((address_space(3)))
; __device__ __forceinline__ void gla_cumdecay(const Ptrs& A, int l, int n, int hd, LAS float* bl, const int wv0) {
;     ...
;     for (int tt = 0; tt < 16; ++tt) {
;         float pre = bias;
;         const f32x4 g0 = *(const LAS f32x4*)(ga + tt * 16), g1 = *(const LAS f32x4*)(ga + tt * 16 + 4), g2 = *(const LAS f32x4*)(ga + tt * 16 + 8), g3 = *(const LAS f32x4*)(ga + tt * 16 + 12);
;         pre += (g0.x * w[0] + g0.y * w[1]) + (g0.z * w[2] + g0.w * w[3]); pre += (g1.x * w[4] + g1.y * w[5]) + (g1.z * w[6] + g1.w * w[7]);
;         pre += (g2.x * w[8] + g2.y * w[9]) + (g2.z * w[10] + g2.w * w[11]); pre += (g3.x * w[12] + g3.y * w[13]) + (g3.z * w[14] + g3.w * w[15]);
;         const float la = (fminf(pre, 0.f) - __logf(1.0f + __expf(-fabsf(pre)))) * (1.0f / 16.0f);
;         run += la; bl[(16 * tq + tt) * BLS + d] = run;
;     }
;     __syncthreads();
;     float add = 0.f;
; #pragma unroll
;     for (int q = 0; q < 3; ++q) if (q < tq) add += bl[(16 * q + 15) * BLS + d];
	v_mul_f32_e32 v37, v31, v151
	v_fmac_f32_e32 v37, v28, v150
	v_mul_f32_e32 v38, v30, v153
	v_fmac_f32_e32 v38, v26, v152
	v_add_f32_e32 v37, v37, v38
	s_waitcnt lgkmcnt(2)
	v_mul_f32_e32 v38, v27, v155
	v_mul_f32_e32 v39, v32, v157
	v_fmac_f32_e32 v38, v23, v154
	v_fmac_f32_e32 v39, v29, v156
	v_add_f32_e32 v37, v33, v37
	v_add_f32_e32 v38, v38, v39
	v_add_f32_e32 v37, v37, v38
	s_waitcnt lgkmcnt(1)
	v_mul_f32_e32 v38, v19, v159
	v_mul_f32_e32 v39, v25, v161
	v_fmac_f32_e32 v38, v24, v158
	v_fmac_f32_e32 v39, v22, v160
	v_add_f32_e32 v38, v38, v39
	v_add_f32_e32 v37, v37, v38
	s_waitcnt lgkmcnt(0)
	ds_read_b128 v[166:169], v35 offset:832
	ds_read_b128 v[170:173], v35 offset:848
	ds_read_b128 v[174:177], v35 offset:864
	ds_read_b128 v[178:181], v35 offset:880
	v_mul_f32_e32 v38, v17, v163
	v_mul_f32_e32 v39, v21, v165
	v_fmac_f32_e32 v38, v20, v162
	v_fmac_f32_e32 v39, v18, v164
	v_add_f32_e32 v38, v38, v39
	v_add_f32_e32 v37, v37, v38
	v_mul_f32_e64 v38, |v37|, s84
	v_exp_f32_e32 v38, v38
	v_min_f32_e32 v37, 0, v37
	v_add_f32_e32 v38, 1.0, v38
	v_cmp_gt_f32_e32 vcc, s85, v38
	s_nop 1
	v_cndmask_b32_e64 v39, 0, 32, vcc
	v_ldexp_f32 v38, v38, v39
	v_log_f32_e32 v38, v38
	s_nop 0
	v_mul_f32_e32 v39, 0x3f317217, v38
	v_fma_f32 v39, v38, s86, -v39
	v_fmac_f32_e32 v39, 0x3377d1cf, v38
	v_fmac_f32_e32 v39, 0x3f317217, v38
	v_cmp_lt_f32_e64 s[36:37], |v38|, s87
	s_nop 1
	v_cndmask_b32_e64 v38, v38, v39, s[36:37]
	v_cndmask_b32_e32 v39, 0, v95, vcc
	v_sub_f32_e32 v38, v38, v39
	v_sub_f32_e32 v37, v37, v38
	v_fmac_f32_e32 v36, 0x3d800000, v37
	ds_write_b32 v16, v36 offset:6336
	s_waitcnt lgkmcnt(3)
	v_mul_f32_e32 v37, v31, v167
	v_fmac_f32_e32 v37, v28, v166
	v_mul_f32_e32 v38, v30, v169
	v_fmac_f32_e32 v38, v26, v168
	v_add_f32_e32 v37, v37, v38
	s_waitcnt lgkmcnt(2)
	v_mul_f32_e32 v38, v27, v171
	v_mul_f32_e32 v39, v32, v173
	v_fmac_f32_e32 v38, v23, v170
	v_fmac_f32_e32 v39, v29, v172
	v_add_f32_e32 v37, v33, v37
	v_add_f32_e32 v38, v38, v39
	v_add_f32_e32 v37, v37, v38
	s_waitcnt lgkmcnt(1)
	v_mul_f32_e32 v38, v19, v175
	v_mul_f32_e32 v39, v25, v177
	v_fmac_f32_e32 v38, v24, v174
	v_fmac_f32_e32 v39, v22, v176
	v_add_f32_e32 v38, v38, v39
	v_add_f32_e32 v37, v37, v38
	s_waitcnt lgkmcnt(0)
	ds_read_b128 v[150:153], v35 offset:896
	ds_read_b128 v[154:157], v35 offset:912
	ds_read_b128 v[158:161], v35 offset:928
	ds_read_b128 v[162:165], v35 offset:944
	v_mul_f32_e32 v38, v17, v179
	v_mul_f32_e32 v39, v21, v181
	v_fmac_f32_e32 v38, v20, v178
	v_fmac_f32_e32 v39, v18, v180
	v_add_f32_e32 v38, v38, v39
	v_add_f32_e32 v37, v37, v38
	v_mul_f32_e64 v38, |v37|, s84
	v_exp_f32_e32 v38, v38
	v_min_f32_e32 v37, 0, v37
	v_add_f32_e32 v38, 1.0, v38
	v_cmp_gt_f32_e32 vcc, s85, v38
	s_nop 1
	v_cndmask_b32_e64 v39, 0, 32, vcc
	v_ldexp_f32 v38, v38, v39
	v_log_f32_e32 v38, v38
	s_nop 0
	v_mul_f32_e32 v39, 0x3f317217, v38
	v_fma_f32 v39, v38, s86, -v39
	v_fmac_f32_e32 v39, 0x3377d1cf, v38
	v_fmac_f32_e32 v39, 0x3f317217, v38
	v_cmp_lt_f32_e64 s[36:37], |v38|, s87
	s_nop 1
	v_cndmask_b32_e64 v38, v38, v39, s[36:37]
	v_cndmask_b32_e32 v39, 0, v95, vcc
	v_sub_f32_e32 v38, v38, v39
	v_sub_f32_e32 v37, v37, v38
	v_fmac_f32_e32 v36, 0x3d800000, v37
	ds_write_b32 v16, v36 offset:6864
	s_waitcnt lgkmcnt(3)
	v_mul_f32_e32 v37, v31, v151
	v_fmac_f32_e32 v37, v28, v150
	v_mul_f32_e32 v38, v30, v153
	v_fmac_f32_e32 v38, v26, v152
	v_add_f32_e32 v37, v37, v38
	s_waitcnt lgkmcnt(2)
	v_mul_f32_e32 v38, v27, v155
	v_mul_f32_e32 v39, v32, v157
	v_fmac_f32_e32 v38, v23, v154
	v_fmac_f32_e32 v39, v29, v156
	v_add_f32_e32 v37, v33, v37
	v_add_f32_e32 v38, v38, v39
	v_add_f32_e32 v37, v37, v38
	s_waitcnt lgkmcnt(1)
	v_mul_f32_e32 v38, v19, v159
	v_mul_f32_e32 v39, v25, v161
	v_fmac_f32_e32 v38, v24, v158
	v_fmac_f32_e32 v39, v22, v160
	v_add_f32_e32 v38, v38, v39
	v_add_f32_e32 v37, v37, v38
	s_waitcnt lgkmcnt(0)
	ds_read_b128 v[166:169], v35 offset:960
	ds_read_b128 v[170:173], v35 offset:976
	ds_read_b128 v[174:177], v35 offset:992
	ds_read_b128 v[178:181], v35 offset:1008
	v_mul_f32_e32 v38, v17, v163
	v_mul_f32_e32 v39, v21, v165
	v_fmac_f32_e32 v38, v20, v162
	v_fmac_f32_e32 v39, v18, v164
	v_add_f32_e32 v38, v38, v39
	v_add_f32_e32 v37, v37, v38
	v_mul_f32_e64 v38, |v37|, s84
	v_exp_f32_e32 v38, v38
	v_min_f32_e32 v37, 0, v37
	v_add_f32_e32 v38, 1.0, v38
	v_cmp_gt_f32_e32 vcc, s85, v38
	s_nop 1
	v_cndmask_b32_e64 v39, 0, 32, vcc
	v_ldexp_f32 v38, v38, v39
	v_log_f32_e32 v38, v38
	s_nop 0
	v_mul_f32_e32 v39, 0x3f317217, v38
	v_fma_f32 v39, v38, s86, -v39
	v_fmac_f32_e32 v39, 0x3377d1cf, v38
	v_fmac_f32_e32 v39, 0x3f317217, v38
	v_cmp_lt_f32_e64 s[36:37], |v38|, s87
	s_nop 1
	v_cndmask_b32_e64 v38, v38, v39, s[36:37]
	v_cndmask_b32_e32 v39, 0, v95, vcc
	v_sub_f32_e32 v38, v38, v39
	v_sub_f32_e32 v37, v37, v38
	v_fmac_f32_e32 v36, 0x3d800000, v37
	ds_write_b32 v16, v36 offset:7392
	s_waitcnt lgkmcnt(3)
	v_mul_f32_e32 v31, v31, v167
	v_fmac_f32_e32 v31, v28, v166
	v_mul_f32_e32 v28, v30, v169
	s_waitcnt lgkmcnt(2)
	v_mul_f32_e32 v27, v27, v171
	v_fmac_f32_e32 v28, v26, v168
	v_fmac_f32_e32 v27, v23, v170
	v_mul_f32_e32 v23, v32, v173
	s_waitcnt lgkmcnt(1)
	v_mul_f32_e32 v19, v19, v175
	v_add_f32_e32 v26, v31, v28
	v_fmac_f32_e32 v23, v29, v172
	v_fmac_f32_e32 v19, v24, v174
	v_mul_f32_e32 v24, v25, v177
	s_waitcnt lgkmcnt(0)
	v_mul_f32_e32 v17, v17, v179
	v_add_f32_e32 v26, v33, v26
	v_add_f32_e32 v23, v27, v23
	v_fmac_f32_e32 v24, v22, v176
	v_fmac_f32_e32 v17, v20, v178
	v_mul_f32_e32 v20, v21, v181
	v_add_f32_e32 v23, v26, v23
	v_add_f32_e32 v19, v19, v24
	v_fmac_f32_e32 v20, v18, v180
	v_add_f32_e32 v19, v23, v19
	v_add_f32_e32 v17, v17, v20
	v_add_f32_e32 v17, v19, v17
	v_mul_f32_e64 v18, |v17|, s84
	v_exp_f32_e32 v18, v18
	v_min_f32_e32 v17, 0, v17
	v_add_f32_e32 v18, 1.0, v18
	v_cmp_gt_f32_e32 vcc, s85, v18
	s_nop 1
	v_cndmask_b32_e64 v19, 0, 32, vcc
	v_ldexp_f32 v18, v18, v19
	v_log_f32_e32 v18, v18
	s_nop 0
	v_mul_f32_e32 v19, 0x3f317217, v18
	v_fma_f32 v19, v18, s86, -v19
	v_fmac_f32_e32 v19, 0x3377d1cf, v18
	v_fmac_f32_e32 v19, 0x3f317217, v18
	v_cmp_lt_f32_e64 s[36:37], |v18|, s87
	s_nop 1
	v_cndmask_b32_e64 v18, v18, v19, s[36:37]
	v_cndmask_b32_e32 v19, 0, v95, vcc
	v_sub_f32_e32 v18, v18, v19
	v_sub_f32_e32 v17, v17, v18
	s_cselect_b64 s[36:37], -1, 0
	v_fmac_f32_e32 v36, 0x3d800000, v17
	s_and_b64 vcc, exec, s[36:37]
	v_mov_b32_e32 v17, 0
	ds_write_b32 v16, v36 offset:7920
	s_waitcnt lgkmcnt(0)
	s_barrier
	s_cbranch_vccz .LBB0_1326
	ds_read_b32 v17, v34 offset:7920
	s_waitcnt lgkmcnt(0)
	v_add_f32_e32 v17, 0, v17

; #define LAS __attribute__((address_space(3)))
; __device__ __forceinline__ unsigned pk2(float lo, float hi) { return f2bf(lo) | (f2bf(hi) << 16); }
; __device__ __forceinline__ float wave_sum(float v) { return swap32_sum(red32(v)); }
;     __device__ __forceinline__ const float* in(int k) const { return (const float*)(const __attribute__((address_space(1))) float*)get(k); }
;     __device__ __forceinline__ unsigned char* ws() const { return (unsigned char*)(__attribute__((address_space(1))) unsigned char*)get(21); }
; template <bool GA, bool XBF = false>
; __device__ __forceinline__ void norm_rows(const float* X, const float* gain, bf16* H, float* GA1, const LAS float* waT, int nrows, int gw, int NGW, int lane_) {
;     ...
;     for (int m = gw; m < nrows; m += NGW) {
;         f32x4 v[8]; float s = 0.f;
;         if constexpr (XBF) { const u32x2* xb = (const u32x2*)((const bf16*)X + (size_t)m * DM) + lane;
; #pragma unroll
;             for (int j = 0; j < 8; ++j) { const u32x2 w = xb[64 * j]; v[j] = (f32x4){bflo(w.x), bfhi(w.x), bflo(w.y), bfhi(w.y)}; }
;         } else { const f32x4* xr = (const f32x4*)(X + (size_t)m * DM) + lane;
; #pragma unroll
;             for (int j = 0; j < 8; ++j) v[j] = __builtin_nontemporal_load(xr + 64 * j); }
; #pragma unroll
;         for (int j = 0; j < 8; ++j) s += (v[j].x * v[j].x + v[j].y * v[j].y) + (v[j].z * v[j].z + v[j].w * v[j].w);
;         const float rinv = 1.0f / sqrtf(wave_sum(s) * (1.0f / DM) + EPS);
;         unsigned long long* o8 = (unsigned long long*)(H + (size_t)m * DM) + lane;
; #pragma unroll
;         for (int j = 0; j < 8; ++j) { const f32x4 g = ((const f32x4*)gain)[lane + 64 * j]; v[j] = v[j] * rinv * g;
;             o8[64 * j] = (unsigned long long)pk2(v[j].x, v[j].y) | ((unsigned long long)pk2(v[j].z, v[j].w) << 32); }
; template <int l>
; __device__ __forceinline__ void layer_body(const Ptrs& A, LAS unsigned char* lds, unsigned char* lds_raw, const int wv0) {
;     ...
;         if (PH(8)) norm_rows<false, true>((const float*)(ws + WS_X), A.in(17) + (size_t)l * DM, (bf16*)(ws + WS_H), nullptr, (const LAS float*)lds, T, gw, NGW, lane);
.LBB0_1667:
	s_or_b64 exec, exec, s[0:1]
	s_waitcnt lgkmcnt(0)
	s_barrier
	v_mov_b32 v0, s77
	ds_read_b64 v[0:1], v0 offset:168
	v_mov_b32_e32 v2, v204
	s_mov_b32 s0, s76
	s_mov_b32 s1, s33
	s_waitcnt lgkmcnt(0)
	v_readfirstlane_b32 s3, v1
	v_readfirstlane_b32 s2, v0
	v_mov_b32 v0, s77
	ds_read_b64 v[0:1], v0 offset:136
	v_readfirstlane_b32 s4, v2
	s_ashr_i32 s4, s4, 6
	s_lshl_b32 s1, s1, 3
	s_add_i32 s4, s1, s4
	v_and_b32_e32 v10, 63, v2
	s_waitcnt lgkmcnt(0)
	v_readfirstlane_b32 s9, v1
	v_readfirstlane_b32 s8, v0
	s_cmpk_gt_i32 s4, 0x3fff
	s_cbranch_scc1 .LBB0_1670
	v_ashrrev_i32_e32 v11, 31, v10
	v_lshl_add_u64 v[8:9], v[10:11], 4, s[8:9]
	s_mov_b64 s[8:9], 0x2000
	v_lshl_add_u64 v[0:1], v[8:9], 0, s[8:9]
	s_mov_b64 s[8:9], 0x3000
	v_lshl_add_u64 v[2:3], v[8:9], 0, s[8:9]
	s_mov_b64 s[8:9], 0x3400
	v_lshl_add_u64 v[4:5], v[8:9], 0, s[8:9]
	s_mov_b64 s[8:9], 0x3800
	v_lshl_add_u64 v[6:7], v[8:9], 0, s[8:9]
	s_mov_b64 s[8:9], 0x3c00
	s_ashr_i32 s5, s4, 31
	s_lshl_b32 s6, s0, 3
	v_lshl_add_u64 v[8:9], v[8:9], 0, s[8:9]
	s_lshl_b64 s[8:9], s[4:5], 12
	s_add_u32 s2, s2, s8
	s_addc_u32 s3, s3, s9
	v_lshl_add_u64 v[10:11], v[10:11], 3, s[2:3]
	s_mov_b64 s[2:3], 0x2e500e00
	s_ashr_i32 s7, s6, 31
	v_cmp_eq_u32_e64 s[0:1], 32, v205
	v_lshl_add_u64 v[10:11], v[10:11], 0, s[2:3]
	s_lshl_b64 s[8:9], s[6:7], 12
	s_mov_b32 s5, 0xffff0000
	v_mov_b32_e32 v24, 0x358637bd
	s_mov_b32 s7, 0xf800000
	v_mov_b32_e32 v25, 0x260
	s_movk_i32 s10, 0x7fff
	s_mov_b32 s11, 0xdb500000
	global_load_dwordx4 v[208:211], v[0:1], off
	global_load_dwordx4 v[212:215], v[0:1], off offset:1024
	global_load_dwordx4 v[216:219], v[0:1], off offset:2048
	global_load_dwordx4 v[220:223], v[0:1], off offset:3072
	global_load_dwordx4 v[224:227], v[2:3], off
	global_load_dwordx4 v[228:231], v[4:5], off
	global_load_dwordx4 v[232:235], v[6:7], off
	global_load_dwordx4 v[236:239], v[8:9], off
	s_waitcnt vmcnt(0)
